# branch A: 7 K tiles in flight during QK (14 fragment quads) and the next block's ALiBi bias computed inside the current block's PV loop
# speedup vs baseline: 1.0392x; 1.0392x over previous
; #define LAS __attribute__((address_space(3)))
; template <bool MASK> __device__ __forceinline__ void a_scores(f32x4& S0, f32x4& S1, float basef, float c1, float slope2, int krow0, int kstart) {
; #pragma unroll
;     for (int r = 0; r < 4; ++r) {
;         const float d0 = fabsf(basef - (float)r), d1 = fabsf(basef - (float)(16 + r));
;         const float v0 = S0[r] - slope2 * d0, v1 = S1[r] - slope2 * d1;
;         if (MASK) { const int p0 = kstart + krow0 + r, p1 = p0 + 16;
;             S0[r] = (d0 <= 128.f && p0 >= 0 && p0 < SEQ) ? v0 : -INFINITY; S1[r] = (d1 <= 128.f && p1 >= 0 && p1 < SEQ) ? v1 : -INFINITY; }
;         else { S0[r] = v0; S1[r] = v1; }
;     }
; }
; __device__ __forceinline__ void attn_a_unit(LAS unsigned char* lds, const bf16* Z, bf16* Y, const float* sink, int unit) {
;     ...
;         const LAS unsigned char* kp0 = Kl + swz(qoffA + lq, g); const LAS unsigned char* kp1 = Kl + swz(qoffA + lq, 4 + g);
;         const LAS unsigned char* vp[4];
;         { const int i = lane & 15, rq4 = i >> 2, p = i & 3;
; #pragma unroll
;           for (int db = 0; db < 4; ++db) vp[db] = Vl + swz(qoffA + 4 * g + rq4, 2 * db + (p >> 1)) + 8 * (p & 1); }
;         float basef = (float)(128 + lq - 4 * g);
.LBB0_257:
	s_waitcnt vmcnt(14)
	v_and_b32_e32 v219, 15, v218
	v_bfe_u32 v244, v218, 4, 2
	v_add_u32_e32 v245, s85, v219
	v_lshlrev_b32_e32 v245, 7, v245
	v_bitop3_b32 v120, v219, v244, 7 bitop3:0x6c
	v_lshl_add_u32 v122, v120, 4, v245
	v_xor_b32_e32 v120, 4, v120
	v_lshl_add_u32 v123, v120, 4, v245
	v_lshlrev_b32_e32 v245, 2, v244
	v_sub_u32_e32 v120, v219, v245
	v_cmp_ge_i32_e64 s[16:17], 0, v120
	v_cmp_le_i32_e64 s[28:29], 0, v120
	v_cmp_ge_i32_e64 s[18:19], 1, v120
	v_cmp_le_i32_e64 s[52:53], 1, v120
	v_cmp_ge_i32_e64 s[22:23], 2, v120
	v_cmp_le_i32_e64 s[54:55], 2, v120
	v_cmp_ge_i32_e64 s[24:25], 3, v120
	v_cmp_le_i32_e64 s[88:89], 3, v120
	v_cmp_eq_u32_e64 s[74:75], 0, v244
	v_cvt_f32_i32_e32 v129, v120
	v_lshrrev_b32_e32 v120, 2, v219
	v_add_u32_e32 v245, v245, v120
	v_bfe_u32 v120, v219, 1, 1
	v_and_b32_e32 v219, 1, v219
	v_lshlrev_b32_e32 v219, 3, v219
	v_add_u32_e32 v244, s85, v245
	v_lshl_add_u32 v219, v244, 7, v219
	v_add_u32_e32 v219, 0xc800, v219
	v_or_b32_e32 v245, 0, v120
	v_bitop3_b32 v245, v244, v245, 7 bitop3:0x6c
	v_lshl_add_u32 v124, v245, 4, v219
	v_or_b32_e32 v245, 2, v120
	v_bitop3_b32 v245, v244, v245, 7 bitop3:0x6c
	v_lshl_add_u32 v125, v245, 4, v219
	v_or_b32_e32 v245, 4, v120
	v_bitop3_b32 v245, v244, v245, 7 bitop3:0x6c
	v_lshl_add_u32 v126, v245, 4, v219
	v_or_b32_e32 v245, 6, v120
	v_bitop3_b32 v245, v244, v245, 7 bitop3:0x6c
	v_lshl_add_u32 v127, v245, 4, v219
	v_mov_b32_e32 v131, s84
	v_xor_b32_e32 v130, 0x80000000, v131
	v_mov_b32_e32 v219, s76
	v_mul_f32_e32 v145, 0x3fb8aa3b, v219
	v_mul_f32_e32 v132, v130, v129
	v_mul_f32_e32 v133, v131, v129
	s_cmp_eq_u32 s77, 0
	s_cbranch_scc1 .La_edge_lo
	s_cmp_eq_u32 s77, 63
	s_cbranch_scc1 .La_edge_hi
	v_fmamk_f32 v50, v130, 0x43000000, v132
	v_fmamk_f32 v51, v130, 0x42fe0000, v132
	v_fmamk_f32 v52, v130, 0x42fc0000, v132
	v_fmamk_f32 v53, v130, 0x42fa0000, v132
	v_mov_b32_e32 v245, 0xff800000
	v_cndmask_b32_e64 v50, v245, v50, s[16:17]
	v_cndmask_b32_e64 v51, v245, v51, s[18:19]
	v_cndmask_b32_e64 v52, v245, v52, s[22:23]
	v_cndmask_b32_e64 v53, v245, v53, s[24:25]
	v_fmamk_f32 v54, v130, 0x42e00000, v132
	v_fmamk_f32 v55, v130, 0x42de0000, v132
	v_fmamk_f32 v56, v130, 0x42dc0000, v132
	v_fmamk_f32 v57, v130, 0x42da0000, v132
	v_fmamk_f32 v58, v130, 0x42c00000, v132
	v_fmamk_f32 v59, v130, 0x42be0000, v132
	v_fmamk_f32 v60, v130, 0x42bc0000, v132
	v_fmamk_f32 v61, v130, 0x42ba0000, v132
	v_fmamk_f32 v62, v130, 0x42a00000, v132
	v_fmamk_f32 v63, v130, 0x429e0000, v132
	v_fmamk_f32 v64, v130, 0x429c0000, v132
	v_fmamk_f32 v65, v130, 0x429a0000, v132
	v_fmamk_f32 v66, v130, 0x42800000, v132
	v_fmamk_f32 v67, v130, 0x427c0000, v132
	v_fmamk_f32 v68, v130, 0x42780000, v132
	v_fmamk_f32 v69, v130, 0x42740000, v132
	v_fmamk_f32 v70, v130, 0x42400000, v132
	v_fmamk_f32 v71, v130, 0x423c0000, v132
	v_fmamk_f32 v72, v130, 0x42380000, v132
	v_fmamk_f32 v73, v130, 0x42340000, v132
	v_fmamk_f32 v74, v130, 0x42000000, v132
	v_fmamk_f32 v75, v130, 0x41f80000, v132
	v_fmamk_f32 v76, v130, 0x41f00000, v132
	v_fmamk_f32 v77, v130, 0x41e80000, v132
	v_fmamk_f32 v78, v130, 0x41800000, v132
	v_fmamk_f32 v79, v130, 0x41700000, v132
	v_fmamk_f32 v80, v130, 0x41600000, v132
	v_fmamk_f32 v81, v130, 0x41500000, v132
	v_add_f32_e32 v219, 0, v129
	v_mul_f32_e64 v82, v130, |v219|
	v_add_f32_e32 v245, 0xbf800000, v129
	v_mul_f32_e64 v83, v130, |v245|
	v_add_f32_e32 v219, 0xc0000000, v129
	v_mul_f32_e64 v84, v130, |v219|
	v_add_f32_e32 v245, 0xc0400000, v129
	v_mul_f32_e64 v85, v130, |v245|
	v_fmamk_f32 v86, v131, 0xc1800000, v133
	v_fmamk_f32 v87, v131, 0xc1880000, v133
	v_fmamk_f32 v88, v131, 0xc1900000, v133
	v_fmamk_f32 v89, v131, 0xc1980000, v133
	v_fmamk_f32 v90, v131, 0xc2000000, v133
	v_fmamk_f32 v91, v131, 0xc2040000, v133
	v_fmamk_f32 v92, v131, 0xc2080000, v133
	v_fmamk_f32 v93, v131, 0xc20c0000, v133
	v_fmamk_f32 v94, v131, 0xc2400000, v133
	v_fmamk_f32 v95, v131, 0xc2440000, v133
	v_fmamk_f32 v96, v131, 0xc2480000, v133
	v_fmamk_f32 v97, v131, 0xc24c0000, v133
	v_fmamk_f32 v98, v131, 0xc2800000, v133
	v_fmamk_f32 v99, v131, 0xc2820000, v133
	v_fmamk_f32 v100, v131, 0xc2840000, v133
	v_fmamk_f32 v101, v131, 0xc2860000, v133
	v_fmamk_f32 v102, v131, 0xc2a00000, v133
	v_fmamk_f32 v103, v131, 0xc2a20000, v133
	v_fmamk_f32 v104, v131, 0xc2a40000, v133
	v_fmamk_f32 v105, v131, 0xc2a60000, v133
	v_fmamk_f32 v106, v131, 0xc2c00000, v133
	v_fmamk_f32 v107, v131, 0xc2c20000, v133
	v_fmamk_f32 v108, v131, 0xc2c40000, v133
	v_fmamk_f32 v109, v131, 0xc2c60000, v133
	v_fmamk_f32 v110, v131, 0xc2e00000, v133
	v_fmamk_f32 v111, v131, 0xc2e20000, v133
	v_fmamk_f32 v112, v131, 0xc2e40000, v133
	v_fmamk_f32 v113, v131, 0xc2e60000, v133
	v_fmamk_f32 v114, v131, 0xc3000000, v133
	v_fmamk_f32 v115, v131, 0xc3010000, v133
	v_fmamk_f32 v116, v131, 0xc3020000, v133
	v_fmamk_f32 v117, v131, 0xc3030000, v133
	v_mov_b32_e32 v245, 0xff800000
	v_cndmask_b32_e64 v114, v245, v114, s[28:29]
	v_cndmask_b32_e64 v115, v245, v115, s[52:53]
	v_cndmask_b32_e64 v116, v245, v116, s[54:55]
	v_cndmask_b32_e64 v117, v245, v117, s[88:89]
	ds_read_b128 v[186:189], v122 offset:0
	ds_read_b128 v[190:193], v123 offset:0
	ds_read_b128 v[194:197], v122 offset:2048
	ds_read_b128 v[198:201], v123 offset:2048
	ds_read_b128 v[202:205], v122 offset:4096
	ds_read_b128 v[206:209], v123 offset:4096
	ds_read_b128 v[210:213], v122 offset:6144
	ds_read_b128 v[214:217], v123 offset:6144
	ds_read_b128 v[220:223], v122 offset:8192
	ds_read_b128 v[224:227], v123 offset:8192
	ds_read_b128 v[228:231], v122 offset:10240
	ds_read_b128 v[232:235], v123 offset:10240
	ds_read_b128 v[236:239], v122 offset:12288
	ds_read_b128 v[240:243], v123 offset:12288
	s_waitcnt lgkmcnt(13)
; #define LAS __attribute__((address_space(3)))
; #define MFMA16(a, b, c) __builtin_amdgcn_mfma_f32_16x16x32_bf16((a), (b), (c), 0, 0, 0)
; __device__ __forceinline__ void qk_at(const LAS unsigned char* kp0, const LAS unsigned char* kp1, int off, bf16x8 qf0, bf16x8 qf1, f32x4& S0, f32x4& S1) {
;     const bf16x8 k00 = *(const LAS bf16x8*)(kp0 + off), k01 = *(const LAS bf16x8*)(kp1 + off);
;     const bf16x8 k10 = *(const LAS bf16x8*)(kp0 + off + 2048), k11 = *(const LAS bf16x8*)(kp1 + off + 2048);
;     const f32x4 z = {0.f, 0.f, 0.f, 0.f};
;     S0 = MFMA16(k00, qf0, z); S0 = MFMA16(k01, qf1, S0);
;     S1 = MFMA16(k10, qf0, z); S1 = MFMA16(k11, qf1, S1);
; }
; __device__ __forceinline__ void softmax_step(f32x4& s0, f32x4& s1, float& m, float& l, f32x4 (&O)[4]) {
;     float t = fmaxf(fmaxf(fmaxf(s0[0], s0[1]), fmaxf(s0[2], s0[3])), fmaxf(fmaxf(s1[0], s1[1]), fmaxf(s1[2], s1[3])));
;     t = xrow16_max(t);
	v_mfma_f32_16x16x32_bf16 v[50:53], v[186:189], v[146:149], v[50:53]
	s_waitcnt lgkmcnt(12)
	v_mfma_f32_16x16x32_bf16 v[50:53], v[190:193], v[150:153], v[50:53]
	ds_read_b128 v[186:189], v122 offset:14336
	ds_read_b128 v[190:193], v123 offset:14336
	s_waitcnt lgkmcnt(13)
	v_mfma_f32_16x16x32_bf16 v[54:57], v[194:197], v[146:149], v[54:57]
	s_waitcnt lgkmcnt(12)
	v_mfma_f32_16x16x32_bf16 v[54:57], v[198:201], v[150:153], v[54:57]
	ds_read_b128 v[194:197], v122 offset:16384
	ds_read_b128 v[198:201], v123 offset:16384
	s_waitcnt lgkmcnt(13)
	v_mfma_f32_16x16x32_bf16 v[58:61], v[202:205], v[146:149], v[58:61]
	s_waitcnt lgkmcnt(12)
	v_mfma_f32_16x16x32_bf16 v[58:61], v[206:209], v[150:153], v[58:61]
	ds_read_b128 v[202:205], v122 offset:18432
	ds_read_b128 v[206:209], v123 offset:18432
	s_waitcnt lgkmcnt(13)
	v_mfma_f32_16x16x32_bf16 v[62:65], v[210:213], v[146:149], v[62:65]
	s_waitcnt lgkmcnt(12)
	v_mfma_f32_16x16x32_bf16 v[62:65], v[214:217], v[150:153], v[62:65]
	ds_read_b128 v[210:213], v122 offset:20480
	ds_read_b128 v[214:217], v123 offset:20480
	s_waitcnt lgkmcnt(13)
	v_mfma_f32_16x16x32_bf16 v[66:69], v[220:223], v[146:149], v[66:69]
	s_waitcnt lgkmcnt(12)
	v_mfma_f32_16x16x32_bf16 v[66:69], v[224:227], v[150:153], v[66:69]
	ds_read_b128 v[220:223], v122 offset:22528
	ds_read_b128 v[224:227], v123 offset:22528
	s_waitcnt lgkmcnt(13)
	v_mfma_f32_16x16x32_bf16 v[70:73], v[228:231], v[146:149], v[70:73]
	s_waitcnt lgkmcnt(12)
	v_mfma_f32_16x16x32_bf16 v[70:73], v[232:235], v[150:153], v[70:73]
	ds_read_b128 v[228:231], v122 offset:24576
	ds_read_b128 v[232:235], v123 offset:24576
	s_waitcnt lgkmcnt(13)
	v_mfma_f32_16x16x32_bf16 v[74:77], v[236:239], v[146:149], v[74:77]
	s_waitcnt lgkmcnt(12)
	v_mfma_f32_16x16x32_bf16 v[74:77], v[240:243], v[150:153], v[74:77]
	ds_read_b128 v[236:239], v122 offset:26624
	ds_read_b128 v[240:243], v123 offset:26624
	s_waitcnt lgkmcnt(13)
	v_mfma_f32_16x16x32_bf16 v[78:81], v[186:189], v[146:149], v[78:81]
	s_waitcnt lgkmcnt(12)
	v_mfma_f32_16x16x32_bf16 v[78:81], v[190:193], v[150:153], v[78:81]
	ds_read_b128 v[186:189], v122 offset:28672
	ds_read_b128 v[190:193], v123 offset:28672
	s_waitcnt lgkmcnt(13)
	v_mfma_f32_16x16x32_bf16 v[82:85], v[194:197], v[146:149], v[82:85]
	s_waitcnt lgkmcnt(12)
	v_mfma_f32_16x16x32_bf16 v[82:85], v[198:201], v[150:153], v[82:85]
	ds_read_b128 v[194:197], v122 offset:30720
	ds_read_b128 v[198:201], v123 offset:30720
	s_waitcnt lgkmcnt(13)
	v_mfma_f32_16x16x32_bf16 v[86:89], v[202:205], v[146:149], v[86:89]
	s_waitcnt lgkmcnt(12)
	v_mfma_f32_16x16x32_bf16 v[86:89], v[206:209], v[150:153], v[86:89]
	ds_read_b128 v[202:205], v122 offset:32768
	ds_read_b128 v[206:209], v123 offset:32768
	s_waitcnt lgkmcnt(13)
	v_mfma_f32_16x16x32_bf16 v[90:93], v[210:213], v[146:149], v[90:93]
	s_waitcnt lgkmcnt(12)
	v_mfma_f32_16x16x32_bf16 v[90:93], v[214:217], v[150:153], v[90:93]
	s_waitcnt lgkmcnt(11)
	v_mfma_f32_16x16x32_bf16 v[94:97], v[220:223], v[146:149], v[94:97]
	s_waitcnt lgkmcnt(10)
	v_mfma_f32_16x16x32_bf16 v[94:97], v[224:227], v[150:153], v[94:97]
	s_waitcnt lgkmcnt(9)
	v_mfma_f32_16x16x32_bf16 v[98:101], v[228:231], v[146:149], v[98:101]
	s_waitcnt lgkmcnt(8)
	v_mfma_f32_16x16x32_bf16 v[98:101], v[232:235], v[150:153], v[98:101]
	s_waitcnt lgkmcnt(7)
	v_mfma_f32_16x16x32_bf16 v[102:105], v[236:239], v[146:149], v[102:105]
	s_waitcnt lgkmcnt(6)
	v_mfma_f32_16x16x32_bf16 v[102:105], v[240:243], v[150:153], v[102:105]
	s_waitcnt lgkmcnt(5)
	v_mfma_f32_16x16x32_bf16 v[106:109], v[186:189], v[146:149], v[106:109]
	s_waitcnt lgkmcnt(4)
	v_mfma_f32_16x16x32_bf16 v[106:109], v[190:193], v[150:153], v[106:109]
	s_waitcnt lgkmcnt(3)
	v_mfma_f32_16x16x32_bf16 v[110:113], v[194:197], v[146:149], v[110:113]
	s_waitcnt lgkmcnt(2)
	v_mfma_f32_16x16x32_bf16 v[110:113], v[198:201], v[150:153], v[110:113]
	s_waitcnt lgkmcnt(1)
	v_mfma_f32_16x16x32_bf16 v[114:117], v[202:205], v[146:149], v[114:117]
	s_waitcnt lgkmcnt(0)
	v_mfma_f32_16x16x32_bf16 v[114:117], v[206:209], v[150:153], v[114:117]
	v_max3_f32 v219, v50, v51, v52
	v_max3_f32 v244, v54, v55, v56
	v_max3_f32 v245, v58, v59, v60
	v_max3_f32 v120, v62, v63, v64
	v_max3_f32 v219, v219, v53, v66
	v_max3_f32 v244, v244, v57, v70
	v_max3_f32 v245, v245, v61, v74
	v_max3_f32 v120, v120, v65, v78
	v_max3_f32 v219, v219, v67, v68
	v_max3_f32 v244, v244, v71, v72
	v_max3_f32 v245, v245, v75, v76
	v_max3_f32 v120, v120, v79, v80
	ds_read_b64_tr_b16 v[186:187], v124 offset:0
	ds_read_b64_tr_b16 v[188:189], v124 offset:2048
	ds_read_b64_tr_b16 v[190:191], v125 offset:0
	ds_read_b64_tr_b16 v[192:193], v125 offset:2048
	ds_read_b64_tr_b16 v[194:195], v126 offset:0
	ds_read_b64_tr_b16 v[196:197], v126 offset:2048
	ds_read_b64_tr_b16 v[198:199], v127 offset:0
	ds_read_b64_tr_b16 v[200:201], v127 offset:2048
	v_max3_f32 v219, v219, v69, v82
	v_max3_f32 v244, v244, v73, v86
	v_max3_f32 v245, v245, v77, v90
	v_max3_f32 v120, v120, v81, v94
	v_max3_f32 v219, v219, v83, v84
	v_max3_f32 v244, v244, v87, v88
	v_max3_f32 v245, v245, v91, v92
	v_max3_f32 v120, v120, v95, v96
	v_max3_f32 v219, v219, v85, v98
	v_max3_f32 v244, v244, v89, v102
	v_max3_f32 v245, v245, v93, v106
	v_max3_f32 v120, v120, v97, v110
	v_max3_f32 v219, v219, v99, v100
	v_max3_f32 v244, v244, v103, v104
	v_max3_f32 v245, v245, v107, v108
	v_max3_f32 v120, v120, v111, v112
	v_max3_f32 v219, v219, v101, v114
	v_max3_f32 v219, v219, v115, v116
	v_max_f32_e32 v219, v219, v117
	v_max_f32_e32 v244, v244, v105
	v_max_f32_e32 v245, v245, v109
	v_max_f32_e32 v120, v120, v113
	v_max3_f32 v178, v219, v244, v245
	v_max_f32_e32 v178, v178, v120
	v_mov_b32_e32 v219, v178
	s_nop 1
	v_permlane16_swap_b32_e32 v178, v219
	v_max_f32_e32 v178, v178, v219
	v_mov_b32_e32 v219, v178
	s_nop 1
	v_permlane32_swap_b32_e32 v178, v219
	v_max3_f32 v178, v178, v219, v145
	s_waitcnt lgkmcnt(7)
; __device__ __forceinline__ void softmax_step(f32x4& s0, f32x4& s1, float& m, float& l, f32x4 (&O)[4]) {
;     float t = fmaxf(fmaxf(fmaxf(s0[0], s0[1]), fmaxf(s0[2], s0[3])), fmaxf(fmaxf(s1[0], s1[1]), fmaxf(s1[2], s1[3])));
;     t = xrow16_max(t);
;     const float mn = fmaxf(m, t), alpha = __builtin_amdgcn_exp2f(m - mn);
;     m = mn;
; #pragma unroll
;     for (int k = 0; k < 4; ++k) { s0[k] = __builtin_amdgcn_exp2f(s0[k] - mn); s1[k] = __builtin_amdgcn_exp2f(s1[k] - mn); }
;     l = l * alpha + ((s0[0] + s0[1]) + (s0[2] + s0[3])) + ((s1[0] + s1[1]) + (s1[2] + s1[3]));
; #pragma unroll
;     for (int db = 0; db < 4; ++db) O[db] *= alpha;
	ds_read_b64_tr_b16 v[202:203], v124 offset:4096
	ds_read_b64_tr_b16 v[204:205], v124 offset:6144
	ds_read_b64_tr_b16 v[206:207], v125 offset:4096
	ds_read_b64_tr_b16 v[208:209], v125 offset:6144
	ds_read_b64_tr_b16 v[228:229], v126 offset:4096
	ds_read_b64_tr_b16 v[230:231], v126 offset:6144
	ds_read_b64_tr_b16 v[232:233], v127 offset:4096
	ds_read_b64_tr_b16 v[234:235], v127 offset:6144
	v_mov_b32_e32 v244, v178
	v_pk_add_f32 v[50:51], v[50:51], v[244:245] op_sel_hi:[1,0] neg_lo:[0,1] neg_hi:[0,1]
	v_pk_add_f32 v[52:53], v[52:53], v[244:245] op_sel_hi:[1,0] neg_lo:[0,1] neg_hi:[0,1]
	v_pk_add_f32 v[54:55], v[54:55], v[244:245] op_sel_hi:[1,0] neg_lo:[0,1] neg_hi:[0,1]
	v_pk_add_f32 v[56:57], v[56:57], v[244:245] op_sel_hi:[1,0] neg_lo:[0,1] neg_hi:[0,1]
	v_pk_add_f32 v[58:59], v[58:59], v[244:245] op_sel_hi:[1,0] neg_lo:[0,1] neg_hi:[0,1]
	v_pk_add_f32 v[60:61], v[60:61], v[244:245] op_sel_hi:[1,0] neg_lo:[0,1] neg_hi:[0,1]
	v_pk_add_f32 v[62:63], v[62:63], v[244:245] op_sel_hi:[1,0] neg_lo:[0,1] neg_hi:[0,1]
	v_pk_add_f32 v[64:65], v[64:65], v[244:245] op_sel_hi:[1,0] neg_lo:[0,1] neg_hi:[0,1]
	v_pk_add_f32 v[66:67], v[66:67], v[244:245] op_sel_hi:[1,0] neg_lo:[0,1] neg_hi:[0,1]
	v_pk_add_f32 v[68:69], v[68:69], v[244:245] op_sel_hi:[1,0] neg_lo:[0,1] neg_hi:[0,1]
	v_pk_add_f32 v[70:71], v[70:71], v[244:245] op_sel_hi:[1,0] neg_lo:[0,1] neg_hi:[0,1]
	v_pk_add_f32 v[72:73], v[72:73], v[244:245] op_sel_hi:[1,0] neg_lo:[0,1] neg_hi:[0,1]
	v_pk_add_f32 v[74:75], v[74:75], v[244:245] op_sel_hi:[1,0] neg_lo:[0,1] neg_hi:[0,1]
	v_pk_add_f32 v[76:77], v[76:77], v[244:245] op_sel_hi:[1,0] neg_lo:[0,1] neg_hi:[0,1]
	v_pk_add_f32 v[78:79], v[78:79], v[244:245] op_sel_hi:[1,0] neg_lo:[0,1] neg_hi:[0,1]
	v_pk_add_f32 v[80:81], v[80:81], v[244:245] op_sel_hi:[1,0] neg_lo:[0,1] neg_hi:[0,1]
	v_pk_add_f32 v[82:83], v[82:83], v[244:245] op_sel_hi:[1,0] neg_lo:[0,1] neg_hi:[0,1]
	v_pk_add_f32 v[84:85], v[84:85], v[244:245] op_sel_hi:[1,0] neg_lo:[0,1] neg_hi:[0,1]
	v_pk_add_f32 v[86:87], v[86:87], v[244:245] op_sel_hi:[1,0] neg_lo:[0,1] neg_hi:[0,1]
	v_pk_add_f32 v[88:89], v[88:89], v[244:245] op_sel_hi:[1,0] neg_lo:[0,1] neg_hi:[0,1]
	v_pk_add_f32 v[90:91], v[90:91], v[244:245] op_sel_hi:[1,0] neg_lo:[0,1] neg_hi:[0,1]
	v_pk_add_f32 v[92:93], v[92:93], v[244:245] op_sel_hi:[1,0] neg_lo:[0,1] neg_hi:[0,1]
	v_pk_add_f32 v[94:95], v[94:95], v[244:245] op_sel_hi:[1,0] neg_lo:[0,1] neg_hi:[0,1]
	v_pk_add_f32 v[96:97], v[96:97], v[244:245] op_sel_hi:[1,0] neg_lo:[0,1] neg_hi:[0,1]
	v_pk_add_f32 v[98:99], v[98:99], v[244:245] op_sel_hi:[1,0] neg_lo:[0,1] neg_hi:[0,1]
	v_pk_add_f32 v[100:101], v[100:101], v[244:245] op_sel_hi:[1,0] neg_lo:[0,1] neg_hi:[0,1]
	v_pk_add_f32 v[102:103], v[102:103], v[244:245] op_sel_hi:[1,0] neg_lo:[0,1] neg_hi:[0,1]
	v_pk_add_f32 v[104:105], v[104:105], v[244:245] op_sel_hi:[1,0] neg_lo:[0,1] neg_hi:[0,1]
	v_pk_add_f32 v[106:107], v[106:107], v[244:245] op_sel_hi:[1,0] neg_lo:[0,1] neg_hi:[0,1]
	v_pk_add_f32 v[108:109], v[108:109], v[244:245] op_sel_hi:[1,0] neg_lo:[0,1] neg_hi:[0,1]
	v_pk_add_f32 v[110:111], v[110:111], v[244:245] op_sel_hi:[1,0] neg_lo:[0,1] neg_hi:[0,1]
	v_pk_add_f32 v[112:113], v[112:113], v[244:245] op_sel_hi:[1,0] neg_lo:[0,1] neg_hi:[0,1]
	v_pk_add_f32 v[114:115], v[114:115], v[244:245] op_sel_hi:[1,0] neg_lo:[0,1] neg_hi:[0,1]
	v_pk_add_f32 v[116:117], v[116:117], v[244:245] op_sel_hi:[1,0] neg_lo:[0,1] neg_hi:[0,1]
	v_sub_f32_e32 v219, v145, v178
	v_exp_f32_e32 v50, v50
	v_exp_f32_e32 v51, v51
	v_exp_f32_e32 v52, v52
	v_exp_f32_e32 v53, v53
	v_exp_f32_e32 v54, v54
	v_exp_f32_e32 v55, v55
	v_exp_f32_e32 v56, v56
	v_exp_f32_e32 v57, v57
	v_exp_f32_e32 v58, v58
	v_exp_f32_e32 v59, v59
	v_exp_f32_e32 v60, v60
	v_exp_f32_e32 v61, v61
	v_exp_f32_e32 v62, v62
	v_exp_f32_e32 v63, v63
	v_exp_f32_e32 v64, v64
	v_exp_f32_e32 v65, v65
	v_exp_f32_e32 v66, v66
	v_exp_f32_e32 v67, v67
	v_exp_f32_e32 v68, v68
	v_exp_f32_e32 v69, v69
	v_exp_f32_e32 v70, v70
	v_exp_f32_e32 v71, v71
	v_exp_f32_e32 v72, v72
	v_exp_f32_e32 v73, v73
	v_exp_f32_e32 v74, v74
	v_exp_f32_e32 v75, v75
	v_exp_f32_e32 v76, v76
	v_exp_f32_e32 v77, v77
	v_exp_f32_e32 v78, v78
	v_exp_f32_e32 v79, v79
	v_exp_f32_e32 v80, v80
	v_exp_f32_e32 v81, v81
	v_exp_f32_e32 v82, v82
	v_exp_f32_e32 v83, v83
	v_exp_f32_e32 v84, v84
	v_exp_f32_e32 v85, v85
	v_exp_f32_e32 v86, v86
	v_exp_f32_e32 v87, v87
	v_exp_f32_e32 v88, v88
	v_exp_f32_e32 v89, v89
	v_exp_f32_e32 v90, v90
	v_exp_f32_e32 v91, v91
	v_exp_f32_e32 v92, v92
	v_exp_f32_e32 v93, v93
	v_exp_f32_e32 v94, v94
	v_exp_f32_e32 v95, v95
	v_exp_f32_e32 v96, v96
	v_exp_f32_e32 v97, v97
	v_exp_f32_e32 v98, v98
	v_exp_f32_e32 v99, v99
	v_exp_f32_e32 v100, v100
	v_exp_f32_e32 v101, v101
	v_exp_f32_e32 v102, v102
	v_exp_f32_e32 v103, v103
	v_exp_f32_e32 v104, v104
	v_exp_f32_e32 v105, v105
	v_exp_f32_e32 v106, v106
	v_exp_f32_e32 v107, v107
	v_exp_f32_e32 v108, v108
	v_exp_f32_e32 v109, v109
	v_exp_f32_e32 v110, v110
	v_exp_f32_e32 v111, v111
	v_exp_f32_e32 v112, v112
	v_exp_f32_e32 v113, v113
	v_exp_f32_e32 v114, v114
	v_exp_f32_e32 v115, v115
	v_exp_f32_e32 v116, v116
	v_exp_f32_e32 v117, v117
	v_exp_f32_e32 v219, v219
	v_pk_add_f32 v[236:237], v[50:51], v[52:53]
	v_pk_add_f32 v[238:239], v[54:55], v[56:57]
	v_pk_add_f32 v[240:241], v[58:59], v[60:61]
	v_pk_add_f32 v[242:243], v[62:63], v[64:65]
	v_pk_add_f32 v[236:237], v[236:237], v[66:67]
	v_pk_add_f32 v[238:239], v[238:239], v[70:71]
	v_pk_add_f32 v[240:241], v[240:241], v[74:75]
	v_pk_add_f32 v[242:243], v[242:243], v[78:79]
	v_pk_add_f32 v[236:237], v[236:237], v[68:69]
	v_pk_add_f32 v[238:239], v[238:239], v[72:73]
	v_pk_add_f32 v[240:241], v[240:241], v[76:77]
	v_pk_add_f32 v[242:243], v[242:243], v[80:81]
	v_pk_add_f32 v[236:237], v[236:237], v[82:83]
	v_pk_add_f32 v[238:239], v[238:239], v[86:87]
	v_pk_add_f32 v[240:241], v[240:241], v[90:91]
	v_pk_add_f32 v[242:243], v[242:243], v[94:95]
	v_pk_add_f32 v[236:237], v[236:237], v[84:85]
	v_pk_add_f32 v[238:239], v[238:239], v[88:89]
	v_pk_add_f32 v[240:241], v[240:241], v[92:93]
	v_pk_add_f32 v[242:243], v[242:243], v[96:97]
	v_pk_add_f32 v[236:237], v[236:237], v[98:99]
	v_pk_add_f32 v[238:239], v[238:239], v[102:103]
	v_pk_add_f32 v[240:241], v[240:241], v[106:107]
	v_pk_add_f32 v[242:243], v[242:243], v[110:111]
	v_pk_add_f32 v[236:237], v[236:237], v[100:101]
	v_pk_add_f32 v[238:239], v[238:239], v[104:105]
	v_pk_add_f32 v[240:241], v[240:241], v[108:109]
	v_pk_add_f32 v[242:243], v[242:243], v[112:113]
	v_pk_add_f32 v[236:237], v[236:237], v[114:115]
	v_pk_add_f32 v[236:237], v[236:237], v[116:117]
	v_pk_add_f32 v[236:237], v[236:237], v[238:239]
	v_pk_add_f32 v[240:241], v[240:241], v[242:243]
	v_cndmask_b32_e64 v219, 0, v219, s[74:75]
	v_pk_add_f32 v[236:237], v[236:237], v[240:241]
	v_add_f32_e32 v185, v236, v237
	v_add_f32_e32 v185, v185, v219
	v_cvt_pk_bf16_f32 v236, v50, v51
	v_cvt_pk_bf16_f32 v237, v52, v53
	v_cvt_pk_bf16_f32 v238, v54, v55
	v_cvt_pk_bf16_f32 v239, v56, v57
	s_nop 1
	s_waitcnt lgkmcnt(14)
; #define LAS __attribute__((address_space(3)))
; __device__ __forceinline__ unsigned pk2(float lo, float hi) { return pg8::cvt_pk_bf16(lo, hi); }
; __device__ __forceinline__ s16x4 vtr(const LAS unsigned char* p) { return __builtin_bit_cast(s16x4, __builtin_amdgcn_ds_read_tr16_b64_v4i16((LAS s16x4*)p)); }
; #define MFMA16(a, b, c) __builtin_amdgcn_mfma_f32_16x16x32_bf16((a), (b), (c), 0, 0, 0)
; __device__ __forceinline__ void pv_at(const LAS unsigned char* const (&vp)[4], int off, const f32x4& P0, const f32x4& P1, f32x4 (&O)[4]) {
;     v4u pw; pw.x = pk2(P0[0], P0[1]); pw.y = pk2(P0[2], P0[3]); pw.z = pk2(P1[0], P1[1]); pw.w = pk2(P1[2], P1[3]);
;     const bf16x8 pb = __builtin_bit_cast(bf16x8, pw);
; #pragma unroll
;     for (int db = 0; db < 4; ++db) {
;         const s16x4 lo = vtr(vp[db] + off), hi = vtr(vp[db] + off + 2048);
;         const bf16x8 vt = (bf16x8){lo[0], lo[1], lo[2], lo[3], hi[0], hi[1], hi[2], hi[3]};
;         O[db] = MFMA16(vt, pb, O[db]);
;     }
; }
; template <bool MASK> __device__ __forceinline__ void a_scores(f32x4& S0, f32x4& S1, float basef, float c1, float slope2, int krow0, int kstart) {
; #pragma unroll
;     for (int r = 0; r < 4; ++r) {
;         const float d0 = fabsf(basef - (float)r), d1 = fabsf(basef - (float)(16 + r));
;         const float v0 = S0[r] - slope2 * d0, v1 = S1[r] - slope2 * d1;
;         if (MASK) { const int p0 = kstart + krow0 + r, p1 = p0 + 16;
;             S0[r] = (d0 <= 128.f && p0 >= 0 && p0 < SEQ) ? v0 : -INFINITY; S1[r] = (d1 <= 128.f && p1 >= 0 && p1 < SEQ) ? v1 : -INFINITY; }
;         else { S0[r] = v0; S1[r] = v1; }
;     }
; }
	v_mfma_f32_16x16x32_bf16 v[210:213], v[186:189], v[236:239], 0
	s_waitcnt lgkmcnt(12)
	v_mfma_f32_16x16x32_bf16 v[214:217], v[190:193], v[236:239], 0
	s_waitcnt lgkmcnt(10)
	v_mfma_f32_16x16x32_bf16 v[220:223], v[194:197], v[236:239], 0
	s_waitcnt lgkmcnt(8)
	v_mfma_f32_16x16x32_bf16 v[224:227], v[198:201], v[236:239], 0
	v_cvt_pk_bf16_f32 v240, v58, v59
	v_cvt_pk_bf16_f32 v241, v60, v61
	v_cvt_pk_bf16_f32 v242, v62, v63
	v_cvt_pk_bf16_f32 v243, v64, v65
	s_waitcnt lgkmcnt(7)
	ds_read_b64_tr_b16 v[186:187], v124 offset:8192
	ds_read_b64_tr_b16 v[188:189], v124 offset:10240
	ds_read_b64_tr_b16 v[190:191], v125 offset:8192
	ds_read_b64_tr_b16 v[192:193], v125 offset:10240
	ds_read_b64_tr_b16 v[194:195], v126 offset:8192
	ds_read_b64_tr_b16 v[196:197], v126 offset:10240
	ds_read_b64_tr_b16 v[198:199], v127 offset:8192
	ds_read_b64_tr_b16 v[200:201], v127 offset:10240
	v_fmamk_f32 v50, v130, 0x43000000, v132
	v_fmamk_f32 v51, v130, 0x42fe0000, v132
	v_fmamk_f32 v52, v130, 0x42fc0000, v132
	v_fmamk_f32 v53, v130, 0x42fa0000, v132
	v_mov_b32_e32 v245, 0xff800000
	v_cndmask_b32_e64 v50, v245, v50, s[16:17]
	v_cndmask_b32_e64 v51, v245, v51, s[18:19]
	v_cndmask_b32_e64 v52, v245, v52, s[22:23]
	v_cndmask_b32_e64 v53, v245, v53, s[24:25]
	v_fmamk_f32 v54, v130, 0x42e00000, v132
	v_fmamk_f32 v55, v130, 0x42de0000, v132
	v_fmamk_f32 v56, v130, 0x42dc0000, v132
	v_fmamk_f32 v57, v130, 0x42da0000, v132
	s_waitcnt lgkmcnt(14)
	v_mfma_f32_16x16x32_bf16 v[210:213], v[202:205], v[240:243], v[210:213]
	s_waitcnt lgkmcnt(12)
	v_mfma_f32_16x16x32_bf16 v[214:217], v[206:209], v[240:243], v[214:217]
	s_waitcnt lgkmcnt(10)
	v_mfma_f32_16x16x32_bf16 v[220:223], v[228:231], v[240:243], v[220:223]
	s_waitcnt lgkmcnt(8)
	v_mfma_f32_16x16x32_bf16 v[224:227], v[232:235], v[240:243], v[224:227]
	v_cvt_pk_bf16_f32 v236, v66, v67
	v_cvt_pk_bf16_f32 v237, v68, v69
	v_cvt_pk_bf16_f32 v238, v70, v71
	v_cvt_pk_bf16_f32 v239, v72, v73
	s_waitcnt lgkmcnt(7)
	ds_read_b64_tr_b16 v[202:203], v124 offset:12288
	ds_read_b64_tr_b16 v[204:205], v124 offset:14336
	ds_read_b64_tr_b16 v[206:207], v125 offset:12288
	ds_read_b64_tr_b16 v[208:209], v125 offset:14336
	ds_read_b64_tr_b16 v[228:229], v126 offset:12288
	ds_read_b64_tr_b16 v[230:231], v126 offset:14336
	ds_read_b64_tr_b16 v[232:233], v127 offset:12288
	ds_read_b64_tr_b16 v[234:235], v127 offset:14336
	v_fmamk_f32 v58, v130, 0x42c00000, v132
	v_fmamk_f32 v59, v130, 0x42be0000, v132
	v_fmamk_f32 v60, v130, 0x42bc0000, v132
	v_fmamk_f32 v61, v130, 0x42ba0000, v132
	v_fmamk_f32 v62, v130, 0x42a00000, v132
	v_fmamk_f32 v63, v130, 0x429e0000, v132
	v_fmamk_f32 v64, v130, 0x429c0000, v132
	v_fmamk_f32 v65, v130, 0x429a0000, v132
	s_waitcnt lgkmcnt(14)
	v_mfma_f32_16x16x32_bf16 v[210:213], v[186:189], v[236:239], v[210:213]
	s_waitcnt lgkmcnt(12)
	v_mfma_f32_16x16x32_bf16 v[214:217], v[190:193], v[236:239], v[214:217]
	s_waitcnt lgkmcnt(10)
	v_mfma_f32_16x16x32_bf16 v[220:223], v[194:197], v[236:239], v[220:223]
	s_waitcnt lgkmcnt(8)
	v_mfma_f32_16x16x32_bf16 v[224:227], v[198:201], v[236:239], v[224:227]
	v_cvt_pk_bf16_f32 v240, v74, v75
	v_cvt_pk_bf16_f32 v241, v76, v77
	v_cvt_pk_bf16_f32 v242, v78, v79
	v_cvt_pk_bf16_f32 v243, v80, v81
	s_waitcnt lgkmcnt(7)
	ds_read_b64_tr_b16 v[186:187], v124 offset:16384
	ds_read_b64_tr_b16 v[188:189], v124 offset:18432
	ds_read_b64_tr_b16 v[190:191], v125 offset:16384
	ds_read_b64_tr_b16 v[192:193], v125 offset:18432
	ds_read_b64_tr_b16 v[194:195], v126 offset:16384
	ds_read_b64_tr_b16 v[196:197], v126 offset:18432
	ds_read_b64_tr_b16 v[198:199], v127 offset:16384
	ds_read_b64_tr_b16 v[200:201], v127 offset:18432
	v_fmamk_f32 v66, v130, 0x42800000, v132
	v_fmamk_f32 v67, v130, 0x427c0000, v132
	v_fmamk_f32 v68, v130, 0x42780000, v132
	v_fmamk_f32 v69, v130, 0x42740000, v132
	v_fmamk_f32 v70, v130, 0x42400000, v132
	v_fmamk_f32 v71, v130, 0x423c0000, v132
	v_fmamk_f32 v72, v130, 0x42380000, v132
	v_fmamk_f32 v73, v130, 0x42340000, v132
	s_waitcnt lgkmcnt(14)
	v_mfma_f32_16x16x32_bf16 v[210:213], v[202:205], v[240:243], v[210:213]
	s_waitcnt lgkmcnt(12)
	v_mfma_f32_16x16x32_bf16 v[214:217], v[206:209], v[240:243], v[214:217]
	s_waitcnt lgkmcnt(10)
	v_mfma_f32_16x16x32_bf16 v[220:223], v[228:231], v[240:243], v[220:223]
	s_waitcnt lgkmcnt(8)
	v_mfma_f32_16x16x32_bf16 v[224:227], v[232:235], v[240:243], v[224:227]
	v_cvt_pk_bf16_f32 v236, v82, v83
	v_cvt_pk_bf16_f32 v237, v84, v85
	v_cvt_pk_bf16_f32 v238, v86, v87
	v_cvt_pk_bf16_f32 v239, v88, v89
	s_waitcnt lgkmcnt(7)
	ds_read_b64_tr_b16 v[202:203], v124 offset:20480
	ds_read_b64_tr_b16 v[204:205], v124 offset:22528
	ds_read_b64_tr_b16 v[206:207], v125 offset:20480
	ds_read_b64_tr_b16 v[208:209], v125 offset:22528
	ds_read_b64_tr_b16 v[228:229], v126 offset:20480
	ds_read_b64_tr_b16 v[230:231], v126 offset:22528
	ds_read_b64_tr_b16 v[232:233], v127 offset:20480
	ds_read_b64_tr_b16 v[234:235], v127 offset:22528
	v_fmamk_f32 v74, v130, 0x42000000, v132
	v_fmamk_f32 v75, v130, 0x41f80000, v132
	v_fmamk_f32 v76, v130, 0x41f00000, v132
	v_fmamk_f32 v77, v130, 0x41e80000, v132
	v_fmamk_f32 v78, v130, 0x41800000, v132
	v_fmamk_f32 v79, v130, 0x41700000, v132
	v_fmamk_f32 v80, v130, 0x41600000, v132
	v_fmamk_f32 v81, v130, 0x41500000, v132
	s_waitcnt lgkmcnt(14)
	v_mfma_f32_16x16x32_bf16 v[210:213], v[186:189], v[236:239], v[210:213]
	s_waitcnt lgkmcnt(12)
	v_mfma_f32_16x16x32_bf16 v[214:217], v[190:193], v[236:239], v[214:217]
	s_waitcnt lgkmcnt(10)
	v_mfma_f32_16x16x32_bf16 v[220:223], v[194:197], v[236:239], v[220:223]
	s_waitcnt lgkmcnt(8)
; #define LAS __attribute__((address_space(3)))
; __device__ __forceinline__ unsigned pk2(float lo, float hi) { return pg8::cvt_pk_bf16(lo, hi); }
; __device__ __forceinline__ s16x4 vtr(const LAS unsigned char* p) { return __builtin_bit_cast(s16x4, __builtin_amdgcn_ds_read_tr16_b64_v4i16((LAS s16x4*)p)); }
; #define MFMA16(a, b, c) __builtin_amdgcn_mfma_f32_16x16x32_bf16((a), (b), (c), 0, 0, 0)
; __device__ __forceinline__ void pv_at(const LAS unsigned char* const (&vp)[4], int off, const f32x4& P0, const f32x4& P1, f32x4 (&O)[4]) {
;     v4u pw; pw.x = pk2(P0[0], P0[1]); pw.y = pk2(P0[2], P0[3]); pw.z = pk2(P1[0], P1[1]); pw.w = pk2(P1[2], P1[3]);
;     const bf16x8 pb = __builtin_bit_cast(bf16x8, pw);
; #pragma unroll
;     for (int db = 0; db < 4; ++db) {
;         const s16x4 lo = vtr(vp[db] + off), hi = vtr(vp[db] + off + 2048);
;         const bf16x8 vt = (bf16x8){lo[0], lo[1], lo[2], lo[3], hi[0], hi[1], hi[2], hi[3]};
;         O[db] = MFMA16(vt, pb, O[db]);
;     }
; }
; template <bool MASK> __device__ __forceinline__ void a_scores(f32x4& S0, f32x4& S1, float basef, float c1, float slope2, int krow0, int kstart) {
; #pragma unroll
;     for (int r = 0; r < 4; ++r) {
;         const float d0 = fabsf(basef - (float)r), d1 = fabsf(basef - (float)(16 + r));
;         const float v0 = S0[r] - slope2 * d0, v1 = S1[r] - slope2 * d1;
;         if (MASK) { const int p0 = kstart + krow0 + r, p1 = p0 + 16;
;             S0[r] = (d0 <= 128.f && p0 >= 0 && p0 < SEQ) ? v0 : -INFINITY; S1[r] = (d1 <= 128.f && p1 >= 0 && p1 < SEQ) ? v1 : -INFINITY; }
;         else { S0[r] = v0; S1[r] = v1; }
;     }
; }
	v_mfma_f32_16x16x32_bf16 v[224:227], v[198:201], v[236:239], v[224:227]
	v_cvt_pk_bf16_f32 v240, v90, v91
	v_cvt_pk_bf16_f32 v241, v92, v93
	v_cvt_pk_bf16_f32 v242, v94, v95
	v_cvt_pk_bf16_f32 v243, v96, v97
	s_waitcnt lgkmcnt(7)
	ds_read_b64_tr_b16 v[186:187], v124 offset:24576
	ds_read_b64_tr_b16 v[188:189], v124 offset:26624
	ds_read_b64_tr_b16 v[190:191], v125 offset:24576
	ds_read_b64_tr_b16 v[192:193], v125 offset:26624
	ds_read_b64_tr_b16 v[194:195], v126 offset:24576
	ds_read_b64_tr_b16 v[196:197], v126 offset:26624
	ds_read_b64_tr_b16 v[198:199], v127 offset:24576
	ds_read_b64_tr_b16 v[200:201], v127 offset:26624
	v_add_f32_e32 v219, 0, v129
	v_mul_f32_e64 v82, v130, |v219|
	v_add_f32_e32 v245, 0xbf800000, v129
	v_mul_f32_e64 v83, v130, |v245|
	v_add_f32_e32 v219, 0xc0000000, v129
	v_mul_f32_e64 v84, v130, |v219|
	v_add_f32_e32 v245, 0xc0400000, v129
	v_mul_f32_e64 v85, v130, |v245|
	v_fmamk_f32 v86, v131, 0xc1800000, v133
	v_fmamk_f32 v87, v131, 0xc1880000, v133
	v_fmamk_f32 v88, v131, 0xc1900000, v133
	v_fmamk_f32 v89, v131, 0xc1980000, v133
	s_waitcnt lgkmcnt(14)
	v_mfma_f32_16x16x32_bf16 v[210:213], v[202:205], v[240:243], v[210:213]
	s_waitcnt lgkmcnt(12)
	v_mfma_f32_16x16x32_bf16 v[214:217], v[206:209], v[240:243], v[214:217]
	s_waitcnt lgkmcnt(10)
	v_mfma_f32_16x16x32_bf16 v[220:223], v[228:231], v[240:243], v[220:223]
	s_waitcnt lgkmcnt(8)
	v_mfma_f32_16x16x32_bf16 v[224:227], v[232:235], v[240:243], v[224:227]
	v_cvt_pk_bf16_f32 v236, v98, v99
	v_cvt_pk_bf16_f32 v237, v100, v101
	v_cvt_pk_bf16_f32 v238, v102, v103
	v_cvt_pk_bf16_f32 v239, v104, v105
	s_waitcnt lgkmcnt(7)
	ds_read_b64_tr_b16 v[202:203], v124 offset:28672
	ds_read_b64_tr_b16 v[204:205], v124 offset:30720
	ds_read_b64_tr_b16 v[206:207], v125 offset:28672
	ds_read_b64_tr_b16 v[208:209], v125 offset:30720
	ds_read_b64_tr_b16 v[228:229], v126 offset:28672
	ds_read_b64_tr_b16 v[230:231], v126 offset:30720
	ds_read_b64_tr_b16 v[232:233], v127 offset:28672
	ds_read_b64_tr_b16 v[234:235], v127 offset:30720
	v_fmamk_f32 v90, v131, 0xc2000000, v133
	v_fmamk_f32 v91, v131, 0xc2040000, v133
	v_fmamk_f32 v92, v131, 0xc2080000, v133
	v_fmamk_f32 v93, v131, 0xc20c0000, v133
	v_fmamk_f32 v94, v131, 0xc2400000, v133
	v_fmamk_f32 v95, v131, 0xc2440000, v133
	v_fmamk_f32 v96, v131, 0xc2480000, v133
	v_fmamk_f32 v97, v131, 0xc24c0000, v133
	s_waitcnt lgkmcnt(14)
	v_mfma_f32_16x16x32_bf16 v[210:213], v[186:189], v[236:239], v[210:213]
	s_waitcnt lgkmcnt(12)
	v_mfma_f32_16x16x32_bf16 v[214:217], v[190:193], v[236:239], v[214:217]
	s_waitcnt lgkmcnt(10)
	v_mfma_f32_16x16x32_bf16 v[220:223], v[194:197], v[236:239], v[220:223]
	s_waitcnt lgkmcnt(8)
	v_mfma_f32_16x16x32_bf16 v[224:227], v[198:201], v[236:239], v[224:227]
	v_cvt_pk_bf16_f32 v240, v106, v107
	v_cvt_pk_bf16_f32 v241, v108, v109
	v_cvt_pk_bf16_f32 v242, v110, v111
	v_cvt_pk_bf16_f32 v243, v112, v113
	s_waitcnt lgkmcnt(7)
	ds_read_b64_tr_b16 v[186:187], v124 offset:32768
	ds_read_b64_tr_b16 v[188:189], v124 offset:34816
	ds_read_b64_tr_b16 v[190:191], v125 offset:32768
	ds_read_b64_tr_b16 v[192:193], v125 offset:34816
	ds_read_b64_tr_b16 v[194:195], v126 offset:32768
	ds_read_b64_tr_b16 v[196:197], v126 offset:34816
	ds_read_b64_tr_b16 v[198:199], v127 offset:32768
	ds_read_b64_tr_b16 v[200:201], v127 offset:34816
	v_fmamk_f32 v98, v131, 0xc2800000, v133
	v_fmamk_f32 v99, v131, 0xc2820000, v133
	v_fmamk_f32 v100, v131, 0xc2840000, v133
	v_fmamk_f32 v101, v131, 0xc2860000, v133
	v_fmamk_f32 v102, v131, 0xc2a00000, v133
	v_fmamk_f32 v103, v131, 0xc2a20000, v133
	v_fmamk_f32 v104, v131, 0xc2a40000, v133
	v_fmamk_f32 v105, v131, 0xc2a60000, v133
	s_waitcnt lgkmcnt(14)
	v_mfma_f32_16x16x32_bf16 v[210:213], v[202:205], v[240:243], v[210:213]
	s_waitcnt lgkmcnt(12)
	v_mfma_f32_16x16x32_bf16 v[214:217], v[206:209], v[240:243], v[214:217]
	s_waitcnt lgkmcnt(10)
	v_mfma_f32_16x16x32_bf16 v[220:223], v[228:231], v[240:243], v[220:223]
	s_waitcnt lgkmcnt(8)
	v_mfma_f32_16x16x32_bf16 v[224:227], v[232:235], v[240:243], v[224:227]
	v_cvt_pk_bf16_f32 v236, v114, v115
	v_cvt_pk_bf16_f32 v237, v116, v117
	v_mov_b32_e32 v238, 0
	v_mov_b32_e32 v239, 0
	s_nop 1
	v_fmamk_f32 v106, v131, 0xc2c00000, v133
	v_fmamk_f32 v107, v131, 0xc2c20000, v133
	v_fmamk_f32 v108, v131, 0xc2c40000, v133
	v_fmamk_f32 v109, v131, 0xc2c60000, v133
	v_fmamk_f32 v110, v131, 0xc2e00000, v133
	v_fmamk_f32 v111, v131, 0xc2e20000, v133
	v_fmamk_f32 v112, v131, 0xc2e40000, v133
	v_fmamk_f32 v113, v131, 0xc2e60000, v133
	s_waitcnt lgkmcnt(6)
	v_mfma_f32_16x16x32_bf16 v[210:213], v[186:189], v[236:239], v[210:213]
	s_waitcnt lgkmcnt(4)
	v_mfma_f32_16x16x32_bf16 v[214:217], v[190:193], v[236:239], v[214:217]
	s_waitcnt lgkmcnt(2)
	v_mfma_f32_16x16x32_bf16 v[220:223], v[194:197], v[236:239], v[220:223]
	s_waitcnt lgkmcnt(0)
; #define LAS __attribute__((address_space(3)))
; __device__ __forceinline__ unsigned pk2(float lo, float hi) { return pg8::cvt_pk_bf16(lo, hi); }
; #define MFMA16(a, b, c) __builtin_amdgcn_mfma_f32_16x16x32_bf16((a), (b), (c), 0, 0, 0)
; __device__ __forceinline__ void qk_at(const LAS unsigned char* kp0, const LAS unsigned char* kp1, int off, bf16x8 qf0, bf16x8 qf1, f32x4& S0, f32x4& S1) {
;     const bf16x8 k00 = *(const LAS bf16x8*)(kp0 + off), k01 = *(const LAS bf16x8*)(kp1 + off);
;     const bf16x8 k10 = *(const LAS bf16x8*)(kp0 + off + 2048), k11 = *(const LAS bf16x8*)(kp1 + off + 2048);
;     const f32x4 z = {0.f, 0.f, 0.f, 0.f};
;     S0 = MFMA16(k00, qf0, z); S0 = MFMA16(k01, qf1, S0);
;     S1 = MFMA16(k10, qf0, z); S1 = MFMA16(k11, qf1, S1);
; }
; __device__ __forceinline__ void store_o(bf16* yrow, int g, float l, const f32x4 (&O)[4]) {
;     const float inv = 1.0f / xrow16_sum(l);
;     unsigned wx[4], wy[4];
; #pragma unroll
;     for (int db = 0; db < 4; ++db) { wx[db] = pk2(O[db][0] * inv, O[db][1] * inv); wy[db] = pk2(O[db][2] * inv, O[db][3] * inv); }
; #pragma unroll
;     for (int p = 0; p < 2; ++p) {
;         auto rx = __builtin_amdgcn_permlane16_swap(wx[2 * p], wx[2 * p + 1], false, false); wx[2 * p] = rx[0]; wx[2 * p + 1] = rx[1];
;         auto ry = __builtin_amdgcn_permlane16_swap(wy[2 * p], wy[2 * p + 1], false, false); wy[2 * p] = ry[0]; wy[2 * p + 1] = ry[1]; }
; #pragma unroll
;     for (int p = 0; p < 2; ++p) {
;         auto rx = __builtin_amdgcn_permlane32_swap(wx[p], wx[p + 2], false, false); wx[p] = rx[0]; wx[p + 2] = rx[1];
;         auto ry = __builtin_amdgcn_permlane32_swap(wy[p], wy[p + 2], false, false); wy[p] = ry[0]; wy[p + 2] = ry[1]; }
;     v4u lo = {wx[0], wy[0], wx[1], wy[1]}, hi = {wx[2], wy[2], wx[3], wy[3]};
;     *(v4u*)(yrow + 16 * g) = lo; *(v4u*)(yrow + 16 * g + 8) = hi;
; }
	v_mfma_f32_16x16x32_bf16 v[224:227], v[198:201], v[236:239], v[224:227]
	v_fmamk_f32 v114, v131, 0xc3000000, v133
	v_fmamk_f32 v115, v131, 0xc3010000, v133
	v_fmamk_f32 v116, v131, 0xc3020000, v133
	v_fmamk_f32 v117, v131, 0xc3030000, v133
	v_mov_b32_e32 v245, 0xff800000
	v_cndmask_b32_e64 v114, v245, v114, s[28:29]
	v_cndmask_b32_e64 v115, v245, v115, s[52:53]
	v_cndmask_b32_e64 v116, v245, v116, s[54:55]
	v_cndmask_b32_e64 v117, v245, v117, s[88:89]
	v_mov_b32_e32 v219, v185
	s_nop 1
	v_permlane16_swap_b32_e32 v185, v219
	v_add_f32_e32 v185, v185, v219
	v_mov_b32_e32 v219, v185
	s_nop 1
	v_permlane32_swap_b32_e32 v185, v219
	v_add_f32_e32 v185, v185, v219
	v_div_scale_f32 v236, s[78:79], v185, v185, 1.0
	v_div_scale_f32 v237, vcc, 1.0, v185, 1.0
	v_rcp_f32_e32 v238, v236
	s_nop 0
	v_fma_f32 v239, -v236, v238, 1.0
	v_fmac_f32_e32 v238, v239, v238
	v_mul_f32_e32 v240, v237, v238
	v_fma_f32 v241, -v236, v240, v237
	v_fmac_f32_e32 v240, v241, v238
	v_fma_f32 v237, -v236, v240, v237
	v_div_fmas_f32 v237, v237, v238, v240
	v_div_fixup_f32 v244, v237, v185, 1.0
	v_mul_f32_e32 v240, v210, v244
	v_mul_f32_e32 v241, v211, v244
	v_mul_f32_e32 v242, v212, v244
	v_mul_f32_e32 v243, v213, v244
	v_cvt_pk_bf16_f32 v186, v240, v241
	v_cvt_pk_bf16_f32 v187, v242, v243
	v_mul_f32_e32 v240, v214, v244
	v_mul_f32_e32 v241, v215, v244
	v_mul_f32_e32 v242, v216, v244
	v_mul_f32_e32 v243, v217, v244
	v_cvt_pk_bf16_f32 v188, v240, v241
	v_cvt_pk_bf16_f32 v189, v242, v243
	v_mul_f32_e32 v240, v220, v244
	v_mul_f32_e32 v241, v221, v244
	v_mul_f32_e32 v242, v222, v244
	v_mul_f32_e32 v243, v223, v244
	v_cvt_pk_bf16_f32 v190, v240, v241
	v_cvt_pk_bf16_f32 v191, v242, v243
	v_mul_f32_e32 v240, v224, v244
	v_mul_f32_e32 v241, v225, v244
	v_mul_f32_e32 v242, v226, v244
	v_mul_f32_e32 v243, v227, v244
	v_cvt_pk_bf16_f32 v192, v240, v241
	v_cvt_pk_bf16_f32 v193, v242, v243
	s_nop 1
	v_permlane16_swap_b32_e32 v186, v188
	v_permlane16_swap_b32_e32 v187, v189
	v_permlane16_swap_b32_e32 v190, v192
	v_permlane16_swap_b32_e32 v191, v193
	s_nop 0
	v_permlane32_swap_b32_e32 v186, v190
	v_permlane32_swap_b32_e32 v187, v191
	v_permlane32_swap_b32_e32 v188, v192
	v_permlane32_swap_b32_e32 v189, v193
	global_store_dwordx4 v128, v[186:189], s[82:83] offset:0
	global_store_dwordx4 v128, v[190:193], s[82:83] offset:16
	s_nop 1
	ds_read_b128 v[186:189], v122 offset:2048
	ds_read_b128 v[190:193], v123 offset:2048
	ds_read_b128 v[194:197], v122 offset:4096
	ds_read_b128 v[198:201], v123 offset:4096
	ds_read_b128 v[202:205], v122 offset:6144
	ds_read_b128 v[206:209], v123 offset:6144
	ds_read_b128 v[210:213], v122 offset:8192
	ds_read_b128 v[214:217], v123 offset:8192
	ds_read_b128 v[220:223], v122 offset:10240
	ds_read_b128 v[224:227], v123 offset:10240
	ds_read_b128 v[228:231], v122 offset:12288
	ds_read_b128 v[232:235], v123 offset:12288
	ds_read_b128 v[236:239], v122 offset:14336
	ds_read_b128 v[240:243], v123 offset:14336
	s_waitcnt lgkmcnt(13)
	v_mfma_f32_16x16x32_bf16 v[50:53], v[186:189], v[154:157], v[50:53]
	s_waitcnt lgkmcnt(12)
	v_mfma_f32_16x16x32_bf16 v[50:53], v[190:193], v[158:161], v[50:53]
	ds_read_b128 v[186:189], v122 offset:16384
	ds_read_b128 v[190:193], v123 offset:16384
	s_waitcnt lgkmcnt(13)
	v_mfma_f32_16x16x32_bf16 v[54:57], v[194:197], v[154:157], v[54:57]
	s_waitcnt lgkmcnt(12)
	v_mfma_f32_16x16x32_bf16 v[54:57], v[198:201], v[158:161], v[54:57]
	ds_read_b128 v[194:197], v122 offset:18432
	ds_read_b128 v[198:201], v123 offset:18432
	s_waitcnt lgkmcnt(13)
	v_mfma_f32_16x16x32_bf16 v[58:61], v[202:205], v[154:157], v[58:61]
	s_waitcnt lgkmcnt(12)
	v_mfma_f32_16x16x32_bf16 v[58:61], v[206:209], v[158:161], v[58:61]
	ds_read_b128 v[202:205], v122 offset:20480
	ds_read_b128 v[206:209], v123 offset:20480
	s_waitcnt lgkmcnt(13)
	v_mfma_f32_16x16x32_bf16 v[62:65], v[210:213], v[154:157], v[62:65]
	s_waitcnt lgkmcnt(12)
	v_mfma_f32_16x16x32_bf16 v[62:65], v[214:217], v[158:161], v[62:65]
	ds_read_b128 v[210:213], v122 offset:22528
	ds_read_b128 v[214:217], v123 offset:22528
	s_waitcnt lgkmcnt(13)
	v_mfma_f32_16x16x32_bf16 v[66:69], v[220:223], v[154:157], v[66:69]
	s_waitcnt lgkmcnt(12)
	v_mfma_f32_16x16x32_bf16 v[66:69], v[224:227], v[158:161], v[66:69]
	ds_read_b128 v[220:223], v122 offset:24576
	ds_read_b128 v[224:227], v123 offset:24576
	s_waitcnt lgkmcnt(13)
	v_mfma_f32_16x16x32_bf16 v[70:73], v[228:231], v[154:157], v[70:73]
	s_waitcnt lgkmcnt(12)
	v_mfma_f32_16x16x32_bf16 v[70:73], v[232:235], v[158:161], v[70:73]
	ds_read_b128 v[228:231], v122 offset:26624
	ds_read_b128 v[232:235], v123 offset:26624
	s_waitcnt lgkmcnt(13)
	v_mfma_f32_16x16x32_bf16 v[74:77], v[236:239], v[154:157], v[74:77]
	s_waitcnt lgkmcnt(12)
	v_mfma_f32_16x16x32_bf16 v[74:77], v[240:243], v[158:161], v[74:77]
	ds_read_b128 v[236:239], v122 offset:28672
	ds_read_b128 v[240:243], v123 offset:28672
	s_waitcnt lgkmcnt(13)
	v_mfma_f32_16x16x32_bf16 v[78:81], v[186:189], v[154:157], v[78:81]
	s_waitcnt lgkmcnt(12)
	v_mfma_f32_16x16x32_bf16 v[78:81], v[190:193], v[158:161], v[78:81]
	ds_read_b128 v[186:189], v122 offset:30720
	ds_read_b128 v[190:193], v123 offset:30720
	s_waitcnt lgkmcnt(13)
	v_mfma_f32_16x16x32_bf16 v[82:85], v[194:197], v[154:157], v[82:85]
	s_waitcnt lgkmcnt(12)
	v_mfma_f32_16x16x32_bf16 v[82:85], v[198:201], v[158:161], v[82:85]
	ds_read_b128 v[194:197], v122 offset:32768
	ds_read_b128 v[198:201], v123 offset:32768
	s_waitcnt lgkmcnt(13)
	v_mfma_f32_16x16x32_bf16 v[86:89], v[202:205], v[154:157], v[86:89]
	s_waitcnt lgkmcnt(12)
	v_mfma_f32_16x16x32_bf16 v[86:89], v[206:209], v[158:161], v[86:89]
	ds_read_b128 v[202:205], v122 offset:34816
	ds_read_b128 v[206:209], v123 offset:34816
	s_waitcnt lgkmcnt(13)
; #define LAS __attribute__((address_space(3)))
; #define MFMA16(a, b, c) __builtin_amdgcn_mfma_f32_16x16x32_bf16((a), (b), (c), 0, 0, 0)
; __device__ __forceinline__ void qk_at(const LAS unsigned char* kp0, const LAS unsigned char* kp1, int off, bf16x8 qf0, bf16x8 qf1, f32x4& S0, f32x4& S1) {
;     const bf16x8 k00 = *(const LAS bf16x8*)(kp0 + off), k01 = *(const LAS bf16x8*)(kp1 + off);
;     const bf16x8 k10 = *(const LAS bf16x8*)(kp0 + off + 2048), k11 = *(const LAS bf16x8*)(kp1 + off + 2048);
;     const f32x4 z = {0.f, 0.f, 0.f, 0.f};
;     S0 = MFMA16(k00, qf0, z); S0 = MFMA16(k01, qf1, S0);
;     S1 = MFMA16(k10, qf0, z); S1 = MFMA16(k11, qf1, S1);
; }
; __device__ __forceinline__ void softmax_step(f32x4& s0, f32x4& s1, float& m, float& l, f32x4 (&O)[4]) {
;     float t = fmaxf(fmaxf(fmaxf(s0[0], s0[1]), fmaxf(s0[2], s0[3])), fmaxf(fmaxf(s1[0], s1[1]), fmaxf(s1[2], s1[3])));
;     t = xrow16_max(t);
;     const float mn = fmaxf(m, t), alpha = __builtin_amdgcn_exp2f(m - mn);
;     m = mn;
; #pragma unroll
;     for (int k = 0; k < 4; ++k) { s0[k] = __builtin_amdgcn_exp2f(s0[k] - mn); s1[k] = __builtin_amdgcn_exp2f(s1[k] - mn); }
	v_mfma_f32_16x16x32_bf16 v[90:93], v[210:213], v[154:157], v[90:93]
	s_waitcnt lgkmcnt(12)
	v_mfma_f32_16x16x32_bf16 v[90:93], v[214:217], v[158:161], v[90:93]
	s_waitcnt lgkmcnt(11)
	v_mfma_f32_16x16x32_bf16 v[94:97], v[220:223], v[154:157], v[94:97]
	s_waitcnt lgkmcnt(10)
	v_mfma_f32_16x16x32_bf16 v[94:97], v[224:227], v[158:161], v[94:97]
	s_waitcnt lgkmcnt(9)
	v_mfma_f32_16x16x32_bf16 v[98:101], v[228:231], v[154:157], v[98:101]
	s_waitcnt lgkmcnt(8)
	v_mfma_f32_16x16x32_bf16 v[98:101], v[232:235], v[158:161], v[98:101]
	s_waitcnt lgkmcnt(7)
	v_mfma_f32_16x16x32_bf16 v[102:105], v[236:239], v[154:157], v[102:105]
	s_waitcnt lgkmcnt(6)
	v_mfma_f32_16x16x32_bf16 v[102:105], v[240:243], v[158:161], v[102:105]
	s_waitcnt lgkmcnt(5)
	v_mfma_f32_16x16x32_bf16 v[106:109], v[186:189], v[154:157], v[106:109]
	s_waitcnt lgkmcnt(4)
	v_mfma_f32_16x16x32_bf16 v[106:109], v[190:193], v[158:161], v[106:109]
	s_waitcnt lgkmcnt(3)
	v_mfma_f32_16x16x32_bf16 v[110:113], v[194:197], v[154:157], v[110:113]
	s_waitcnt lgkmcnt(2)
	v_mfma_f32_16x16x32_bf16 v[110:113], v[198:201], v[158:161], v[110:113]
	s_waitcnt lgkmcnt(1)
	v_mfma_f32_16x16x32_bf16 v[114:117], v[202:205], v[154:157], v[114:117]
	s_waitcnt lgkmcnt(0)
	v_mfma_f32_16x16x32_bf16 v[114:117], v[206:209], v[158:161], v[114:117]
	v_max3_f32 v219, v50, v51, v52
	v_max3_f32 v244, v54, v55, v56
	v_max3_f32 v245, v58, v59, v60
	v_max3_f32 v120, v62, v63, v64
	v_max3_f32 v219, v219, v53, v66
	v_max3_f32 v244, v244, v57, v70
	v_max3_f32 v245, v245, v61, v74
	v_max3_f32 v120, v120, v65, v78
	v_max3_f32 v219, v219, v67, v68
	v_max3_f32 v244, v244, v71, v72
	v_max3_f32 v245, v245, v75, v76
	v_max3_f32 v120, v120, v79, v80
	ds_read_b64_tr_b16 v[186:187], v124 offset:2048
	ds_read_b64_tr_b16 v[188:189], v124 offset:4096
	ds_read_b64_tr_b16 v[190:191], v125 offset:2048
	ds_read_b64_tr_b16 v[192:193], v125 offset:4096
	ds_read_b64_tr_b16 v[194:195], v126 offset:2048
	ds_read_b64_tr_b16 v[196:197], v126 offset:4096
	ds_read_b64_tr_b16 v[198:199], v127 offset:2048
	ds_read_b64_tr_b16 v[200:201], v127 offset:4096
	v_max3_f32 v219, v219, v69, v82
	v_max3_f32 v244, v244, v73, v86
	v_max3_f32 v245, v245, v77, v90
	v_max3_f32 v120, v120, v81, v94
	v_max3_f32 v219, v219, v83, v84
	v_max3_f32 v244, v244, v87, v88
	v_max3_f32 v245, v245, v91, v92
	v_max3_f32 v120, v120, v95, v96
	v_max3_f32 v219, v219, v85, v98
	v_max3_f32 v244, v244, v89, v102
	v_max3_f32 v245, v245, v93, v106
	v_max3_f32 v120, v120, v97, v110
	v_max3_f32 v219, v219, v99, v100
	v_max3_f32 v244, v244, v103, v104
	v_max3_f32 v245, v245, v107, v108
	v_max3_f32 v120, v120, v111, v112
	v_max3_f32 v219, v219, v101, v114
	v_max3_f32 v219, v219, v115, v116
	v_max_f32_e32 v219, v219, v117
	v_max_f32_e32 v244, v244, v105
	v_max_f32_e32 v245, v245, v109
	v_max_f32_e32 v120, v120, v113
	v_max3_f32 v178, v219, v244, v245
	v_max_f32_e32 v178, v178, v120
	v_mov_b32_e32 v219, v178
	s_nop 1
	v_permlane16_swap_b32_e32 v178, v219
	v_max_f32_e32 v178, v178, v219
	v_mov_b32_e32 v219, v178
	s_nop 1
	v_permlane32_swap_b32_e32 v178, v219
	v_max3_f32 v178, v178, v219, v145
	s_waitcnt lgkmcnt(7)
	ds_read_b64_tr_b16 v[202:203], v124 offset:6144
	ds_read_b64_tr_b16 v[204:205], v124 offset:8192
	ds_read_b64_tr_b16 v[206:207], v125 offset:6144
	ds_read_b64_tr_b16 v[208:209], v125 offset:8192
	ds_read_b64_tr_b16 v[228:229], v126 offset:6144
	ds_read_b64_tr_b16 v[230:231], v126 offset:8192
	ds_read_b64_tr_b16 v[232:233], v127 offset:6144
	ds_read_b64_tr_b16 v[234:235], v127 offset:8192
	v_mov_b32_e32 v244, v178
	v_pk_add_f32 v[50:51], v[50:51], v[244:245] op_sel_hi:[1,0] neg_lo:[0,1] neg_hi:[0,1]
	v_pk_add_f32 v[52:53], v[52:53], v[244:245] op_sel_hi:[1,0] neg_lo:[0,1] neg_hi:[0,1]
	v_pk_add_f32 v[54:55], v[54:55], v[244:245] op_sel_hi:[1,0] neg_lo:[0,1] neg_hi:[0,1]
	v_pk_add_f32 v[56:57], v[56:57], v[244:245] op_sel_hi:[1,0] neg_lo:[0,1] neg_hi:[0,1]
	v_pk_add_f32 v[58:59], v[58:59], v[244:245] op_sel_hi:[1,0] neg_lo:[0,1] neg_hi:[0,1]
	v_pk_add_f32 v[60:61], v[60:61], v[244:245] op_sel_hi:[1,0] neg_lo:[0,1] neg_hi:[0,1]
	v_pk_add_f32 v[62:63], v[62:63], v[244:245] op_sel_hi:[1,0] neg_lo:[0,1] neg_hi:[0,1]
	v_pk_add_f32 v[64:65], v[64:65], v[244:245] op_sel_hi:[1,0] neg_lo:[0,1] neg_hi:[0,1]
	v_pk_add_f32 v[66:67], v[66:67], v[244:245] op_sel_hi:[1,0] neg_lo:[0,1] neg_hi:[0,1]
	v_pk_add_f32 v[68:69], v[68:69], v[244:245] op_sel_hi:[1,0] neg_lo:[0,1] neg_hi:[0,1]
	v_pk_add_f32 v[70:71], v[70:71], v[244:245] op_sel_hi:[1,0] neg_lo:[0,1] neg_hi:[0,1]
	v_pk_add_f32 v[72:73], v[72:73], v[244:245] op_sel_hi:[1,0] neg_lo:[0,1] neg_hi:[0,1]
	v_pk_add_f32 v[74:75], v[74:75], v[244:245] op_sel_hi:[1,0] neg_lo:[0,1] neg_hi:[0,1]
	v_pk_add_f32 v[76:77], v[76:77], v[244:245] op_sel_hi:[1,0] neg_lo:[0,1] neg_hi:[0,1]
	v_pk_add_f32 v[78:79], v[78:79], v[244:245] op_sel_hi:[1,0] neg_lo:[0,1] neg_hi:[0,1]
	v_pk_add_f32 v[80:81], v[80:81], v[244:245] op_sel_hi:[1,0] neg_lo:[0,1] neg_hi:[0,1]
	v_pk_add_f32 v[82:83], v[82:83], v[244:245] op_sel_hi:[1,0] neg_lo:[0,1] neg_hi:[0,1]
	v_pk_add_f32 v[84:85], v[84:85], v[244:245] op_sel_hi:[1,0] neg_lo:[0,1] neg_hi:[0,1]
	v_pk_add_f32 v[86:87], v[86:87], v[244:245] op_sel_hi:[1,0] neg_lo:[0,1] neg_hi:[0,1]
	v_pk_add_f32 v[88:89], v[88:89], v[244:245] op_sel_hi:[1,0] neg_lo:[0,1] neg_hi:[0,1]
	v_pk_add_f32 v[90:91], v[90:91], v[244:245] op_sel_hi:[1,0] neg_lo:[0,1] neg_hi:[0,1]
	v_pk_add_f32 v[92:93], v[92:93], v[244:245] op_sel_hi:[1,0] neg_lo:[0,1] neg_hi:[0,1]
	v_pk_add_f32 v[94:95], v[94:95], v[244:245] op_sel_hi:[1,0] neg_lo:[0,1] neg_hi:[0,1]
	v_pk_add_f32 v[96:97], v[96:97], v[244:245] op_sel_hi:[1,0] neg_lo:[0,1] neg_hi:[0,1]
; #define LAS __attribute__((address_space(3)))
; __device__ __forceinline__ unsigned pk2(float lo, float hi) { return pg8::cvt_pk_bf16(lo, hi); }
; __device__ __forceinline__ s16x4 vtr(const LAS unsigned char* p) { return __builtin_bit_cast(s16x4, __builtin_amdgcn_ds_read_tr16_b64_v4i16((LAS s16x4*)p)); }
; #define MFMA16(a, b, c) __builtin_amdgcn_mfma_f32_16x16x32_bf16((a), (b), (c), 0, 0, 0)
; __device__ __forceinline__ void pv_at(const LAS unsigned char* const (&vp)[4], int off, const f32x4& P0, const f32x4& P1, f32x4 (&O)[4]) {
;     v4u pw; pw.x = pk2(P0[0], P0[1]); pw.y = pk2(P0[2], P0[3]); pw.z = pk2(P1[0], P1[1]); pw.w = pk2(P1[2], P1[3]);
;     const bf16x8 pb = __builtin_bit_cast(bf16x8, pw);
; #pragma unroll
;     for (int db = 0; db < 4; ++db) {
;         const s16x4 lo = vtr(vp[db] + off), hi = vtr(vp[db] + off + 2048);
;         const bf16x8 vt = (bf16x8){lo[0], lo[1], lo[2], lo[3], hi[0], hi[1], hi[2], hi[3]};
;         O[db] = MFMA16(vt, pb, O[db]);
;     }
; }
; __device__ __forceinline__ void softmax_step(f32x4& s0, f32x4& s1, float& m, float& l, f32x4 (&O)[4]) {
;     float t = fmaxf(fmaxf(fmaxf(s0[0], s0[1]), fmaxf(s0[2], s0[3])), fmaxf(fmaxf(s1[0], s1[1]), fmaxf(s1[2], s1[3])));
;     t = xrow16_max(t);
;     const float mn = fmaxf(m, t), alpha = __builtin_amdgcn_exp2f(m - mn);
;     m = mn;
; #pragma unroll
;     for (int k = 0; k < 4; ++k) { s0[k] = __builtin_amdgcn_exp2f(s0[k] - mn); s1[k] = __builtin_amdgcn_exp2f(s1[k] - mn); }
;     l = l * alpha + ((s0[0] + s0[1]) + (s0[2] + s0[3])) + ((s1[0] + s1[1]) + (s1[2] + s1[3]));
; #pragma unroll
;     for (int db = 0; db < 4; ++db) O[db] *= alpha;
; }
	v_pk_add_f32 v[98:99], v[98:99], v[244:245] op_sel_hi:[1,0] neg_lo:[0,1] neg_hi:[0,1]
	v_pk_add_f32 v[100:101], v[100:101], v[244:245] op_sel_hi:[1,0] neg_lo:[0,1] neg_hi:[0,1]
	v_pk_add_f32 v[102:103], v[102:103], v[244:245] op_sel_hi:[1,0] neg_lo:[0,1] neg_hi:[0,1]
	v_pk_add_f32 v[104:105], v[104:105], v[244:245] op_sel_hi:[1,0] neg_lo:[0,1] neg_hi:[0,1]
	v_pk_add_f32 v[106:107], v[106:107], v[244:245] op_sel_hi:[1,0] neg_lo:[0,1] neg_hi:[0,1]
	v_pk_add_f32 v[108:109], v[108:109], v[244:245] op_sel_hi:[1,0] neg_lo:[0,1] neg_hi:[0,1]
	v_pk_add_f32 v[110:111], v[110:111], v[244:245] op_sel_hi:[1,0] neg_lo:[0,1] neg_hi:[0,1]
	v_pk_add_f32 v[112:113], v[112:113], v[244:245] op_sel_hi:[1,0] neg_lo:[0,1] neg_hi:[0,1]
	v_pk_add_f32 v[114:115], v[114:115], v[244:245] op_sel_hi:[1,0] neg_lo:[0,1] neg_hi:[0,1]
	v_pk_add_f32 v[116:117], v[116:117], v[244:245] op_sel_hi:[1,0] neg_lo:[0,1] neg_hi:[0,1]
	v_sub_f32_e32 v219, v145, v178
	v_exp_f32_e32 v50, v50
	v_exp_f32_e32 v51, v51
	v_exp_f32_e32 v52, v52
	v_exp_f32_e32 v53, v53
	v_exp_f32_e32 v54, v54
	v_exp_f32_e32 v55, v55
	v_exp_f32_e32 v56, v56
	v_exp_f32_e32 v57, v57
	v_exp_f32_e32 v58, v58
	v_exp_f32_e32 v59, v59
	v_exp_f32_e32 v60, v60
	v_exp_f32_e32 v61, v61
	v_exp_f32_e32 v62, v62
	v_exp_f32_e32 v63, v63
	v_exp_f32_e32 v64, v64
	v_exp_f32_e32 v65, v65
	v_exp_f32_e32 v66, v66
	v_exp_f32_e32 v67, v67
	v_exp_f32_e32 v68, v68
	v_exp_f32_e32 v69, v69
	v_exp_f32_e32 v70, v70
	v_exp_f32_e32 v71, v71
	v_exp_f32_e32 v72, v72
	v_exp_f32_e32 v73, v73
	v_exp_f32_e32 v74, v74
	v_exp_f32_e32 v75, v75
	v_exp_f32_e32 v76, v76
	v_exp_f32_e32 v77, v77
	v_exp_f32_e32 v78, v78
	v_exp_f32_e32 v79, v79
	v_exp_f32_e32 v80, v80
	v_exp_f32_e32 v81, v81
	v_exp_f32_e32 v82, v82
	v_exp_f32_e32 v83, v83
	v_exp_f32_e32 v84, v84
	v_exp_f32_e32 v85, v85
	v_exp_f32_e32 v86, v86
	v_exp_f32_e32 v87, v87
	v_exp_f32_e32 v88, v88
	v_exp_f32_e32 v89, v89
	v_exp_f32_e32 v90, v90
	v_exp_f32_e32 v91, v91
	v_exp_f32_e32 v92, v92
	v_exp_f32_e32 v93, v93
	v_exp_f32_e32 v94, v94
	v_exp_f32_e32 v95, v95
	v_exp_f32_e32 v96, v96
	v_exp_f32_e32 v97, v97
	v_exp_f32_e32 v98, v98
	v_exp_f32_e32 v99, v99
	v_exp_f32_e32 v100, v100
	v_exp_f32_e32 v101, v101
	v_exp_f32_e32 v102, v102
	v_exp_f32_e32 v103, v103
	v_exp_f32_e32 v104, v104
	v_exp_f32_e32 v105, v105
	v_exp_f32_e32 v106, v106
	v_exp_f32_e32 v107, v107
	v_exp_f32_e32 v108, v108
	v_exp_f32_e32 v109, v109
	v_exp_f32_e32 v110, v110
	v_exp_f32_e32 v111, v111
	v_exp_f32_e32 v112, v112
	v_exp_f32_e32 v113, v113
	v_exp_f32_e32 v114, v114
	v_exp_f32_e32 v115, v115
	v_exp_f32_e32 v116, v116
	v_exp_f32_e32 v117, v117
	v_exp_f32_e32 v219, v219
	v_pk_add_f32 v[236:237], v[50:51], v[52:53]
	v_pk_add_f32 v[238:239], v[54:55], v[56:57]
	v_pk_add_f32 v[240:241], v[58:59], v[60:61]
	v_pk_add_f32 v[242:243], v[62:63], v[64:65]
	v_pk_add_f32 v[236:237], v[236:237], v[66:67]
	v_pk_add_f32 v[238:239], v[238:239], v[70:71]
	v_pk_add_f32 v[240:241], v[240:241], v[74:75]
	v_pk_add_f32 v[242:243], v[242:243], v[78:79]
	v_pk_add_f32 v[236:237], v[236:237], v[68:69]
	v_pk_add_f32 v[238:239], v[238:239], v[72:73]
	v_pk_add_f32 v[240:241], v[240:241], v[76:77]
	v_pk_add_f32 v[242:243], v[242:243], v[80:81]
	v_pk_add_f32 v[236:237], v[236:237], v[82:83]
	v_pk_add_f32 v[238:239], v[238:239], v[86:87]
	v_pk_add_f32 v[240:241], v[240:241], v[90:91]
	v_pk_add_f32 v[242:243], v[242:243], v[94:95]
	v_pk_add_f32 v[236:237], v[236:237], v[84:85]
	v_pk_add_f32 v[238:239], v[238:239], v[88:89]
	v_pk_add_f32 v[240:241], v[240:241], v[92:93]
	v_pk_add_f32 v[242:243], v[242:243], v[96:97]
	v_pk_add_f32 v[236:237], v[236:237], v[98:99]
	v_pk_add_f32 v[238:239], v[238:239], v[102:103]
	v_pk_add_f32 v[240:241], v[240:241], v[106:107]
	v_pk_add_f32 v[242:243], v[242:243], v[110:111]
	v_pk_add_f32 v[236:237], v[236:237], v[100:101]
	v_pk_add_f32 v[238:239], v[238:239], v[104:105]
	v_pk_add_f32 v[240:241], v[240:241], v[108:109]
	v_pk_add_f32 v[242:243], v[242:243], v[112:113]
	v_pk_add_f32 v[236:237], v[236:237], v[114:115]
	v_pk_add_f32 v[236:237], v[236:237], v[116:117]
	v_pk_add_f32 v[236:237], v[236:237], v[238:239]
	v_pk_add_f32 v[240:241], v[240:241], v[242:243]
	v_cndmask_b32_e64 v219, 0, v219, s[74:75]
	v_pk_add_f32 v[236:237], v[236:237], v[240:241]
	v_add_f32_e32 v185, v236, v237
	v_add_f32_e32 v185, v185, v219
	v_cvt_pk_bf16_f32 v236, v50, v51
	v_cvt_pk_bf16_f32 v237, v52, v53
	v_cvt_pk_bf16_f32 v238, v54, v55
	v_cvt_pk_bf16_f32 v239, v56, v57
	s_nop 1
	s_waitcnt lgkmcnt(14)
	v_mfma_f32_16x16x32_bf16 v[210:213], v[186:189], v[236:239], 0
	s_waitcnt lgkmcnt(12)
	v_mfma_f32_16x16x32_bf16 v[214:217], v[190:193], v[236:239], 0
	s_waitcnt lgkmcnt(10)
	v_mfma_f32_16x16x32_bf16 v[220:223], v[194:197], v[236:239], 0
	s_waitcnt lgkmcnt(8)
	v_mfma_f32_16x16x32_bf16 v[224:227], v[198:201], v[236:239], 0
	v_cvt_pk_bf16_f32 v240, v58, v59
	v_cvt_pk_bf16_f32 v241, v60, v61
	v_cvt_pk_bf16_f32 v242, v62, v63
	v_cvt_pk_bf16_f32 v243, v64, v65
	s_waitcnt lgkmcnt(7)
	ds_read_b64_tr_b16 v[186:187], v124 offset:10240
	ds_read_b64_tr_b16 v[188:189], v124 offset:12288
	ds_read_b64_tr_b16 v[190:191], v125 offset:10240
	ds_read_b64_tr_b16 v[192:193], v125 offset:12288
	ds_read_b64_tr_b16 v[194:195], v126 offset:10240
	ds_read_b64_tr_b16 v[196:197], v126 offset:12288
	ds_read_b64_tr_b16 v[198:199], v127 offset:10240
	ds_read_b64_tr_b16 v[200:201], v127 offset:12288
	v_fmamk_f32 v50, v130, 0x43000000, v132
	v_fmamk_f32 v51, v130, 0x42fe0000, v132
	v_fmamk_f32 v52, v130, 0x42fc0000, v132
	v_fmamk_f32 v53, v130, 0x42fa0000, v132
	v_mov_b32_e32 v245, 0xff800000
	v_cndmask_b32_e64 v50, v245, v50, s[16:17]
	v_cndmask_b32_e64 v51, v245, v51, s[18:19]
	v_cndmask_b32_e64 v52, v245, v52, s[22:23]
	v_cndmask_b32_e64 v53, v245, v53, s[24:25]
	v_fmamk_f32 v54, v130, 0x42e00000, v132
	v_fmamk_f32 v55, v130, 0x42de0000, v132
	v_fmamk_f32 v56, v130, 0x42dc0000, v132
	v_fmamk_f32 v57, v130, 0x42da0000, v132
	s_waitcnt lgkmcnt(14)
; #define LAS __attribute__((address_space(3)))
; __device__ __forceinline__ unsigned pk2(float lo, float hi) { return pg8::cvt_pk_bf16(lo, hi); }
; __device__ __forceinline__ s16x4 vtr(const LAS unsigned char* p) { return __builtin_bit_cast(s16x4, __builtin_amdgcn_ds_read_tr16_b64_v4i16((LAS s16x4*)p)); }
; #define MFMA16(a, b, c) __builtin_amdgcn_mfma_f32_16x16x32_bf16((a), (b), (c), 0, 0, 0)
; __device__ __forceinline__ void pv_at(const LAS unsigned char* const (&vp)[4], int off, const f32x4& P0, const f32x4& P1, f32x4 (&O)[4]) {
;     v4u pw; pw.x = pk2(P0[0], P0[1]); pw.y = pk2(P0[2], P0[3]); pw.z = pk2(P1[0], P1[1]); pw.w = pk2(P1[2], P1[3]);
;     const bf16x8 pb = __builtin_bit_cast(bf16x8, pw);
; #pragma unroll
;     for (int db = 0; db < 4; ++db) {
;         const s16x4 lo = vtr(vp[db] + off), hi = vtr(vp[db] + off + 2048);
;         const bf16x8 vt = (bf16x8){lo[0], lo[1], lo[2], lo[3], hi[0], hi[1], hi[2], hi[3]};
;         O[db] = MFMA16(vt, pb, O[db]);
;     }
; }
; template <bool MASK> __device__ __forceinline__ void a_scores(f32x4& S0, f32x4& S1, float basef, float c1, float slope2, int krow0, int kstart) {
; #pragma unroll
;     for (int r = 0; r < 4; ++r) {
;         const float d0 = fabsf(basef - (float)r), d1 = fabsf(basef - (float)(16 + r));
;         const float v0 = S0[r] - slope2 * d0, v1 = S1[r] - slope2 * d1;
;         if (MASK) { const int p0 = kstart + krow0 + r, p1 = p0 + 16;
;             S0[r] = (d0 <= 128.f && p0 >= 0 && p0 < SEQ) ? v0 : -INFINITY; S1[r] = (d1 <= 128.f && p1 >= 0 && p1 < SEQ) ? v1 : -INFINITY; }
;         else { S0[r] = v0; S1[r] = v1; }
;     }
; }
	v_mfma_f32_16x16x32_bf16 v[210:213], v[202:205], v[240:243], v[210:213]
	s_waitcnt lgkmcnt(12)
	v_mfma_f32_16x16x32_bf16 v[214:217], v[206:209], v[240:243], v[214:217]
	s_waitcnt lgkmcnt(10)
	v_mfma_f32_16x16x32_bf16 v[220:223], v[228:231], v[240:243], v[220:223]
	s_waitcnt lgkmcnt(8)
	v_mfma_f32_16x16x32_bf16 v[224:227], v[232:235], v[240:243], v[224:227]
	v_cvt_pk_bf16_f32 v236, v66, v67
	v_cvt_pk_bf16_f32 v237, v68, v69
	v_cvt_pk_bf16_f32 v238, v70, v71
	v_cvt_pk_bf16_f32 v239, v72, v73
	s_waitcnt lgkmcnt(7)
	ds_read_b64_tr_b16 v[202:203], v124 offset:14336
	ds_read_b64_tr_b16 v[204:205], v124 offset:16384
	ds_read_b64_tr_b16 v[206:207], v125 offset:14336
	ds_read_b64_tr_b16 v[208:209], v125 offset:16384
	ds_read_b64_tr_b16 v[228:229], v126 offset:14336
	ds_read_b64_tr_b16 v[230:231], v126 offset:16384
	ds_read_b64_tr_b16 v[232:233], v127 offset:14336
	ds_read_b64_tr_b16 v[234:235], v127 offset:16384
	v_fmamk_f32 v58, v130, 0x42c00000, v132
	v_fmamk_f32 v59, v130, 0x42be0000, v132
	v_fmamk_f32 v60, v130, 0x42bc0000, v132
	v_fmamk_f32 v61, v130, 0x42ba0000, v132
	v_fmamk_f32 v62, v130, 0x42a00000, v132
	v_fmamk_f32 v63, v130, 0x429e0000, v132
	v_fmamk_f32 v64, v130, 0x429c0000, v132
	v_fmamk_f32 v65, v130, 0x429a0000, v132
	s_waitcnt lgkmcnt(14)
	v_mfma_f32_16x16x32_bf16 v[210:213], v[186:189], v[236:239], v[210:213]
	s_waitcnt lgkmcnt(12)
	v_mfma_f32_16x16x32_bf16 v[214:217], v[190:193], v[236:239], v[214:217]
	s_waitcnt lgkmcnt(10)
	v_mfma_f32_16x16x32_bf16 v[220:223], v[194:197], v[236:239], v[220:223]
	s_waitcnt lgkmcnt(8)
	v_mfma_f32_16x16x32_bf16 v[224:227], v[198:201], v[236:239], v[224:227]
	v_cvt_pk_bf16_f32 v240, v74, v75
	v_cvt_pk_bf16_f32 v241, v76, v77
	v_cvt_pk_bf16_f32 v242, v78, v79
	v_cvt_pk_bf16_f32 v243, v80, v81
	s_waitcnt lgkmcnt(7)
	ds_read_b64_tr_b16 v[186:187], v124 offset:18432
	ds_read_b64_tr_b16 v[188:189], v124 offset:20480
	ds_read_b64_tr_b16 v[190:191], v125 offset:18432
	ds_read_b64_tr_b16 v[192:193], v125 offset:20480
	ds_read_b64_tr_b16 v[194:195], v126 offset:18432
	ds_read_b64_tr_b16 v[196:197], v126 offset:20480
	ds_read_b64_tr_b16 v[198:199], v127 offset:18432
	ds_read_b64_tr_b16 v[200:201], v127 offset:20480
	v_fmamk_f32 v66, v130, 0x42800000, v132
	v_fmamk_f32 v67, v130, 0x427c0000, v132
	v_fmamk_f32 v68, v130, 0x42780000, v132
	v_fmamk_f32 v69, v130, 0x42740000, v132
	v_fmamk_f32 v70, v130, 0x42400000, v132
	v_fmamk_f32 v71, v130, 0x423c0000, v132
	v_fmamk_f32 v72, v130, 0x42380000, v132
	v_fmamk_f32 v73, v130, 0x42340000, v132
	s_waitcnt lgkmcnt(14)
	v_mfma_f32_16x16x32_bf16 v[210:213], v[202:205], v[240:243], v[210:213]
	s_waitcnt lgkmcnt(12)
	v_mfma_f32_16x16x32_bf16 v[214:217], v[206:209], v[240:243], v[214:217]
	s_waitcnt lgkmcnt(10)
	v_mfma_f32_16x16x32_bf16 v[220:223], v[228:231], v[240:243], v[220:223]
	s_waitcnt lgkmcnt(8)
	v_mfma_f32_16x16x32_bf16 v[224:227], v[232:235], v[240:243], v[224:227]
	v_cvt_pk_bf16_f32 v236, v82, v83
	v_cvt_pk_bf16_f32 v237, v84, v85
	v_cvt_pk_bf16_f32 v238, v86, v87
	v_cvt_pk_bf16_f32 v239, v88, v89
	s_waitcnt lgkmcnt(7)
	ds_read_b64_tr_b16 v[202:203], v124 offset:22528
	ds_read_b64_tr_b16 v[204:205], v124 offset:24576
	ds_read_b64_tr_b16 v[206:207], v125 offset:22528
	ds_read_b64_tr_b16 v[208:209], v125 offset:24576
	ds_read_b64_tr_b16 v[228:229], v126 offset:22528
	ds_read_b64_tr_b16 v[230:231], v126 offset:24576
	ds_read_b64_tr_b16 v[232:233], v127 offset:22528
	ds_read_b64_tr_b16 v[234:235], v127 offset:24576
	v_fmamk_f32 v74, v130, 0x42000000, v132
	v_fmamk_f32 v75, v130, 0x41f80000, v132
	v_fmamk_f32 v76, v130, 0x41f00000, v132
	v_fmamk_f32 v77, v130, 0x41e80000, v132
	v_fmamk_f32 v78, v130, 0x41800000, v132
	v_fmamk_f32 v79, v130, 0x41700000, v132
	v_fmamk_f32 v80, v130, 0x41600000, v132
	v_fmamk_f32 v81, v130, 0x41500000, v132
	s_waitcnt lgkmcnt(14)
	v_mfma_f32_16x16x32_bf16 v[210:213], v[186:189], v[236:239], v[210:213]
	s_waitcnt lgkmcnt(12)
	v_mfma_f32_16x16x32_bf16 v[214:217], v[190:193], v[236:239], v[214:217]
	s_waitcnt lgkmcnt(10)
	v_mfma_f32_16x16x32_bf16 v[220:223], v[194:197], v[236:239], v[220:223]
	s_waitcnt lgkmcnt(8)
	v_mfma_f32_16x16x32_bf16 v[224:227], v[198:201], v[236:239], v[224:227]
	v_cvt_pk_bf16_f32 v240, v90, v91
	v_cvt_pk_bf16_f32 v241, v92, v93
	v_cvt_pk_bf16_f32 v242, v94, v95
	v_cvt_pk_bf16_f32 v243, v96, v97
	s_waitcnt lgkmcnt(7)
	ds_read_b64_tr_b16 v[186:187], v124 offset:26624
	ds_read_b64_tr_b16 v[188:189], v124 offset:28672
	ds_read_b64_tr_b16 v[190:191], v125 offset:26624
	ds_read_b64_tr_b16 v[192:193], v125 offset:28672
	ds_read_b64_tr_b16 v[194:195], v126 offset:26624
	ds_read_b64_tr_b16 v[196:197], v126 offset:28672
	ds_read_b64_tr_b16 v[198:199], v127 offset:26624
	ds_read_b64_tr_b16 v[200:201], v127 offset:28672
	v_add_f32_e32 v219, 0, v129
	v_mul_f32_e64 v82, v130, |v219|
	v_add_f32_e32 v245, 0xbf800000, v129
	v_mul_f32_e64 v83, v130, |v245|
	v_add_f32_e32 v219, 0xc0000000, v129
	v_mul_f32_e64 v84, v130, |v219|
	v_add_f32_e32 v245, 0xc0400000, v129
	v_mul_f32_e64 v85, v130, |v245|
	v_fmamk_f32 v86, v131, 0xc1800000, v133
	v_fmamk_f32 v87, v131, 0xc1880000, v133
	v_fmamk_f32 v88, v131, 0xc1900000, v133
	v_fmamk_f32 v89, v131, 0xc1980000, v133
	s_waitcnt lgkmcnt(14)
	v_mfma_f32_16x16x32_bf16 v[210:213], v[202:205], v[240:243], v[210:213]
	s_waitcnt lgkmcnt(12)
	v_mfma_f32_16x16x32_bf16 v[214:217], v[206:209], v[240:243], v[214:217]
	s_waitcnt lgkmcnt(10)
	v_mfma_f32_16x16x32_bf16 v[220:223], v[228:231], v[240:243], v[220:223]
	s_waitcnt lgkmcnt(8)
	v_mfma_f32_16x16x32_bf16 v[224:227], v[232:235], v[240:243], v[224:227]
	v_cvt_pk_bf16_f32 v236, v98, v99
	v_cvt_pk_bf16_f32 v237, v100, v101
	v_cvt_pk_bf16_f32 v238, v102, v103
	v_cvt_pk_bf16_f32 v239, v104, v105
	s_waitcnt lgkmcnt(7)
; __device__ __forceinline__ unsigned pk2(float lo, float hi) { return pg8::cvt_pk_bf16(lo, hi); }
; __device__ __forceinline__ void store_o(bf16* yrow, int g, float l, const f32x4 (&O)[4]) {
;     const float inv = 1.0f / xrow16_sum(l);
;     unsigned wx[4], wy[4];
; #pragma unroll
;     for (int db = 0; db < 4; ++db) { wx[db] = pk2(O[db][0] * inv, O[db][1] * inv); wy[db] = pk2(O[db][2] * inv, O[db][3] * inv); }
; #pragma unroll
;     for (int p = 0; p < 2; ++p) {
;         auto rx = __builtin_amdgcn_permlane16_swap(wx[2 * p], wx[2 * p + 1], false, false); wx[2 * p] = rx[0]; wx[2 * p + 1] = rx[1];
;         auto ry = __builtin_amdgcn_permlane16_swap(wy[2 * p], wy[2 * p + 1], false, false); wy[2 * p] = ry[0]; wy[2 * p + 1] = ry[1]; }
; #pragma unroll
;     for (int p = 0; p < 2; ++p) {
;         auto rx = __builtin_amdgcn_permlane32_swap(wx[p], wx[p + 2], false, false); wx[p] = rx[0]; wx[p + 2] = rx[1];
;         auto ry = __builtin_amdgcn_permlane32_swap(wy[p], wy[p + 2], false, false); wy[p] = ry[0]; wy[p + 2] = ry[1]; }
;     v4u lo = {wx[0], wy[0], wx[1], wy[1]}, hi = {wx[2], wy[2], wx[3], wy[3]};
;     *(v4u*)(yrow + 16 * g) = lo; *(v4u*)(yrow + 16 * g + 8) = hi;
; }
; template <bool MASK> __device__ __forceinline__ void a_scores(f32x4& S0, f32x4& S1, float basef, float c1, float slope2, int krow0, int kstart) {
; #pragma unroll
;     for (int r = 0; r < 4; ++r) {
;         const float d0 = fabsf(basef - (float)r), d1 = fabsf(basef - (float)(16 + r));
;         const float v0 = S0[r] - slope2 * d0, v1 = S1[r] - slope2 * d1;
;         if (MASK) { const int p0 = kstart + krow0 + r, p1 = p0 + 16;
;             S0[r] = (d0 <= 128.f && p0 >= 0 && p0 < SEQ) ? v0 : -INFINITY; S1[r] = (d1 <= 128.f && p1 >= 0 && p1 < SEQ) ? v1 : -INFINITY; }
;         else { S0[r] = v0; S1[r] = v1; }
;     }
; }
	ds_read_b64_tr_b16 v[202:203], v124 offset:30720
	ds_read_b64_tr_b16 v[204:205], v124 offset:32768
	ds_read_b64_tr_b16 v[206:207], v125 offset:30720
	ds_read_b64_tr_b16 v[208:209], v125 offset:32768
	ds_read_b64_tr_b16 v[228:229], v126 offset:30720
	ds_read_b64_tr_b16 v[230:231], v126 offset:32768
	ds_read_b64_tr_b16 v[232:233], v127 offset:30720
	ds_read_b64_tr_b16 v[234:235], v127 offset:32768
	v_fmamk_f32 v90, v131, 0xc2000000, v133
	v_fmamk_f32 v91, v131, 0xc2040000, v133
	v_fmamk_f32 v92, v131, 0xc2080000, v133
	v_fmamk_f32 v93, v131, 0xc20c0000, v133
	v_fmamk_f32 v94, v131, 0xc2400000, v133
	v_fmamk_f32 v95, v131, 0xc2440000, v133
	v_fmamk_f32 v96, v131, 0xc2480000, v133
	v_fmamk_f32 v97, v131, 0xc24c0000, v133
	s_waitcnt lgkmcnt(14)
	v_mfma_f32_16x16x32_bf16 v[210:213], v[186:189], v[236:239], v[210:213]
	s_waitcnt lgkmcnt(12)
	v_mfma_f32_16x16x32_bf16 v[214:217], v[190:193], v[236:239], v[214:217]
	s_waitcnt lgkmcnt(10)
	v_mfma_f32_16x16x32_bf16 v[220:223], v[194:197], v[236:239], v[220:223]
	s_waitcnt lgkmcnt(8)
	v_mfma_f32_16x16x32_bf16 v[224:227], v[198:201], v[236:239], v[224:227]
	v_cvt_pk_bf16_f32 v240, v106, v107
	v_cvt_pk_bf16_f32 v241, v108, v109
	v_cvt_pk_bf16_f32 v242, v110, v111
	v_cvt_pk_bf16_f32 v243, v112, v113
	s_waitcnt lgkmcnt(7)
	ds_read_b64_tr_b16 v[186:187], v124 offset:34816
	ds_read_b64_tr_b16 v[188:189], v124 offset:36864
	ds_read_b64_tr_b16 v[190:191], v125 offset:34816
	ds_read_b64_tr_b16 v[192:193], v125 offset:36864
	ds_read_b64_tr_b16 v[194:195], v126 offset:34816
	ds_read_b64_tr_b16 v[196:197], v126 offset:36864
	ds_read_b64_tr_b16 v[198:199], v127 offset:34816
	ds_read_b64_tr_b16 v[200:201], v127 offset:36864
	v_fmamk_f32 v98, v131, 0xc2800000, v133
	v_fmamk_f32 v99, v131, 0xc2820000, v133
	v_fmamk_f32 v100, v131, 0xc2840000, v133
	v_fmamk_f32 v101, v131, 0xc2860000, v133
	v_fmamk_f32 v102, v131, 0xc2a00000, v133
	v_fmamk_f32 v103, v131, 0xc2a20000, v133
	v_fmamk_f32 v104, v131, 0xc2a40000, v133
	v_fmamk_f32 v105, v131, 0xc2a60000, v133
	s_waitcnt lgkmcnt(14)
	v_mfma_f32_16x16x32_bf16 v[210:213], v[202:205], v[240:243], v[210:213]
	s_waitcnt lgkmcnt(12)
	v_mfma_f32_16x16x32_bf16 v[214:217], v[206:209], v[240:243], v[214:217]
	s_waitcnt lgkmcnt(10)
	v_mfma_f32_16x16x32_bf16 v[220:223], v[228:231], v[240:243], v[220:223]
	s_waitcnt lgkmcnt(8)
	v_mfma_f32_16x16x32_bf16 v[224:227], v[232:235], v[240:243], v[224:227]
	v_cvt_pk_bf16_f32 v236, v114, v115
	v_cvt_pk_bf16_f32 v237, v116, v117
	v_mov_b32_e32 v238, 0
	v_mov_b32_e32 v239, 0
	s_nop 1
	v_fmamk_f32 v106, v131, 0xc2c00000, v133
	v_fmamk_f32 v107, v131, 0xc2c20000, v133
	v_fmamk_f32 v108, v131, 0xc2c40000, v133
	v_fmamk_f32 v109, v131, 0xc2c60000, v133
	v_fmamk_f32 v110, v131, 0xc2e00000, v133
	v_fmamk_f32 v111, v131, 0xc2e20000, v133
	v_fmamk_f32 v112, v131, 0xc2e40000, v133
	v_fmamk_f32 v113, v131, 0xc2e60000, v133
	s_waitcnt lgkmcnt(6)
	v_mfma_f32_16x16x32_bf16 v[210:213], v[186:189], v[236:239], v[210:213]
	s_waitcnt lgkmcnt(4)
	v_mfma_f32_16x16x32_bf16 v[214:217], v[190:193], v[236:239], v[214:217]
	s_waitcnt lgkmcnt(2)
	v_mfma_f32_16x16x32_bf16 v[220:223], v[194:197], v[236:239], v[220:223]
	s_waitcnt lgkmcnt(0)
	v_mfma_f32_16x16x32_bf16 v[224:227], v[198:201], v[236:239], v[224:227]
	v_fmamk_f32 v114, v131, 0xc3000000, v133
	v_fmamk_f32 v115, v131, 0xc3010000, v133
	v_fmamk_f32 v116, v131, 0xc3020000, v133
	v_fmamk_f32 v117, v131, 0xc3030000, v133
	v_mov_b32_e32 v245, 0xff800000
	v_cndmask_b32_e64 v114, v245, v114, s[28:29]
	v_cndmask_b32_e64 v115, v245, v115, s[52:53]
	v_cndmask_b32_e64 v116, v245, v116, s[54:55]
	v_cndmask_b32_e64 v117, v245, v117, s[88:89]
	v_mov_b32_e32 v219, v185
	s_nop 1
	v_permlane16_swap_b32_e32 v185, v219
	v_add_f32_e32 v185, v185, v219
	v_mov_b32_e32 v219, v185
	s_nop 1
	v_permlane32_swap_b32_e32 v185, v219
	v_add_f32_e32 v185, v185, v219
	v_div_scale_f32 v236, s[78:79], v185, v185, 1.0
	v_div_scale_f32 v237, vcc, 1.0, v185, 1.0
	v_rcp_f32_e32 v238, v236
	s_nop 0
	v_fma_f32 v239, -v236, v238, 1.0
	v_fmac_f32_e32 v238, v239, v238
	v_mul_f32_e32 v240, v237, v238
	v_fma_f32 v241, -v236, v240, v237
	v_fmac_f32_e32 v240, v241, v238
	v_fma_f32 v237, -v236, v240, v237
	v_div_fmas_f32 v237, v237, v238, v240
	v_div_fixup_f32 v244, v237, v185, 1.0
	v_mul_f32_e32 v240, v210, v244
	v_mul_f32_e32 v241, v211, v244
	v_mul_f32_e32 v242, v212, v244
	v_mul_f32_e32 v243, v213, v244
	v_cvt_pk_bf16_f32 v186, v240, v241
	v_cvt_pk_bf16_f32 v187, v242, v243
	v_mul_f32_e32 v240, v214, v244
	v_mul_f32_e32 v241, v215, v244
	v_mul_f32_e32 v242, v216, v244
	v_mul_f32_e32 v243, v217, v244
	v_cvt_pk_bf16_f32 v188, v240, v241
	v_cvt_pk_bf16_f32 v189, v242, v243
	v_mul_f32_e32 v240, v220, v244
	v_mul_f32_e32 v241, v221, v244
	v_mul_f32_e32 v242, v222, v244
	v_mul_f32_e32 v243, v223, v244
	v_cvt_pk_bf16_f32 v190, v240, v241
	v_cvt_pk_bf16_f32 v191, v242, v243
	v_mul_f32_e32 v240, v224, v244
	v_mul_f32_e32 v241, v225, v244
	v_mul_f32_e32 v242, v226, v244
	v_mul_f32_e32 v243, v227, v244
	v_cvt_pk_bf16_f32 v192, v240, v241
	v_cvt_pk_bf16_f32 v193, v242, v243
	s_nop 1
	v_permlane16_swap_b32_e32 v186, v188
	v_permlane16_swap_b32_e32 v187, v189
	v_permlane16_swap_b32_e32 v190, v192
	v_permlane16_swap_b32_e32 v191, v193
	s_nop 0
	v_permlane32_swap_b32_e32 v186, v190
	v_permlane32_swap_b32_e32 v187, v191
	v_permlane32_swap_b32_e32 v188, v192
	v_permlane32_swap_b32_e32 v189, v193
	global_store_dwordx4 v128, v[186:189], s[82:83] offset:2048
	global_store_dwordx4 v128, v[190:193], s[82:83] offset:2064
	s_nop 1
	ds_read_b128 v[186:189], v122 offset:4096
	ds_read_b128 v[190:193], v123 offset:4096
	ds_read_b128 v[194:197], v122 offset:6144
	ds_read_b128 v[198:201], v123 offset:6144
	ds_read_b128 v[202:205], v122 offset:8192
	ds_read_b128 v[206:209], v123 offset:8192
	ds_read_b128 v[210:213], v122 offset:10240
	ds_read_b128 v[214:217], v123 offset:10240
	ds_read_b128 v[220:223], v122 offset:12288
	ds_read_b128 v[224:227], v123 offset:12288
	ds_read_b128 v[228:231], v122 offset:14336
	ds_read_b128 v[232:235], v123 offset:14336
	ds_read_b128 v[236:239], v122 offset:16384
	ds_read_b128 v[240:243], v123 offset:16384
	s_waitcnt lgkmcnt(13)
; #define LAS __attribute__((address_space(3)))
; #define MFMA16(a, b, c) __builtin_amdgcn_mfma_f32_16x16x32_bf16((a), (b), (c), 0, 0, 0)
; __device__ __forceinline__ void qk_at(const LAS unsigned char* kp0, const LAS unsigned char* kp1, int off, bf16x8 qf0, bf16x8 qf1, f32x4& S0, f32x4& S1) {
;     const bf16x8 k00 = *(const LAS bf16x8*)(kp0 + off), k01 = *(const LAS bf16x8*)(kp1 + off);
;     const bf16x8 k10 = *(const LAS bf16x8*)(kp0 + off + 2048), k11 = *(const LAS bf16x8*)(kp1 + off + 2048);
;     const f32x4 z = {0.f, 0.f, 0.f, 0.f};
;     S0 = MFMA16(k00, qf0, z); S0 = MFMA16(k01, qf1, S0);
;     S1 = MFMA16(k10, qf0, z); S1 = MFMA16(k11, qf1, S1);
; }
; __device__ __forceinline__ void softmax_step(f32x4& s0, f32x4& s1, float& m, float& l, f32x4 (&O)[4]) {
;     float t = fmaxf(fmaxf(fmaxf(s0[0], s0[1]), fmaxf(s0[2], s0[3])), fmaxf(fmaxf(s1[0], s1[1]), fmaxf(s1[2], s1[3])));
;     t = xrow16_max(t);
;     const float mn = fmaxf(m, t), alpha = __builtin_amdgcn_exp2f(m - mn);
	v_mfma_f32_16x16x32_bf16 v[50:53], v[186:189], v[162:165], v[50:53]
	s_waitcnt lgkmcnt(12)
	v_mfma_f32_16x16x32_bf16 v[50:53], v[190:193], v[166:169], v[50:53]
	ds_read_b128 v[186:189], v122 offset:18432
	ds_read_b128 v[190:193], v123 offset:18432
	s_waitcnt lgkmcnt(13)
	v_mfma_f32_16x16x32_bf16 v[54:57], v[194:197], v[162:165], v[54:57]
	s_waitcnt lgkmcnt(12)
	v_mfma_f32_16x16x32_bf16 v[54:57], v[198:201], v[166:169], v[54:57]
	ds_read_b128 v[194:197], v122 offset:20480
	ds_read_b128 v[198:201], v123 offset:20480
	s_waitcnt lgkmcnt(13)
	v_mfma_f32_16x16x32_bf16 v[58:61], v[202:205], v[162:165], v[58:61]
	s_waitcnt lgkmcnt(12)
	v_mfma_f32_16x16x32_bf16 v[58:61], v[206:209], v[166:169], v[58:61]
	ds_read_b128 v[202:205], v122 offset:22528
	ds_read_b128 v[206:209], v123 offset:22528
	s_waitcnt lgkmcnt(13)
	v_mfma_f32_16x16x32_bf16 v[62:65], v[210:213], v[162:165], v[62:65]
	s_waitcnt lgkmcnt(12)
	v_mfma_f32_16x16x32_bf16 v[62:65], v[214:217], v[166:169], v[62:65]
	ds_read_b128 v[210:213], v122 offset:24576
	ds_read_b128 v[214:217], v123 offset:24576
	s_waitcnt lgkmcnt(13)
	v_mfma_f32_16x16x32_bf16 v[66:69], v[220:223], v[162:165], v[66:69]
	s_waitcnt lgkmcnt(12)
	v_mfma_f32_16x16x32_bf16 v[66:69], v[224:227], v[166:169], v[66:69]
	ds_read_b128 v[220:223], v122 offset:26624
	ds_read_b128 v[224:227], v123 offset:26624
	s_waitcnt lgkmcnt(13)
	v_mfma_f32_16x16x32_bf16 v[70:73], v[228:231], v[162:165], v[70:73]
	s_waitcnt lgkmcnt(12)
	v_mfma_f32_16x16x32_bf16 v[70:73], v[232:235], v[166:169], v[70:73]
	ds_read_b128 v[228:231], v122 offset:28672
	ds_read_b128 v[232:235], v123 offset:28672
	s_waitcnt lgkmcnt(13)
	v_mfma_f32_16x16x32_bf16 v[74:77], v[236:239], v[162:165], v[74:77]
	s_waitcnt lgkmcnt(12)
	v_mfma_f32_16x16x32_bf16 v[74:77], v[240:243], v[166:169], v[74:77]
	ds_read_b128 v[236:239], v122 offset:30720
	ds_read_b128 v[240:243], v123 offset:30720
	s_waitcnt lgkmcnt(13)
	v_mfma_f32_16x16x32_bf16 v[78:81], v[186:189], v[162:165], v[78:81]
	s_waitcnt lgkmcnt(12)
	v_mfma_f32_16x16x32_bf16 v[78:81], v[190:193], v[166:169], v[78:81]
	ds_read_b128 v[186:189], v122 offset:32768
	ds_read_b128 v[190:193], v123 offset:32768
	s_waitcnt lgkmcnt(13)
	v_mfma_f32_16x16x32_bf16 v[82:85], v[194:197], v[162:165], v[82:85]
	s_waitcnt lgkmcnt(12)
	v_mfma_f32_16x16x32_bf16 v[82:85], v[198:201], v[166:169], v[82:85]
	ds_read_b128 v[194:197], v122 offset:34816
	ds_read_b128 v[198:201], v123 offset:34816
	s_waitcnt lgkmcnt(13)
	v_mfma_f32_16x16x32_bf16 v[86:89], v[202:205], v[162:165], v[86:89]
	s_waitcnt lgkmcnt(12)
	v_mfma_f32_16x16x32_bf16 v[86:89], v[206:209], v[166:169], v[86:89]
	ds_read_b128 v[202:205], v122 offset:36864
	ds_read_b128 v[206:209], v123 offset:36864
	s_waitcnt lgkmcnt(13)
	v_mfma_f32_16x16x32_bf16 v[90:93], v[210:213], v[162:165], v[90:93]
	s_waitcnt lgkmcnt(12)
	v_mfma_f32_16x16x32_bf16 v[90:93], v[214:217], v[166:169], v[90:93]
	s_waitcnt lgkmcnt(11)
	v_mfma_f32_16x16x32_bf16 v[94:97], v[220:223], v[162:165], v[94:97]
	s_waitcnt lgkmcnt(10)
	v_mfma_f32_16x16x32_bf16 v[94:97], v[224:227], v[166:169], v[94:97]
	s_waitcnt lgkmcnt(9)
	v_mfma_f32_16x16x32_bf16 v[98:101], v[228:231], v[162:165], v[98:101]
	s_waitcnt lgkmcnt(8)
	v_mfma_f32_16x16x32_bf16 v[98:101], v[232:235], v[166:169], v[98:101]
	s_waitcnt lgkmcnt(7)
	v_mfma_f32_16x16x32_bf16 v[102:105], v[236:239], v[162:165], v[102:105]
	s_waitcnt lgkmcnt(6)
	v_mfma_f32_16x16x32_bf16 v[102:105], v[240:243], v[166:169], v[102:105]
	s_waitcnt lgkmcnt(5)
	v_mfma_f32_16x16x32_bf16 v[106:109], v[186:189], v[162:165], v[106:109]
	s_waitcnt lgkmcnt(4)
	v_mfma_f32_16x16x32_bf16 v[106:109], v[190:193], v[166:169], v[106:109]
	s_waitcnt lgkmcnt(3)
	v_mfma_f32_16x16x32_bf16 v[110:113], v[194:197], v[162:165], v[110:113]
	s_waitcnt lgkmcnt(2)
	v_mfma_f32_16x16x32_bf16 v[110:113], v[198:201], v[166:169], v[110:113]
	s_waitcnt lgkmcnt(1)
	v_mfma_f32_16x16x32_bf16 v[114:117], v[202:205], v[162:165], v[114:117]
	s_waitcnt lgkmcnt(0)
	v_mfma_f32_16x16x32_bf16 v[114:117], v[206:209], v[166:169], v[114:117]
	v_max3_f32 v219, v50, v51, v52
	v_max3_f32 v244, v54, v55, v56
	v_max3_f32 v245, v58, v59, v60
	v_max3_f32 v120, v62, v63, v64
	v_max3_f32 v219, v219, v53, v66
	v_max3_f32 v244, v244, v57, v70
	v_max3_f32 v245, v245, v61, v74
	v_max3_f32 v120, v120, v65, v78
	v_max3_f32 v219, v219, v67, v68
	v_max3_f32 v244, v244, v71, v72
	v_max3_f32 v245, v245, v75, v76
	v_max3_f32 v120, v120, v79, v80
	ds_read_b64_tr_b16 v[186:187], v124 offset:4096
	ds_read_b64_tr_b16 v[188:189], v124 offset:6144
	ds_read_b64_tr_b16 v[190:191], v125 offset:4096
	ds_read_b64_tr_b16 v[192:193], v125 offset:6144
	ds_read_b64_tr_b16 v[194:195], v126 offset:4096
	ds_read_b64_tr_b16 v[196:197], v126 offset:6144
	ds_read_b64_tr_b16 v[198:199], v127 offset:4096
	ds_read_b64_tr_b16 v[200:201], v127 offset:6144
	v_max3_f32 v219, v219, v69, v82
	v_max3_f32 v244, v244, v73, v86
	v_max3_f32 v245, v245, v77, v90
	v_max3_f32 v120, v120, v81, v94
	v_max3_f32 v219, v219, v83, v84
	v_max3_f32 v244, v244, v87, v88
	v_max3_f32 v245, v245, v91, v92
	v_max3_f32 v120, v120, v95, v96
	v_max3_f32 v219, v219, v85, v98
	v_max3_f32 v244, v244, v89, v102
	v_max3_f32 v245, v245, v93, v106
	v_max3_f32 v120, v120, v97, v110
	v_max3_f32 v219, v219, v99, v100
	v_max3_f32 v244, v244, v103, v104
	v_max3_f32 v245, v245, v107, v108
	v_max3_f32 v120, v120, v111, v112
	v_max3_f32 v219, v219, v101, v114
	v_max3_f32 v219, v219, v115, v116
	v_max_f32_e32 v219, v219, v117
	v_max_f32_e32 v244, v244, v105
	v_max_f32_e32 v245, v245, v109
	v_max_f32_e32 v120, v120, v113
	v_max3_f32 v178, v219, v244, v245
	v_max_f32_e32 v178, v178, v120
	v_mov_b32_e32 v219, v178
	s_nop 1
	v_permlane16_swap_b32_e32 v178, v219
	v_max_f32_e32 v178, v178, v219
	v_mov_b32_e32 v219, v178
	s_nop 1
	v_permlane32_swap_b32_e32 v178, v219
	v_max3_f32 v178, v178, v219, v145
	s_waitcnt lgkmcnt(7)
; __device__ __forceinline__ void softmax_step(f32x4& s0, f32x4& s1, float& m, float& l, f32x4 (&O)[4]) {
;     float t = fmaxf(fmaxf(fmaxf(s0[0], s0[1]), fmaxf(s0[2], s0[3])), fmaxf(fmaxf(s1[0], s1[1]), fmaxf(s1[2], s1[3])));
;     t = xrow16_max(t);
;     const float mn = fmaxf(m, t), alpha = __builtin_amdgcn_exp2f(m - mn);
;     m = mn;
; #pragma unroll
;     for (int k = 0; k < 4; ++k) { s0[k] = __builtin_amdgcn_exp2f(s0[k] - mn); s1[k] = __builtin_amdgcn_exp2f(s1[k] - mn); }
;     l = l * alpha + ((s0[0] + s0[1]) + (s0[2] + s0[3])) + ((s1[0] + s1[1]) + (s1[2] + s1[3]));
; #pragma unroll
;     for (int db = 0; db < 4; ++db) O[db] *= alpha;
; }
	ds_read_b64_tr_b16 v[202:203], v124 offset:8192
	ds_read_b64_tr_b16 v[204:205], v124 offset:10240
	ds_read_b64_tr_b16 v[206:207], v125 offset:8192
	ds_read_b64_tr_b16 v[208:209], v125 offset:10240
	ds_read_b64_tr_b16 v[228:229], v126 offset:8192
	ds_read_b64_tr_b16 v[230:231], v126 offset:10240
	ds_read_b64_tr_b16 v[232:233], v127 offset:8192
	ds_read_b64_tr_b16 v[234:235], v127 offset:10240
	v_mov_b32_e32 v244, v178
	v_pk_add_f32 v[50:51], v[50:51], v[244:245] op_sel_hi:[1,0] neg_lo:[0,1] neg_hi:[0,1]
	v_pk_add_f32 v[52:53], v[52:53], v[244:245] op_sel_hi:[1,0] neg_lo:[0,1] neg_hi:[0,1]
	v_pk_add_f32 v[54:55], v[54:55], v[244:245] op_sel_hi:[1,0] neg_lo:[0,1] neg_hi:[0,1]
	v_pk_add_f32 v[56:57], v[56:57], v[244:245] op_sel_hi:[1,0] neg_lo:[0,1] neg_hi:[0,1]
	v_pk_add_f32 v[58:59], v[58:59], v[244:245] op_sel_hi:[1,0] neg_lo:[0,1] neg_hi:[0,1]
	v_pk_add_f32 v[60:61], v[60:61], v[244:245] op_sel_hi:[1,0] neg_lo:[0,1] neg_hi:[0,1]
	v_pk_add_f32 v[62:63], v[62:63], v[244:245] op_sel_hi:[1,0] neg_lo:[0,1] neg_hi:[0,1]
	v_pk_add_f32 v[64:65], v[64:65], v[244:245] op_sel_hi:[1,0] neg_lo:[0,1] neg_hi:[0,1]
	v_pk_add_f32 v[66:67], v[66:67], v[244:245] op_sel_hi:[1,0] neg_lo:[0,1] neg_hi:[0,1]
	v_pk_add_f32 v[68:69], v[68:69], v[244:245] op_sel_hi:[1,0] neg_lo:[0,1] neg_hi:[0,1]
	v_pk_add_f32 v[70:71], v[70:71], v[244:245] op_sel_hi:[1,0] neg_lo:[0,1] neg_hi:[0,1]
	v_pk_add_f32 v[72:73], v[72:73], v[244:245] op_sel_hi:[1,0] neg_lo:[0,1] neg_hi:[0,1]
	v_pk_add_f32 v[74:75], v[74:75], v[244:245] op_sel_hi:[1,0] neg_lo:[0,1] neg_hi:[0,1]
	v_pk_add_f32 v[76:77], v[76:77], v[244:245] op_sel_hi:[1,0] neg_lo:[0,1] neg_hi:[0,1]
	v_pk_add_f32 v[78:79], v[78:79], v[244:245] op_sel_hi:[1,0] neg_lo:[0,1] neg_hi:[0,1]
	v_pk_add_f32 v[80:81], v[80:81], v[244:245] op_sel_hi:[1,0] neg_lo:[0,1] neg_hi:[0,1]
	v_pk_add_f32 v[82:83], v[82:83], v[244:245] op_sel_hi:[1,0] neg_lo:[0,1] neg_hi:[0,1]
	v_pk_add_f32 v[84:85], v[84:85], v[244:245] op_sel_hi:[1,0] neg_lo:[0,1] neg_hi:[0,1]
	v_pk_add_f32 v[86:87], v[86:87], v[244:245] op_sel_hi:[1,0] neg_lo:[0,1] neg_hi:[0,1]
	v_pk_add_f32 v[88:89], v[88:89], v[244:245] op_sel_hi:[1,0] neg_lo:[0,1] neg_hi:[0,1]
	v_pk_add_f32 v[90:91], v[90:91], v[244:245] op_sel_hi:[1,0] neg_lo:[0,1] neg_hi:[0,1]
	v_pk_add_f32 v[92:93], v[92:93], v[244:245] op_sel_hi:[1,0] neg_lo:[0,1] neg_hi:[0,1]
	v_pk_add_f32 v[94:95], v[94:95], v[244:245] op_sel_hi:[1,0] neg_lo:[0,1] neg_hi:[0,1]
	v_pk_add_f32 v[96:97], v[96:97], v[244:245] op_sel_hi:[1,0] neg_lo:[0,1] neg_hi:[0,1]
	v_pk_add_f32 v[98:99], v[98:99], v[244:245] op_sel_hi:[1,0] neg_lo:[0,1] neg_hi:[0,1]
	v_pk_add_f32 v[100:101], v[100:101], v[244:245] op_sel_hi:[1,0] neg_lo:[0,1] neg_hi:[0,1]
	v_pk_add_f32 v[102:103], v[102:103], v[244:245] op_sel_hi:[1,0] neg_lo:[0,1] neg_hi:[0,1]
	v_pk_add_f32 v[104:105], v[104:105], v[244:245] op_sel_hi:[1,0] neg_lo:[0,1] neg_hi:[0,1]
	v_pk_add_f32 v[106:107], v[106:107], v[244:245] op_sel_hi:[1,0] neg_lo:[0,1] neg_hi:[0,1]
	v_pk_add_f32 v[108:109], v[108:109], v[244:245] op_sel_hi:[1,0] neg_lo:[0,1] neg_hi:[0,1]
	v_pk_add_f32 v[110:111], v[110:111], v[244:245] op_sel_hi:[1,0] neg_lo:[0,1] neg_hi:[0,1]
	v_pk_add_f32 v[112:113], v[112:113], v[244:245] op_sel_hi:[1,0] neg_lo:[0,1] neg_hi:[0,1]
	v_pk_add_f32 v[114:115], v[114:115], v[244:245] op_sel_hi:[1,0] neg_lo:[0,1] neg_hi:[0,1]
	v_pk_add_f32 v[116:117], v[116:117], v[244:245] op_sel_hi:[1,0] neg_lo:[0,1] neg_hi:[0,1]
	v_sub_f32_e32 v219, v145, v178
	v_exp_f32_e32 v50, v50
	v_exp_f32_e32 v51, v51
	v_exp_f32_e32 v52, v52
	v_exp_f32_e32 v53, v53
	v_exp_f32_e32 v54, v54
	v_exp_f32_e32 v55, v55
	v_exp_f32_e32 v56, v56
	v_exp_f32_e32 v57, v57
	v_exp_f32_e32 v58, v58
	v_exp_f32_e32 v59, v59
	v_exp_f32_e32 v60, v60
	v_exp_f32_e32 v61, v61
	v_exp_f32_e32 v62, v62
	v_exp_f32_e32 v63, v63
	v_exp_f32_e32 v64, v64
	v_exp_f32_e32 v65, v65
	v_exp_f32_e32 v66, v66
	v_exp_f32_e32 v67, v67
	v_exp_f32_e32 v68, v68
	v_exp_f32_e32 v69, v69
	v_exp_f32_e32 v70, v70
	v_exp_f32_e32 v71, v71
	v_exp_f32_e32 v72, v72
	v_exp_f32_e32 v73, v73
	v_exp_f32_e32 v74, v74
	v_exp_f32_e32 v75, v75
	v_exp_f32_e32 v76, v76
	v_exp_f32_e32 v77, v77
	v_exp_f32_e32 v78, v78
	v_exp_f32_e32 v79, v79
	v_exp_f32_e32 v80, v80
	v_exp_f32_e32 v81, v81
	v_exp_f32_e32 v82, v82
	v_exp_f32_e32 v83, v83
	v_exp_f32_e32 v84, v84
	v_exp_f32_e32 v85, v85
	v_exp_f32_e32 v86, v86
	v_exp_f32_e32 v87, v87
	v_exp_f32_e32 v88, v88
	v_exp_f32_e32 v89, v89
	v_exp_f32_e32 v90, v90
	v_exp_f32_e32 v91, v91
	v_exp_f32_e32 v92, v92
	v_exp_f32_e32 v93, v93
	v_exp_f32_e32 v94, v94
	v_exp_f32_e32 v95, v95
	v_exp_f32_e32 v96, v96
	v_exp_f32_e32 v97, v97
	v_exp_f32_e32 v98, v98
	v_exp_f32_e32 v99, v99
	v_exp_f32_e32 v100, v100
	v_exp_f32_e32 v101, v101
	v_exp_f32_e32 v102, v102
	v_exp_f32_e32 v103, v103
	v_exp_f32_e32 v104, v104
	v_exp_f32_e32 v105, v105
	v_exp_f32_e32 v106, v106
	v_exp_f32_e32 v107, v107
	v_exp_f32_e32 v108, v108
	v_exp_f32_e32 v109, v109
	v_exp_f32_e32 v110, v110
	v_exp_f32_e32 v111, v111
	v_exp_f32_e32 v112, v112
	v_exp_f32_e32 v113, v113
	v_exp_f32_e32 v114, v114
	v_exp_f32_e32 v115, v115
	v_exp_f32_e32 v116, v116
	v_exp_f32_e32 v117, v117
	v_exp_f32_e32 v219, v219
	v_pk_add_f32 v[236:237], v[50:51], v[52:53]
	v_pk_add_f32 v[238:239], v[54:55], v[56:57]
	v_pk_add_f32 v[240:241], v[58:59], v[60:61]
	v_pk_add_f32 v[242:243], v[62:63], v[64:65]
	v_pk_add_f32 v[236:237], v[236:237], v[66:67]
	v_pk_add_f32 v[238:239], v[238:239], v[70:71]
	v_pk_add_f32 v[240:241], v[240:241], v[74:75]
	v_pk_add_f32 v[242:243], v[242:243], v[78:79]
	v_pk_add_f32 v[236:237], v[236:237], v[68:69]
	v_pk_add_f32 v[238:239], v[238:239], v[72:73]
	v_pk_add_f32 v[240:241], v[240:241], v[76:77]
	v_pk_add_f32 v[242:243], v[242:243], v[80:81]
	v_pk_add_f32 v[236:237], v[236:237], v[82:83]
	v_pk_add_f32 v[238:239], v[238:239], v[86:87]
	v_pk_add_f32 v[240:241], v[240:241], v[90:91]
	v_pk_add_f32 v[242:243], v[242:243], v[94:95]
	v_pk_add_f32 v[236:237], v[236:237], v[84:85]
	v_pk_add_f32 v[238:239], v[238:239], v[88:89]
	v_pk_add_f32 v[240:241], v[240:241], v[92:93]
	v_pk_add_f32 v[242:243], v[242:243], v[96:97]
	v_pk_add_f32 v[236:237], v[236:237], v[98:99]
	v_pk_add_f32 v[238:239], v[238:239], v[102:103]
	v_pk_add_f32 v[240:241], v[240:241], v[106:107]
	v_pk_add_f32 v[242:243], v[242:243], v[110:111]
	v_pk_add_f32 v[236:237], v[236:237], v[100:101]
	v_pk_add_f32 v[238:239], v[238:239], v[104:105]
	v_pk_add_f32 v[240:241], v[240:241], v[108:109]
	v_pk_add_f32 v[242:243], v[242:243], v[112:113]
	v_pk_add_f32 v[236:237], v[236:237], v[114:115]
	v_pk_add_f32 v[236:237], v[236:237], v[116:117]
	v_pk_add_f32 v[236:237], v[236:237], v[238:239]
	v_pk_add_f32 v[240:241], v[240:241], v[242:243]
	v_cndmask_b32_e64 v219, 0, v219, s[74:75]
	v_pk_add_f32 v[236:237], v[236:237], v[240:241]
	v_add_f32_e32 v185, v236, v237
	v_add_f32_e32 v185, v185, v219
	v_cvt_pk_bf16_f32 v236, v50, v51
	v_cvt_pk_bf16_f32 v237, v52, v53
	v_cvt_pk_bf16_f32 v238, v54, v55
	v_cvt_pk_bf16_f32 v239, v56, v57
	s_nop 1
	s_waitcnt lgkmcnt(14)
; #define LAS __attribute__((address_space(3)))
; __device__ __forceinline__ unsigned pk2(float lo, float hi) { return pg8::cvt_pk_bf16(lo, hi); }
; __device__ __forceinline__ s16x4 vtr(const LAS unsigned char* p) { return __builtin_bit_cast(s16x4, __builtin_amdgcn_ds_read_tr16_b64_v4i16((LAS s16x4*)p)); }
; #define MFMA16(a, b, c) __builtin_amdgcn_mfma_f32_16x16x32_bf16((a), (b), (c), 0, 0, 0)
; __device__ __forceinline__ void pv_at(const LAS unsigned char* const (&vp)[4], int off, const f32x4& P0, const f32x4& P1, f32x4 (&O)[4]) {
;     v4u pw; pw.x = pk2(P0[0], P0[1]); pw.y = pk2(P0[2], P0[3]); pw.z = pk2(P1[0], P1[1]); pw.w = pk2(P1[2], P1[3]);
;     const bf16x8 pb = __builtin_bit_cast(bf16x8, pw);
; #pragma unroll
;     for (int db = 0; db < 4; ++db) {
;         const s16x4 lo = vtr(vp[db] + off), hi = vtr(vp[db] + off + 2048);
;         const bf16x8 vt = (bf16x8){lo[0], lo[1], lo[2], lo[3], hi[0], hi[1], hi[2], hi[3]};
;         O[db] = MFMA16(vt, pb, O[db]);
;     }
; }
; template <bool MASK> __device__ __forceinline__ void a_scores(f32x4& S0, f32x4& S1, float basef, float c1, float slope2, int krow0, int kstart) {
; #pragma unroll
;     for (int r = 0; r < 4; ++r) {
;         const float d0 = fabsf(basef - (float)r), d1 = fabsf(basef - (float)(16 + r));
;         const float v0 = S0[r] - slope2 * d0, v1 = S1[r] - slope2 * d1;
;         if (MASK) { const int p0 = kstart + krow0 + r, p1 = p0 + 16;
;             S0[r] = (d0 <= 128.f && p0 >= 0 && p0 < SEQ) ? v0 : -INFINITY; S1[r] = (d1 <= 128.f && p1 >= 0 && p1 < SEQ) ? v1 : -INFINITY; }
;         else { S0[r] = v0; S1[r] = v1; }
;     }
; }
	v_mfma_f32_16x16x32_bf16 v[210:213], v[186:189], v[236:239], 0
	s_waitcnt lgkmcnt(12)
	v_mfma_f32_16x16x32_bf16 v[214:217], v[190:193], v[236:239], 0
	s_waitcnt lgkmcnt(10)
	v_mfma_f32_16x16x32_bf16 v[220:223], v[194:197], v[236:239], 0
	s_waitcnt lgkmcnt(8)
	v_mfma_f32_16x16x32_bf16 v[224:227], v[198:201], v[236:239], 0
	v_cvt_pk_bf16_f32 v240, v58, v59
	v_cvt_pk_bf16_f32 v241, v60, v61
	v_cvt_pk_bf16_f32 v242, v62, v63
	v_cvt_pk_bf16_f32 v243, v64, v65
	s_waitcnt lgkmcnt(7)
	ds_read_b64_tr_b16 v[186:187], v124 offset:12288
	ds_read_b64_tr_b16 v[188:189], v124 offset:14336
	ds_read_b64_tr_b16 v[190:191], v125 offset:12288
	ds_read_b64_tr_b16 v[192:193], v125 offset:14336
	ds_read_b64_tr_b16 v[194:195], v126 offset:12288
	ds_read_b64_tr_b16 v[196:197], v126 offset:14336
	ds_read_b64_tr_b16 v[198:199], v127 offset:12288
	ds_read_b64_tr_b16 v[200:201], v127 offset:14336
	v_fmamk_f32 v50, v130, 0x43000000, v132
	v_fmamk_f32 v51, v130, 0x42fe0000, v132
	v_fmamk_f32 v52, v130, 0x42fc0000, v132
	v_fmamk_f32 v53, v130, 0x42fa0000, v132
	v_mov_b32_e32 v245, 0xff800000
	v_cndmask_b32_e64 v50, v245, v50, s[16:17]
	v_cndmask_b32_e64 v51, v245, v51, s[18:19]
	v_cndmask_b32_e64 v52, v245, v52, s[22:23]
	v_cndmask_b32_e64 v53, v245, v53, s[24:25]
	v_fmamk_f32 v54, v130, 0x42e00000, v132
	v_fmamk_f32 v55, v130, 0x42de0000, v132
	v_fmamk_f32 v56, v130, 0x42dc0000, v132
	v_fmamk_f32 v57, v130, 0x42da0000, v132
	s_waitcnt lgkmcnt(14)
	v_mfma_f32_16x16x32_bf16 v[210:213], v[202:205], v[240:243], v[210:213]
	s_waitcnt lgkmcnt(12)
	v_mfma_f32_16x16x32_bf16 v[214:217], v[206:209], v[240:243], v[214:217]
	s_waitcnt lgkmcnt(10)
	v_mfma_f32_16x16x32_bf16 v[220:223], v[228:231], v[240:243], v[220:223]
	s_waitcnt lgkmcnt(8)
	v_mfma_f32_16x16x32_bf16 v[224:227], v[232:235], v[240:243], v[224:227]
	v_cvt_pk_bf16_f32 v236, v66, v67
	v_cvt_pk_bf16_f32 v237, v68, v69
	v_cvt_pk_bf16_f32 v238, v70, v71
	v_cvt_pk_bf16_f32 v239, v72, v73
	s_waitcnt lgkmcnt(7)
	ds_read_b64_tr_b16 v[202:203], v124 offset:16384
	ds_read_b64_tr_b16 v[204:205], v124 offset:18432
	ds_read_b64_tr_b16 v[206:207], v125 offset:16384
	ds_read_b64_tr_b16 v[208:209], v125 offset:18432
	ds_read_b64_tr_b16 v[228:229], v126 offset:16384
	ds_read_b64_tr_b16 v[230:231], v126 offset:18432
	ds_read_b64_tr_b16 v[232:233], v127 offset:16384
	ds_read_b64_tr_b16 v[234:235], v127 offset:18432
	v_fmamk_f32 v58, v130, 0x42c00000, v132
	v_fmamk_f32 v59, v130, 0x42be0000, v132
	v_fmamk_f32 v60, v130, 0x42bc0000, v132
	v_fmamk_f32 v61, v130, 0x42ba0000, v132
	v_fmamk_f32 v62, v130, 0x42a00000, v132
	v_fmamk_f32 v63, v130, 0x429e0000, v132
	v_fmamk_f32 v64, v130, 0x429c0000, v132
	v_fmamk_f32 v65, v130, 0x429a0000, v132
	s_waitcnt lgkmcnt(14)
	v_mfma_f32_16x16x32_bf16 v[210:213], v[186:189], v[236:239], v[210:213]
	s_waitcnt lgkmcnt(12)
	v_mfma_f32_16x16x32_bf16 v[214:217], v[190:193], v[236:239], v[214:217]
	s_waitcnt lgkmcnt(10)
	v_mfma_f32_16x16x32_bf16 v[220:223], v[194:197], v[236:239], v[220:223]
	s_waitcnt lgkmcnt(8)
	v_mfma_f32_16x16x32_bf16 v[224:227], v[198:201], v[236:239], v[224:227]
	v_cvt_pk_bf16_f32 v240, v74, v75
	v_cvt_pk_bf16_f32 v241, v76, v77
	v_cvt_pk_bf16_f32 v242, v78, v79
	v_cvt_pk_bf16_f32 v243, v80, v81
	s_waitcnt lgkmcnt(7)
	ds_read_b64_tr_b16 v[186:187], v124 offset:20480
	ds_read_b64_tr_b16 v[188:189], v124 offset:22528
	ds_read_b64_tr_b16 v[190:191], v125 offset:20480
	ds_read_b64_tr_b16 v[192:193], v125 offset:22528
	ds_read_b64_tr_b16 v[194:195], v126 offset:20480
	ds_read_b64_tr_b16 v[196:197], v126 offset:22528
	ds_read_b64_tr_b16 v[198:199], v127 offset:20480
	ds_read_b64_tr_b16 v[200:201], v127 offset:22528
	v_fmamk_f32 v66, v130, 0x42800000, v132
	v_fmamk_f32 v67, v130, 0x427c0000, v132
	v_fmamk_f32 v68, v130, 0x42780000, v132
	v_fmamk_f32 v69, v130, 0x42740000, v132
	v_fmamk_f32 v70, v130, 0x42400000, v132
	v_fmamk_f32 v71, v130, 0x423c0000, v132
	v_fmamk_f32 v72, v130, 0x42380000, v132
	v_fmamk_f32 v73, v130, 0x42340000, v132
	s_waitcnt lgkmcnt(14)
	v_mfma_f32_16x16x32_bf16 v[210:213], v[202:205], v[240:243], v[210:213]
	s_waitcnt lgkmcnt(12)
	v_mfma_f32_16x16x32_bf16 v[214:217], v[206:209], v[240:243], v[214:217]
	s_waitcnt lgkmcnt(10)
	v_mfma_f32_16x16x32_bf16 v[220:223], v[228:231], v[240:243], v[220:223]
	s_waitcnt lgkmcnt(8)
	v_mfma_f32_16x16x32_bf16 v[224:227], v[232:235], v[240:243], v[224:227]
	v_cvt_pk_bf16_f32 v236, v82, v83
	v_cvt_pk_bf16_f32 v237, v84, v85
	v_cvt_pk_bf16_f32 v238, v86, v87
	v_cvt_pk_bf16_f32 v239, v88, v89
	s_waitcnt lgkmcnt(7)
	ds_read_b64_tr_b16 v[202:203], v124 offset:24576
	ds_read_b64_tr_b16 v[204:205], v124 offset:26624
	ds_read_b64_tr_b16 v[206:207], v125 offset:24576
	ds_read_b64_tr_b16 v[208:209], v125 offset:26624
	ds_read_b64_tr_b16 v[228:229], v126 offset:24576
	ds_read_b64_tr_b16 v[230:231], v126 offset:26624
	ds_read_b64_tr_b16 v[232:233], v127 offset:24576
	ds_read_b64_tr_b16 v[234:235], v127 offset:26624
	v_fmamk_f32 v74, v130, 0x42000000, v132
	v_fmamk_f32 v75, v130, 0x41f80000, v132
	v_fmamk_f32 v76, v130, 0x41f00000, v132
	v_fmamk_f32 v77, v130, 0x41e80000, v132
	v_fmamk_f32 v78, v130, 0x41800000, v132
	v_fmamk_f32 v79, v130, 0x41700000, v132
	v_fmamk_f32 v80, v130, 0x41600000, v132
	v_fmamk_f32 v81, v130, 0x41500000, v132
	s_waitcnt lgkmcnt(14)
	v_mfma_f32_16x16x32_bf16 v[210:213], v[186:189], v[236:239], v[210:213]
	s_waitcnt lgkmcnt(12)
	v_mfma_f32_16x16x32_bf16 v[214:217], v[190:193], v[236:239], v[214:217]
	s_waitcnt lgkmcnt(10)
	v_mfma_f32_16x16x32_bf16 v[220:223], v[194:197], v[236:239], v[220:223]
	s_waitcnt lgkmcnt(8)
; #define LAS __attribute__((address_space(3)))
; __device__ __forceinline__ unsigned pk2(float lo, float hi) { return pg8::cvt_pk_bf16(lo, hi); }
; __device__ __forceinline__ s16x4 vtr(const LAS unsigned char* p) { return __builtin_bit_cast(s16x4, __builtin_amdgcn_ds_read_tr16_b64_v4i16((LAS s16x4*)p)); }
; #define MFMA16(a, b, c) __builtin_amdgcn_mfma_f32_16x16x32_bf16((a), (b), (c), 0, 0, 0)
; __device__ __forceinline__ void pv_at(const LAS unsigned char* const (&vp)[4], int off, const f32x4& P0, const f32x4& P1, f32x4 (&O)[4]) {
;     v4u pw; pw.x = pk2(P0[0], P0[1]); pw.y = pk2(P0[2], P0[3]); pw.z = pk2(P1[0], P1[1]); pw.w = pk2(P1[2], P1[3]);
;     const bf16x8 pb = __builtin_bit_cast(bf16x8, pw);
; #pragma unroll
;     for (int db = 0; db < 4; ++db) {
;         const s16x4 lo = vtr(vp[db] + off), hi = vtr(vp[db] + off + 2048);
;         const bf16x8 vt = (bf16x8){lo[0], lo[1], lo[2], lo[3], hi[0], hi[1], hi[2], hi[3]};
;         O[db] = MFMA16(vt, pb, O[db]);
;     }
; }
; template <bool MASK> __device__ __forceinline__ void a_scores(f32x4& S0, f32x4& S1, float basef, float c1, float slope2, int krow0, int kstart) {
; #pragma unroll
;     for (int r = 0; r < 4; ++r) {
;         const float d0 = fabsf(basef - (float)r), d1 = fabsf(basef - (float)(16 + r));
;         const float v0 = S0[r] - slope2 * d0, v1 = S1[r] - slope2 * d1;
;         if (MASK) { const int p0 = kstart + krow0 + r, p1 = p0 + 16;
;             S0[r] = (d0 <= 128.f && p0 >= 0 && p0 < SEQ) ? v0 : -INFINITY; S1[r] = (d1 <= 128.f && p1 >= 0 && p1 < SEQ) ? v1 : -INFINITY; }
;         else { S0[r] = v0; S1[r] = v1; }
;     }
; }
	v_mfma_f32_16x16x32_bf16 v[224:227], v[198:201], v[236:239], v[224:227]
	v_cvt_pk_bf16_f32 v240, v90, v91
	v_cvt_pk_bf16_f32 v241, v92, v93
	v_cvt_pk_bf16_f32 v242, v94, v95
	v_cvt_pk_bf16_f32 v243, v96, v97
	s_waitcnt lgkmcnt(7)
	ds_read_b64_tr_b16 v[186:187], v124 offset:28672
	ds_read_b64_tr_b16 v[188:189], v124 offset:30720
	ds_read_b64_tr_b16 v[190:191], v125 offset:28672
	ds_read_b64_tr_b16 v[192:193], v125 offset:30720
	ds_read_b64_tr_b16 v[194:195], v126 offset:28672
	ds_read_b64_tr_b16 v[196:197], v126 offset:30720
	ds_read_b64_tr_b16 v[198:199], v127 offset:28672
	ds_read_b64_tr_b16 v[200:201], v127 offset:30720
	v_add_f32_e32 v219, 0, v129
	v_mul_f32_e64 v82, v130, |v219|
	v_add_f32_e32 v245, 0xbf800000, v129
	v_mul_f32_e64 v83, v130, |v245|
	v_add_f32_e32 v219, 0xc0000000, v129
	v_mul_f32_e64 v84, v130, |v219|
	v_add_f32_e32 v245, 0xc0400000, v129
	v_mul_f32_e64 v85, v130, |v245|
	v_fmamk_f32 v86, v131, 0xc1800000, v133
	v_fmamk_f32 v87, v131, 0xc1880000, v133
	v_fmamk_f32 v88, v131, 0xc1900000, v133
	v_fmamk_f32 v89, v131, 0xc1980000, v133
	s_waitcnt lgkmcnt(14)
	v_mfma_f32_16x16x32_bf16 v[210:213], v[202:205], v[240:243], v[210:213]
	s_waitcnt lgkmcnt(12)
	v_mfma_f32_16x16x32_bf16 v[214:217], v[206:209], v[240:243], v[214:217]
	s_waitcnt lgkmcnt(10)
	v_mfma_f32_16x16x32_bf16 v[220:223], v[228:231], v[240:243], v[220:223]
	s_waitcnt lgkmcnt(8)
	v_mfma_f32_16x16x32_bf16 v[224:227], v[232:235], v[240:243], v[224:227]
	v_cvt_pk_bf16_f32 v236, v98, v99
	v_cvt_pk_bf16_f32 v237, v100, v101
	v_cvt_pk_bf16_f32 v238, v102, v103
	v_cvt_pk_bf16_f32 v239, v104, v105
	s_waitcnt lgkmcnt(7)
	ds_read_b64_tr_b16 v[202:203], v124 offset:32768
	ds_read_b64_tr_b16 v[204:205], v124 offset:34816
	ds_read_b64_tr_b16 v[206:207], v125 offset:32768
	ds_read_b64_tr_b16 v[208:209], v125 offset:34816
	ds_read_b64_tr_b16 v[228:229], v126 offset:32768
	ds_read_b64_tr_b16 v[230:231], v126 offset:34816
	ds_read_b64_tr_b16 v[232:233], v127 offset:32768
	ds_read_b64_tr_b16 v[234:235], v127 offset:34816
	v_fmamk_f32 v90, v131, 0xc2000000, v133
	v_fmamk_f32 v91, v131, 0xc2040000, v133
	v_fmamk_f32 v92, v131, 0xc2080000, v133
	v_fmamk_f32 v93, v131, 0xc20c0000, v133
	v_fmamk_f32 v94, v131, 0xc2400000, v133
	v_fmamk_f32 v95, v131, 0xc2440000, v133
	v_fmamk_f32 v96, v131, 0xc2480000, v133
	v_fmamk_f32 v97, v131, 0xc24c0000, v133
	s_waitcnt lgkmcnt(14)
	v_mfma_f32_16x16x32_bf16 v[210:213], v[186:189], v[236:239], v[210:213]
	s_waitcnt lgkmcnt(12)
	v_mfma_f32_16x16x32_bf16 v[214:217], v[190:193], v[236:239], v[214:217]
	s_waitcnt lgkmcnt(10)
	v_mfma_f32_16x16x32_bf16 v[220:223], v[194:197], v[236:239], v[220:223]
	s_waitcnt lgkmcnt(8)
	v_mfma_f32_16x16x32_bf16 v[224:227], v[198:201], v[236:239], v[224:227]
	v_cvt_pk_bf16_f32 v240, v106, v107
	v_cvt_pk_bf16_f32 v241, v108, v109
	v_cvt_pk_bf16_f32 v242, v110, v111
	v_cvt_pk_bf16_f32 v243, v112, v113
	s_waitcnt lgkmcnt(7)
	ds_read_b64_tr_b16 v[186:187], v124 offset:36864
	ds_read_b64_tr_b16 v[188:189], v124 offset:38912
	ds_read_b64_tr_b16 v[190:191], v125 offset:36864
	ds_read_b64_tr_b16 v[192:193], v125 offset:38912
	ds_read_b64_tr_b16 v[194:195], v126 offset:36864
	ds_read_b64_tr_b16 v[196:197], v126 offset:38912
	ds_read_b64_tr_b16 v[198:199], v127 offset:36864
	ds_read_b64_tr_b16 v[200:201], v127 offset:38912
	v_fmamk_f32 v98, v131, 0xc2800000, v133
	v_fmamk_f32 v99, v131, 0xc2820000, v133
	v_fmamk_f32 v100, v131, 0xc2840000, v133
	v_fmamk_f32 v101, v131, 0xc2860000, v133
	v_fmamk_f32 v102, v131, 0xc2a00000, v133
	v_fmamk_f32 v103, v131, 0xc2a20000, v133
	v_fmamk_f32 v104, v131, 0xc2a40000, v133
	v_fmamk_f32 v105, v131, 0xc2a60000, v133
	s_waitcnt lgkmcnt(14)
	v_mfma_f32_16x16x32_bf16 v[210:213], v[202:205], v[240:243], v[210:213]
	s_waitcnt lgkmcnt(12)
	v_mfma_f32_16x16x32_bf16 v[214:217], v[206:209], v[240:243], v[214:217]
	s_waitcnt lgkmcnt(10)
	v_mfma_f32_16x16x32_bf16 v[220:223], v[228:231], v[240:243], v[220:223]
	s_waitcnt lgkmcnt(8)
	v_mfma_f32_16x16x32_bf16 v[224:227], v[232:235], v[240:243], v[224:227]
	v_cvt_pk_bf16_f32 v236, v114, v115
	v_cvt_pk_bf16_f32 v237, v116, v117
	v_mov_b32_e32 v238, 0
	v_mov_b32_e32 v239, 0
	s_nop 1
	v_fmamk_f32 v106, v131, 0xc2c00000, v133
	v_fmamk_f32 v107, v131, 0xc2c20000, v133
	v_fmamk_f32 v108, v131, 0xc2c40000, v133
	v_fmamk_f32 v109, v131, 0xc2c60000, v133
	v_fmamk_f32 v110, v131, 0xc2e00000, v133
	v_fmamk_f32 v111, v131, 0xc2e20000, v133
	v_fmamk_f32 v112, v131, 0xc2e40000, v133
	v_fmamk_f32 v113, v131, 0xc2e60000, v133
	s_waitcnt lgkmcnt(6)
	v_mfma_f32_16x16x32_bf16 v[210:213], v[186:189], v[236:239], v[210:213]
	s_waitcnt lgkmcnt(4)
	v_mfma_f32_16x16x32_bf16 v[214:217], v[190:193], v[236:239], v[214:217]
	s_waitcnt lgkmcnt(2)
	v_mfma_f32_16x16x32_bf16 v[220:223], v[194:197], v[236:239], v[220:223]
	s_waitcnt lgkmcnt(0)
; #define LAS __attribute__((address_space(3)))
; __device__ __forceinline__ unsigned pk2(float lo, float hi) { return pg8::cvt_pk_bf16(lo, hi); }
; #define MFMA16(a, b, c) __builtin_amdgcn_mfma_f32_16x16x32_bf16((a), (b), (c), 0, 0, 0)
; __device__ __forceinline__ void qk_at(const LAS unsigned char* kp0, const LAS unsigned char* kp1, int off, bf16x8 qf0, bf16x8 qf1, f32x4& S0, f32x4& S1) {
;     const bf16x8 k00 = *(const LAS bf16x8*)(kp0 + off), k01 = *(const LAS bf16x8*)(kp1 + off);
;     const bf16x8 k10 = *(const LAS bf16x8*)(kp0 + off + 2048), k11 = *(const LAS bf16x8*)(kp1 + off + 2048);
;     const f32x4 z = {0.f, 0.f, 0.f, 0.f};
;     S0 = MFMA16(k00, qf0, z); S0 = MFMA16(k01, qf1, S0);
;     S1 = MFMA16(k10, qf0, z); S1 = MFMA16(k11, qf1, S1);
; }
; __device__ __forceinline__ void store_o(bf16* yrow, int g, float l, const f32x4 (&O)[4]) {
;     const float inv = 1.0f / xrow16_sum(l);
;     unsigned wx[4], wy[4];
; #pragma unroll
;     for (int db = 0; db < 4; ++db) { wx[db] = pk2(O[db][0] * inv, O[db][1] * inv); wy[db] = pk2(O[db][2] * inv, O[db][3] * inv); }
; #pragma unroll
;     for (int p = 0; p < 2; ++p) {
;         auto rx = __builtin_amdgcn_permlane16_swap(wx[2 * p], wx[2 * p + 1], false, false); wx[2 * p] = rx[0]; wx[2 * p + 1] = rx[1];
;         auto ry = __builtin_amdgcn_permlane16_swap(wy[2 * p], wy[2 * p + 1], false, false); wy[2 * p] = ry[0]; wy[2 * p + 1] = ry[1]; }
; #pragma unroll
;     for (int p = 0; p < 2; ++p) {
;         auto rx = __builtin_amdgcn_permlane32_swap(wx[p], wx[p + 2], false, false); wx[p] = rx[0]; wx[p + 2] = rx[1];
;         auto ry = __builtin_amdgcn_permlane32_swap(wy[p], wy[p + 2], false, false); wy[p] = ry[0]; wy[p + 2] = ry[1]; }
;     v4u lo = {wx[0], wy[0], wx[1], wy[1]}, hi = {wx[2], wy[2], wx[3], wy[3]};
;     *(v4u*)(yrow + 16 * g) = lo; *(v4u*)(yrow + 16 * g + 8) = hi;
; }
	v_mfma_f32_16x16x32_bf16 v[224:227], v[198:201], v[236:239], v[224:227]
	v_fmamk_f32 v114, v131, 0xc3000000, v133
	v_fmamk_f32 v115, v131, 0xc3010000, v133
	v_fmamk_f32 v116, v131, 0xc3020000, v133
	v_fmamk_f32 v117, v131, 0xc3030000, v133
	v_mov_b32_e32 v245, 0xff800000
	v_cndmask_b32_e64 v114, v245, v114, s[28:29]
	v_cndmask_b32_e64 v115, v245, v115, s[52:53]
	v_cndmask_b32_e64 v116, v245, v116, s[54:55]
	v_cndmask_b32_e64 v117, v245, v117, s[88:89]
	v_mov_b32_e32 v219, v185
	s_nop 1
	v_permlane16_swap_b32_e32 v185, v219
	v_add_f32_e32 v185, v185, v219
	v_mov_b32_e32 v219, v185
	s_nop 1
	v_permlane32_swap_b32_e32 v185, v219
	v_add_f32_e32 v185, v185, v219
	v_div_scale_f32 v236, s[78:79], v185, v185, 1.0
	v_div_scale_f32 v237, vcc, 1.0, v185, 1.0
	v_rcp_f32_e32 v238, v236
	s_nop 0
	v_fma_f32 v239, -v236, v238, 1.0
	v_fmac_f32_e32 v238, v239, v238
	v_mul_f32_e32 v240, v237, v238
	v_fma_f32 v241, -v236, v240, v237
	v_fmac_f32_e32 v240, v241, v238
	v_fma_f32 v237, -v236, v240, v237
	v_div_fmas_f32 v237, v237, v238, v240
	v_div_fixup_f32 v244, v237, v185, 1.0
	v_mul_f32_e32 v240, v210, v244
	v_mul_f32_e32 v241, v211, v244
	v_mul_f32_e32 v242, v212, v244
	v_mul_f32_e32 v243, v213, v244
	v_cvt_pk_bf16_f32 v186, v240, v241
	v_cvt_pk_bf16_f32 v187, v242, v243
	v_mul_f32_e32 v240, v214, v244
	v_mul_f32_e32 v241, v215, v244
	v_mul_f32_e32 v242, v216, v244
	v_mul_f32_e32 v243, v217, v244
	v_cvt_pk_bf16_f32 v188, v240, v241
	v_cvt_pk_bf16_f32 v189, v242, v243
	v_mul_f32_e32 v240, v220, v244
	v_mul_f32_e32 v241, v221, v244
	v_mul_f32_e32 v242, v222, v244
	v_mul_f32_e32 v243, v223, v244
	v_cvt_pk_bf16_f32 v190, v240, v241
	v_cvt_pk_bf16_f32 v191, v242, v243
	v_mul_f32_e32 v240, v224, v244
	v_mul_f32_e32 v241, v225, v244
	v_mul_f32_e32 v242, v226, v244
	v_mul_f32_e32 v243, v227, v244
	v_cvt_pk_bf16_f32 v192, v240, v241
	v_cvt_pk_bf16_f32 v193, v242, v243
	s_nop 1
	v_permlane16_swap_b32_e32 v186, v188
	v_permlane16_swap_b32_e32 v187, v189
	v_permlane16_swap_b32_e32 v190, v192
	v_permlane16_swap_b32_e32 v191, v193
	s_nop 0
	v_permlane32_swap_b32_e32 v186, v190
	v_permlane32_swap_b32_e32 v187, v191
	v_permlane32_swap_b32_e32 v188, v192
	v_permlane32_swap_b32_e32 v189, v193
	v_add_u32_e32 v219, 0x1000, v128
	global_store_dwordx4 v219, v[186:189], s[82:83] offset:0
	global_store_dwordx4 v219, v[190:193], s[82:83] offset:16
	s_nop 1
	ds_read_b128 v[186:189], v122 offset:6144
	ds_read_b128 v[190:193], v123 offset:6144
	ds_read_b128 v[194:197], v122 offset:8192
	ds_read_b128 v[198:201], v123 offset:8192
	ds_read_b128 v[202:205], v122 offset:10240
	ds_read_b128 v[206:209], v123 offset:10240
	ds_read_b128 v[210:213], v122 offset:12288
	ds_read_b128 v[214:217], v123 offset:12288
	ds_read_b128 v[220:223], v122 offset:14336
	ds_read_b128 v[224:227], v123 offset:14336
	ds_read_b128 v[228:231], v122 offset:16384
	ds_read_b128 v[232:235], v123 offset:16384
	ds_read_b128 v[236:239], v122 offset:18432
	ds_read_b128 v[240:243], v123 offset:18432
	s_waitcnt lgkmcnt(13)
	v_mfma_f32_16x16x32_bf16 v[50:53], v[186:189], v[170:173], v[50:53]
	s_waitcnt lgkmcnt(12)
	v_mfma_f32_16x16x32_bf16 v[50:53], v[190:193], v[174:177], v[50:53]
	ds_read_b128 v[186:189], v122 offset:20480
	ds_read_b128 v[190:193], v123 offset:20480
	s_waitcnt lgkmcnt(13)
	v_mfma_f32_16x16x32_bf16 v[54:57], v[194:197], v[170:173], v[54:57]
	s_waitcnt lgkmcnt(12)
	v_mfma_f32_16x16x32_bf16 v[54:57], v[198:201], v[174:177], v[54:57]
	ds_read_b128 v[194:197], v122 offset:22528
	ds_read_b128 v[198:201], v123 offset:22528
	s_waitcnt lgkmcnt(13)
	v_mfma_f32_16x16x32_bf16 v[58:61], v[202:205], v[170:173], v[58:61]
	s_waitcnt lgkmcnt(12)
	v_mfma_f32_16x16x32_bf16 v[58:61], v[206:209], v[174:177], v[58:61]
	ds_read_b128 v[202:205], v122 offset:24576
	ds_read_b128 v[206:209], v123 offset:24576
	s_waitcnt lgkmcnt(13)
	v_mfma_f32_16x16x32_bf16 v[62:65], v[210:213], v[170:173], v[62:65]
	s_waitcnt lgkmcnt(12)
	v_mfma_f32_16x16x32_bf16 v[62:65], v[214:217], v[174:177], v[62:65]
	ds_read_b128 v[210:213], v122 offset:26624
	ds_read_b128 v[214:217], v123 offset:26624
	s_waitcnt lgkmcnt(13)
	v_mfma_f32_16x16x32_bf16 v[66:69], v[220:223], v[170:173], v[66:69]
	s_waitcnt lgkmcnt(12)
	v_mfma_f32_16x16x32_bf16 v[66:69], v[224:227], v[174:177], v[66:69]
	ds_read_b128 v[220:223], v122 offset:28672
	ds_read_b128 v[224:227], v123 offset:28672
	s_waitcnt lgkmcnt(13)
	v_mfma_f32_16x16x32_bf16 v[70:73], v[228:231], v[170:173], v[70:73]
	s_waitcnt lgkmcnt(12)
	v_mfma_f32_16x16x32_bf16 v[70:73], v[232:235], v[174:177], v[70:73]
	ds_read_b128 v[228:231], v122 offset:30720
	ds_read_b128 v[232:235], v123 offset:30720
	s_waitcnt lgkmcnt(13)
	v_mfma_f32_16x16x32_bf16 v[74:77], v[236:239], v[170:173], v[74:77]
	s_waitcnt lgkmcnt(12)
	v_mfma_f32_16x16x32_bf16 v[74:77], v[240:243], v[174:177], v[74:77]
	ds_read_b128 v[236:239], v122 offset:32768
	ds_read_b128 v[240:243], v123 offset:32768
	s_waitcnt lgkmcnt(13)
	v_mfma_f32_16x16x32_bf16 v[78:81], v[186:189], v[170:173], v[78:81]
	s_waitcnt lgkmcnt(12)
	v_mfma_f32_16x16x32_bf16 v[78:81], v[190:193], v[174:177], v[78:81]
	ds_read_b128 v[186:189], v122 offset:34816
	ds_read_b128 v[190:193], v123 offset:34816
	s_waitcnt lgkmcnt(13)
	v_mfma_f32_16x16x32_bf16 v[82:85], v[194:197], v[170:173], v[82:85]
	s_waitcnt lgkmcnt(12)
	v_mfma_f32_16x16x32_bf16 v[82:85], v[198:201], v[174:177], v[82:85]
	ds_read_b128 v[194:197], v122 offset:36864
	ds_read_b128 v[198:201], v123 offset:36864
	s_waitcnt lgkmcnt(13)
	v_mfma_f32_16x16x32_bf16 v[86:89], v[202:205], v[170:173], v[86:89]
	s_waitcnt lgkmcnt(12)
	v_mfma_f32_16x16x32_bf16 v[86:89], v[206:209], v[174:177], v[86:89]
	ds_read_b128 v[202:205], v122 offset:38912
	ds_read_b128 v[206:209], v123 offset:38912
	s_waitcnt lgkmcnt(13)
; #define LAS __attribute__((address_space(3)))
; #define MFMA16(a, b, c) __builtin_amdgcn_mfma_f32_16x16x32_bf16((a), (b), (c), 0, 0, 0)
; __device__ __forceinline__ void qk_at(const LAS unsigned char* kp0, const LAS unsigned char* kp1, int off, bf16x8 qf0, bf16x8 qf1, f32x4& S0, f32x4& S1) {
;     const bf16x8 k00 = *(const LAS bf16x8*)(kp0 + off), k01 = *(const LAS bf16x8*)(kp1 + off);
;     const bf16x8 k10 = *(const LAS bf16x8*)(kp0 + off + 2048), k11 = *(const LAS bf16x8*)(kp1 + off + 2048);
;     const f32x4 z = {0.f, 0.f, 0.f, 0.f};
;     S0 = MFMA16(k00, qf0, z); S0 = MFMA16(k01, qf1, S0);
;     S1 = MFMA16(k10, qf0, z); S1 = MFMA16(k11, qf1, S1);
; }
; __device__ __forceinline__ void softmax_step(f32x4& s0, f32x4& s1, float& m, float& l, f32x4 (&O)[4]) {
;     float t = fmaxf(fmaxf(fmaxf(s0[0], s0[1]), fmaxf(s0[2], s0[3])), fmaxf(fmaxf(s1[0], s1[1]), fmaxf(s1[2], s1[3])));
;     t = xrow16_max(t);
;     const float mn = fmaxf(m, t), alpha = __builtin_amdgcn_exp2f(m - mn);
;     m = mn;
; #pragma unroll
;     for (int k = 0; k < 4; ++k) { s0[k] = __builtin_amdgcn_exp2f(s0[k] - mn); s1[k] = __builtin_amdgcn_exp2f(s1[k] - mn); }
;     l = l * alpha + ((s0[0] + s0[1]) + (s0[2] + s0[3])) + ((s1[0] + s1[1]) + (s1[2] + s1[3]));
; #pragma unroll
;     for (int db = 0; db < 4; ++db) O[db] *= alpha;
; }
	v_mfma_f32_16x16x32_bf16 v[90:93], v[210:213], v[170:173], v[90:93]
	s_waitcnt lgkmcnt(12)
	v_mfma_f32_16x16x32_bf16 v[90:93], v[214:217], v[174:177], v[90:93]
	s_waitcnt lgkmcnt(11)
	v_mfma_f32_16x16x32_bf16 v[94:97], v[220:223], v[170:173], v[94:97]
	s_waitcnt lgkmcnt(10)
	v_mfma_f32_16x16x32_bf16 v[94:97], v[224:227], v[174:177], v[94:97]
	s_waitcnt lgkmcnt(9)
	v_mfma_f32_16x16x32_bf16 v[98:101], v[228:231], v[170:173], v[98:101]
	s_waitcnt lgkmcnt(8)
	v_mfma_f32_16x16x32_bf16 v[98:101], v[232:235], v[174:177], v[98:101]
	s_waitcnt lgkmcnt(7)
	v_mfma_f32_16x16x32_bf16 v[102:105], v[236:239], v[170:173], v[102:105]
	s_waitcnt lgkmcnt(6)
	v_mfma_f32_16x16x32_bf16 v[102:105], v[240:243], v[174:177], v[102:105]
	s_waitcnt lgkmcnt(5)
	v_mfma_f32_16x16x32_bf16 v[106:109], v[186:189], v[170:173], v[106:109]
	s_waitcnt lgkmcnt(4)
	v_mfma_f32_16x16x32_bf16 v[106:109], v[190:193], v[174:177], v[106:109]
	s_waitcnt lgkmcnt(3)
	v_mfma_f32_16x16x32_bf16 v[110:113], v[194:197], v[170:173], v[110:113]
	s_waitcnt lgkmcnt(2)
	v_mfma_f32_16x16x32_bf16 v[110:113], v[198:201], v[174:177], v[110:113]
	s_waitcnt lgkmcnt(1)
	v_mfma_f32_16x16x32_bf16 v[114:117], v[202:205], v[170:173], v[114:117]
	s_waitcnt lgkmcnt(0)
	v_mfma_f32_16x16x32_bf16 v[114:117], v[206:209], v[174:177], v[114:117]
	v_max3_f32 v219, v50, v51, v52
	v_max3_f32 v244, v54, v55, v56
	v_max3_f32 v245, v58, v59, v60
	v_max3_f32 v120, v62, v63, v64
	v_max3_f32 v219, v219, v53, v66
	v_max3_f32 v244, v244, v57, v70
	v_max3_f32 v245, v245, v61, v74
	v_max3_f32 v120, v120, v65, v78
	v_max3_f32 v219, v219, v67, v68
	v_max3_f32 v244, v244, v71, v72
	v_max3_f32 v245, v245, v75, v76
	v_max3_f32 v120, v120, v79, v80
	ds_read_b64_tr_b16 v[186:187], v124 offset:6144
	ds_read_b64_tr_b16 v[188:189], v124 offset:8192
	ds_read_b64_tr_b16 v[190:191], v125 offset:6144
	ds_read_b64_tr_b16 v[192:193], v125 offset:8192
	ds_read_b64_tr_b16 v[194:195], v126 offset:6144
	ds_read_b64_tr_b16 v[196:197], v126 offset:8192
	ds_read_b64_tr_b16 v[198:199], v127 offset:6144
	ds_read_b64_tr_b16 v[200:201], v127 offset:8192
	v_max3_f32 v219, v219, v69, v82
	v_max3_f32 v244, v244, v73, v86
	v_max3_f32 v245, v245, v77, v90
	v_max3_f32 v120, v120, v81, v94
	v_max3_f32 v219, v219, v83, v84
	v_max3_f32 v244, v244, v87, v88
	v_max3_f32 v245, v245, v91, v92
	v_max3_f32 v120, v120, v95, v96
	v_max3_f32 v219, v219, v85, v98
	v_max3_f32 v244, v244, v89, v102
	v_max3_f32 v245, v245, v93, v106
	v_max3_f32 v120, v120, v97, v110
	v_max3_f32 v219, v219, v99, v100
	v_max3_f32 v244, v244, v103, v104
	v_max3_f32 v245, v245, v107, v108
	v_max3_f32 v120, v120, v111, v112
	v_max3_f32 v219, v219, v101, v114
	v_max3_f32 v219, v219, v115, v116
	v_max_f32_e32 v219, v219, v117
	v_max_f32_e32 v244, v244, v105
	v_max_f32_e32 v245, v245, v109
	v_max_f32_e32 v120, v120, v113
	v_max3_f32 v178, v219, v244, v245
	v_max_f32_e32 v178, v178, v120
	v_mov_b32_e32 v219, v178
	s_nop 1
	v_permlane16_swap_b32_e32 v178, v219
	v_max_f32_e32 v178, v178, v219
	v_mov_b32_e32 v219, v178
	s_nop 1
	v_permlane32_swap_b32_e32 v178, v219
	v_max3_f32 v178, v178, v219, v145
	s_waitcnt lgkmcnt(7)
	ds_read_b64_tr_b16 v[202:203], v124 offset:10240
	ds_read_b64_tr_b16 v[204:205], v124 offset:12288
	ds_read_b64_tr_b16 v[206:207], v125 offset:10240
	ds_read_b64_tr_b16 v[208:209], v125 offset:12288
	ds_read_b64_tr_b16 v[228:229], v126 offset:10240
	ds_read_b64_tr_b16 v[230:231], v126 offset:12288
	ds_read_b64_tr_b16 v[232:233], v127 offset:10240
	ds_read_b64_tr_b16 v[234:235], v127 offset:12288
	v_mov_b32_e32 v244, v178
	v_pk_add_f32 v[50:51], v[50:51], v[244:245] op_sel_hi:[1,0] neg_lo:[0,1] neg_hi:[0,1]
	v_pk_add_f32 v[52:53], v[52:53], v[244:245] op_sel_hi:[1,0] neg_lo:[0,1] neg_hi:[0,1]
	v_pk_add_f32 v[54:55], v[54:55], v[244:245] op_sel_hi:[1,0] neg_lo:[0,1] neg_hi:[0,1]
	v_pk_add_f32 v[56:57], v[56:57], v[244:245] op_sel_hi:[1,0] neg_lo:[0,1] neg_hi:[0,1]
	v_pk_add_f32 v[58:59], v[58:59], v[244:245] op_sel_hi:[1,0] neg_lo:[0,1] neg_hi:[0,1]
	v_pk_add_f32 v[60:61], v[60:61], v[244:245] op_sel_hi:[1,0] neg_lo:[0,1] neg_hi:[0,1]
	v_pk_add_f32 v[62:63], v[62:63], v[244:245] op_sel_hi:[1,0] neg_lo:[0,1] neg_hi:[0,1]
	v_pk_add_f32 v[64:65], v[64:65], v[244:245] op_sel_hi:[1,0] neg_lo:[0,1] neg_hi:[0,1]
	v_pk_add_f32 v[66:67], v[66:67], v[244:245] op_sel_hi:[1,0] neg_lo:[0,1] neg_hi:[0,1]
	v_pk_add_f32 v[68:69], v[68:69], v[244:245] op_sel_hi:[1,0] neg_lo:[0,1] neg_hi:[0,1]
	v_pk_add_f32 v[70:71], v[70:71], v[244:245] op_sel_hi:[1,0] neg_lo:[0,1] neg_hi:[0,1]
	v_pk_add_f32 v[72:73], v[72:73], v[244:245] op_sel_hi:[1,0] neg_lo:[0,1] neg_hi:[0,1]
	v_pk_add_f32 v[74:75], v[74:75], v[244:245] op_sel_hi:[1,0] neg_lo:[0,1] neg_hi:[0,1]
	v_pk_add_f32 v[76:77], v[76:77], v[244:245] op_sel_hi:[1,0] neg_lo:[0,1] neg_hi:[0,1]
	v_pk_add_f32 v[78:79], v[78:79], v[244:245] op_sel_hi:[1,0] neg_lo:[0,1] neg_hi:[0,1]
	v_pk_add_f32 v[80:81], v[80:81], v[244:245] op_sel_hi:[1,0] neg_lo:[0,1] neg_hi:[0,1]
	v_pk_add_f32 v[82:83], v[82:83], v[244:245] op_sel_hi:[1,0] neg_lo:[0,1] neg_hi:[0,1]
	v_pk_add_f32 v[84:85], v[84:85], v[244:245] op_sel_hi:[1,0] neg_lo:[0,1] neg_hi:[0,1]
	v_pk_add_f32 v[86:87], v[86:87], v[244:245] op_sel_hi:[1,0] neg_lo:[0,1] neg_hi:[0,1]
	v_pk_add_f32 v[88:89], v[88:89], v[244:245] op_sel_hi:[1,0] neg_lo:[0,1] neg_hi:[0,1]
	v_pk_add_f32 v[90:91], v[90:91], v[244:245] op_sel_hi:[1,0] neg_lo:[0,1] neg_hi:[0,1]
	v_pk_add_f32 v[92:93], v[92:93], v[244:245] op_sel_hi:[1,0] neg_lo:[0,1] neg_hi:[0,1]
	v_pk_add_f32 v[94:95], v[94:95], v[244:245] op_sel_hi:[1,0] neg_lo:[0,1] neg_hi:[0,1]
	v_pk_add_f32 v[96:97], v[96:97], v[244:245] op_sel_hi:[1,0] neg_lo:[0,1] neg_hi:[0,1]
; #define LAS __attribute__((address_space(3)))
; __device__ __forceinline__ unsigned pk2(float lo, float hi) { return pg8::cvt_pk_bf16(lo, hi); }
; __device__ __forceinline__ s16x4 vtr(const LAS unsigned char* p) { return __builtin_bit_cast(s16x4, __builtin_amdgcn_ds_read_tr16_b64_v4i16((LAS s16x4*)p)); }
; #define MFMA16(a, b, c) __builtin_amdgcn_mfma_f32_16x16x32_bf16((a), (b), (c), 0, 0, 0)
; __device__ __forceinline__ void pv_at(const LAS unsigned char* const (&vp)[4], int off, const f32x4& P0, const f32x4& P1, f32x4 (&O)[4]) {
;     v4u pw; pw.x = pk2(P0[0], P0[1]); pw.y = pk2(P0[2], P0[3]); pw.z = pk2(P1[0], P1[1]); pw.w = pk2(P1[2], P1[3]);
;     const bf16x8 pb = __builtin_bit_cast(bf16x8, pw);
; #pragma unroll
;     for (int db = 0; db < 4; ++db) {
;         const s16x4 lo = vtr(vp[db] + off), hi = vtr(vp[db] + off + 2048);
;         const bf16x8 vt = (bf16x8){lo[0], lo[1], lo[2], lo[3], hi[0], hi[1], hi[2], hi[3]};
;         O[db] = MFMA16(vt, pb, O[db]);
;     }
; }
; __device__ __forceinline__ void softmax_step(f32x4& s0, f32x4& s1, float& m, float& l, f32x4 (&O)[4]) {
;     float t = fmaxf(fmaxf(fmaxf(s0[0], s0[1]), fmaxf(s0[2], s0[3])), fmaxf(fmaxf(s1[0], s1[1]), fmaxf(s1[2], s1[3])));
;     t = xrow16_max(t);
;     const float mn = fmaxf(m, t), alpha = __builtin_amdgcn_exp2f(m - mn);
;     m = mn;
; #pragma unroll
;     for (int k = 0; k < 4; ++k) { s0[k] = __builtin_amdgcn_exp2f(s0[k] - mn); s1[k] = __builtin_amdgcn_exp2f(s1[k] - mn); }
;     l = l * alpha + ((s0[0] + s0[1]) + (s0[2] + s0[3])) + ((s1[0] + s1[1]) + (s1[2] + s1[3]));
; #pragma unroll
;     for (int db = 0; db < 4; ++db) O[db] *= alpha;
; }
	v_pk_add_f32 v[98:99], v[98:99], v[244:245] op_sel_hi:[1,0] neg_lo:[0,1] neg_hi:[0,1]
	v_pk_add_f32 v[100:101], v[100:101], v[244:245] op_sel_hi:[1,0] neg_lo:[0,1] neg_hi:[0,1]
	v_pk_add_f32 v[102:103], v[102:103], v[244:245] op_sel_hi:[1,0] neg_lo:[0,1] neg_hi:[0,1]
	v_pk_add_f32 v[104:105], v[104:105], v[244:245] op_sel_hi:[1,0] neg_lo:[0,1] neg_hi:[0,1]
	v_pk_add_f32 v[106:107], v[106:107], v[244:245] op_sel_hi:[1,0] neg_lo:[0,1] neg_hi:[0,1]
	v_pk_add_f32 v[108:109], v[108:109], v[244:245] op_sel_hi:[1,0] neg_lo:[0,1] neg_hi:[0,1]
	v_pk_add_f32 v[110:111], v[110:111], v[244:245] op_sel_hi:[1,0] neg_lo:[0,1] neg_hi:[0,1]
	v_pk_add_f32 v[112:113], v[112:113], v[244:245] op_sel_hi:[1,0] neg_lo:[0,1] neg_hi:[0,1]
	v_pk_add_f32 v[114:115], v[114:115], v[244:245] op_sel_hi:[1,0] neg_lo:[0,1] neg_hi:[0,1]
	v_pk_add_f32 v[116:117], v[116:117], v[244:245] op_sel_hi:[1,0] neg_lo:[0,1] neg_hi:[0,1]
	v_sub_f32_e32 v219, v145, v178
	v_exp_f32_e32 v50, v50
	v_exp_f32_e32 v51, v51
	v_exp_f32_e32 v52, v52
	v_exp_f32_e32 v53, v53
	v_exp_f32_e32 v54, v54
	v_exp_f32_e32 v55, v55
	v_exp_f32_e32 v56, v56
	v_exp_f32_e32 v57, v57
	v_exp_f32_e32 v58, v58
	v_exp_f32_e32 v59, v59
	v_exp_f32_e32 v60, v60
	v_exp_f32_e32 v61, v61
	v_exp_f32_e32 v62, v62
	v_exp_f32_e32 v63, v63
	v_exp_f32_e32 v64, v64
	v_exp_f32_e32 v65, v65
	v_exp_f32_e32 v66, v66
	v_exp_f32_e32 v67, v67
	v_exp_f32_e32 v68, v68
	v_exp_f32_e32 v69, v69
	v_exp_f32_e32 v70, v70
	v_exp_f32_e32 v71, v71
	v_exp_f32_e32 v72, v72
	v_exp_f32_e32 v73, v73
	v_exp_f32_e32 v74, v74
	v_exp_f32_e32 v75, v75
	v_exp_f32_e32 v76, v76
	v_exp_f32_e32 v77, v77
	v_exp_f32_e32 v78, v78
	v_exp_f32_e32 v79, v79
	v_exp_f32_e32 v80, v80
	v_exp_f32_e32 v81, v81
	v_exp_f32_e32 v82, v82
	v_exp_f32_e32 v83, v83
	v_exp_f32_e32 v84, v84
	v_exp_f32_e32 v85, v85
	v_exp_f32_e32 v86, v86
	v_exp_f32_e32 v87, v87
	v_exp_f32_e32 v88, v88
	v_exp_f32_e32 v89, v89
	v_exp_f32_e32 v90, v90
	v_exp_f32_e32 v91, v91
	v_exp_f32_e32 v92, v92
	v_exp_f32_e32 v93, v93
	v_exp_f32_e32 v94, v94
	v_exp_f32_e32 v95, v95
	v_exp_f32_e32 v96, v96
	v_exp_f32_e32 v97, v97
	v_exp_f32_e32 v98, v98
	v_exp_f32_e32 v99, v99
	v_exp_f32_e32 v100, v100
	v_exp_f32_e32 v101, v101
	v_exp_f32_e32 v102, v102
	v_exp_f32_e32 v103, v103
	v_exp_f32_e32 v104, v104
	v_exp_f32_e32 v105, v105
	v_exp_f32_e32 v106, v106
	v_exp_f32_e32 v107, v107
	v_exp_f32_e32 v108, v108
	v_exp_f32_e32 v109, v109
	v_exp_f32_e32 v110, v110
	v_exp_f32_e32 v111, v111
	v_exp_f32_e32 v112, v112
	v_exp_f32_e32 v113, v113
	v_exp_f32_e32 v114, v114
	v_exp_f32_e32 v115, v115
	v_exp_f32_e32 v116, v116
	v_exp_f32_e32 v117, v117
	v_exp_f32_e32 v219, v219
	v_pk_add_f32 v[236:237], v[50:51], v[52:53]
	v_pk_add_f32 v[238:239], v[54:55], v[56:57]
	v_pk_add_f32 v[240:241], v[58:59], v[60:61]
	v_pk_add_f32 v[242:243], v[62:63], v[64:65]
	v_pk_add_f32 v[236:237], v[236:237], v[66:67]
	v_pk_add_f32 v[238:239], v[238:239], v[70:71]
	v_pk_add_f32 v[240:241], v[240:241], v[74:75]
	v_pk_add_f32 v[242:243], v[242:243], v[78:79]
	v_pk_add_f32 v[236:237], v[236:237], v[68:69]
	v_pk_add_f32 v[238:239], v[238:239], v[72:73]
	v_pk_add_f32 v[240:241], v[240:241], v[76:77]
	v_pk_add_f32 v[242:243], v[242:243], v[80:81]
	v_pk_add_f32 v[236:237], v[236:237], v[82:83]
	v_pk_add_f32 v[238:239], v[238:239], v[86:87]
	v_pk_add_f32 v[240:241], v[240:241], v[90:91]
	v_pk_add_f32 v[242:243], v[242:243], v[94:95]
	v_pk_add_f32 v[236:237], v[236:237], v[84:85]
	v_pk_add_f32 v[238:239], v[238:239], v[88:89]
	v_pk_add_f32 v[240:241], v[240:241], v[92:93]
	v_pk_add_f32 v[242:243], v[242:243], v[96:97]
	v_pk_add_f32 v[236:237], v[236:237], v[98:99]
	v_pk_add_f32 v[238:239], v[238:239], v[102:103]
	v_pk_add_f32 v[240:241], v[240:241], v[106:107]
	v_pk_add_f32 v[242:243], v[242:243], v[110:111]
	v_pk_add_f32 v[236:237], v[236:237], v[100:101]
	v_pk_add_f32 v[238:239], v[238:239], v[104:105]
	v_pk_add_f32 v[240:241], v[240:241], v[108:109]
	v_pk_add_f32 v[242:243], v[242:243], v[112:113]
	v_pk_add_f32 v[236:237], v[236:237], v[114:115]
	v_pk_add_f32 v[236:237], v[236:237], v[116:117]
	v_pk_add_f32 v[236:237], v[236:237], v[238:239]
	v_pk_add_f32 v[240:241], v[240:241], v[242:243]
	v_cndmask_b32_e64 v219, 0, v219, s[74:75]
	v_pk_add_f32 v[236:237], v[236:237], v[240:241]
	v_add_f32_e32 v185, v236, v237
	v_add_f32_e32 v185, v185, v219
	v_cvt_pk_bf16_f32 v236, v50, v51
	v_cvt_pk_bf16_f32 v237, v52, v53
	v_cvt_pk_bf16_f32 v238, v54, v55
	v_cvt_pk_bf16_f32 v239, v56, v57
	s_nop 1
	s_waitcnt lgkmcnt(14)
	v_mfma_f32_16x16x32_bf16 v[210:213], v[186:189], v[236:239], 0
	s_waitcnt lgkmcnt(12)
	v_mfma_f32_16x16x32_bf16 v[214:217], v[190:193], v[236:239], 0
	s_waitcnt lgkmcnt(10)
	v_mfma_f32_16x16x32_bf16 v[220:223], v[194:197], v[236:239], 0
	s_waitcnt lgkmcnt(8)
	v_mfma_f32_16x16x32_bf16 v[224:227], v[198:201], v[236:239], 0
	v_cvt_pk_bf16_f32 v240, v58, v59
	v_cvt_pk_bf16_f32 v241, v60, v61
	v_cvt_pk_bf16_f32 v242, v62, v63
	v_cvt_pk_bf16_f32 v243, v64, v65
	s_waitcnt lgkmcnt(7)
	ds_read_b64_tr_b16 v[186:187], v124 offset:14336
	ds_read_b64_tr_b16 v[188:189], v124 offset:16384
	ds_read_b64_tr_b16 v[190:191], v125 offset:14336
	ds_read_b64_tr_b16 v[192:193], v125 offset:16384
	ds_read_b64_tr_b16 v[194:195], v126 offset:14336
	ds_read_b64_tr_b16 v[196:197], v126 offset:16384
	ds_read_b64_tr_b16 v[198:199], v127 offset:14336
	ds_read_b64_tr_b16 v[200:201], v127 offset:16384
	s_waitcnt lgkmcnt(14)
	v_mfma_f32_16x16x32_bf16 v[210:213], v[202:205], v[240:243], v[210:213]
	s_waitcnt lgkmcnt(12)
	v_mfma_f32_16x16x32_bf16 v[214:217], v[206:209], v[240:243], v[214:217]
	s_waitcnt lgkmcnt(10)
	v_mfma_f32_16x16x32_bf16 v[220:223], v[228:231], v[240:243], v[220:223]
	s_waitcnt lgkmcnt(8)
; #define LAS __attribute__((address_space(3)))
; __device__ __forceinline__ unsigned pk2(float lo, float hi) { return pg8::cvt_pk_bf16(lo, hi); }
; __device__ __forceinline__ s16x4 vtr(const LAS unsigned char* p) { return __builtin_bit_cast(s16x4, __builtin_amdgcn_ds_read_tr16_b64_v4i16((LAS s16x4*)p)); }
; #define MFMA16(a, b, c) __builtin_amdgcn_mfma_f32_16x16x32_bf16((a), (b), (c), 0, 0, 0)
; __device__ __forceinline__ void pv_at(const LAS unsigned char* const (&vp)[4], int off, const f32x4& P0, const f32x4& P1, f32x4 (&O)[4]) {
;     v4u pw; pw.x = pk2(P0[0], P0[1]); pw.y = pk2(P0[2], P0[3]); pw.z = pk2(P1[0], P1[1]); pw.w = pk2(P1[2], P1[3]);
;     const bf16x8 pb = __builtin_bit_cast(bf16x8, pw);
; #pragma unroll
;     for (int db = 0; db < 4; ++db) {
;         const s16x4 lo = vtr(vp[db] + off), hi = vtr(vp[db] + off + 2048);
;         const bf16x8 vt = (bf16x8){lo[0], lo[1], lo[2], lo[3], hi[0], hi[1], hi[2], hi[3]};
;         O[db] = MFMA16(vt, pb, O[db]);
;     }
; }
	v_mfma_f32_16x16x32_bf16 v[224:227], v[232:235], v[240:243], v[224:227]
	v_cvt_pk_bf16_f32 v236, v66, v67
	v_cvt_pk_bf16_f32 v237, v68, v69
	v_cvt_pk_bf16_f32 v238, v70, v71
	v_cvt_pk_bf16_f32 v239, v72, v73
	s_waitcnt lgkmcnt(7)
	ds_read_b64_tr_b16 v[202:203], v124 offset:18432
	ds_read_b64_tr_b16 v[204:205], v124 offset:20480
	ds_read_b64_tr_b16 v[206:207], v125 offset:18432
	ds_read_b64_tr_b16 v[208:209], v125 offset:20480
	ds_read_b64_tr_b16 v[228:229], v126 offset:18432
	ds_read_b64_tr_b16 v[230:231], v126 offset:20480
	ds_read_b64_tr_b16 v[232:233], v127 offset:18432
	ds_read_b64_tr_b16 v[234:235], v127 offset:20480
	s_waitcnt lgkmcnt(14)
	v_mfma_f32_16x16x32_bf16 v[210:213], v[186:189], v[236:239], v[210:213]
	s_waitcnt lgkmcnt(12)
	v_mfma_f32_16x16x32_bf16 v[214:217], v[190:193], v[236:239], v[214:217]
	s_waitcnt lgkmcnt(10)
	v_mfma_f32_16x16x32_bf16 v[220:223], v[194:197], v[236:239], v[220:223]
	s_waitcnt lgkmcnt(8)
	v_mfma_f32_16x16x32_bf16 v[224:227], v[198:201], v[236:239], v[224:227]
	v_cvt_pk_bf16_f32 v240, v74, v75
	v_cvt_pk_bf16_f32 v241, v76, v77
	v_cvt_pk_bf16_f32 v242, v78, v79
	v_cvt_pk_bf16_f32 v243, v80, v81
	s_waitcnt lgkmcnt(7)
	ds_read_b64_tr_b16 v[186:187], v124 offset:22528
	ds_read_b64_tr_b16 v[188:189], v124 offset:24576
	ds_read_b64_tr_b16 v[190:191], v125 offset:22528
	ds_read_b64_tr_b16 v[192:193], v125 offset:24576
	ds_read_b64_tr_b16 v[194:195], v126 offset:22528
	ds_read_b64_tr_b16 v[196:197], v126 offset:24576
	ds_read_b64_tr_b16 v[198:199], v127 offset:22528
	ds_read_b64_tr_b16 v[200:201], v127 offset:24576
	s_waitcnt lgkmcnt(14)
	v_mfma_f32_16x16x32_bf16 v[210:213], v[202:205], v[240:243], v[210:213]
	s_waitcnt lgkmcnt(12)
	v_mfma_f32_16x16x32_bf16 v[214:217], v[206:209], v[240:243], v[214:217]
	s_waitcnt lgkmcnt(10)
	v_mfma_f32_16x16x32_bf16 v[220:223], v[228:231], v[240:243], v[220:223]
	s_waitcnt lgkmcnt(8)
	v_mfma_f32_16x16x32_bf16 v[224:227], v[232:235], v[240:243], v[224:227]
	v_cvt_pk_bf16_f32 v236, v82, v83
	v_cvt_pk_bf16_f32 v237, v84, v85
	v_cvt_pk_bf16_f32 v238, v86, v87
	v_cvt_pk_bf16_f32 v239, v88, v89
	s_waitcnt lgkmcnt(7)
	ds_read_b64_tr_b16 v[202:203], v124 offset:26624
	ds_read_b64_tr_b16 v[204:205], v124 offset:28672
	ds_read_b64_tr_b16 v[206:207], v125 offset:26624
	ds_read_b64_tr_b16 v[208:209], v125 offset:28672
	ds_read_b64_tr_b16 v[228:229], v126 offset:26624
	ds_read_b64_tr_b16 v[230:231], v126 offset:28672
	ds_read_b64_tr_b16 v[232:233], v127 offset:26624
	ds_read_b64_tr_b16 v[234:235], v127 offset:28672
	s_waitcnt lgkmcnt(14)
	v_mfma_f32_16x16x32_bf16 v[210:213], v[186:189], v[236:239], v[210:213]
	s_waitcnt lgkmcnt(12)
	v_mfma_f32_16x16x32_bf16 v[214:217], v[190:193], v[236:239], v[214:217]
	s_waitcnt lgkmcnt(10)
	v_mfma_f32_16x16x32_bf16 v[220:223], v[194:197], v[236:239], v[220:223]
	s_waitcnt lgkmcnt(8)
	v_mfma_f32_16x16x32_bf16 v[224:227], v[198:201], v[236:239], v[224:227]
	v_cvt_pk_bf16_f32 v240, v90, v91
	v_cvt_pk_bf16_f32 v241, v92, v93
	v_cvt_pk_bf16_f32 v242, v94, v95
	v_cvt_pk_bf16_f32 v243, v96, v97
	s_waitcnt lgkmcnt(7)
	ds_read_b64_tr_b16 v[186:187], v124 offset:30720
	ds_read_b64_tr_b16 v[188:189], v124 offset:32768
	ds_read_b64_tr_b16 v[190:191], v125 offset:30720
	ds_read_b64_tr_b16 v[192:193], v125 offset:32768
	ds_read_b64_tr_b16 v[194:195], v126 offset:30720
	ds_read_b64_tr_b16 v[196:197], v126 offset:32768
	ds_read_b64_tr_b16 v[198:199], v127 offset:30720
	ds_read_b64_tr_b16 v[200:201], v127 offset:32768
	s_waitcnt lgkmcnt(14)
	v_mfma_f32_16x16x32_bf16 v[210:213], v[202:205], v[240:243], v[210:213]
	s_waitcnt lgkmcnt(12)
	v_mfma_f32_16x16x32_bf16 v[214:217], v[206:209], v[240:243], v[214:217]
	s_waitcnt lgkmcnt(10)
	v_mfma_f32_16x16x32_bf16 v[220:223], v[228:231], v[240:243], v[220:223]
	s_waitcnt lgkmcnt(8)
	v_mfma_f32_16x16x32_bf16 v[224:227], v[232:235], v[240:243], v[224:227]
	v_cvt_pk_bf16_f32 v236, v98, v99
	v_cvt_pk_bf16_f32 v237, v100, v101
	v_cvt_pk_bf16_f32 v238, v102, v103
	v_cvt_pk_bf16_f32 v239, v104, v105
	s_waitcnt lgkmcnt(7)
; #define LAS __attribute__((address_space(3)))
; __device__ __forceinline__ unsigned pk2(float lo, float hi) { return pg8::cvt_pk_bf16(lo, hi); }
; __device__ __forceinline__ s16x4 vtr(const LAS unsigned char* p) { return __builtin_bit_cast(s16x4, __builtin_amdgcn_ds_read_tr16_b64_v4i16((LAS s16x4*)p)); }
; #define MFMA16(a, b, c) __builtin_amdgcn_mfma_f32_16x16x32_bf16((a), (b), (c), 0, 0, 0)
; __device__ __forceinline__ void pv_at(const LAS unsigned char* const (&vp)[4], int off, const f32x4& P0, const f32x4& P1, f32x4 (&O)[4]) {
;     v4u pw; pw.x = pk2(P0[0], P0[1]); pw.y = pk2(P0[2], P0[3]); pw.z = pk2(P1[0], P1[1]); pw.w = pk2(P1[2], P1[3]);
;     const bf16x8 pb = __builtin_bit_cast(bf16x8, pw);
; #pragma unroll
;     for (int db = 0; db < 4; ++db) {
;         const s16x4 lo = vtr(vp[db] + off), hi = vtr(vp[db] + off + 2048);
;         const bf16x8 vt = (bf16x8){lo[0], lo[1], lo[2], lo[3], hi[0], hi[1], hi[2], hi[3]};
;         O[db] = MFMA16(vt, pb, O[db]);
;     }
; }
; __device__ __forceinline__ void store_o(bf16* yrow, int g, float l, const f32x4 (&O)[4]) {
;     const float inv = 1.0f / xrow16_sum(l);
;     unsigned wx[4], wy[4];
; #pragma unroll
;     for (int db = 0; db < 4; ++db) { wx[db] = pk2(O[db][0] * inv, O[db][1] * inv); wy[db] = pk2(O[db][2] * inv, O[db][3] * inv); }
; #pragma unroll
;     for (int p = 0; p < 2; ++p) {
;         auto rx = __builtin_amdgcn_permlane16_swap(wx[2 * p], wx[2 * p + 1], false, false); wx[2 * p] = rx[0]; wx[2 * p + 1] = rx[1];
;         auto ry = __builtin_amdgcn_permlane16_swap(wy[2 * p], wy[2 * p + 1], false, false); wy[2 * p] = ry[0]; wy[2 * p + 1] = ry[1]; }
; #pragma unroll
;     for (int p = 0; p < 2; ++p) {
;         auto rx = __builtin_amdgcn_permlane32_swap(wx[p], wx[p + 2], false, false); wx[p] = rx[0]; wx[p + 2] = rx[1];
;         auto ry = __builtin_amdgcn_permlane32_swap(wy[p], wy[p + 2], false, false); wy[p] = ry[0]; wy[p + 2] = ry[1]; }
;     v4u lo = {wx[0], wy[0], wx[1], wy[1]}, hi = {wx[2], wy[2], wx[3], wy[3]};
;     *(v4u*)(yrow + 16 * g) = lo; *(v4u*)(yrow + 16 * g + 8) = hi;
; }
	ds_read_b64_tr_b16 v[202:203], v124 offset:34816
	ds_read_b64_tr_b16 v[204:205], v124 offset:36864
	ds_read_b64_tr_b16 v[206:207], v125 offset:34816
	ds_read_b64_tr_b16 v[208:209], v125 offset:36864
	ds_read_b64_tr_b16 v[228:229], v126 offset:34816
	ds_read_b64_tr_b16 v[230:231], v126 offset:36864
	ds_read_b64_tr_b16 v[232:233], v127 offset:34816
	ds_read_b64_tr_b16 v[234:235], v127 offset:36864
	s_waitcnt lgkmcnt(14)
	v_mfma_f32_16x16x32_bf16 v[210:213], v[186:189], v[236:239], v[210:213]
	s_waitcnt lgkmcnt(12)
	v_mfma_f32_16x16x32_bf16 v[214:217], v[190:193], v[236:239], v[214:217]
	s_waitcnt lgkmcnt(10)
	v_mfma_f32_16x16x32_bf16 v[220:223], v[194:197], v[236:239], v[220:223]
	s_waitcnt lgkmcnt(8)
	v_mfma_f32_16x16x32_bf16 v[224:227], v[198:201], v[236:239], v[224:227]
	v_cvt_pk_bf16_f32 v240, v106, v107
	v_cvt_pk_bf16_f32 v241, v108, v109
	v_cvt_pk_bf16_f32 v242, v110, v111
	v_cvt_pk_bf16_f32 v243, v112, v113
	s_waitcnt lgkmcnt(7)
	ds_read_b64_tr_b16 v[186:187], v124 offset:38912
	ds_read_b64_tr_b16 v[188:189], v124 offset:40960
	ds_read_b64_tr_b16 v[190:191], v125 offset:38912
	ds_read_b64_tr_b16 v[192:193], v125 offset:40960
	ds_read_b64_tr_b16 v[194:195], v126 offset:38912
	ds_read_b64_tr_b16 v[196:197], v126 offset:40960
	ds_read_b64_tr_b16 v[198:199], v127 offset:38912
	ds_read_b64_tr_b16 v[200:201], v127 offset:40960
	s_waitcnt lgkmcnt(14)
	v_mfma_f32_16x16x32_bf16 v[210:213], v[202:205], v[240:243], v[210:213]
	s_waitcnt lgkmcnt(12)
	v_mfma_f32_16x16x32_bf16 v[214:217], v[206:209], v[240:243], v[214:217]
	s_waitcnt lgkmcnt(10)
	v_mfma_f32_16x16x32_bf16 v[220:223], v[228:231], v[240:243], v[220:223]
	s_waitcnt lgkmcnt(8)
	v_mfma_f32_16x16x32_bf16 v[224:227], v[232:235], v[240:243], v[224:227]
	v_cvt_pk_bf16_f32 v236, v114, v115
	v_cvt_pk_bf16_f32 v237, v116, v117
	v_mov_b32_e32 v238, 0
	v_mov_b32_e32 v239, 0
	s_nop 1
	s_waitcnt lgkmcnt(6)
	v_mfma_f32_16x16x32_bf16 v[210:213], v[186:189], v[236:239], v[210:213]
	s_waitcnt lgkmcnt(4)
	v_mfma_f32_16x16x32_bf16 v[214:217], v[190:193], v[236:239], v[214:217]
	s_waitcnt lgkmcnt(2)
	v_mfma_f32_16x16x32_bf16 v[220:223], v[194:197], v[236:239], v[220:223]
	s_waitcnt lgkmcnt(0)
	v_mfma_f32_16x16x32_bf16 v[224:227], v[198:201], v[236:239], v[224:227]
	v_mov_b32_e32 v219, v185
	s_nop 1
	v_permlane16_swap_b32_e32 v185, v219
	v_add_f32_e32 v185, v185, v219
	v_mov_b32_e32 v219, v185
	s_nop 1
	v_permlane32_swap_b32_e32 v185, v219
	v_add_f32_e32 v185, v185, v219
	v_div_scale_f32 v236, s[78:79], v185, v185, 1.0
	v_div_scale_f32 v237, vcc, 1.0, v185, 1.0
	v_rcp_f32_e32 v238, v236
	s_nop 0
	v_fma_f32 v239, -v236, v238, 1.0
	v_fmac_f32_e32 v238, v239, v238
	v_mul_f32_e32 v240, v237, v238
	v_fma_f32 v241, -v236, v240, v237
	v_fmac_f32_e32 v240, v241, v238
	v_fma_f32 v237, -v236, v240, v237
	v_div_fmas_f32 v237, v237, v238, v240
	v_div_fixup_f32 v244, v237, v185, 1.0
	v_mul_f32_e32 v240, v210, v244
	v_mul_f32_e32 v241, v211, v244
	v_mul_f32_e32 v242, v212, v244
	v_mul_f32_e32 v243, v213, v244
	v_cvt_pk_bf16_f32 v186, v240, v241
	v_cvt_pk_bf16_f32 v187, v242, v243
	v_mul_f32_e32 v240, v214, v244
	v_mul_f32_e32 v241, v215, v244
	v_mul_f32_e32 v242, v216, v244
	v_mul_f32_e32 v243, v217, v244
	v_cvt_pk_bf16_f32 v188, v240, v241
	v_cvt_pk_bf16_f32 v189, v242, v243
	v_mul_f32_e32 v240, v220, v244
	v_mul_f32_e32 v241, v221, v244
	v_mul_f32_e32 v242, v222, v244
	v_mul_f32_e32 v243, v223, v244
	v_cvt_pk_bf16_f32 v190, v240, v241
	v_cvt_pk_bf16_f32 v191, v242, v243
	v_mul_f32_e32 v240, v224, v244
	v_mul_f32_e32 v241, v225, v244
	v_mul_f32_e32 v242, v226, v244
	v_mul_f32_e32 v243, v227, v244
	v_cvt_pk_bf16_f32 v192, v240, v241
	v_cvt_pk_bf16_f32 v193, v242, v243
	s_nop 1
	v_permlane16_swap_b32_e32 v186, v188
	v_permlane16_swap_b32_e32 v187, v189
	v_permlane16_swap_b32_e32 v190, v192
	v_permlane16_swap_b32_e32 v191, v193
	s_nop 0
	v_permlane32_swap_b32_e32 v186, v190
	v_permlane32_swap_b32_e32 v187, v191
	v_permlane32_swap_b32_e32 v188, v192
	v_permlane32_swap_b32_e32 v189, v193
	v_add_u32_e32 v219, 0x1000, v128
	global_store_dwordx4 v219, v[186:189], s[82:83] offset:2048
	global_store_dwordx4 v219, v[190:193], s[82:83] offset:2064
	s_nop 1
	s_branch .LBB0_240

; #define LAS __attribute__((address_space(3)))
; #define MFMA16(a, b, c) __builtin_amdgcn_mfma_f32_16x16x32_bf16((a), (b), (c), 0, 0, 0)
; __device__ __forceinline__ void qk_at(const LAS unsigned char* kp0, const LAS unsigned char* kp1, int off, bf16x8 qf0, bf16x8 qf1, f32x4& S0, f32x4& S1) {
;     const bf16x8 k00 = *(const LAS bf16x8*)(kp0 + off), k01 = *(const LAS bf16x8*)(kp1 + off);
;     const bf16x8 k10 = *(const LAS bf16x8*)(kp0 + off + 2048), k11 = *(const LAS bf16x8*)(kp1 + off + 2048);
;     const f32x4 z = {0.f, 0.f, 0.f, 0.f};
;     S0 = MFMA16(k00, qf0, z); S0 = MFMA16(k01, qf1, S0);
;     S1 = MFMA16(k10, qf0, z); S1 = MFMA16(k11, qf1, S1);
; }
; template <bool MASK> __device__ __forceinline__ void a_scores(f32x4& S0, f32x4& S1, float basef, float c1, float slope2, int krow0, int kstart) {
; #pragma unroll
;     for (int r = 0; r < 4; ++r) {
;         const float d0 = fabsf(basef - (float)r), d1 = fabsf(basef - (float)(16 + r));
;         const float v0 = S0[r] - slope2 * d0, v1 = S1[r] - slope2 * d1;
;         if (MASK) { const int p0 = kstart + krow0 + r, p1 = p0 + 16;
;             S0[r] = (d0 <= 128.f && p0 >= 0 && p0 < SEQ) ? v0 : -INFINITY; S1[r] = (d1 <= 128.f && p1 >= 0 && p1 < SEQ) ? v1 : -INFINITY; }
;         else { S0[r] = v0; S1[r] = v1; }
;     }
; }
.La_edge_go:
	s_bitcmp1_b32 s87, 0
	s_cselect_b32 s21, 0, 0xff800000
	v_add_f32_e32 v120, s21, v132
	v_fmamk_f32 v50, v130, 0x43000000, v120
	v_fmamk_f32 v51, v130, 0x42fe0000, v120
	v_fmamk_f32 v52, v130, 0x42fc0000, v120
	v_fmamk_f32 v53, v130, 0x42fa0000, v120
	v_mov_b32_e32 v245, 0xff800000
	v_cndmask_b32_e64 v50, v245, v50, s[16:17]
	v_cndmask_b32_e64 v51, v245, v51, s[18:19]
	v_cndmask_b32_e64 v52, v245, v52, s[22:23]
	v_cndmask_b32_e64 v53, v245, v53, s[24:25]
	s_bitcmp1_b32 s87, 1
	s_cselect_b32 s21, 0, 0xff800000
	v_add_f32_e32 v120, s21, v132
	v_fmamk_f32 v54, v130, 0x42e00000, v120
	v_fmamk_f32 v55, v130, 0x42de0000, v120
	v_fmamk_f32 v56, v130, 0x42dc0000, v120
	v_fmamk_f32 v57, v130, 0x42da0000, v120
	s_bitcmp1_b32 s87, 2
	s_cselect_b32 s21, 0, 0xff800000
	v_add_f32_e32 v120, s21, v132
	v_fmamk_f32 v58, v130, 0x42c00000, v120
	v_fmamk_f32 v59, v130, 0x42be0000, v120
	v_fmamk_f32 v60, v130, 0x42bc0000, v120
	v_fmamk_f32 v61, v130, 0x42ba0000, v120
	s_bitcmp1_b32 s87, 3
	s_cselect_b32 s21, 0, 0xff800000
	v_add_f32_e32 v120, s21, v132
	v_fmamk_f32 v62, v130, 0x42a00000, v120
	v_fmamk_f32 v63, v130, 0x429e0000, v120
	v_fmamk_f32 v64, v130, 0x429c0000, v120
	v_fmamk_f32 v65, v130, 0x429a0000, v120
	s_bitcmp1_b32 s87, 4
	s_cselect_b32 s21, 0, 0xff800000
	v_add_f32_e32 v120, s21, v132
	v_fmamk_f32 v66, v130, 0x42800000, v120
	v_fmamk_f32 v67, v130, 0x427c0000, v120
	v_fmamk_f32 v68, v130, 0x42780000, v120
	v_fmamk_f32 v69, v130, 0x42740000, v120
	s_bitcmp1_b32 s87, 5
	s_cselect_b32 s21, 0, 0xff800000
	v_add_f32_e32 v120, s21, v132
	v_fmamk_f32 v70, v130, 0x42400000, v120
	v_fmamk_f32 v71, v130, 0x423c0000, v120
	v_fmamk_f32 v72, v130, 0x42380000, v120
	v_fmamk_f32 v73, v130, 0x42340000, v120
	s_bitcmp1_b32 s87, 6
	s_cselect_b32 s21, 0, 0xff800000
	v_add_f32_e32 v120, s21, v132
	v_fmamk_f32 v74, v130, 0x42000000, v120
	v_fmamk_f32 v75, v130, 0x41f80000, v120
	v_fmamk_f32 v76, v130, 0x41f00000, v120
	v_fmamk_f32 v77, v130, 0x41e80000, v120
	s_bitcmp1_b32 s87, 7
	s_cselect_b32 s21, 0, 0xff800000
	v_add_f32_e32 v120, s21, v132
	v_fmamk_f32 v78, v130, 0x41800000, v120
	v_fmamk_f32 v79, v130, 0x41700000, v120
	v_fmamk_f32 v80, v130, 0x41600000, v120
	v_fmamk_f32 v81, v130, 0x41500000, v120
	s_bitcmp1_b32 s87, 8
	s_cselect_b32 s21, 0, 0xff800000
	v_add_f32_e32 v219, 0, v129
	v_fma_f32 v82, v130, |v219|, s21
	v_add_f32_e32 v245, 0xbf800000, v129
	v_fma_f32 v83, v130, |v245|, s21
	v_add_f32_e32 v219, 0xc0000000, v129
	v_fma_f32 v84, v130, |v219|, s21
	v_add_f32_e32 v245, 0xc0400000, v129
	v_fma_f32 v85, v130, |v245|, s21
	s_bitcmp1_b32 s87, 9
	s_cselect_b32 s21, 0, 0xff800000
	v_add_f32_e32 v120, s21, v133
	v_fmamk_f32 v86, v131, 0xc1800000, v120
	v_fmamk_f32 v87, v131, 0xc1880000, v120
	v_fmamk_f32 v88, v131, 0xc1900000, v120
	v_fmamk_f32 v89, v131, 0xc1980000, v120
	s_bitcmp1_b32 s87, 10
	s_cselect_b32 s21, 0, 0xff800000
	v_add_f32_e32 v120, s21, v133
	v_fmamk_f32 v90, v131, 0xc2000000, v120
	v_fmamk_f32 v91, v131, 0xc2040000, v120
	v_fmamk_f32 v92, v131, 0xc2080000, v120
	v_fmamk_f32 v93, v131, 0xc20c0000, v120
	s_bitcmp1_b32 s87, 11
	s_cselect_b32 s21, 0, 0xff800000
	v_add_f32_e32 v120, s21, v133
	v_fmamk_f32 v94, v131, 0xc2400000, v120
	v_fmamk_f32 v95, v131, 0xc2440000, v120
	v_fmamk_f32 v96, v131, 0xc2480000, v120
	v_fmamk_f32 v97, v131, 0xc24c0000, v120
	s_bitcmp1_b32 s87, 12
	s_cselect_b32 s21, 0, 0xff800000
	v_add_f32_e32 v120, s21, v133
	v_fmamk_f32 v98, v131, 0xc2800000, v120
	v_fmamk_f32 v99, v131, 0xc2820000, v120
	v_fmamk_f32 v100, v131, 0xc2840000, v120
	v_fmamk_f32 v101, v131, 0xc2860000, v120
	s_bitcmp1_b32 s87, 13
	s_cselect_b32 s21, 0, 0xff800000
	v_add_f32_e32 v120, s21, v133
	v_fmamk_f32 v102, v131, 0xc2a00000, v120
	v_fmamk_f32 v103, v131, 0xc2a20000, v120
	v_fmamk_f32 v104, v131, 0xc2a40000, v120
	v_fmamk_f32 v105, v131, 0xc2a60000, v120
	s_bitcmp1_b32 s87, 14
	s_cselect_b32 s21, 0, 0xff800000
	v_add_f32_e32 v120, s21, v133
	v_fmamk_f32 v106, v131, 0xc2c00000, v120
	v_fmamk_f32 v107, v131, 0xc2c20000, v120
	v_fmamk_f32 v108, v131, 0xc2c40000, v120
	v_fmamk_f32 v109, v131, 0xc2c60000, v120
	s_bitcmp1_b32 s87, 15
	s_cselect_b32 s21, 0, 0xff800000
	v_add_f32_e32 v120, s21, v133
	v_fmamk_f32 v110, v131, 0xc2e00000, v120
	v_fmamk_f32 v111, v131, 0xc2e20000, v120
	v_fmamk_f32 v112, v131, 0xc2e40000, v120
	v_fmamk_f32 v113, v131, 0xc2e60000, v120
	s_bitcmp1_b32 s87, 16
	s_cselect_b32 s21, 0, 0xff800000
	v_add_f32_e32 v120, s21, v133
	v_fmamk_f32 v114, v131, 0xc3000000, v120
	v_fmamk_f32 v115, v131, 0xc3010000, v120
	v_fmamk_f32 v116, v131, 0xc3020000, v120
	v_fmamk_f32 v117, v131, 0xc3030000, v120
	v_mov_b32_e32 v245, 0xff800000
	v_cndmask_b32_e64 v114, v245, v114, s[28:29]
	v_cndmask_b32_e64 v115, v245, v115, s[52:53]
	v_cndmask_b32_e64 v116, v245, v116, s[54:55]
	v_cndmask_b32_e64 v117, v245, v117, s[88:89]
	ds_read_b128 v[186:189], v122 offset:0
	ds_read_b128 v[190:193], v123 offset:0
	ds_read_b128 v[194:197], v122 offset:2048
	ds_read_b128 v[198:201], v123 offset:2048
	ds_read_b128 v[202:205], v122 offset:4096
	ds_read_b128 v[206:209], v123 offset:4096
	ds_read_b128 v[210:213], v122 offset:6144
	ds_read_b128 v[214:217], v123 offset:6144
	ds_read_b128 v[220:223], v122 offset:8192
	ds_read_b128 v[224:227], v123 offset:8192
	ds_read_b128 v[228:231], v122 offset:10240
	ds_read_b128 v[232:235], v123 offset:10240
	ds_read_b128 v[236:239], v122 offset:12288
	ds_read_b128 v[240:243], v123 offset:12288
	s_waitcnt lgkmcnt(13)
	v_mfma_f32_16x16x32_bf16 v[50:53], v[186:189], v[146:149], v[50:53]
	s_waitcnt lgkmcnt(12)
	v_mfma_f32_16x16x32_bf16 v[50:53], v[190:193], v[150:153], v[50:53]
	ds_read_b128 v[186:189], v122 offset:14336
	ds_read_b128 v[190:193], v123 offset:14336
	s_waitcnt lgkmcnt(13)
; #define LAS __attribute__((address_space(3)))
; #define MFMA16(a, b, c) __builtin_amdgcn_mfma_f32_16x16x32_bf16((a), (b), (c), 0, 0, 0)
; __device__ __forceinline__ void qk_at(const LAS unsigned char* kp0, const LAS unsigned char* kp1, int off, bf16x8 qf0, bf16x8 qf1, f32x4& S0, f32x4& S1) {
;     const bf16x8 k00 = *(const LAS bf16x8*)(kp0 + off), k01 = *(const LAS bf16x8*)(kp1 + off);
;     const bf16x8 k10 = *(const LAS bf16x8*)(kp0 + off + 2048), k11 = *(const LAS bf16x8*)(kp1 + off + 2048);
;     const f32x4 z = {0.f, 0.f, 0.f, 0.f};
;     S0 = MFMA16(k00, qf0, z); S0 = MFMA16(k01, qf1, S0);
;     S1 = MFMA16(k10, qf0, z); S1 = MFMA16(k11, qf1, S1);
; }
; __device__ __forceinline__ void softmax_step(f32x4& s0, f32x4& s1, float& m, float& l, f32x4 (&O)[4]) {
;     float t = fmaxf(fmaxf(fmaxf(s0[0], s0[1]), fmaxf(s0[2], s0[3])), fmaxf(fmaxf(s1[0], s1[1]), fmaxf(s1[2], s1[3])));
;     t = xrow16_max(t);
;     const float mn = fmaxf(m, t), alpha = __builtin_amdgcn_exp2f(m - mn);
	v_mfma_f32_16x16x32_bf16 v[54:57], v[194:197], v[146:149], v[54:57]
	s_waitcnt lgkmcnt(12)
	v_mfma_f32_16x16x32_bf16 v[54:57], v[198:201], v[150:153], v[54:57]
	ds_read_b128 v[194:197], v122 offset:16384
	ds_read_b128 v[198:201], v123 offset:16384
	s_waitcnt lgkmcnt(13)
	v_mfma_f32_16x16x32_bf16 v[58:61], v[202:205], v[146:149], v[58:61]
	s_waitcnt lgkmcnt(12)
	v_mfma_f32_16x16x32_bf16 v[58:61], v[206:209], v[150:153], v[58:61]
	ds_read_b128 v[202:205], v122 offset:18432
	ds_read_b128 v[206:209], v123 offset:18432
	s_waitcnt lgkmcnt(13)
	v_mfma_f32_16x16x32_bf16 v[62:65], v[210:213], v[146:149], v[62:65]
	s_waitcnt lgkmcnt(12)
	v_mfma_f32_16x16x32_bf16 v[62:65], v[214:217], v[150:153], v[62:65]
	ds_read_b128 v[210:213], v122 offset:20480
	ds_read_b128 v[214:217], v123 offset:20480
	s_waitcnt lgkmcnt(13)
	v_mfma_f32_16x16x32_bf16 v[66:69], v[220:223], v[146:149], v[66:69]
	s_waitcnt lgkmcnt(12)
	v_mfma_f32_16x16x32_bf16 v[66:69], v[224:227], v[150:153], v[66:69]
	ds_read_b128 v[220:223], v122 offset:22528
	ds_read_b128 v[224:227], v123 offset:22528
	s_waitcnt lgkmcnt(13)
	v_mfma_f32_16x16x32_bf16 v[70:73], v[228:231], v[146:149], v[70:73]
	s_waitcnt lgkmcnt(12)
	v_mfma_f32_16x16x32_bf16 v[70:73], v[232:235], v[150:153], v[70:73]
	ds_read_b128 v[228:231], v122 offset:24576
	ds_read_b128 v[232:235], v123 offset:24576
	s_waitcnt lgkmcnt(13)
	v_mfma_f32_16x16x32_bf16 v[74:77], v[236:239], v[146:149], v[74:77]
	s_waitcnt lgkmcnt(12)
	v_mfma_f32_16x16x32_bf16 v[74:77], v[240:243], v[150:153], v[74:77]
	ds_read_b128 v[236:239], v122 offset:26624
	ds_read_b128 v[240:243], v123 offset:26624
	s_waitcnt lgkmcnt(13)
	v_mfma_f32_16x16x32_bf16 v[78:81], v[186:189], v[146:149], v[78:81]
	s_waitcnt lgkmcnt(12)
	v_mfma_f32_16x16x32_bf16 v[78:81], v[190:193], v[150:153], v[78:81]
	ds_read_b128 v[186:189], v122 offset:28672
	ds_read_b128 v[190:193], v123 offset:28672
	s_waitcnt lgkmcnt(13)
	v_mfma_f32_16x16x32_bf16 v[82:85], v[194:197], v[146:149], v[82:85]
	s_waitcnt lgkmcnt(12)
	v_mfma_f32_16x16x32_bf16 v[82:85], v[198:201], v[150:153], v[82:85]
	ds_read_b128 v[194:197], v122 offset:30720
	ds_read_b128 v[198:201], v123 offset:30720
	s_waitcnt lgkmcnt(13)
	v_mfma_f32_16x16x32_bf16 v[86:89], v[202:205], v[146:149], v[86:89]
	s_waitcnt lgkmcnt(12)
	v_mfma_f32_16x16x32_bf16 v[86:89], v[206:209], v[150:153], v[86:89]
	ds_read_b128 v[202:205], v122 offset:32768
	ds_read_b128 v[206:209], v123 offset:32768
	s_waitcnt lgkmcnt(13)
	v_mfma_f32_16x16x32_bf16 v[90:93], v[210:213], v[146:149], v[90:93]
	s_waitcnt lgkmcnt(12)
	v_mfma_f32_16x16x32_bf16 v[90:93], v[214:217], v[150:153], v[90:93]
	s_waitcnt lgkmcnt(11)
	v_mfma_f32_16x16x32_bf16 v[94:97], v[220:223], v[146:149], v[94:97]
	s_waitcnt lgkmcnt(10)
	v_mfma_f32_16x16x32_bf16 v[94:97], v[224:227], v[150:153], v[94:97]
	s_waitcnt lgkmcnt(9)
	v_mfma_f32_16x16x32_bf16 v[98:101], v[228:231], v[146:149], v[98:101]
	s_waitcnt lgkmcnt(8)
	v_mfma_f32_16x16x32_bf16 v[98:101], v[232:235], v[150:153], v[98:101]
	s_waitcnt lgkmcnt(7)
	v_mfma_f32_16x16x32_bf16 v[102:105], v[236:239], v[146:149], v[102:105]
	s_waitcnt lgkmcnt(6)
	v_mfma_f32_16x16x32_bf16 v[102:105], v[240:243], v[150:153], v[102:105]
	s_waitcnt lgkmcnt(5)
	v_mfma_f32_16x16x32_bf16 v[106:109], v[186:189], v[146:149], v[106:109]
	s_waitcnt lgkmcnt(4)
	v_mfma_f32_16x16x32_bf16 v[106:109], v[190:193], v[150:153], v[106:109]
	s_waitcnt lgkmcnt(3)
	v_mfma_f32_16x16x32_bf16 v[110:113], v[194:197], v[146:149], v[110:113]
	s_waitcnt lgkmcnt(2)
	v_mfma_f32_16x16x32_bf16 v[110:113], v[198:201], v[150:153], v[110:113]
	s_waitcnt lgkmcnt(1)
	v_mfma_f32_16x16x32_bf16 v[114:117], v[202:205], v[146:149], v[114:117]
	s_waitcnt lgkmcnt(0)
	v_mfma_f32_16x16x32_bf16 v[114:117], v[206:209], v[150:153], v[114:117]
	v_max3_f32 v219, v50, v51, v52
	v_max3_f32 v244, v54, v55, v56
	v_max3_f32 v245, v58, v59, v60
	v_max3_f32 v120, v62, v63, v64
	v_max3_f32 v219, v219, v53, v66
	v_max3_f32 v244, v244, v57, v70
	v_max3_f32 v245, v245, v61, v74
	v_max3_f32 v120, v120, v65, v78
	v_max3_f32 v219, v219, v67, v68
	v_max3_f32 v244, v244, v71, v72
	v_max3_f32 v245, v245, v75, v76
	v_max3_f32 v120, v120, v79, v80
	ds_read_b64_tr_b16 v[186:187], v124 offset:0
	ds_read_b64_tr_b16 v[188:189], v124 offset:2048
	ds_read_b64_tr_b16 v[190:191], v125 offset:0
	ds_read_b64_tr_b16 v[192:193], v125 offset:2048
	ds_read_b64_tr_b16 v[194:195], v126 offset:0
	ds_read_b64_tr_b16 v[196:197], v126 offset:2048
	ds_read_b64_tr_b16 v[198:199], v127 offset:0
	ds_read_b64_tr_b16 v[200:201], v127 offset:2048
	v_max3_f32 v219, v219, v69, v82
	v_max3_f32 v244, v244, v73, v86
	v_max3_f32 v245, v245, v77, v90
	v_max3_f32 v120, v120, v81, v94
	v_max3_f32 v219, v219, v83, v84
	v_max3_f32 v244, v244, v87, v88
	v_max3_f32 v245, v245, v91, v92
	v_max3_f32 v120, v120, v95, v96
	v_max3_f32 v219, v219, v85, v98
	v_max3_f32 v244, v244, v89, v102
	v_max3_f32 v245, v245, v93, v106
	v_max3_f32 v120, v120, v97, v110
	v_max3_f32 v219, v219, v99, v100
	v_max3_f32 v244, v244, v103, v104
	v_max3_f32 v245, v245, v107, v108
	v_max3_f32 v120, v120, v111, v112
	v_max3_f32 v219, v219, v101, v114
	v_max3_f32 v219, v219, v115, v116
	v_max_f32_e32 v219, v219, v117
	v_max_f32_e32 v244, v244, v105
	v_max_f32_e32 v245, v245, v109
	v_max_f32_e32 v120, v120, v113
	v_max3_f32 v178, v219, v244, v245
	v_max_f32_e32 v178, v178, v120
	v_mov_b32_e32 v219, v178
	s_nop 1
	v_permlane16_swap_b32_e32 v178, v219
	v_max_f32_e32 v178, v178, v219
	v_mov_b32_e32 v219, v178
	s_nop 1
	v_permlane32_swap_b32_e32 v178, v219
	v_max3_f32 v178, v178, v219, v145
	s_waitcnt lgkmcnt(7)
; __device__ __forceinline__ void softmax_step(f32x4& s0, f32x4& s1, float& m, float& l, f32x4 (&O)[4]) {
;     float t = fmaxf(fmaxf(fmaxf(s0[0], s0[1]), fmaxf(s0[2], s0[3])), fmaxf(fmaxf(s1[0], s1[1]), fmaxf(s1[2], s1[3])));
;     t = xrow16_max(t);
;     const float mn = fmaxf(m, t), alpha = __builtin_amdgcn_exp2f(m - mn);
;     m = mn;
; #pragma unroll
;     for (int k = 0; k < 4; ++k) { s0[k] = __builtin_amdgcn_exp2f(s0[k] - mn); s1[k] = __builtin_amdgcn_exp2f(s1[k] - mn); }
;     l = l * alpha + ((s0[0] + s0[1]) + (s0[2] + s0[3])) + ((s1[0] + s1[1]) + (s1[2] + s1[3]));
; #pragma unroll
;     for (int db = 0; db < 4; ++db) O[db] *= alpha;
; }
	ds_read_b64_tr_b16 v[202:203], v124 offset:4096
	ds_read_b64_tr_b16 v[204:205], v124 offset:6144
	ds_read_b64_tr_b16 v[206:207], v125 offset:4096
	ds_read_b64_tr_b16 v[208:209], v125 offset:6144
	ds_read_b64_tr_b16 v[228:229], v126 offset:4096
	ds_read_b64_tr_b16 v[230:231], v126 offset:6144
	ds_read_b64_tr_b16 v[232:233], v127 offset:4096
	ds_read_b64_tr_b16 v[234:235], v127 offset:6144
	v_mov_b32_e32 v244, v178
	v_pk_add_f32 v[50:51], v[50:51], v[244:245] op_sel_hi:[1,0] neg_lo:[0,1] neg_hi:[0,1]
	v_pk_add_f32 v[52:53], v[52:53], v[244:245] op_sel_hi:[1,0] neg_lo:[0,1] neg_hi:[0,1]
	v_pk_add_f32 v[54:55], v[54:55], v[244:245] op_sel_hi:[1,0] neg_lo:[0,1] neg_hi:[0,1]
	v_pk_add_f32 v[56:57], v[56:57], v[244:245] op_sel_hi:[1,0] neg_lo:[0,1] neg_hi:[0,1]
	v_pk_add_f32 v[58:59], v[58:59], v[244:245] op_sel_hi:[1,0] neg_lo:[0,1] neg_hi:[0,1]
	v_pk_add_f32 v[60:61], v[60:61], v[244:245] op_sel_hi:[1,0] neg_lo:[0,1] neg_hi:[0,1]
	v_pk_add_f32 v[62:63], v[62:63], v[244:245] op_sel_hi:[1,0] neg_lo:[0,1] neg_hi:[0,1]
	v_pk_add_f32 v[64:65], v[64:65], v[244:245] op_sel_hi:[1,0] neg_lo:[0,1] neg_hi:[0,1]
	v_pk_add_f32 v[66:67], v[66:67], v[244:245] op_sel_hi:[1,0] neg_lo:[0,1] neg_hi:[0,1]
	v_pk_add_f32 v[68:69], v[68:69], v[244:245] op_sel_hi:[1,0] neg_lo:[0,1] neg_hi:[0,1]
	v_pk_add_f32 v[70:71], v[70:71], v[244:245] op_sel_hi:[1,0] neg_lo:[0,1] neg_hi:[0,1]
	v_pk_add_f32 v[72:73], v[72:73], v[244:245] op_sel_hi:[1,0] neg_lo:[0,1] neg_hi:[0,1]
	v_pk_add_f32 v[74:75], v[74:75], v[244:245] op_sel_hi:[1,0] neg_lo:[0,1] neg_hi:[0,1]
	v_pk_add_f32 v[76:77], v[76:77], v[244:245] op_sel_hi:[1,0] neg_lo:[0,1] neg_hi:[0,1]
	v_pk_add_f32 v[78:79], v[78:79], v[244:245] op_sel_hi:[1,0] neg_lo:[0,1] neg_hi:[0,1]
	v_pk_add_f32 v[80:81], v[80:81], v[244:245] op_sel_hi:[1,0] neg_lo:[0,1] neg_hi:[0,1]
	v_pk_add_f32 v[82:83], v[82:83], v[244:245] op_sel_hi:[1,0] neg_lo:[0,1] neg_hi:[0,1]
	v_pk_add_f32 v[84:85], v[84:85], v[244:245] op_sel_hi:[1,0] neg_lo:[0,1] neg_hi:[0,1]
	v_pk_add_f32 v[86:87], v[86:87], v[244:245] op_sel_hi:[1,0] neg_lo:[0,1] neg_hi:[0,1]
	v_pk_add_f32 v[88:89], v[88:89], v[244:245] op_sel_hi:[1,0] neg_lo:[0,1] neg_hi:[0,1]
	v_pk_add_f32 v[90:91], v[90:91], v[244:245] op_sel_hi:[1,0] neg_lo:[0,1] neg_hi:[0,1]
	v_pk_add_f32 v[92:93], v[92:93], v[244:245] op_sel_hi:[1,0] neg_lo:[0,1] neg_hi:[0,1]
	v_pk_add_f32 v[94:95], v[94:95], v[244:245] op_sel_hi:[1,0] neg_lo:[0,1] neg_hi:[0,1]
	v_pk_add_f32 v[96:97], v[96:97], v[244:245] op_sel_hi:[1,0] neg_lo:[0,1] neg_hi:[0,1]
	v_pk_add_f32 v[98:99], v[98:99], v[244:245] op_sel_hi:[1,0] neg_lo:[0,1] neg_hi:[0,1]
	v_pk_add_f32 v[100:101], v[100:101], v[244:245] op_sel_hi:[1,0] neg_lo:[0,1] neg_hi:[0,1]
	v_pk_add_f32 v[102:103], v[102:103], v[244:245] op_sel_hi:[1,0] neg_lo:[0,1] neg_hi:[0,1]
	v_pk_add_f32 v[104:105], v[104:105], v[244:245] op_sel_hi:[1,0] neg_lo:[0,1] neg_hi:[0,1]
	v_pk_add_f32 v[106:107], v[106:107], v[244:245] op_sel_hi:[1,0] neg_lo:[0,1] neg_hi:[0,1]
	v_pk_add_f32 v[108:109], v[108:109], v[244:245] op_sel_hi:[1,0] neg_lo:[0,1] neg_hi:[0,1]
	v_pk_add_f32 v[110:111], v[110:111], v[244:245] op_sel_hi:[1,0] neg_lo:[0,1] neg_hi:[0,1]
	v_pk_add_f32 v[112:113], v[112:113], v[244:245] op_sel_hi:[1,0] neg_lo:[0,1] neg_hi:[0,1]
	v_pk_add_f32 v[114:115], v[114:115], v[244:245] op_sel_hi:[1,0] neg_lo:[0,1] neg_hi:[0,1]
	v_pk_add_f32 v[116:117], v[116:117], v[244:245] op_sel_hi:[1,0] neg_lo:[0,1] neg_hi:[0,1]
	v_sub_f32_e32 v219, v145, v178
	v_exp_f32_e32 v50, v50
	v_exp_f32_e32 v51, v51
	v_exp_f32_e32 v52, v52
	v_exp_f32_e32 v53, v53
	v_exp_f32_e32 v54, v54
	v_exp_f32_e32 v55, v55
	v_exp_f32_e32 v56, v56
	v_exp_f32_e32 v57, v57
	v_exp_f32_e32 v58, v58
	v_exp_f32_e32 v59, v59
	v_exp_f32_e32 v60, v60
	v_exp_f32_e32 v61, v61
	v_exp_f32_e32 v62, v62
	v_exp_f32_e32 v63, v63
	v_exp_f32_e32 v64, v64
	v_exp_f32_e32 v65, v65
	v_exp_f32_e32 v66, v66
	v_exp_f32_e32 v67, v67
	v_exp_f32_e32 v68, v68
	v_exp_f32_e32 v69, v69
	v_exp_f32_e32 v70, v70
	v_exp_f32_e32 v71, v71
	v_exp_f32_e32 v72, v72
	v_exp_f32_e32 v73, v73
	v_exp_f32_e32 v74, v74
	v_exp_f32_e32 v75, v75
	v_exp_f32_e32 v76, v76
	v_exp_f32_e32 v77, v77
	v_exp_f32_e32 v78, v78
	v_exp_f32_e32 v79, v79
	v_exp_f32_e32 v80, v80
	v_exp_f32_e32 v81, v81
	v_exp_f32_e32 v82, v82
	v_exp_f32_e32 v83, v83
	v_exp_f32_e32 v84, v84
	v_exp_f32_e32 v85, v85
	v_exp_f32_e32 v86, v86
	v_exp_f32_e32 v87, v87
	v_exp_f32_e32 v88, v88
	v_exp_f32_e32 v89, v89
	v_exp_f32_e32 v90, v90
	v_exp_f32_e32 v91, v91
	v_exp_f32_e32 v92, v92
	v_exp_f32_e32 v93, v93
	v_exp_f32_e32 v94, v94
	v_exp_f32_e32 v95, v95
	v_exp_f32_e32 v96, v96
	v_exp_f32_e32 v97, v97
	v_exp_f32_e32 v98, v98
	v_exp_f32_e32 v99, v99
	v_exp_f32_e32 v100, v100
	v_exp_f32_e32 v101, v101
	v_exp_f32_e32 v102, v102
	v_exp_f32_e32 v103, v103
	v_exp_f32_e32 v104, v104
	v_exp_f32_e32 v105, v105
	v_exp_f32_e32 v106, v106
	v_exp_f32_e32 v107, v107
	v_exp_f32_e32 v108, v108
	v_exp_f32_e32 v109, v109
	v_exp_f32_e32 v110, v110
	v_exp_f32_e32 v111, v111
	v_exp_f32_e32 v112, v112
	v_exp_f32_e32 v113, v113
	v_exp_f32_e32 v114, v114
	v_exp_f32_e32 v115, v115
	v_exp_f32_e32 v116, v116
	v_exp_f32_e32 v117, v117
	v_exp_f32_e32 v219, v219
	v_pk_add_f32 v[236:237], v[50:51], v[52:53]
	v_pk_add_f32 v[238:239], v[54:55], v[56:57]
	v_pk_add_f32 v[240:241], v[58:59], v[60:61]
	v_pk_add_f32 v[242:243], v[62:63], v[64:65]
	v_pk_add_f32 v[236:237], v[236:237], v[66:67]
	v_pk_add_f32 v[238:239], v[238:239], v[70:71]
	v_pk_add_f32 v[240:241], v[240:241], v[74:75]
	v_pk_add_f32 v[242:243], v[242:243], v[78:79]
	v_pk_add_f32 v[236:237], v[236:237], v[68:69]
	v_pk_add_f32 v[238:239], v[238:239], v[72:73]
	v_pk_add_f32 v[240:241], v[240:241], v[76:77]
	v_pk_add_f32 v[242:243], v[242:243], v[80:81]
	v_pk_add_f32 v[236:237], v[236:237], v[82:83]
	v_pk_add_f32 v[238:239], v[238:239], v[86:87]
	v_pk_add_f32 v[240:241], v[240:241], v[90:91]
	v_pk_add_f32 v[242:243], v[242:243], v[94:95]
	v_pk_add_f32 v[236:237], v[236:237], v[84:85]
	v_pk_add_f32 v[238:239], v[238:239], v[88:89]
	v_pk_add_f32 v[240:241], v[240:241], v[92:93]
	v_pk_add_f32 v[242:243], v[242:243], v[96:97]
	v_pk_add_f32 v[236:237], v[236:237], v[98:99]
	v_pk_add_f32 v[238:239], v[238:239], v[102:103]
	v_pk_add_f32 v[240:241], v[240:241], v[106:107]
	v_pk_add_f32 v[242:243], v[242:243], v[110:111]
	v_pk_add_f32 v[236:237], v[236:237], v[100:101]
	v_pk_add_f32 v[238:239], v[238:239], v[104:105]
	v_pk_add_f32 v[240:241], v[240:241], v[108:109]
	v_pk_add_f32 v[242:243], v[242:243], v[112:113]
	v_pk_add_f32 v[236:237], v[236:237], v[114:115]
	v_pk_add_f32 v[236:237], v[236:237], v[116:117]
	v_pk_add_f32 v[236:237], v[236:237], v[238:239]
	v_pk_add_f32 v[240:241], v[240:241], v[242:243]
	v_cndmask_b32_e64 v219, 0, v219, s[74:75]
	v_pk_add_f32 v[236:237], v[236:237], v[240:241]
	v_add_f32_e32 v185, v236, v237
	v_add_f32_e32 v185, v185, v219
	v_cvt_pk_bf16_f32 v236, v50, v51
	v_cvt_pk_bf16_f32 v237, v52, v53
	v_cvt_pk_bf16_f32 v238, v54, v55
	v_cvt_pk_bf16_f32 v239, v56, v57
	s_nop 1
	s_waitcnt lgkmcnt(14)
; #define LAS __attribute__((address_space(3)))
; __device__ __forceinline__ unsigned pk2(float lo, float hi) { return pg8::cvt_pk_bf16(lo, hi); }
; __device__ __forceinline__ s16x4 vtr(const LAS unsigned char* p) { return __builtin_bit_cast(s16x4, __builtin_amdgcn_ds_read_tr16_b64_v4i16((LAS s16x4*)p)); }
; #define MFMA16(a, b, c) __builtin_amdgcn_mfma_f32_16x16x32_bf16((a), (b), (c), 0, 0, 0)
; __device__ __forceinline__ void pv_at(const LAS unsigned char* const (&vp)[4], int off, const f32x4& P0, const f32x4& P1, f32x4 (&O)[4]) {
;     v4u pw; pw.x = pk2(P0[0], P0[1]); pw.y = pk2(P0[2], P0[3]); pw.z = pk2(P1[0], P1[1]); pw.w = pk2(P1[2], P1[3]);
;     const bf16x8 pb = __builtin_bit_cast(bf16x8, pw);
; #pragma unroll
;     for (int db = 0; db < 4; ++db) {
;         const s16x4 lo = vtr(vp[db] + off), hi = vtr(vp[db] + off + 2048);
;         const bf16x8 vt = (bf16x8){lo[0], lo[1], lo[2], lo[3], hi[0], hi[1], hi[2], hi[3]};
;         O[db] = MFMA16(vt, pb, O[db]);
;     }
; }
; template <bool MASK> __device__ __forceinline__ void a_scores(f32x4& S0, f32x4& S1, float basef, float c1, float slope2, int krow0, int kstart) {
; #pragma unroll
;     for (int r = 0; r < 4; ++r) {
;         const float d0 = fabsf(basef - (float)r), d1 = fabsf(basef - (float)(16 + r));
;         const float v0 = S0[r] - slope2 * d0, v1 = S1[r] - slope2 * d1;
;         if (MASK) { const int p0 = kstart + krow0 + r, p1 = p0 + 16;
;             S0[r] = (d0 <= 128.f && p0 >= 0 && p0 < SEQ) ? v0 : -INFINITY; S1[r] = (d1 <= 128.f && p1 >= 0 && p1 < SEQ) ? v1 : -INFINITY; }
;         else { S0[r] = v0; S1[r] = v1; }
;     }
; }
	v_mfma_f32_16x16x32_bf16 v[210:213], v[186:189], v[236:239], 0
	s_waitcnt lgkmcnt(12)
	v_mfma_f32_16x16x32_bf16 v[214:217], v[190:193], v[236:239], 0
	s_waitcnt lgkmcnt(10)
	v_mfma_f32_16x16x32_bf16 v[220:223], v[194:197], v[236:239], 0
	s_waitcnt lgkmcnt(8)
	v_mfma_f32_16x16x32_bf16 v[224:227], v[198:201], v[236:239], 0
	v_cvt_pk_bf16_f32 v240, v58, v59
	v_cvt_pk_bf16_f32 v241, v60, v61
	v_cvt_pk_bf16_f32 v242, v62, v63
	v_cvt_pk_bf16_f32 v243, v64, v65
	s_waitcnt lgkmcnt(7)
	ds_read_b64_tr_b16 v[186:187], v124 offset:8192
	ds_read_b64_tr_b16 v[188:189], v124 offset:10240
	ds_read_b64_tr_b16 v[190:191], v125 offset:8192
	ds_read_b64_tr_b16 v[192:193], v125 offset:10240
	ds_read_b64_tr_b16 v[194:195], v126 offset:8192
	ds_read_b64_tr_b16 v[196:197], v126 offset:10240
	ds_read_b64_tr_b16 v[198:199], v127 offset:8192
	ds_read_b64_tr_b16 v[200:201], v127 offset:10240
	s_bitcmp1_b32 s87, 1
	s_cselect_b32 s21, 0, 0xff800000
	v_add_f32_e32 v120, s21, v132
	v_fmamk_f32 v50, v130, 0x43000000, v120
	v_fmamk_f32 v51, v130, 0x42fe0000, v120
	v_fmamk_f32 v52, v130, 0x42fc0000, v120
	v_fmamk_f32 v53, v130, 0x42fa0000, v120
	v_mov_b32_e32 v245, 0xff800000
	v_cndmask_b32_e64 v50, v245, v50, s[16:17]
	v_cndmask_b32_e64 v51, v245, v51, s[18:19]
	v_cndmask_b32_e64 v52, v245, v52, s[22:23]
	v_cndmask_b32_e64 v53, v245, v53, s[24:25]
	s_bitcmp1_b32 s87, 2
	s_cselect_b32 s21, 0, 0xff800000
	v_add_f32_e32 v120, s21, v132
	v_fmamk_f32 v54, v130, 0x42e00000, v120
	v_fmamk_f32 v55, v130, 0x42de0000, v120
	v_fmamk_f32 v56, v130, 0x42dc0000, v120
	v_fmamk_f32 v57, v130, 0x42da0000, v120
	s_waitcnt lgkmcnt(14)
	v_mfma_f32_16x16x32_bf16 v[210:213], v[202:205], v[240:243], v[210:213]
	s_waitcnt lgkmcnt(12)
	v_mfma_f32_16x16x32_bf16 v[214:217], v[206:209], v[240:243], v[214:217]
	s_waitcnt lgkmcnt(10)
	v_mfma_f32_16x16x32_bf16 v[220:223], v[228:231], v[240:243], v[220:223]
	s_waitcnt lgkmcnt(8)
	v_mfma_f32_16x16x32_bf16 v[224:227], v[232:235], v[240:243], v[224:227]
	v_cvt_pk_bf16_f32 v236, v66, v67
	v_cvt_pk_bf16_f32 v237, v68, v69
	v_cvt_pk_bf16_f32 v238, v70, v71
	v_cvt_pk_bf16_f32 v239, v72, v73
	s_waitcnt lgkmcnt(7)
	ds_read_b64_tr_b16 v[202:203], v124 offset:12288
	ds_read_b64_tr_b16 v[204:205], v124 offset:14336
	ds_read_b64_tr_b16 v[206:207], v125 offset:12288
	ds_read_b64_tr_b16 v[208:209], v125 offset:14336
	ds_read_b64_tr_b16 v[228:229], v126 offset:12288
	ds_read_b64_tr_b16 v[230:231], v126 offset:14336
	ds_read_b64_tr_b16 v[232:233], v127 offset:12288
	ds_read_b64_tr_b16 v[234:235], v127 offset:14336
	s_bitcmp1_b32 s87, 3
	s_cselect_b32 s21, 0, 0xff800000
	v_add_f32_e32 v120, s21, v132
	v_fmamk_f32 v58, v130, 0x42c00000, v120
	v_fmamk_f32 v59, v130, 0x42be0000, v120
	v_fmamk_f32 v60, v130, 0x42bc0000, v120
	v_fmamk_f32 v61, v130, 0x42ba0000, v120
	s_bitcmp1_b32 s87, 4
	s_cselect_b32 s21, 0, 0xff800000
	v_add_f32_e32 v120, s21, v132
	v_fmamk_f32 v62, v130, 0x42a00000, v120
	v_fmamk_f32 v63, v130, 0x429e0000, v120
	v_fmamk_f32 v64, v130, 0x429c0000, v120
	v_fmamk_f32 v65, v130, 0x429a0000, v120
	s_waitcnt lgkmcnt(14)
	v_mfma_f32_16x16x32_bf16 v[210:213], v[186:189], v[236:239], v[210:213]
	s_waitcnt lgkmcnt(12)
	v_mfma_f32_16x16x32_bf16 v[214:217], v[190:193], v[236:239], v[214:217]
	s_waitcnt lgkmcnt(10)
	v_mfma_f32_16x16x32_bf16 v[220:223], v[194:197], v[236:239], v[220:223]
	s_waitcnt lgkmcnt(8)
	v_mfma_f32_16x16x32_bf16 v[224:227], v[198:201], v[236:239], v[224:227]
	v_cvt_pk_bf16_f32 v240, v74, v75
	v_cvt_pk_bf16_f32 v241, v76, v77
	v_cvt_pk_bf16_f32 v242, v78, v79
	v_cvt_pk_bf16_f32 v243, v80, v81
	s_waitcnt lgkmcnt(7)
	ds_read_b64_tr_b16 v[186:187], v124 offset:16384
	ds_read_b64_tr_b16 v[188:189], v124 offset:18432
	ds_read_b64_tr_b16 v[190:191], v125 offset:16384
	ds_read_b64_tr_b16 v[192:193], v125 offset:18432
	ds_read_b64_tr_b16 v[194:195], v126 offset:16384
	ds_read_b64_tr_b16 v[196:197], v126 offset:18432
	ds_read_b64_tr_b16 v[198:199], v127 offset:16384
	ds_read_b64_tr_b16 v[200:201], v127 offset:18432
	s_bitcmp1_b32 s87, 5
	s_cselect_b32 s21, 0, 0xff800000
	v_add_f32_e32 v120, s21, v132
	v_fmamk_f32 v66, v130, 0x42800000, v120
	v_fmamk_f32 v67, v130, 0x427c0000, v120
	v_fmamk_f32 v68, v130, 0x42780000, v120
	v_fmamk_f32 v69, v130, 0x42740000, v120
	s_bitcmp1_b32 s87, 6
	s_cselect_b32 s21, 0, 0xff800000
	v_add_f32_e32 v120, s21, v132
	v_fmamk_f32 v70, v130, 0x42400000, v120
	v_fmamk_f32 v71, v130, 0x423c0000, v120
	v_fmamk_f32 v72, v130, 0x42380000, v120
	v_fmamk_f32 v73, v130, 0x42340000, v120
	s_waitcnt lgkmcnt(14)
	v_mfma_f32_16x16x32_bf16 v[210:213], v[202:205], v[240:243], v[210:213]
	s_waitcnt lgkmcnt(12)
	v_mfma_f32_16x16x32_bf16 v[214:217], v[206:209], v[240:243], v[214:217]
	s_waitcnt lgkmcnt(10)
	v_mfma_f32_16x16x32_bf16 v[220:223], v[228:231], v[240:243], v[220:223]
	s_waitcnt lgkmcnt(8)
	v_mfma_f32_16x16x32_bf16 v[224:227], v[232:235], v[240:243], v[224:227]
	v_cvt_pk_bf16_f32 v236, v82, v83
	v_cvt_pk_bf16_f32 v237, v84, v85
	v_cvt_pk_bf16_f32 v238, v86, v87
	v_cvt_pk_bf16_f32 v239, v88, v89
	s_waitcnt lgkmcnt(7)
	ds_read_b64_tr_b16 v[202:203], v124 offset:20480
	ds_read_b64_tr_b16 v[204:205], v124 offset:22528
	ds_read_b64_tr_b16 v[206:207], v125 offset:20480
	ds_read_b64_tr_b16 v[208:209], v125 offset:22528
	ds_read_b64_tr_b16 v[228:229], v126 offset:20480
	ds_read_b64_tr_b16 v[230:231], v126 offset:22528
	ds_read_b64_tr_b16 v[232:233], v127 offset:20480
	ds_read_b64_tr_b16 v[234:235], v127 offset:22528
	s_bitcmp1_b32 s87, 7
	s_cselect_b32 s21, 0, 0xff800000
	v_add_f32_e32 v120, s21, v132
	v_fmamk_f32 v74, v130, 0x42000000, v120
	v_fmamk_f32 v75, v130, 0x41f80000, v120
	v_fmamk_f32 v76, v130, 0x41f00000, v120
	v_fmamk_f32 v77, v130, 0x41e80000, v120
	s_bitcmp1_b32 s87, 8
	s_cselect_b32 s21, 0, 0xff800000
	v_add_f32_e32 v120, s21, v132
	v_fmamk_f32 v78, v130, 0x41800000, v120
	v_fmamk_f32 v79, v130, 0x41700000, v120
	v_fmamk_f32 v80, v130, 0x41600000, v120
	v_fmamk_f32 v81, v130, 0x41500000, v120
	s_waitcnt lgkmcnt(14)
; #define LAS __attribute__((address_space(3)))
; __device__ __forceinline__ unsigned pk2(float lo, float hi) { return pg8::cvt_pk_bf16(lo, hi); }
; __device__ __forceinline__ s16x4 vtr(const LAS unsigned char* p) { return __builtin_bit_cast(s16x4, __builtin_amdgcn_ds_read_tr16_b64_v4i16((LAS s16x4*)p)); }
; #define MFMA16(a, b, c) __builtin_amdgcn_mfma_f32_16x16x32_bf16((a), (b), (c), 0, 0, 0)
; __device__ __forceinline__ void pv_at(const LAS unsigned char* const (&vp)[4], int off, const f32x4& P0, const f32x4& P1, f32x4 (&O)[4]) {
;     v4u pw; pw.x = pk2(P0[0], P0[1]); pw.y = pk2(P0[2], P0[3]); pw.z = pk2(P1[0], P1[1]); pw.w = pk2(P1[2], P1[3]);
;     const bf16x8 pb = __builtin_bit_cast(bf16x8, pw);
; #pragma unroll
;     for (int db = 0; db < 4; ++db) {
;         const s16x4 lo = vtr(vp[db] + off), hi = vtr(vp[db] + off + 2048);
;         const bf16x8 vt = (bf16x8){lo[0], lo[1], lo[2], lo[3], hi[0], hi[1], hi[2], hi[3]};
;         O[db] = MFMA16(vt, pb, O[db]);
;     }
; }
; template <bool MASK> __device__ __forceinline__ void a_scores(f32x4& S0, f32x4& S1, float basef, float c1, float slope2, int krow0, int kstart) {
; #pragma unroll
;     for (int r = 0; r < 4; ++r) {
;         const float d0 = fabsf(basef - (float)r), d1 = fabsf(basef - (float)(16 + r));
;         const float v0 = S0[r] - slope2 * d0, v1 = S1[r] - slope2 * d1;
;         if (MASK) { const int p0 = kstart + krow0 + r, p1 = p0 + 16;
;             S0[r] = (d0 <= 128.f && p0 >= 0 && p0 < SEQ) ? v0 : -INFINITY; S1[r] = (d1 <= 128.f && p1 >= 0 && p1 < SEQ) ? v1 : -INFINITY; }
;         else { S0[r] = v0; S1[r] = v1; }
;     }
; }
	v_mfma_f32_16x16x32_bf16 v[210:213], v[186:189], v[236:239], v[210:213]
	s_waitcnt lgkmcnt(12)
	v_mfma_f32_16x16x32_bf16 v[214:217], v[190:193], v[236:239], v[214:217]
	s_waitcnt lgkmcnt(10)
	v_mfma_f32_16x16x32_bf16 v[220:223], v[194:197], v[236:239], v[220:223]
	s_waitcnt lgkmcnt(8)
	v_mfma_f32_16x16x32_bf16 v[224:227], v[198:201], v[236:239], v[224:227]
	v_cvt_pk_bf16_f32 v240, v90, v91
	v_cvt_pk_bf16_f32 v241, v92, v93
	v_cvt_pk_bf16_f32 v242, v94, v95
	v_cvt_pk_bf16_f32 v243, v96, v97
	s_waitcnt lgkmcnt(7)
	ds_read_b64_tr_b16 v[186:187], v124 offset:24576
	ds_read_b64_tr_b16 v[188:189], v124 offset:26624
	ds_read_b64_tr_b16 v[190:191], v125 offset:24576
	ds_read_b64_tr_b16 v[192:193], v125 offset:26624
	ds_read_b64_tr_b16 v[194:195], v126 offset:24576
	ds_read_b64_tr_b16 v[196:197], v126 offset:26624
	ds_read_b64_tr_b16 v[198:199], v127 offset:24576
	ds_read_b64_tr_b16 v[200:201], v127 offset:26624
	s_bitcmp1_b32 s87, 9
	s_cselect_b32 s21, 0, 0xff800000
	v_add_f32_e32 v219, 0, v129
	v_fma_f32 v82, v130, |v219|, s21
	v_add_f32_e32 v245, 0xbf800000, v129
	v_fma_f32 v83, v130, |v245|, s21
	v_add_f32_e32 v219, 0xc0000000, v129
	v_fma_f32 v84, v130, |v219|, s21
	v_add_f32_e32 v245, 0xc0400000, v129
	v_fma_f32 v85, v130, |v245|, s21
	s_bitcmp1_b32 s87, 10
	s_cselect_b32 s21, 0, 0xff800000
	v_add_f32_e32 v120, s21, v133
	v_fmamk_f32 v86, v131, 0xc1800000, v120
	v_fmamk_f32 v87, v131, 0xc1880000, v120
	v_fmamk_f32 v88, v131, 0xc1900000, v120
	v_fmamk_f32 v89, v131, 0xc1980000, v120
	s_waitcnt lgkmcnt(14)
	v_mfma_f32_16x16x32_bf16 v[210:213], v[202:205], v[240:243], v[210:213]
	s_waitcnt lgkmcnt(12)
	v_mfma_f32_16x16x32_bf16 v[214:217], v[206:209], v[240:243], v[214:217]
	s_waitcnt lgkmcnt(10)
	v_mfma_f32_16x16x32_bf16 v[220:223], v[228:231], v[240:243], v[220:223]
	s_waitcnt lgkmcnt(8)
	v_mfma_f32_16x16x32_bf16 v[224:227], v[232:235], v[240:243], v[224:227]
	v_cvt_pk_bf16_f32 v236, v98, v99
	v_cvt_pk_bf16_f32 v237, v100, v101
	v_cvt_pk_bf16_f32 v238, v102, v103
	v_cvt_pk_bf16_f32 v239, v104, v105
	s_waitcnt lgkmcnt(7)
	ds_read_b64_tr_b16 v[202:203], v124 offset:28672
	ds_read_b64_tr_b16 v[204:205], v124 offset:30720
	ds_read_b64_tr_b16 v[206:207], v125 offset:28672
	ds_read_b64_tr_b16 v[208:209], v125 offset:30720
	ds_read_b64_tr_b16 v[228:229], v126 offset:28672
	ds_read_b64_tr_b16 v[230:231], v126 offset:30720
	ds_read_b64_tr_b16 v[232:233], v127 offset:28672
	ds_read_b64_tr_b16 v[234:235], v127 offset:30720
	s_bitcmp1_b32 s87, 11
	s_cselect_b32 s21, 0, 0xff800000
	v_add_f32_e32 v120, s21, v133
	v_fmamk_f32 v90, v131, 0xc2000000, v120
	v_fmamk_f32 v91, v131, 0xc2040000, v120
	v_fmamk_f32 v92, v131, 0xc2080000, v120
	v_fmamk_f32 v93, v131, 0xc20c0000, v120
	s_bitcmp1_b32 s87, 12
	s_cselect_b32 s21, 0, 0xff800000
	v_add_f32_e32 v120, s21, v133
	v_fmamk_f32 v94, v131, 0xc2400000, v120
	v_fmamk_f32 v95, v131, 0xc2440000, v120
	v_fmamk_f32 v96, v131, 0xc2480000, v120
	v_fmamk_f32 v97, v131, 0xc24c0000, v120
	s_waitcnt lgkmcnt(14)
	v_mfma_f32_16x16x32_bf16 v[210:213], v[186:189], v[236:239], v[210:213]
	s_waitcnt lgkmcnt(12)
	v_mfma_f32_16x16x32_bf16 v[214:217], v[190:193], v[236:239], v[214:217]
	s_waitcnt lgkmcnt(10)
	v_mfma_f32_16x16x32_bf16 v[220:223], v[194:197], v[236:239], v[220:223]
	s_waitcnt lgkmcnt(8)
	v_mfma_f32_16x16x32_bf16 v[224:227], v[198:201], v[236:239], v[224:227]
	v_cvt_pk_bf16_f32 v240, v106, v107
	v_cvt_pk_bf16_f32 v241, v108, v109
	v_cvt_pk_bf16_f32 v242, v110, v111
	v_cvt_pk_bf16_f32 v243, v112, v113
	s_waitcnt lgkmcnt(7)
	ds_read_b64_tr_b16 v[186:187], v124 offset:32768
	ds_read_b64_tr_b16 v[188:189], v124 offset:34816
	ds_read_b64_tr_b16 v[190:191], v125 offset:32768
	ds_read_b64_tr_b16 v[192:193], v125 offset:34816
	ds_read_b64_tr_b16 v[194:195], v126 offset:32768
	ds_read_b64_tr_b16 v[196:197], v126 offset:34816
	ds_read_b64_tr_b16 v[198:199], v127 offset:32768
	ds_read_b64_tr_b16 v[200:201], v127 offset:34816
	s_bitcmp1_b32 s87, 13
	s_cselect_b32 s21, 0, 0xff800000
	v_add_f32_e32 v120, s21, v133
	v_fmamk_f32 v98, v131, 0xc2800000, v120
	v_fmamk_f32 v99, v131, 0xc2820000, v120
	v_fmamk_f32 v100, v131, 0xc2840000, v120
	v_fmamk_f32 v101, v131, 0xc2860000, v120
	s_bitcmp1_b32 s87, 14
	s_cselect_b32 s21, 0, 0xff800000
	v_add_f32_e32 v120, s21, v133
	v_fmamk_f32 v102, v131, 0xc2a00000, v120
	v_fmamk_f32 v103, v131, 0xc2a20000, v120
	v_fmamk_f32 v104, v131, 0xc2a40000, v120
	v_fmamk_f32 v105, v131, 0xc2a60000, v120
	s_waitcnt lgkmcnt(14)
	v_mfma_f32_16x16x32_bf16 v[210:213], v[202:205], v[240:243], v[210:213]
	s_waitcnt lgkmcnt(12)
	v_mfma_f32_16x16x32_bf16 v[214:217], v[206:209], v[240:243], v[214:217]
	s_waitcnt lgkmcnt(10)
	v_mfma_f32_16x16x32_bf16 v[220:223], v[228:231], v[240:243], v[220:223]
	s_waitcnt lgkmcnt(8)
	v_mfma_f32_16x16x32_bf16 v[224:227], v[232:235], v[240:243], v[224:227]
	v_cvt_pk_bf16_f32 v236, v114, v115
	v_cvt_pk_bf16_f32 v237, v116, v117
	v_mov_b32_e32 v238, 0
	v_mov_b32_e32 v239, 0
	s_nop 1
	s_bitcmp1_b32 s87, 15
	s_cselect_b32 s21, 0, 0xff800000
	v_add_f32_e32 v120, s21, v133
	v_fmamk_f32 v106, v131, 0xc2c00000, v120
	v_fmamk_f32 v107, v131, 0xc2c20000, v120
	v_fmamk_f32 v108, v131, 0xc2c40000, v120
	v_fmamk_f32 v109, v131, 0xc2c60000, v120
	s_bitcmp1_b32 s87, 16
	s_cselect_b32 s21, 0, 0xff800000
	v_add_f32_e32 v120, s21, v133
	v_fmamk_f32 v110, v131, 0xc2e00000, v120
	v_fmamk_f32 v111, v131, 0xc2e20000, v120
	v_fmamk_f32 v112, v131, 0xc2e40000, v120
	v_fmamk_f32 v113, v131, 0xc2e60000, v120
	s_waitcnt lgkmcnt(6)
	v_mfma_f32_16x16x32_bf16 v[210:213], v[186:189], v[236:239], v[210:213]
	s_waitcnt lgkmcnt(4)
	v_mfma_f32_16x16x32_bf16 v[214:217], v[190:193], v[236:239], v[214:217]
	s_waitcnt lgkmcnt(2)
; #define LAS __attribute__((address_space(3)))
; __device__ __forceinline__ unsigned pk2(float lo, float hi) { return pg8::cvt_pk_bf16(lo, hi); }
; #define MFMA16(a, b, c) __builtin_amdgcn_mfma_f32_16x16x32_bf16((a), (b), (c), 0, 0, 0)
; __device__ __forceinline__ void qk_at(const LAS unsigned char* kp0, const LAS unsigned char* kp1, int off, bf16x8 qf0, bf16x8 qf1, f32x4& S0, f32x4& S1) {
;     const bf16x8 k00 = *(const LAS bf16x8*)(kp0 + off), k01 = *(const LAS bf16x8*)(kp1 + off);
;     const bf16x8 k10 = *(const LAS bf16x8*)(kp0 + off + 2048), k11 = *(const LAS bf16x8*)(kp1 + off + 2048);
;     const f32x4 z = {0.f, 0.f, 0.f, 0.f};
;     S0 = MFMA16(k00, qf0, z); S0 = MFMA16(k01, qf1, S0);
;     S1 = MFMA16(k10, qf0, z); S1 = MFMA16(k11, qf1, S1);
; }
; __device__ __forceinline__ void store_o(bf16* yrow, int g, float l, const f32x4 (&O)[4]) {
;     const float inv = 1.0f / xrow16_sum(l);
;     unsigned wx[4], wy[4];
; #pragma unroll
;     for (int db = 0; db < 4; ++db) { wx[db] = pk2(O[db][0] * inv, O[db][1] * inv); wy[db] = pk2(O[db][2] * inv, O[db][3] * inv); }
; #pragma unroll
;     for (int p = 0; p < 2; ++p) {
;         auto rx = __builtin_amdgcn_permlane16_swap(wx[2 * p], wx[2 * p + 1], false, false); wx[2 * p] = rx[0]; wx[2 * p + 1] = rx[1];
;         auto ry = __builtin_amdgcn_permlane16_swap(wy[2 * p], wy[2 * p + 1], false, false); wy[2 * p] = ry[0]; wy[2 * p + 1] = ry[1]; }
; #pragma unroll
;     for (int p = 0; p < 2; ++p) {
;         auto rx = __builtin_amdgcn_permlane32_swap(wx[p], wx[p + 2], false, false); wx[p] = rx[0]; wx[p + 2] = rx[1];
;         auto ry = __builtin_amdgcn_permlane32_swap(wy[p], wy[p + 2], false, false); wy[p] = ry[0]; wy[p + 2] = ry[1]; }
;     v4u lo = {wx[0], wy[0], wx[1], wy[1]}, hi = {wx[2], wy[2], wx[3], wy[3]};
;     *(v4u*)(yrow + 16 * g) = lo; *(v4u*)(yrow + 16 * g + 8) = hi;
; }
	v_mfma_f32_16x16x32_bf16 v[220:223], v[194:197], v[236:239], v[220:223]
	s_waitcnt lgkmcnt(0)
	v_mfma_f32_16x16x32_bf16 v[224:227], v[198:201], v[236:239], v[224:227]
	s_bitcmp1_b32 s87, 17
	s_cselect_b32 s21, 0, 0xff800000
	v_add_f32_e32 v120, s21, v133
	v_fmamk_f32 v114, v131, 0xc3000000, v120
	v_fmamk_f32 v115, v131, 0xc3010000, v120
	v_fmamk_f32 v116, v131, 0xc3020000, v120
	v_fmamk_f32 v117, v131, 0xc3030000, v120
	v_mov_b32_e32 v245, 0xff800000
	v_cndmask_b32_e64 v114, v245, v114, s[28:29]
	v_cndmask_b32_e64 v115, v245, v115, s[52:53]
	v_cndmask_b32_e64 v116, v245, v116, s[54:55]
	v_cndmask_b32_e64 v117, v245, v117, s[88:89]
	v_mov_b32_e32 v219, v185
	s_nop 1
	v_permlane16_swap_b32_e32 v185, v219
	v_add_f32_e32 v185, v185, v219
	v_mov_b32_e32 v219, v185
	s_nop 1
	v_permlane32_swap_b32_e32 v185, v219
	v_add_f32_e32 v185, v185, v219
	v_div_scale_f32 v236, s[78:79], v185, v185, 1.0
	v_div_scale_f32 v237, vcc, 1.0, v185, 1.0
	v_rcp_f32_e32 v238, v236
	s_nop 0
	v_fma_f32 v239, -v236, v238, 1.0
	v_fmac_f32_e32 v238, v239, v238
	v_mul_f32_e32 v240, v237, v238
	v_fma_f32 v241, -v236, v240, v237
	v_fmac_f32_e32 v240, v241, v238
	v_fma_f32 v237, -v236, v240, v237
	v_div_fmas_f32 v237, v237, v238, v240
	v_div_fixup_f32 v244, v237, v185, 1.0
	v_mul_f32_e32 v240, v210, v244
	v_mul_f32_e32 v241, v211, v244
	v_mul_f32_e32 v242, v212, v244
	v_mul_f32_e32 v243, v213, v244
	v_cvt_pk_bf16_f32 v186, v240, v241
	v_cvt_pk_bf16_f32 v187, v242, v243
	v_mul_f32_e32 v240, v214, v244
	v_mul_f32_e32 v241, v215, v244
	v_mul_f32_e32 v242, v216, v244
	v_mul_f32_e32 v243, v217, v244
	v_cvt_pk_bf16_f32 v188, v240, v241
	v_cvt_pk_bf16_f32 v189, v242, v243
	v_mul_f32_e32 v240, v220, v244
	v_mul_f32_e32 v241, v221, v244
	v_mul_f32_e32 v242, v222, v244
	v_mul_f32_e32 v243, v223, v244
	v_cvt_pk_bf16_f32 v190, v240, v241
	v_cvt_pk_bf16_f32 v191, v242, v243
	v_mul_f32_e32 v240, v224, v244
	v_mul_f32_e32 v241, v225, v244
	v_mul_f32_e32 v242, v226, v244
	v_mul_f32_e32 v243, v227, v244
	v_cvt_pk_bf16_f32 v192, v240, v241
	v_cvt_pk_bf16_f32 v193, v242, v243
	s_nop 1
	v_permlane16_swap_b32_e32 v186, v188
	v_permlane16_swap_b32_e32 v187, v189
	v_permlane16_swap_b32_e32 v190, v192
	v_permlane16_swap_b32_e32 v191, v193
	s_nop 0
	v_permlane32_swap_b32_e32 v186, v190
	v_permlane32_swap_b32_e32 v187, v191
	v_permlane32_swap_b32_e32 v188, v192
	v_permlane32_swap_b32_e32 v189, v193
	global_store_dwordx4 v128, v[186:189], s[82:83] offset:0
	global_store_dwordx4 v128, v[190:193], s[82:83] offset:16
	s_nop 1
	ds_read_b128 v[186:189], v122 offset:2048
	ds_read_b128 v[190:193], v123 offset:2048
	ds_read_b128 v[194:197], v122 offset:4096
	ds_read_b128 v[198:201], v123 offset:4096
	ds_read_b128 v[202:205], v122 offset:6144
	ds_read_b128 v[206:209], v123 offset:6144
	ds_read_b128 v[210:213], v122 offset:8192
	ds_read_b128 v[214:217], v123 offset:8192
	ds_read_b128 v[220:223], v122 offset:10240
	ds_read_b128 v[224:227], v123 offset:10240
	ds_read_b128 v[228:231], v122 offset:12288
	ds_read_b128 v[232:235], v123 offset:12288
	ds_read_b128 v[236:239], v122 offset:14336
	ds_read_b128 v[240:243], v123 offset:14336
	s_waitcnt lgkmcnt(13)
	v_mfma_f32_16x16x32_bf16 v[50:53], v[186:189], v[154:157], v[50:53]
	s_waitcnt lgkmcnt(12)
	v_mfma_f32_16x16x32_bf16 v[50:53], v[190:193], v[158:161], v[50:53]
	ds_read_b128 v[186:189], v122 offset:16384
	ds_read_b128 v[190:193], v123 offset:16384
	s_waitcnt lgkmcnt(13)
	v_mfma_f32_16x16x32_bf16 v[54:57], v[194:197], v[154:157], v[54:57]
	s_waitcnt lgkmcnt(12)
	v_mfma_f32_16x16x32_bf16 v[54:57], v[198:201], v[158:161], v[54:57]
	ds_read_b128 v[194:197], v122 offset:18432
	ds_read_b128 v[198:201], v123 offset:18432
	s_waitcnt lgkmcnt(13)
	v_mfma_f32_16x16x32_bf16 v[58:61], v[202:205], v[154:157], v[58:61]
	s_waitcnt lgkmcnt(12)
	v_mfma_f32_16x16x32_bf16 v[58:61], v[206:209], v[158:161], v[58:61]
	ds_read_b128 v[202:205], v122 offset:20480
	ds_read_b128 v[206:209], v123 offset:20480
	s_waitcnt lgkmcnt(13)
	v_mfma_f32_16x16x32_bf16 v[62:65], v[210:213], v[154:157], v[62:65]
	s_waitcnt lgkmcnt(12)
	v_mfma_f32_16x16x32_bf16 v[62:65], v[214:217], v[158:161], v[62:65]
	ds_read_b128 v[210:213], v122 offset:22528
	ds_read_b128 v[214:217], v123 offset:22528
	s_waitcnt lgkmcnt(13)
	v_mfma_f32_16x16x32_bf16 v[66:69], v[220:223], v[154:157], v[66:69]
	s_waitcnt lgkmcnt(12)
	v_mfma_f32_16x16x32_bf16 v[66:69], v[224:227], v[158:161], v[66:69]
	ds_read_b128 v[220:223], v122 offset:24576
	ds_read_b128 v[224:227], v123 offset:24576
	s_waitcnt lgkmcnt(13)
	v_mfma_f32_16x16x32_bf16 v[70:73], v[228:231], v[154:157], v[70:73]
	s_waitcnt lgkmcnt(12)
	v_mfma_f32_16x16x32_bf16 v[70:73], v[232:235], v[158:161], v[70:73]
	ds_read_b128 v[228:231], v122 offset:26624
	ds_read_b128 v[232:235], v123 offset:26624
	s_waitcnt lgkmcnt(13)
	v_mfma_f32_16x16x32_bf16 v[74:77], v[236:239], v[154:157], v[74:77]
	s_waitcnt lgkmcnt(12)
	v_mfma_f32_16x16x32_bf16 v[74:77], v[240:243], v[158:161], v[74:77]
	ds_read_b128 v[236:239], v122 offset:28672
	ds_read_b128 v[240:243], v123 offset:28672
	s_waitcnt lgkmcnt(13)
	v_mfma_f32_16x16x32_bf16 v[78:81], v[186:189], v[154:157], v[78:81]
	s_waitcnt lgkmcnt(12)
	v_mfma_f32_16x16x32_bf16 v[78:81], v[190:193], v[158:161], v[78:81]
	ds_read_b128 v[186:189], v122 offset:30720
	ds_read_b128 v[190:193], v123 offset:30720
	s_waitcnt lgkmcnt(13)
	v_mfma_f32_16x16x32_bf16 v[82:85], v[194:197], v[154:157], v[82:85]
	s_waitcnt lgkmcnt(12)
	v_mfma_f32_16x16x32_bf16 v[82:85], v[198:201], v[158:161], v[82:85]
	ds_read_b128 v[194:197], v122 offset:32768
	ds_read_b128 v[198:201], v123 offset:32768
	s_waitcnt lgkmcnt(13)
	v_mfma_f32_16x16x32_bf16 v[86:89], v[202:205], v[154:157], v[86:89]
	s_waitcnt lgkmcnt(12)
; #define LAS __attribute__((address_space(3)))
; #define MFMA16(a, b, c) __builtin_amdgcn_mfma_f32_16x16x32_bf16((a), (b), (c), 0, 0, 0)
; __device__ __forceinline__ void qk_at(const LAS unsigned char* kp0, const LAS unsigned char* kp1, int off, bf16x8 qf0, bf16x8 qf1, f32x4& S0, f32x4& S1) {
;     const bf16x8 k00 = *(const LAS bf16x8*)(kp0 + off), k01 = *(const LAS bf16x8*)(kp1 + off);
;     const bf16x8 k10 = *(const LAS bf16x8*)(kp0 + off + 2048), k11 = *(const LAS bf16x8*)(kp1 + off + 2048);
;     const f32x4 z = {0.f, 0.f, 0.f, 0.f};
;     S0 = MFMA16(k00, qf0, z); S0 = MFMA16(k01, qf1, S0);
;     S1 = MFMA16(k10, qf0, z); S1 = MFMA16(k11, qf1, S1);
; }
; __device__ __forceinline__ void softmax_step(f32x4& s0, f32x4& s1, float& m, float& l, f32x4 (&O)[4]) {
;     float t = fmaxf(fmaxf(fmaxf(s0[0], s0[1]), fmaxf(s0[2], s0[3])), fmaxf(fmaxf(s1[0], s1[1]), fmaxf(s1[2], s1[3])));
;     t = xrow16_max(t);
;     const float mn = fmaxf(m, t), alpha = __builtin_amdgcn_exp2f(m - mn);
;     m = mn;
; #pragma unroll
;     for (int k = 0; k < 4; ++k) { s0[k] = __builtin_amdgcn_exp2f(s0[k] - mn); s1[k] = __builtin_amdgcn_exp2f(s1[k] - mn); }
;     l = l * alpha + ((s0[0] + s0[1]) + (s0[2] + s0[3])) + ((s1[0] + s1[1]) + (s1[2] + s1[3]));
; #pragma unroll
;     for (int db = 0; db < 4; ++db) O[db] *= alpha;
; }
	v_mfma_f32_16x16x32_bf16 v[86:89], v[206:209], v[158:161], v[86:89]
	ds_read_b128 v[202:205], v122 offset:34816
	ds_read_b128 v[206:209], v123 offset:34816
	s_waitcnt lgkmcnt(13)
	v_mfma_f32_16x16x32_bf16 v[90:93], v[210:213], v[154:157], v[90:93]
	s_waitcnt lgkmcnt(12)
	v_mfma_f32_16x16x32_bf16 v[90:93], v[214:217], v[158:161], v[90:93]
	s_waitcnt lgkmcnt(11)
	v_mfma_f32_16x16x32_bf16 v[94:97], v[220:223], v[154:157], v[94:97]
	s_waitcnt lgkmcnt(10)
	v_mfma_f32_16x16x32_bf16 v[94:97], v[224:227], v[158:161], v[94:97]
	s_waitcnt lgkmcnt(9)
	v_mfma_f32_16x16x32_bf16 v[98:101], v[228:231], v[154:157], v[98:101]
	s_waitcnt lgkmcnt(8)
	v_mfma_f32_16x16x32_bf16 v[98:101], v[232:235], v[158:161], v[98:101]
	s_waitcnt lgkmcnt(7)
	v_mfma_f32_16x16x32_bf16 v[102:105], v[236:239], v[154:157], v[102:105]
	s_waitcnt lgkmcnt(6)
	v_mfma_f32_16x16x32_bf16 v[102:105], v[240:243], v[158:161], v[102:105]
	s_waitcnt lgkmcnt(5)
	v_mfma_f32_16x16x32_bf16 v[106:109], v[186:189], v[154:157], v[106:109]
	s_waitcnt lgkmcnt(4)
	v_mfma_f32_16x16x32_bf16 v[106:109], v[190:193], v[158:161], v[106:109]
	s_waitcnt lgkmcnt(3)
	v_mfma_f32_16x16x32_bf16 v[110:113], v[194:197], v[154:157], v[110:113]
	s_waitcnt lgkmcnt(2)
	v_mfma_f32_16x16x32_bf16 v[110:113], v[198:201], v[158:161], v[110:113]
	s_waitcnt lgkmcnt(1)
	v_mfma_f32_16x16x32_bf16 v[114:117], v[202:205], v[154:157], v[114:117]
	s_waitcnt lgkmcnt(0)
	v_mfma_f32_16x16x32_bf16 v[114:117], v[206:209], v[158:161], v[114:117]
	v_max3_f32 v219, v50, v51, v52
	v_max3_f32 v244, v54, v55, v56
	v_max3_f32 v245, v58, v59, v60
	v_max3_f32 v120, v62, v63, v64
	v_max3_f32 v219, v219, v53, v66
	v_max3_f32 v244, v244, v57, v70
	v_max3_f32 v245, v245, v61, v74
	v_max3_f32 v120, v120, v65, v78
	v_max3_f32 v219, v219, v67, v68
	v_max3_f32 v244, v244, v71, v72
	v_max3_f32 v245, v245, v75, v76
	v_max3_f32 v120, v120, v79, v80
	ds_read_b64_tr_b16 v[186:187], v124 offset:2048
	ds_read_b64_tr_b16 v[188:189], v124 offset:4096
	ds_read_b64_tr_b16 v[190:191], v125 offset:2048
	ds_read_b64_tr_b16 v[192:193], v125 offset:4096
	ds_read_b64_tr_b16 v[194:195], v126 offset:2048
	ds_read_b64_tr_b16 v[196:197], v126 offset:4096
	ds_read_b64_tr_b16 v[198:199], v127 offset:2048
	ds_read_b64_tr_b16 v[200:201], v127 offset:4096
	v_max3_f32 v219, v219, v69, v82
	v_max3_f32 v244, v244, v73, v86
	v_max3_f32 v245, v245, v77, v90
	v_max3_f32 v120, v120, v81, v94
	v_max3_f32 v219, v219, v83, v84
	v_max3_f32 v244, v244, v87, v88
	v_max3_f32 v245, v245, v91, v92
	v_max3_f32 v120, v120, v95, v96
	v_max3_f32 v219, v219, v85, v98
	v_max3_f32 v244, v244, v89, v102
	v_max3_f32 v245, v245, v93, v106
	v_max3_f32 v120, v120, v97, v110
	v_max3_f32 v219, v219, v99, v100
	v_max3_f32 v244, v244, v103, v104
	v_max3_f32 v245, v245, v107, v108
	v_max3_f32 v120, v120, v111, v112
	v_max3_f32 v219, v219, v101, v114
	v_max3_f32 v219, v219, v115, v116
	v_max_f32_e32 v219, v219, v117
	v_max_f32_e32 v244, v244, v105
	v_max_f32_e32 v245, v245, v109
	v_max_f32_e32 v120, v120, v113
	v_max3_f32 v178, v219, v244, v245
	v_max_f32_e32 v178, v178, v120
	v_mov_b32_e32 v219, v178
	s_nop 1
	v_permlane16_swap_b32_e32 v178, v219
	v_max_f32_e32 v178, v178, v219
	v_mov_b32_e32 v219, v178
	s_nop 1
	v_permlane32_swap_b32_e32 v178, v219
	v_max3_f32 v178, v178, v219, v145
	s_waitcnt lgkmcnt(7)
	ds_read_b64_tr_b16 v[202:203], v124 offset:6144
	ds_read_b64_tr_b16 v[204:205], v124 offset:8192
	ds_read_b64_tr_b16 v[206:207], v125 offset:6144
	ds_read_b64_tr_b16 v[208:209], v125 offset:8192
	ds_read_b64_tr_b16 v[228:229], v126 offset:6144
	ds_read_b64_tr_b16 v[230:231], v126 offset:8192
	ds_read_b64_tr_b16 v[232:233], v127 offset:6144
	ds_read_b64_tr_b16 v[234:235], v127 offset:8192
	v_mov_b32_e32 v244, v178
	v_pk_add_f32 v[50:51], v[50:51], v[244:245] op_sel_hi:[1,0] neg_lo:[0,1] neg_hi:[0,1]
	v_pk_add_f32 v[52:53], v[52:53], v[244:245] op_sel_hi:[1,0] neg_lo:[0,1] neg_hi:[0,1]
	v_pk_add_f32 v[54:55], v[54:55], v[244:245] op_sel_hi:[1,0] neg_lo:[0,1] neg_hi:[0,1]
	v_pk_add_f32 v[56:57], v[56:57], v[244:245] op_sel_hi:[1,0] neg_lo:[0,1] neg_hi:[0,1]
	v_pk_add_f32 v[58:59], v[58:59], v[244:245] op_sel_hi:[1,0] neg_lo:[0,1] neg_hi:[0,1]
	v_pk_add_f32 v[60:61], v[60:61], v[244:245] op_sel_hi:[1,0] neg_lo:[0,1] neg_hi:[0,1]
	v_pk_add_f32 v[62:63], v[62:63], v[244:245] op_sel_hi:[1,0] neg_lo:[0,1] neg_hi:[0,1]
	v_pk_add_f32 v[64:65], v[64:65], v[244:245] op_sel_hi:[1,0] neg_lo:[0,1] neg_hi:[0,1]
	v_pk_add_f32 v[66:67], v[66:67], v[244:245] op_sel_hi:[1,0] neg_lo:[0,1] neg_hi:[0,1]
	v_pk_add_f32 v[68:69], v[68:69], v[244:245] op_sel_hi:[1,0] neg_lo:[0,1] neg_hi:[0,1]
	v_pk_add_f32 v[70:71], v[70:71], v[244:245] op_sel_hi:[1,0] neg_lo:[0,1] neg_hi:[0,1]
	v_pk_add_f32 v[72:73], v[72:73], v[244:245] op_sel_hi:[1,0] neg_lo:[0,1] neg_hi:[0,1]
	v_pk_add_f32 v[74:75], v[74:75], v[244:245] op_sel_hi:[1,0] neg_lo:[0,1] neg_hi:[0,1]
	v_pk_add_f32 v[76:77], v[76:77], v[244:245] op_sel_hi:[1,0] neg_lo:[0,1] neg_hi:[0,1]
	v_pk_add_f32 v[78:79], v[78:79], v[244:245] op_sel_hi:[1,0] neg_lo:[0,1] neg_hi:[0,1]
	v_pk_add_f32 v[80:81], v[80:81], v[244:245] op_sel_hi:[1,0] neg_lo:[0,1] neg_hi:[0,1]
	v_pk_add_f32 v[82:83], v[82:83], v[244:245] op_sel_hi:[1,0] neg_lo:[0,1] neg_hi:[0,1]
	v_pk_add_f32 v[84:85], v[84:85], v[244:245] op_sel_hi:[1,0] neg_lo:[0,1] neg_hi:[0,1]
	v_pk_add_f32 v[86:87], v[86:87], v[244:245] op_sel_hi:[1,0] neg_lo:[0,1] neg_hi:[0,1]
	v_pk_add_f32 v[88:89], v[88:89], v[244:245] op_sel_hi:[1,0] neg_lo:[0,1] neg_hi:[0,1]
	v_pk_add_f32 v[90:91], v[90:91], v[244:245] op_sel_hi:[1,0] neg_lo:[0,1] neg_hi:[0,1]
	v_pk_add_f32 v[92:93], v[92:93], v[244:245] op_sel_hi:[1,0] neg_lo:[0,1] neg_hi:[0,1]
; #define LAS __attribute__((address_space(3)))
; __device__ __forceinline__ unsigned pk2(float lo, float hi) { return pg8::cvt_pk_bf16(lo, hi); }
; __device__ __forceinline__ s16x4 vtr(const LAS unsigned char* p) { return __builtin_bit_cast(s16x4, __builtin_amdgcn_ds_read_tr16_b64_v4i16((LAS s16x4*)p)); }
; #define MFMA16(a, b, c) __builtin_amdgcn_mfma_f32_16x16x32_bf16((a), (b), (c), 0, 0, 0)
; __device__ __forceinline__ void pv_at(const LAS unsigned char* const (&vp)[4], int off, const f32x4& P0, const f32x4& P1, f32x4 (&O)[4]) {
;     v4u pw; pw.x = pk2(P0[0], P0[1]); pw.y = pk2(P0[2], P0[3]); pw.z = pk2(P1[0], P1[1]); pw.w = pk2(P1[2], P1[3]);
;     const bf16x8 pb = __builtin_bit_cast(bf16x8, pw);
; #pragma unroll
;     for (int db = 0; db < 4; ++db) {
;         const s16x4 lo = vtr(vp[db] + off), hi = vtr(vp[db] + off + 2048);
;         const bf16x8 vt = (bf16x8){lo[0], lo[1], lo[2], lo[3], hi[0], hi[1], hi[2], hi[3]};
;         O[db] = MFMA16(vt, pb, O[db]);
;     }
; }
; __device__ __forceinline__ void softmax_step(f32x4& s0, f32x4& s1, float& m, float& l, f32x4 (&O)[4]) {
;     float t = fmaxf(fmaxf(fmaxf(s0[0], s0[1]), fmaxf(s0[2], s0[3])), fmaxf(fmaxf(s1[0], s1[1]), fmaxf(s1[2], s1[3])));
;     t = xrow16_max(t);
;     const float mn = fmaxf(m, t), alpha = __builtin_amdgcn_exp2f(m - mn);
;     m = mn;
; #pragma unroll
;     for (int k = 0; k < 4; ++k) { s0[k] = __builtin_amdgcn_exp2f(s0[k] - mn); s1[k] = __builtin_amdgcn_exp2f(s1[k] - mn); }
;     l = l * alpha + ((s0[0] + s0[1]) + (s0[2] + s0[3])) + ((s1[0] + s1[1]) + (s1[2] + s1[3]));
; #pragma unroll
;     for (int db = 0; db < 4; ++db) O[db] *= alpha;
; }
	v_pk_add_f32 v[94:95], v[94:95], v[244:245] op_sel_hi:[1,0] neg_lo:[0,1] neg_hi:[0,1]
	v_pk_add_f32 v[96:97], v[96:97], v[244:245] op_sel_hi:[1,0] neg_lo:[0,1] neg_hi:[0,1]
	v_pk_add_f32 v[98:99], v[98:99], v[244:245] op_sel_hi:[1,0] neg_lo:[0,1] neg_hi:[0,1]
	v_pk_add_f32 v[100:101], v[100:101], v[244:245] op_sel_hi:[1,0] neg_lo:[0,1] neg_hi:[0,1]
	v_pk_add_f32 v[102:103], v[102:103], v[244:245] op_sel_hi:[1,0] neg_lo:[0,1] neg_hi:[0,1]
	v_pk_add_f32 v[104:105], v[104:105], v[244:245] op_sel_hi:[1,0] neg_lo:[0,1] neg_hi:[0,1]
	v_pk_add_f32 v[106:107], v[106:107], v[244:245] op_sel_hi:[1,0] neg_lo:[0,1] neg_hi:[0,1]
	v_pk_add_f32 v[108:109], v[108:109], v[244:245] op_sel_hi:[1,0] neg_lo:[0,1] neg_hi:[0,1]
	v_pk_add_f32 v[110:111], v[110:111], v[244:245] op_sel_hi:[1,0] neg_lo:[0,1] neg_hi:[0,1]
	v_pk_add_f32 v[112:113], v[112:113], v[244:245] op_sel_hi:[1,0] neg_lo:[0,1] neg_hi:[0,1]
	v_pk_add_f32 v[114:115], v[114:115], v[244:245] op_sel_hi:[1,0] neg_lo:[0,1] neg_hi:[0,1]
	v_pk_add_f32 v[116:117], v[116:117], v[244:245] op_sel_hi:[1,0] neg_lo:[0,1] neg_hi:[0,1]
	v_sub_f32_e32 v219, v145, v178
	v_exp_f32_e32 v50, v50
	v_exp_f32_e32 v51, v51
	v_exp_f32_e32 v52, v52
	v_exp_f32_e32 v53, v53
	v_exp_f32_e32 v54, v54
	v_exp_f32_e32 v55, v55
	v_exp_f32_e32 v56, v56
	v_exp_f32_e32 v57, v57
	v_exp_f32_e32 v58, v58
	v_exp_f32_e32 v59, v59
	v_exp_f32_e32 v60, v60
	v_exp_f32_e32 v61, v61
	v_exp_f32_e32 v62, v62
	v_exp_f32_e32 v63, v63
	v_exp_f32_e32 v64, v64
	v_exp_f32_e32 v65, v65
	v_exp_f32_e32 v66, v66
	v_exp_f32_e32 v67, v67
	v_exp_f32_e32 v68, v68
	v_exp_f32_e32 v69, v69
	v_exp_f32_e32 v70, v70
	v_exp_f32_e32 v71, v71
	v_exp_f32_e32 v72, v72
	v_exp_f32_e32 v73, v73
	v_exp_f32_e32 v74, v74
	v_exp_f32_e32 v75, v75
	v_exp_f32_e32 v76, v76
	v_exp_f32_e32 v77, v77
	v_exp_f32_e32 v78, v78
	v_exp_f32_e32 v79, v79
	v_exp_f32_e32 v80, v80
	v_exp_f32_e32 v81, v81
	v_exp_f32_e32 v82, v82
	v_exp_f32_e32 v83, v83
	v_exp_f32_e32 v84, v84
	v_exp_f32_e32 v85, v85
	v_exp_f32_e32 v86, v86
	v_exp_f32_e32 v87, v87
	v_exp_f32_e32 v88, v88
	v_exp_f32_e32 v89, v89
	v_exp_f32_e32 v90, v90
	v_exp_f32_e32 v91, v91
	v_exp_f32_e32 v92, v92
	v_exp_f32_e32 v93, v93
	v_exp_f32_e32 v94, v94
	v_exp_f32_e32 v95, v95
	v_exp_f32_e32 v96, v96
	v_exp_f32_e32 v97, v97
	v_exp_f32_e32 v98, v98
	v_exp_f32_e32 v99, v99
	v_exp_f32_e32 v100, v100
	v_exp_f32_e32 v101, v101
	v_exp_f32_e32 v102, v102
	v_exp_f32_e32 v103, v103
	v_exp_f32_e32 v104, v104
	v_exp_f32_e32 v105, v105
	v_exp_f32_e32 v106, v106
	v_exp_f32_e32 v107, v107
	v_exp_f32_e32 v108, v108
	v_exp_f32_e32 v109, v109
	v_exp_f32_e32 v110, v110
	v_exp_f32_e32 v111, v111
	v_exp_f32_e32 v112, v112
	v_exp_f32_e32 v113, v113
	v_exp_f32_e32 v114, v114
	v_exp_f32_e32 v115, v115
	v_exp_f32_e32 v116, v116
	v_exp_f32_e32 v117, v117
	v_exp_f32_e32 v219, v219
	v_pk_add_f32 v[236:237], v[50:51], v[52:53]
	v_pk_add_f32 v[238:239], v[54:55], v[56:57]
	v_pk_add_f32 v[240:241], v[58:59], v[60:61]
	v_pk_add_f32 v[242:243], v[62:63], v[64:65]
	v_pk_add_f32 v[236:237], v[236:237], v[66:67]
	v_pk_add_f32 v[238:239], v[238:239], v[70:71]
	v_pk_add_f32 v[240:241], v[240:241], v[74:75]
	v_pk_add_f32 v[242:243], v[242:243], v[78:79]
	v_pk_add_f32 v[236:237], v[236:237], v[68:69]
	v_pk_add_f32 v[238:239], v[238:239], v[72:73]
	v_pk_add_f32 v[240:241], v[240:241], v[76:77]
	v_pk_add_f32 v[242:243], v[242:243], v[80:81]
	v_pk_add_f32 v[236:237], v[236:237], v[82:83]
	v_pk_add_f32 v[238:239], v[238:239], v[86:87]
	v_pk_add_f32 v[240:241], v[240:241], v[90:91]
	v_pk_add_f32 v[242:243], v[242:243], v[94:95]
	v_pk_add_f32 v[236:237], v[236:237], v[84:85]
	v_pk_add_f32 v[238:239], v[238:239], v[88:89]
	v_pk_add_f32 v[240:241], v[240:241], v[92:93]
	v_pk_add_f32 v[242:243], v[242:243], v[96:97]
	v_pk_add_f32 v[236:237], v[236:237], v[98:99]
	v_pk_add_f32 v[238:239], v[238:239], v[102:103]
	v_pk_add_f32 v[240:241], v[240:241], v[106:107]
	v_pk_add_f32 v[242:243], v[242:243], v[110:111]
	v_pk_add_f32 v[236:237], v[236:237], v[100:101]
	v_pk_add_f32 v[238:239], v[238:239], v[104:105]
	v_pk_add_f32 v[240:241], v[240:241], v[108:109]
	v_pk_add_f32 v[242:243], v[242:243], v[112:113]
	v_pk_add_f32 v[236:237], v[236:237], v[114:115]
	v_pk_add_f32 v[236:237], v[236:237], v[116:117]
	v_pk_add_f32 v[236:237], v[236:237], v[238:239]
	v_pk_add_f32 v[240:241], v[240:241], v[242:243]
	v_cndmask_b32_e64 v219, 0, v219, s[74:75]
	v_pk_add_f32 v[236:237], v[236:237], v[240:241]
	v_add_f32_e32 v185, v236, v237
	v_add_f32_e32 v185, v185, v219
	v_cvt_pk_bf16_f32 v236, v50, v51
	v_cvt_pk_bf16_f32 v237, v52, v53
	v_cvt_pk_bf16_f32 v238, v54, v55
	v_cvt_pk_bf16_f32 v239, v56, v57
	s_nop 1
	s_waitcnt lgkmcnt(14)
	v_mfma_f32_16x16x32_bf16 v[210:213], v[186:189], v[236:239], 0
	s_waitcnt lgkmcnt(12)
	v_mfma_f32_16x16x32_bf16 v[214:217], v[190:193], v[236:239], 0
	s_waitcnt lgkmcnt(10)
	v_mfma_f32_16x16x32_bf16 v[220:223], v[194:197], v[236:239], 0
	s_waitcnt lgkmcnt(8)
	v_mfma_f32_16x16x32_bf16 v[224:227], v[198:201], v[236:239], 0
	v_cvt_pk_bf16_f32 v240, v58, v59
	v_cvt_pk_bf16_f32 v241, v60, v61
	v_cvt_pk_bf16_f32 v242, v62, v63
	v_cvt_pk_bf16_f32 v243, v64, v65
	s_waitcnt lgkmcnt(7)
; #define LAS __attribute__((address_space(3)))
; __device__ __forceinline__ unsigned pk2(float lo, float hi) { return pg8::cvt_pk_bf16(lo, hi); }
; __device__ __forceinline__ s16x4 vtr(const LAS unsigned char* p) { return __builtin_bit_cast(s16x4, __builtin_amdgcn_ds_read_tr16_b64_v4i16((LAS s16x4*)p)); }
; #define MFMA16(a, b, c) __builtin_amdgcn_mfma_f32_16x16x32_bf16((a), (b), (c), 0, 0, 0)
; __device__ __forceinline__ void pv_at(const LAS unsigned char* const (&vp)[4], int off, const f32x4& P0, const f32x4& P1, f32x4 (&O)[4]) {
;     v4u pw; pw.x = pk2(P0[0], P0[1]); pw.y = pk2(P0[2], P0[3]); pw.z = pk2(P1[0], P1[1]); pw.w = pk2(P1[2], P1[3]);
;     const bf16x8 pb = __builtin_bit_cast(bf16x8, pw);
; #pragma unroll
;     for (int db = 0; db < 4; ++db) {
;         const s16x4 lo = vtr(vp[db] + off), hi = vtr(vp[db] + off + 2048);
;         const bf16x8 vt = (bf16x8){lo[0], lo[1], lo[2], lo[3], hi[0], hi[1], hi[2], hi[3]};
;         O[db] = MFMA16(vt, pb, O[db]);
;     }
; }
; template <bool MASK> __device__ __forceinline__ void a_scores(f32x4& S0, f32x4& S1, float basef, float c1, float slope2, int krow0, int kstart) {
; #pragma unroll
;     for (int r = 0; r < 4; ++r) {
;         const float d0 = fabsf(basef - (float)r), d1 = fabsf(basef - (float)(16 + r));
;         const float v0 = S0[r] - slope2 * d0, v1 = S1[r] - slope2 * d1;
;         if (MASK) { const int p0 = kstart + krow0 + r, p1 = p0 + 16;
;             S0[r] = (d0 <= 128.f && p0 >= 0 && p0 < SEQ) ? v0 : -INFINITY; S1[r] = (d1 <= 128.f && p1 >= 0 && p1 < SEQ) ? v1 : -INFINITY; }
;         else { S0[r] = v0; S1[r] = v1; }
;     }
; }
	ds_read_b64_tr_b16 v[186:187], v124 offset:10240
	ds_read_b64_tr_b16 v[188:189], v124 offset:12288
	ds_read_b64_tr_b16 v[190:191], v125 offset:10240
	ds_read_b64_tr_b16 v[192:193], v125 offset:12288
	ds_read_b64_tr_b16 v[194:195], v126 offset:10240
	ds_read_b64_tr_b16 v[196:197], v126 offset:12288
	ds_read_b64_tr_b16 v[198:199], v127 offset:10240
	ds_read_b64_tr_b16 v[200:201], v127 offset:12288
	s_bitcmp1_b32 s87, 2
	s_cselect_b32 s21, 0, 0xff800000
	v_add_f32_e32 v120, s21, v132
	v_fmamk_f32 v50, v130, 0x43000000, v120
	v_fmamk_f32 v51, v130, 0x42fe0000, v120
	v_fmamk_f32 v52, v130, 0x42fc0000, v120
	v_fmamk_f32 v53, v130, 0x42fa0000, v120
	v_mov_b32_e32 v245, 0xff800000
	v_cndmask_b32_e64 v50, v245, v50, s[16:17]
	v_cndmask_b32_e64 v51, v245, v51, s[18:19]
	v_cndmask_b32_e64 v52, v245, v52, s[22:23]
	v_cndmask_b32_e64 v53, v245, v53, s[24:25]
	s_bitcmp1_b32 s87, 3
	s_cselect_b32 s21, 0, 0xff800000
	v_add_f32_e32 v120, s21, v132
	v_fmamk_f32 v54, v130, 0x42e00000, v120
	v_fmamk_f32 v55, v130, 0x42de0000, v120
	v_fmamk_f32 v56, v130, 0x42dc0000, v120
	v_fmamk_f32 v57, v130, 0x42da0000, v120
	s_waitcnt lgkmcnt(14)
	v_mfma_f32_16x16x32_bf16 v[210:213], v[202:205], v[240:243], v[210:213]
	s_waitcnt lgkmcnt(12)
	v_mfma_f32_16x16x32_bf16 v[214:217], v[206:209], v[240:243], v[214:217]
	s_waitcnt lgkmcnt(10)
	v_mfma_f32_16x16x32_bf16 v[220:223], v[228:231], v[240:243], v[220:223]
	s_waitcnt lgkmcnt(8)
	v_mfma_f32_16x16x32_bf16 v[224:227], v[232:235], v[240:243], v[224:227]
	v_cvt_pk_bf16_f32 v236, v66, v67
	v_cvt_pk_bf16_f32 v237, v68, v69
	v_cvt_pk_bf16_f32 v238, v70, v71
	v_cvt_pk_bf16_f32 v239, v72, v73
	s_waitcnt lgkmcnt(7)
	ds_read_b64_tr_b16 v[202:203], v124 offset:14336
	ds_read_b64_tr_b16 v[204:205], v124 offset:16384
	ds_read_b64_tr_b16 v[206:207], v125 offset:14336
	ds_read_b64_tr_b16 v[208:209], v125 offset:16384
	ds_read_b64_tr_b16 v[228:229], v126 offset:14336
	ds_read_b64_tr_b16 v[230:231], v126 offset:16384
	ds_read_b64_tr_b16 v[232:233], v127 offset:14336
	ds_read_b64_tr_b16 v[234:235], v127 offset:16384
	s_bitcmp1_b32 s87, 4
	s_cselect_b32 s21, 0, 0xff800000
	v_add_f32_e32 v120, s21, v132
	v_fmamk_f32 v58, v130, 0x42c00000, v120
	v_fmamk_f32 v59, v130, 0x42be0000, v120
	v_fmamk_f32 v60, v130, 0x42bc0000, v120
	v_fmamk_f32 v61, v130, 0x42ba0000, v120
	s_bitcmp1_b32 s87, 5
	s_cselect_b32 s21, 0, 0xff800000
	v_add_f32_e32 v120, s21, v132
	v_fmamk_f32 v62, v130, 0x42a00000, v120
	v_fmamk_f32 v63, v130, 0x429e0000, v120
	v_fmamk_f32 v64, v130, 0x429c0000, v120
	v_fmamk_f32 v65, v130, 0x429a0000, v120
	s_waitcnt lgkmcnt(14)
	v_mfma_f32_16x16x32_bf16 v[210:213], v[186:189], v[236:239], v[210:213]
	s_waitcnt lgkmcnt(12)
	v_mfma_f32_16x16x32_bf16 v[214:217], v[190:193], v[236:239], v[214:217]
	s_waitcnt lgkmcnt(10)
	v_mfma_f32_16x16x32_bf16 v[220:223], v[194:197], v[236:239], v[220:223]
	s_waitcnt lgkmcnt(8)
	v_mfma_f32_16x16x32_bf16 v[224:227], v[198:201], v[236:239], v[224:227]
	v_cvt_pk_bf16_f32 v240, v74, v75
	v_cvt_pk_bf16_f32 v241, v76, v77
	v_cvt_pk_bf16_f32 v242, v78, v79
	v_cvt_pk_bf16_f32 v243, v80, v81
	s_waitcnt lgkmcnt(7)
	ds_read_b64_tr_b16 v[186:187], v124 offset:18432
	ds_read_b64_tr_b16 v[188:189], v124 offset:20480
	ds_read_b64_tr_b16 v[190:191], v125 offset:18432
	ds_read_b64_tr_b16 v[192:193], v125 offset:20480
	ds_read_b64_tr_b16 v[194:195], v126 offset:18432
	ds_read_b64_tr_b16 v[196:197], v126 offset:20480
	ds_read_b64_tr_b16 v[198:199], v127 offset:18432
	ds_read_b64_tr_b16 v[200:201], v127 offset:20480
	s_bitcmp1_b32 s87, 6
	s_cselect_b32 s21, 0, 0xff800000
	v_add_f32_e32 v120, s21, v132
	v_fmamk_f32 v66, v130, 0x42800000, v120
	v_fmamk_f32 v67, v130, 0x427c0000, v120
	v_fmamk_f32 v68, v130, 0x42780000, v120
	v_fmamk_f32 v69, v130, 0x42740000, v120
	s_bitcmp1_b32 s87, 7
	s_cselect_b32 s21, 0, 0xff800000
	v_add_f32_e32 v120, s21, v132
	v_fmamk_f32 v70, v130, 0x42400000, v120
	v_fmamk_f32 v71, v130, 0x423c0000, v120
	v_fmamk_f32 v72, v130, 0x42380000, v120
	v_fmamk_f32 v73, v130, 0x42340000, v120
	s_waitcnt lgkmcnt(14)
	v_mfma_f32_16x16x32_bf16 v[210:213], v[202:205], v[240:243], v[210:213]
	s_waitcnt lgkmcnt(12)
	v_mfma_f32_16x16x32_bf16 v[214:217], v[206:209], v[240:243], v[214:217]
	s_waitcnt lgkmcnt(10)
	v_mfma_f32_16x16x32_bf16 v[220:223], v[228:231], v[240:243], v[220:223]
	s_waitcnt lgkmcnt(8)
	v_mfma_f32_16x16x32_bf16 v[224:227], v[232:235], v[240:243], v[224:227]
	v_cvt_pk_bf16_f32 v236, v82, v83
	v_cvt_pk_bf16_f32 v237, v84, v85
	v_cvt_pk_bf16_f32 v238, v86, v87
	v_cvt_pk_bf16_f32 v239, v88, v89
	s_waitcnt lgkmcnt(7)
	ds_read_b64_tr_b16 v[202:203], v124 offset:22528
	ds_read_b64_tr_b16 v[204:205], v124 offset:24576
	ds_read_b64_tr_b16 v[206:207], v125 offset:22528
	ds_read_b64_tr_b16 v[208:209], v125 offset:24576
	ds_read_b64_tr_b16 v[228:229], v126 offset:22528
	ds_read_b64_tr_b16 v[230:231], v126 offset:24576
	ds_read_b64_tr_b16 v[232:233], v127 offset:22528
	ds_read_b64_tr_b16 v[234:235], v127 offset:24576
	s_bitcmp1_b32 s87, 8
	s_cselect_b32 s21, 0, 0xff800000
	v_add_f32_e32 v120, s21, v132
	v_fmamk_f32 v74, v130, 0x42000000, v120
	v_fmamk_f32 v75, v130, 0x41f80000, v120
	v_fmamk_f32 v76, v130, 0x41f00000, v120
	v_fmamk_f32 v77, v130, 0x41e80000, v120
	s_bitcmp1_b32 s87, 9
	s_cselect_b32 s21, 0, 0xff800000
	v_add_f32_e32 v120, s21, v132
	v_fmamk_f32 v78, v130, 0x41800000, v120
	v_fmamk_f32 v79, v130, 0x41700000, v120
	v_fmamk_f32 v80, v130, 0x41600000, v120
	v_fmamk_f32 v81, v130, 0x41500000, v120
	s_waitcnt lgkmcnt(14)
	v_mfma_f32_16x16x32_bf16 v[210:213], v[186:189], v[236:239], v[210:213]
	s_waitcnt lgkmcnt(12)
	v_mfma_f32_16x16x32_bf16 v[214:217], v[190:193], v[236:239], v[214:217]
	s_waitcnt lgkmcnt(10)
; #define LAS __attribute__((address_space(3)))
; __device__ __forceinline__ unsigned pk2(float lo, float hi) { return pg8::cvt_pk_bf16(lo, hi); }
; __device__ __forceinline__ s16x4 vtr(const LAS unsigned char* p) { return __builtin_bit_cast(s16x4, __builtin_amdgcn_ds_read_tr16_b64_v4i16((LAS s16x4*)p)); }
; #define MFMA16(a, b, c) __builtin_amdgcn_mfma_f32_16x16x32_bf16((a), (b), (c), 0, 0, 0)
; __device__ __forceinline__ void pv_at(const LAS unsigned char* const (&vp)[4], int off, const f32x4& P0, const f32x4& P1, f32x4 (&O)[4]) {
;     v4u pw; pw.x = pk2(P0[0], P0[1]); pw.y = pk2(P0[2], P0[3]); pw.z = pk2(P1[0], P1[1]); pw.w = pk2(P1[2], P1[3]);
;     const bf16x8 pb = __builtin_bit_cast(bf16x8, pw);
; #pragma unroll
;     for (int db = 0; db < 4; ++db) {
;         const s16x4 lo = vtr(vp[db] + off), hi = vtr(vp[db] + off + 2048);
;         const bf16x8 vt = (bf16x8){lo[0], lo[1], lo[2], lo[3], hi[0], hi[1], hi[2], hi[3]};
;         O[db] = MFMA16(vt, pb, O[db]);
;     }
; }
; template <bool MASK> __device__ __forceinline__ void a_scores(f32x4& S0, f32x4& S1, float basef, float c1, float slope2, int krow0, int kstart) {
; #pragma unroll
;     for (int r = 0; r < 4; ++r) {
;         const float d0 = fabsf(basef - (float)r), d1 = fabsf(basef - (float)(16 + r));
;         const float v0 = S0[r] - slope2 * d0, v1 = S1[r] - slope2 * d1;
;         if (MASK) { const int p0 = kstart + krow0 + r, p1 = p0 + 16;
;             S0[r] = (d0 <= 128.f && p0 >= 0 && p0 < SEQ) ? v0 : -INFINITY; S1[r] = (d1 <= 128.f && p1 >= 0 && p1 < SEQ) ? v1 : -INFINITY; }
;         else { S0[r] = v0; S1[r] = v1; }
;     }
; }
	v_mfma_f32_16x16x32_bf16 v[220:223], v[194:197], v[236:239], v[220:223]
	s_waitcnt lgkmcnt(8)
	v_mfma_f32_16x16x32_bf16 v[224:227], v[198:201], v[236:239], v[224:227]
	v_cvt_pk_bf16_f32 v240, v90, v91
	v_cvt_pk_bf16_f32 v241, v92, v93
	v_cvt_pk_bf16_f32 v242, v94, v95
	v_cvt_pk_bf16_f32 v243, v96, v97
	s_waitcnt lgkmcnt(7)
	ds_read_b64_tr_b16 v[186:187], v124 offset:26624
	ds_read_b64_tr_b16 v[188:189], v124 offset:28672
	ds_read_b64_tr_b16 v[190:191], v125 offset:26624
	ds_read_b64_tr_b16 v[192:193], v125 offset:28672
	ds_read_b64_tr_b16 v[194:195], v126 offset:26624
	ds_read_b64_tr_b16 v[196:197], v126 offset:28672
	ds_read_b64_tr_b16 v[198:199], v127 offset:26624
	ds_read_b64_tr_b16 v[200:201], v127 offset:28672
	s_bitcmp1_b32 s87, 10
	s_cselect_b32 s21, 0, 0xff800000
	v_add_f32_e32 v219, 0, v129
	v_fma_f32 v82, v130, |v219|, s21
	v_add_f32_e32 v245, 0xbf800000, v129
	v_fma_f32 v83, v130, |v245|, s21
	v_add_f32_e32 v219, 0xc0000000, v129
	v_fma_f32 v84, v130, |v219|, s21
	v_add_f32_e32 v245, 0xc0400000, v129
	v_fma_f32 v85, v130, |v245|, s21
	s_bitcmp1_b32 s87, 11
	s_cselect_b32 s21, 0, 0xff800000
	v_add_f32_e32 v120, s21, v133
	v_fmamk_f32 v86, v131, 0xc1800000, v120
	v_fmamk_f32 v87, v131, 0xc1880000, v120
	v_fmamk_f32 v88, v131, 0xc1900000, v120
	v_fmamk_f32 v89, v131, 0xc1980000, v120
	s_waitcnt lgkmcnt(14)
	v_mfma_f32_16x16x32_bf16 v[210:213], v[202:205], v[240:243], v[210:213]
	s_waitcnt lgkmcnt(12)
	v_mfma_f32_16x16x32_bf16 v[214:217], v[206:209], v[240:243], v[214:217]
	s_waitcnt lgkmcnt(10)
	v_mfma_f32_16x16x32_bf16 v[220:223], v[228:231], v[240:243], v[220:223]
	s_waitcnt lgkmcnt(8)
	v_mfma_f32_16x16x32_bf16 v[224:227], v[232:235], v[240:243], v[224:227]
	v_cvt_pk_bf16_f32 v236, v98, v99
	v_cvt_pk_bf16_f32 v237, v100, v101
	v_cvt_pk_bf16_f32 v238, v102, v103
	v_cvt_pk_bf16_f32 v239, v104, v105
	s_waitcnt lgkmcnt(7)
	ds_read_b64_tr_b16 v[202:203], v124 offset:30720
	ds_read_b64_tr_b16 v[204:205], v124 offset:32768
	ds_read_b64_tr_b16 v[206:207], v125 offset:30720
	ds_read_b64_tr_b16 v[208:209], v125 offset:32768
	ds_read_b64_tr_b16 v[228:229], v126 offset:30720
	ds_read_b64_tr_b16 v[230:231], v126 offset:32768
	ds_read_b64_tr_b16 v[232:233], v127 offset:30720
	ds_read_b64_tr_b16 v[234:235], v127 offset:32768
	s_bitcmp1_b32 s87, 12
	s_cselect_b32 s21, 0, 0xff800000
	v_add_f32_e32 v120, s21, v133
	v_fmamk_f32 v90, v131, 0xc2000000, v120
	v_fmamk_f32 v91, v131, 0xc2040000, v120
	v_fmamk_f32 v92, v131, 0xc2080000, v120
	v_fmamk_f32 v93, v131, 0xc20c0000, v120
	s_bitcmp1_b32 s87, 13
	s_cselect_b32 s21, 0, 0xff800000
	v_add_f32_e32 v120, s21, v133
	v_fmamk_f32 v94, v131, 0xc2400000, v120
	v_fmamk_f32 v95, v131, 0xc2440000, v120
	v_fmamk_f32 v96, v131, 0xc2480000, v120
	v_fmamk_f32 v97, v131, 0xc24c0000, v120
	s_waitcnt lgkmcnt(14)
	v_mfma_f32_16x16x32_bf16 v[210:213], v[186:189], v[236:239], v[210:213]
	s_waitcnt lgkmcnt(12)
	v_mfma_f32_16x16x32_bf16 v[214:217], v[190:193], v[236:239], v[214:217]
	s_waitcnt lgkmcnt(10)
	v_mfma_f32_16x16x32_bf16 v[220:223], v[194:197], v[236:239], v[220:223]
	s_waitcnt lgkmcnt(8)
	v_mfma_f32_16x16x32_bf16 v[224:227], v[198:201], v[236:239], v[224:227]
	v_cvt_pk_bf16_f32 v240, v106, v107
	v_cvt_pk_bf16_f32 v241, v108, v109
	v_cvt_pk_bf16_f32 v242, v110, v111
	v_cvt_pk_bf16_f32 v243, v112, v113
	s_waitcnt lgkmcnt(7)
	ds_read_b64_tr_b16 v[186:187], v124 offset:34816
	ds_read_b64_tr_b16 v[188:189], v124 offset:36864
	ds_read_b64_tr_b16 v[190:191], v125 offset:34816
	ds_read_b64_tr_b16 v[192:193], v125 offset:36864
	ds_read_b64_tr_b16 v[194:195], v126 offset:34816
	ds_read_b64_tr_b16 v[196:197], v126 offset:36864
	ds_read_b64_tr_b16 v[198:199], v127 offset:34816
	ds_read_b64_tr_b16 v[200:201], v127 offset:36864
	s_bitcmp1_b32 s87, 14
	s_cselect_b32 s21, 0, 0xff800000
	v_add_f32_e32 v120, s21, v133
	v_fmamk_f32 v98, v131, 0xc2800000, v120
	v_fmamk_f32 v99, v131, 0xc2820000, v120
	v_fmamk_f32 v100, v131, 0xc2840000, v120
	v_fmamk_f32 v101, v131, 0xc2860000, v120
	s_bitcmp1_b32 s87, 15
	s_cselect_b32 s21, 0, 0xff800000
	v_add_f32_e32 v120, s21, v133
	v_fmamk_f32 v102, v131, 0xc2a00000, v120
	v_fmamk_f32 v103, v131, 0xc2a20000, v120
	v_fmamk_f32 v104, v131, 0xc2a40000, v120
	v_fmamk_f32 v105, v131, 0xc2a60000, v120
	s_waitcnt lgkmcnt(14)
	v_mfma_f32_16x16x32_bf16 v[210:213], v[202:205], v[240:243], v[210:213]
	s_waitcnt lgkmcnt(12)
	v_mfma_f32_16x16x32_bf16 v[214:217], v[206:209], v[240:243], v[214:217]
	s_waitcnt lgkmcnt(10)
	v_mfma_f32_16x16x32_bf16 v[220:223], v[228:231], v[240:243], v[220:223]
	s_waitcnt lgkmcnt(8)
	v_mfma_f32_16x16x32_bf16 v[224:227], v[232:235], v[240:243], v[224:227]
	v_cvt_pk_bf16_f32 v236, v114, v115
	v_cvt_pk_bf16_f32 v237, v116, v117
	v_mov_b32_e32 v238, 0
	v_mov_b32_e32 v239, 0
	s_nop 1
	s_bitcmp1_b32 s87, 16
	s_cselect_b32 s21, 0, 0xff800000
	v_add_f32_e32 v120, s21, v133
	v_fmamk_f32 v106, v131, 0xc2c00000, v120
	v_fmamk_f32 v107, v131, 0xc2c20000, v120
	v_fmamk_f32 v108, v131, 0xc2c40000, v120
	v_fmamk_f32 v109, v131, 0xc2c60000, v120
	s_bitcmp1_b32 s87, 17
	s_cselect_b32 s21, 0, 0xff800000
	v_add_f32_e32 v120, s21, v133
	v_fmamk_f32 v110, v131, 0xc2e00000, v120
	v_fmamk_f32 v111, v131, 0xc2e20000, v120
	v_fmamk_f32 v112, v131, 0xc2e40000, v120
	v_fmamk_f32 v113, v131, 0xc2e60000, v120
	s_waitcnt lgkmcnt(6)
	v_mfma_f32_16x16x32_bf16 v[210:213], v[186:189], v[236:239], v[210:213]
	s_waitcnt lgkmcnt(4)
	v_mfma_f32_16x16x32_bf16 v[214:217], v[190:193], v[236:239], v[214:217]
	s_waitcnt lgkmcnt(2)
	v_mfma_f32_16x16x32_bf16 v[220:223], v[194:197], v[236:239], v[220:223]
	s_waitcnt lgkmcnt(0)
; #define LAS __attribute__((address_space(3)))
; __device__ __forceinline__ unsigned pk2(float lo, float hi) { return pg8::cvt_pk_bf16(lo, hi); }
; #define MFMA16(a, b, c) __builtin_amdgcn_mfma_f32_16x16x32_bf16((a), (b), (c), 0, 0, 0)
; __device__ __forceinline__ void qk_at(const LAS unsigned char* kp0, const LAS unsigned char* kp1, int off, bf16x8 qf0, bf16x8 qf1, f32x4& S0, f32x4& S1) {
;     const bf16x8 k00 = *(const LAS bf16x8*)(kp0 + off), k01 = *(const LAS bf16x8*)(kp1 + off);
;     const bf16x8 k10 = *(const LAS bf16x8*)(kp0 + off + 2048), k11 = *(const LAS bf16x8*)(kp1 + off + 2048);
;     const f32x4 z = {0.f, 0.f, 0.f, 0.f};
;     S0 = MFMA16(k00, qf0, z); S0 = MFMA16(k01, qf1, S0);
;     S1 = MFMA16(k10, qf0, z); S1 = MFMA16(k11, qf1, S1);
; }
; __device__ __forceinline__ void store_o(bf16* yrow, int g, float l, const f32x4 (&O)[4]) {
;     const float inv = 1.0f / xrow16_sum(l);
;     unsigned wx[4], wy[4];
; #pragma unroll
;     for (int db = 0; db < 4; ++db) { wx[db] = pk2(O[db][0] * inv, O[db][1] * inv); wy[db] = pk2(O[db][2] * inv, O[db][3] * inv); }
; #pragma unroll
;     for (int p = 0; p < 2; ++p) {
;         auto rx = __builtin_amdgcn_permlane16_swap(wx[2 * p], wx[2 * p + 1], false, false); wx[2 * p] = rx[0]; wx[2 * p + 1] = rx[1];
;         auto ry = __builtin_amdgcn_permlane16_swap(wy[2 * p], wy[2 * p + 1], false, false); wy[2 * p] = ry[0]; wy[2 * p + 1] = ry[1]; }
; #pragma unroll
;     for (int p = 0; p < 2; ++p) {
;         auto rx = __builtin_amdgcn_permlane32_swap(wx[p], wx[p + 2], false, false); wx[p] = rx[0]; wx[p + 2] = rx[1];
;         auto ry = __builtin_amdgcn_permlane32_swap(wy[p], wy[p + 2], false, false); wy[p] = ry[0]; wy[p + 2] = ry[1]; }
;     v4u lo = {wx[0], wy[0], wx[1], wy[1]}, hi = {wx[2], wy[2], wx[3], wy[3]};
;     *(v4u*)(yrow + 16 * g) = lo; *(v4u*)(yrow + 16 * g + 8) = hi;
	v_mfma_f32_16x16x32_bf16 v[224:227], v[198:201], v[236:239], v[224:227]
	s_bitcmp1_b32 s87, 18
	s_cselect_b32 s21, 0, 0xff800000
	v_add_f32_e32 v120, s21, v133
	v_fmamk_f32 v114, v131, 0xc3000000, v120
	v_fmamk_f32 v115, v131, 0xc3010000, v120
	v_fmamk_f32 v116, v131, 0xc3020000, v120
	v_fmamk_f32 v117, v131, 0xc3030000, v120
	v_mov_b32_e32 v245, 0xff800000
	v_cndmask_b32_e64 v114, v245, v114, s[28:29]
	v_cndmask_b32_e64 v115, v245, v115, s[52:53]
	v_cndmask_b32_e64 v116, v245, v116, s[54:55]
	v_cndmask_b32_e64 v117, v245, v117, s[88:89]
	v_mov_b32_e32 v219, v185
	s_nop 1
	v_permlane16_swap_b32_e32 v185, v219
	v_add_f32_e32 v185, v185, v219
	v_mov_b32_e32 v219, v185
	s_nop 1
	v_permlane32_swap_b32_e32 v185, v219
	v_add_f32_e32 v185, v185, v219
	v_div_scale_f32 v236, s[78:79], v185, v185, 1.0
	v_div_scale_f32 v237, vcc, 1.0, v185, 1.0
	v_rcp_f32_e32 v238, v236
	s_nop 0
	v_fma_f32 v239, -v236, v238, 1.0
	v_fmac_f32_e32 v238, v239, v238
	v_mul_f32_e32 v240, v237, v238
	v_fma_f32 v241, -v236, v240, v237
	v_fmac_f32_e32 v240, v241, v238
	v_fma_f32 v237, -v236, v240, v237
	v_div_fmas_f32 v237, v237, v238, v240
	v_div_fixup_f32 v244, v237, v185, 1.0
	v_mul_f32_e32 v240, v210, v244
	v_mul_f32_e32 v241, v211, v244
	v_mul_f32_e32 v242, v212, v244
	v_mul_f32_e32 v243, v213, v244
	v_cvt_pk_bf16_f32 v186, v240, v241
	v_cvt_pk_bf16_f32 v187, v242, v243
	v_mul_f32_e32 v240, v214, v244
	v_mul_f32_e32 v241, v215, v244
	v_mul_f32_e32 v242, v216, v244
	v_mul_f32_e32 v243, v217, v244
	v_cvt_pk_bf16_f32 v188, v240, v241
	v_cvt_pk_bf16_f32 v189, v242, v243
	v_mul_f32_e32 v240, v220, v244
	v_mul_f32_e32 v241, v221, v244
	v_mul_f32_e32 v242, v222, v244
	v_mul_f32_e32 v243, v223, v244
	v_cvt_pk_bf16_f32 v190, v240, v241
	v_cvt_pk_bf16_f32 v191, v242, v243
	v_mul_f32_e32 v240, v224, v244
	v_mul_f32_e32 v241, v225, v244
	v_mul_f32_e32 v242, v226, v244
	v_mul_f32_e32 v243, v227, v244
	v_cvt_pk_bf16_f32 v192, v240, v241
	v_cvt_pk_bf16_f32 v193, v242, v243
	s_nop 1
	v_permlane16_swap_b32_e32 v186, v188
	v_permlane16_swap_b32_e32 v187, v189
	v_permlane16_swap_b32_e32 v190, v192
	v_permlane16_swap_b32_e32 v191, v193
	s_nop 0
	v_permlane32_swap_b32_e32 v186, v190
	v_permlane32_swap_b32_e32 v187, v191
	v_permlane32_swap_b32_e32 v188, v192
	v_permlane32_swap_b32_e32 v189, v193
	global_store_dwordx4 v128, v[186:189], s[82:83] offset:2048
	global_store_dwordx4 v128, v[190:193], s[82:83] offset:2064
	s_nop 1
	ds_read_b128 v[186:189], v122 offset:4096
	ds_read_b128 v[190:193], v123 offset:4096
	ds_read_b128 v[194:197], v122 offset:6144
	ds_read_b128 v[198:201], v123 offset:6144
	ds_read_b128 v[202:205], v122 offset:8192
	ds_read_b128 v[206:209], v123 offset:8192
	ds_read_b128 v[210:213], v122 offset:10240
	ds_read_b128 v[214:217], v123 offset:10240
	ds_read_b128 v[220:223], v122 offset:12288
	ds_read_b128 v[224:227], v123 offset:12288
	ds_read_b128 v[228:231], v122 offset:14336
	ds_read_b128 v[232:235], v123 offset:14336
	ds_read_b128 v[236:239], v122 offset:16384
	ds_read_b128 v[240:243], v123 offset:16384
	s_waitcnt lgkmcnt(13)
	v_mfma_f32_16x16x32_bf16 v[50:53], v[186:189], v[162:165], v[50:53]
	s_waitcnt lgkmcnt(12)
	v_mfma_f32_16x16x32_bf16 v[50:53], v[190:193], v[166:169], v[50:53]
	ds_read_b128 v[186:189], v122 offset:18432
	ds_read_b128 v[190:193], v123 offset:18432
	s_waitcnt lgkmcnt(13)
	v_mfma_f32_16x16x32_bf16 v[54:57], v[194:197], v[162:165], v[54:57]
	s_waitcnt lgkmcnt(12)
	v_mfma_f32_16x16x32_bf16 v[54:57], v[198:201], v[166:169], v[54:57]
	ds_read_b128 v[194:197], v122 offset:20480
	ds_read_b128 v[198:201], v123 offset:20480
	s_waitcnt lgkmcnt(13)
	v_mfma_f32_16x16x32_bf16 v[58:61], v[202:205], v[162:165], v[58:61]
	s_waitcnt lgkmcnt(12)
	v_mfma_f32_16x16x32_bf16 v[58:61], v[206:209], v[166:169], v[58:61]
	ds_read_b128 v[202:205], v122 offset:22528
	ds_read_b128 v[206:209], v123 offset:22528
	s_waitcnt lgkmcnt(13)
	v_mfma_f32_16x16x32_bf16 v[62:65], v[210:213], v[162:165], v[62:65]
	s_waitcnt lgkmcnt(12)
	v_mfma_f32_16x16x32_bf16 v[62:65], v[214:217], v[166:169], v[62:65]
	ds_read_b128 v[210:213], v122 offset:24576
	ds_read_b128 v[214:217], v123 offset:24576
	s_waitcnt lgkmcnt(13)
	v_mfma_f32_16x16x32_bf16 v[66:69], v[220:223], v[162:165], v[66:69]
	s_waitcnt lgkmcnt(12)
	v_mfma_f32_16x16x32_bf16 v[66:69], v[224:227], v[166:169], v[66:69]
	ds_read_b128 v[220:223], v122 offset:26624
	ds_read_b128 v[224:227], v123 offset:26624
	s_waitcnt lgkmcnt(13)
	v_mfma_f32_16x16x32_bf16 v[70:73], v[228:231], v[162:165], v[70:73]
	s_waitcnt lgkmcnt(12)
	v_mfma_f32_16x16x32_bf16 v[70:73], v[232:235], v[166:169], v[70:73]
	ds_read_b128 v[228:231], v122 offset:28672
	ds_read_b128 v[232:235], v123 offset:28672
	s_waitcnt lgkmcnt(13)
	v_mfma_f32_16x16x32_bf16 v[74:77], v[236:239], v[162:165], v[74:77]
	s_waitcnt lgkmcnt(12)
	v_mfma_f32_16x16x32_bf16 v[74:77], v[240:243], v[166:169], v[74:77]
	ds_read_b128 v[236:239], v122 offset:30720
	ds_read_b128 v[240:243], v123 offset:30720
	s_waitcnt lgkmcnt(13)
	v_mfma_f32_16x16x32_bf16 v[78:81], v[186:189], v[162:165], v[78:81]
	s_waitcnt lgkmcnt(12)
	v_mfma_f32_16x16x32_bf16 v[78:81], v[190:193], v[166:169], v[78:81]
	ds_read_b128 v[186:189], v122 offset:32768
	ds_read_b128 v[190:193], v123 offset:32768
	s_waitcnt lgkmcnt(13)
	v_mfma_f32_16x16x32_bf16 v[82:85], v[194:197], v[162:165], v[82:85]
	s_waitcnt lgkmcnt(12)
	v_mfma_f32_16x16x32_bf16 v[82:85], v[198:201], v[166:169], v[82:85]
	ds_read_b128 v[194:197], v122 offset:34816
	ds_read_b128 v[198:201], v123 offset:34816
	s_waitcnt lgkmcnt(13)
	v_mfma_f32_16x16x32_bf16 v[86:89], v[202:205], v[162:165], v[86:89]
	s_waitcnt lgkmcnt(12)
; #define LAS __attribute__((address_space(3)))
; #define MFMA16(a, b, c) __builtin_amdgcn_mfma_f32_16x16x32_bf16((a), (b), (c), 0, 0, 0)
; __device__ __forceinline__ void qk_at(const LAS unsigned char* kp0, const LAS unsigned char* kp1, int off, bf16x8 qf0, bf16x8 qf1, f32x4& S0, f32x4& S1) {
;     const bf16x8 k00 = *(const LAS bf16x8*)(kp0 + off), k01 = *(const LAS bf16x8*)(kp1 + off);
;     const bf16x8 k10 = *(const LAS bf16x8*)(kp0 + off + 2048), k11 = *(const LAS bf16x8*)(kp1 + off + 2048);
;     const f32x4 z = {0.f, 0.f, 0.f, 0.f};
;     S0 = MFMA16(k00, qf0, z); S0 = MFMA16(k01, qf1, S0);
;     S1 = MFMA16(k10, qf0, z); S1 = MFMA16(k11, qf1, S1);
; }
; __device__ __forceinline__ void softmax_step(f32x4& s0, f32x4& s1, float& m, float& l, f32x4 (&O)[4]) {
;     float t = fmaxf(fmaxf(fmaxf(s0[0], s0[1]), fmaxf(s0[2], s0[3])), fmaxf(fmaxf(s1[0], s1[1]), fmaxf(s1[2], s1[3])));
;     t = xrow16_max(t);
;     const float mn = fmaxf(m, t), alpha = __builtin_amdgcn_exp2f(m - mn);
;     m = mn;
	v_mfma_f32_16x16x32_bf16 v[86:89], v[206:209], v[166:169], v[86:89]
	ds_read_b128 v[202:205], v122 offset:36864
	ds_read_b128 v[206:209], v123 offset:36864
	s_waitcnt lgkmcnt(13)
	v_mfma_f32_16x16x32_bf16 v[90:93], v[210:213], v[162:165], v[90:93]
	s_waitcnt lgkmcnt(12)
	v_mfma_f32_16x16x32_bf16 v[90:93], v[214:217], v[166:169], v[90:93]
	s_waitcnt lgkmcnt(11)
	v_mfma_f32_16x16x32_bf16 v[94:97], v[220:223], v[162:165], v[94:97]
	s_waitcnt lgkmcnt(10)
	v_mfma_f32_16x16x32_bf16 v[94:97], v[224:227], v[166:169], v[94:97]
	s_waitcnt lgkmcnt(9)
	v_mfma_f32_16x16x32_bf16 v[98:101], v[228:231], v[162:165], v[98:101]
	s_waitcnt lgkmcnt(8)
	v_mfma_f32_16x16x32_bf16 v[98:101], v[232:235], v[166:169], v[98:101]
	s_waitcnt lgkmcnt(7)
	v_mfma_f32_16x16x32_bf16 v[102:105], v[236:239], v[162:165], v[102:105]
	s_waitcnt lgkmcnt(6)
	v_mfma_f32_16x16x32_bf16 v[102:105], v[240:243], v[166:169], v[102:105]
	s_waitcnt lgkmcnt(5)
	v_mfma_f32_16x16x32_bf16 v[106:109], v[186:189], v[162:165], v[106:109]
	s_waitcnt lgkmcnt(4)
	v_mfma_f32_16x16x32_bf16 v[106:109], v[190:193], v[166:169], v[106:109]
	s_waitcnt lgkmcnt(3)
	v_mfma_f32_16x16x32_bf16 v[110:113], v[194:197], v[162:165], v[110:113]
	s_waitcnt lgkmcnt(2)
	v_mfma_f32_16x16x32_bf16 v[110:113], v[198:201], v[166:169], v[110:113]
	s_waitcnt lgkmcnt(1)
	v_mfma_f32_16x16x32_bf16 v[114:117], v[202:205], v[162:165], v[114:117]
	s_waitcnt lgkmcnt(0)
	v_mfma_f32_16x16x32_bf16 v[114:117], v[206:209], v[166:169], v[114:117]
	v_max3_f32 v219, v50, v51, v52
	v_max3_f32 v244, v54, v55, v56
	v_max3_f32 v245, v58, v59, v60
	v_max3_f32 v120, v62, v63, v64
	v_max3_f32 v219, v219, v53, v66
	v_max3_f32 v244, v244, v57, v70
	v_max3_f32 v245, v245, v61, v74
	v_max3_f32 v120, v120, v65, v78
	v_max3_f32 v219, v219, v67, v68
	v_max3_f32 v244, v244, v71, v72
	v_max3_f32 v245, v245, v75, v76
	v_max3_f32 v120, v120, v79, v80
	ds_read_b64_tr_b16 v[186:187], v124 offset:4096
	ds_read_b64_tr_b16 v[188:189], v124 offset:6144
	ds_read_b64_tr_b16 v[190:191], v125 offset:4096
	ds_read_b64_tr_b16 v[192:193], v125 offset:6144
	ds_read_b64_tr_b16 v[194:195], v126 offset:4096
	ds_read_b64_tr_b16 v[196:197], v126 offset:6144
	ds_read_b64_tr_b16 v[198:199], v127 offset:4096
	ds_read_b64_tr_b16 v[200:201], v127 offset:6144
	v_max3_f32 v219, v219, v69, v82
	v_max3_f32 v244, v244, v73, v86
	v_max3_f32 v245, v245, v77, v90
	v_max3_f32 v120, v120, v81, v94
	v_max3_f32 v219, v219, v83, v84
	v_max3_f32 v244, v244, v87, v88
	v_max3_f32 v245, v245, v91, v92
	v_max3_f32 v120, v120, v95, v96
	v_max3_f32 v219, v219, v85, v98
	v_max3_f32 v244, v244, v89, v102
	v_max3_f32 v245, v245, v93, v106
	v_max3_f32 v120, v120, v97, v110
	v_max3_f32 v219, v219, v99, v100
	v_max3_f32 v244, v244, v103, v104
	v_max3_f32 v245, v245, v107, v108
	v_max3_f32 v120, v120, v111, v112
	v_max3_f32 v219, v219, v101, v114
	v_max3_f32 v219, v219, v115, v116
	v_max_f32_e32 v219, v219, v117
	v_max_f32_e32 v244, v244, v105
	v_max_f32_e32 v245, v245, v109
	v_max_f32_e32 v120, v120, v113
	v_max3_f32 v178, v219, v244, v245
	v_max_f32_e32 v178, v178, v120
	v_mov_b32_e32 v219, v178
	s_nop 1
	v_permlane16_swap_b32_e32 v178, v219
	v_max_f32_e32 v178, v178, v219
	v_mov_b32_e32 v219, v178
	s_nop 1
	v_permlane32_swap_b32_e32 v178, v219
	v_max3_f32 v178, v178, v219, v145
	s_waitcnt lgkmcnt(7)
	ds_read_b64_tr_b16 v[202:203], v124 offset:8192
	ds_read_b64_tr_b16 v[204:205], v124 offset:10240
	ds_read_b64_tr_b16 v[206:207], v125 offset:8192
	ds_read_b64_tr_b16 v[208:209], v125 offset:10240
	ds_read_b64_tr_b16 v[228:229], v126 offset:8192
	ds_read_b64_tr_b16 v[230:231], v126 offset:10240
	ds_read_b64_tr_b16 v[232:233], v127 offset:8192
	ds_read_b64_tr_b16 v[234:235], v127 offset:10240
	v_mov_b32_e32 v244, v178
	v_pk_add_f32 v[50:51], v[50:51], v[244:245] op_sel_hi:[1,0] neg_lo:[0,1] neg_hi:[0,1]
	v_pk_add_f32 v[52:53], v[52:53], v[244:245] op_sel_hi:[1,0] neg_lo:[0,1] neg_hi:[0,1]
	v_pk_add_f32 v[54:55], v[54:55], v[244:245] op_sel_hi:[1,0] neg_lo:[0,1] neg_hi:[0,1]
	v_pk_add_f32 v[56:57], v[56:57], v[244:245] op_sel_hi:[1,0] neg_lo:[0,1] neg_hi:[0,1]
	v_pk_add_f32 v[58:59], v[58:59], v[244:245] op_sel_hi:[1,0] neg_lo:[0,1] neg_hi:[0,1]
	v_pk_add_f32 v[60:61], v[60:61], v[244:245] op_sel_hi:[1,0] neg_lo:[0,1] neg_hi:[0,1]
	v_pk_add_f32 v[62:63], v[62:63], v[244:245] op_sel_hi:[1,0] neg_lo:[0,1] neg_hi:[0,1]
	v_pk_add_f32 v[64:65], v[64:65], v[244:245] op_sel_hi:[1,0] neg_lo:[0,1] neg_hi:[0,1]
	v_pk_add_f32 v[66:67], v[66:67], v[244:245] op_sel_hi:[1,0] neg_lo:[0,1] neg_hi:[0,1]
	v_pk_add_f32 v[68:69], v[68:69], v[244:245] op_sel_hi:[1,0] neg_lo:[0,1] neg_hi:[0,1]
	v_pk_add_f32 v[70:71], v[70:71], v[244:245] op_sel_hi:[1,0] neg_lo:[0,1] neg_hi:[0,1]
	v_pk_add_f32 v[72:73], v[72:73], v[244:245] op_sel_hi:[1,0] neg_lo:[0,1] neg_hi:[0,1]
	v_pk_add_f32 v[74:75], v[74:75], v[244:245] op_sel_hi:[1,0] neg_lo:[0,1] neg_hi:[0,1]
	v_pk_add_f32 v[76:77], v[76:77], v[244:245] op_sel_hi:[1,0] neg_lo:[0,1] neg_hi:[0,1]
	v_pk_add_f32 v[78:79], v[78:79], v[244:245] op_sel_hi:[1,0] neg_lo:[0,1] neg_hi:[0,1]
	v_pk_add_f32 v[80:81], v[80:81], v[244:245] op_sel_hi:[1,0] neg_lo:[0,1] neg_hi:[0,1]
	v_pk_add_f32 v[82:83], v[82:83], v[244:245] op_sel_hi:[1,0] neg_lo:[0,1] neg_hi:[0,1]
	v_pk_add_f32 v[84:85], v[84:85], v[244:245] op_sel_hi:[1,0] neg_lo:[0,1] neg_hi:[0,1]
	v_pk_add_f32 v[86:87], v[86:87], v[244:245] op_sel_hi:[1,0] neg_lo:[0,1] neg_hi:[0,1]
	v_pk_add_f32 v[88:89], v[88:89], v[244:245] op_sel_hi:[1,0] neg_lo:[0,1] neg_hi:[0,1]
	v_pk_add_f32 v[90:91], v[90:91], v[244:245] op_sel_hi:[1,0] neg_lo:[0,1] neg_hi:[0,1]
	v_pk_add_f32 v[92:93], v[92:93], v[244:245] op_sel_hi:[1,0] neg_lo:[0,1] neg_hi:[0,1]
; __device__ __forceinline__ unsigned pk2(float lo, float hi) { return pg8::cvt_pk_bf16(lo, hi); }
; __device__ __forceinline__ void pv_at(const LAS unsigned char* const (&vp)[4], int off, const f32x4& P0, const f32x4& P1, f32x4 (&O)[4]) {
;     v4u pw; pw.x = pk2(P0[0], P0[1]); pw.y = pk2(P0[2], P0[3]); pw.z = pk2(P1[0], P1[1]); pw.w = pk2(P1[2], P1[3]);
;     const bf16x8 pb = __builtin_bit_cast(bf16x8, pw);
; __device__ __forceinline__ void softmax_step(f32x4& s0, f32x4& s1, float& m, float& l, f32x4 (&O)[4]) {
;     float t = fmaxf(fmaxf(fmaxf(s0[0], s0[1]), fmaxf(s0[2], s0[3])), fmaxf(fmaxf(s1[0], s1[1]), fmaxf(s1[2], s1[3])));
;     t = xrow16_max(t);
;     const float mn = fmaxf(m, t), alpha = __builtin_amdgcn_exp2f(m - mn);
;     m = mn;
; #pragma unroll
;     for (int k = 0; k < 4; ++k) { s0[k] = __builtin_amdgcn_exp2f(s0[k] - mn); s1[k] = __builtin_amdgcn_exp2f(s1[k] - mn); }
;     l = l * alpha + ((s0[0] + s0[1]) + (s0[2] + s0[3])) + ((s1[0] + s1[1]) + (s1[2] + s1[3]));
; #pragma unroll
;     for (int db = 0; db < 4; ++db) O[db] *= alpha;
; }
	v_pk_add_f32 v[94:95], v[94:95], v[244:245] op_sel_hi:[1,0] neg_lo:[0,1] neg_hi:[0,1]
	v_pk_add_f32 v[96:97], v[96:97], v[244:245] op_sel_hi:[1,0] neg_lo:[0,1] neg_hi:[0,1]
	v_pk_add_f32 v[98:99], v[98:99], v[244:245] op_sel_hi:[1,0] neg_lo:[0,1] neg_hi:[0,1]
	v_pk_add_f32 v[100:101], v[100:101], v[244:245] op_sel_hi:[1,0] neg_lo:[0,1] neg_hi:[0,1]
	v_pk_add_f32 v[102:103], v[102:103], v[244:245] op_sel_hi:[1,0] neg_lo:[0,1] neg_hi:[0,1]
	v_pk_add_f32 v[104:105], v[104:105], v[244:245] op_sel_hi:[1,0] neg_lo:[0,1] neg_hi:[0,1]
	v_pk_add_f32 v[106:107], v[106:107], v[244:245] op_sel_hi:[1,0] neg_lo:[0,1] neg_hi:[0,1]
	v_pk_add_f32 v[108:109], v[108:109], v[244:245] op_sel_hi:[1,0] neg_lo:[0,1] neg_hi:[0,1]
	v_pk_add_f32 v[110:111], v[110:111], v[244:245] op_sel_hi:[1,0] neg_lo:[0,1] neg_hi:[0,1]
	v_pk_add_f32 v[112:113], v[112:113], v[244:245] op_sel_hi:[1,0] neg_lo:[0,1] neg_hi:[0,1]
	v_pk_add_f32 v[114:115], v[114:115], v[244:245] op_sel_hi:[1,0] neg_lo:[0,1] neg_hi:[0,1]
	v_pk_add_f32 v[116:117], v[116:117], v[244:245] op_sel_hi:[1,0] neg_lo:[0,1] neg_hi:[0,1]
	v_sub_f32_e32 v219, v145, v178
	v_exp_f32_e32 v50, v50
	v_exp_f32_e32 v51, v51
	v_exp_f32_e32 v52, v52
	v_exp_f32_e32 v53, v53
	v_exp_f32_e32 v54, v54
	v_exp_f32_e32 v55, v55
	v_exp_f32_e32 v56, v56
	v_exp_f32_e32 v57, v57
	v_exp_f32_e32 v58, v58
	v_exp_f32_e32 v59, v59
	v_exp_f32_e32 v60, v60
	v_exp_f32_e32 v61, v61
	v_exp_f32_e32 v62, v62
	v_exp_f32_e32 v63, v63
	v_exp_f32_e32 v64, v64
	v_exp_f32_e32 v65, v65
	v_exp_f32_e32 v66, v66
	v_exp_f32_e32 v67, v67
	v_exp_f32_e32 v68, v68
	v_exp_f32_e32 v69, v69
	v_exp_f32_e32 v70, v70
	v_exp_f32_e32 v71, v71
	v_exp_f32_e32 v72, v72
	v_exp_f32_e32 v73, v73
	v_exp_f32_e32 v74, v74
	v_exp_f32_e32 v75, v75
	v_exp_f32_e32 v76, v76
	v_exp_f32_e32 v77, v77
	v_exp_f32_e32 v78, v78
	v_exp_f32_e32 v79, v79
	v_exp_f32_e32 v80, v80
	v_exp_f32_e32 v81, v81
	v_exp_f32_e32 v82, v82
	v_exp_f32_e32 v83, v83
	v_exp_f32_e32 v84, v84
	v_exp_f32_e32 v85, v85
	v_exp_f32_e32 v86, v86
	v_exp_f32_e32 v87, v87
	v_exp_f32_e32 v88, v88
	v_exp_f32_e32 v89, v89
	v_exp_f32_e32 v90, v90
	v_exp_f32_e32 v91, v91
	v_exp_f32_e32 v92, v92
	v_exp_f32_e32 v93, v93
	v_exp_f32_e32 v94, v94
	v_exp_f32_e32 v95, v95
	v_exp_f32_e32 v96, v96
	v_exp_f32_e32 v97, v97
	v_exp_f32_e32 v98, v98
	v_exp_f32_e32 v99, v99
	v_exp_f32_e32 v100, v100
	v_exp_f32_e32 v101, v101
	v_exp_f32_e32 v102, v102
	v_exp_f32_e32 v103, v103
	v_exp_f32_e32 v104, v104
	v_exp_f32_e32 v105, v105
	v_exp_f32_e32 v106, v106
	v_exp_f32_e32 v107, v107
	v_exp_f32_e32 v108, v108
	v_exp_f32_e32 v109, v109
	v_exp_f32_e32 v110, v110
	v_exp_f32_e32 v111, v111
	v_exp_f32_e32 v112, v112
	v_exp_f32_e32 v113, v113
	v_exp_f32_e32 v114, v114
	v_exp_f32_e32 v115, v115
	v_exp_f32_e32 v116, v116
	v_exp_f32_e32 v117, v117
	v_exp_f32_e32 v219, v219
	v_pk_add_f32 v[236:237], v[50:51], v[52:53]
	v_pk_add_f32 v[238:239], v[54:55], v[56:57]
	v_pk_add_f32 v[240:241], v[58:59], v[60:61]
	v_pk_add_f32 v[242:243], v[62:63], v[64:65]
	v_pk_add_f32 v[236:237], v[236:237], v[66:67]
	v_pk_add_f32 v[238:239], v[238:239], v[70:71]
	v_pk_add_f32 v[240:241], v[240:241], v[74:75]
	v_pk_add_f32 v[242:243], v[242:243], v[78:79]
	v_pk_add_f32 v[236:237], v[236:237], v[68:69]
	v_pk_add_f32 v[238:239], v[238:239], v[72:73]
	v_pk_add_f32 v[240:241], v[240:241], v[76:77]
	v_pk_add_f32 v[242:243], v[242:243], v[80:81]
	v_pk_add_f32 v[236:237], v[236:237], v[82:83]
	v_pk_add_f32 v[238:239], v[238:239], v[86:87]
	v_pk_add_f32 v[240:241], v[240:241], v[90:91]
	v_pk_add_f32 v[242:243], v[242:243], v[94:95]
	v_pk_add_f32 v[236:237], v[236:237], v[84:85]
	v_pk_add_f32 v[238:239], v[238:239], v[88:89]
	v_pk_add_f32 v[240:241], v[240:241], v[92:93]
	v_pk_add_f32 v[242:243], v[242:243], v[96:97]
	v_pk_add_f32 v[236:237], v[236:237], v[98:99]
	v_pk_add_f32 v[238:239], v[238:239], v[102:103]
	v_pk_add_f32 v[240:241], v[240:241], v[106:107]
	v_pk_add_f32 v[242:243], v[242:243], v[110:111]
	v_pk_add_f32 v[236:237], v[236:237], v[100:101]
	v_pk_add_f32 v[238:239], v[238:239], v[104:105]
	v_pk_add_f32 v[240:241], v[240:241], v[108:109]
	v_pk_add_f32 v[242:243], v[242:243], v[112:113]
	v_pk_add_f32 v[236:237], v[236:237], v[114:115]
	v_pk_add_f32 v[236:237], v[236:237], v[116:117]
	v_pk_add_f32 v[236:237], v[236:237], v[238:239]
	v_pk_add_f32 v[240:241], v[240:241], v[242:243]
	v_cndmask_b32_e64 v219, 0, v219, s[74:75]
	v_pk_add_f32 v[236:237], v[236:237], v[240:241]
	v_add_f32_e32 v185, v236, v237
	v_add_f32_e32 v185, v185, v219
	v_cvt_pk_bf16_f32 v236, v50, v51
	v_cvt_pk_bf16_f32 v237, v52, v53
	v_cvt_pk_bf16_f32 v238, v54, v55
	v_cvt_pk_bf16_f32 v239, v56, v57
	s_nop 1
	s_waitcnt lgkmcnt(14)
	v_mfma_f32_16x16x32_bf16 v[210:213], v[186:189], v[236:239], 0
	s_waitcnt lgkmcnt(12)
	v_mfma_f32_16x16x32_bf16 v[214:217], v[190:193], v[236:239], 0
	s_waitcnt lgkmcnt(10)
	v_mfma_f32_16x16x32_bf16 v[220:223], v[194:197], v[236:239], 0
	s_waitcnt lgkmcnt(8)
	v_mfma_f32_16x16x32_bf16 v[224:227], v[198:201], v[236:239], 0
	v_cvt_pk_bf16_f32 v240, v58, v59
	v_cvt_pk_bf16_f32 v241, v60, v61
	v_cvt_pk_bf16_f32 v242, v62, v63
	v_cvt_pk_bf16_f32 v243, v64, v65
	s_waitcnt lgkmcnt(7)
; #define LAS __attribute__((address_space(3)))
; __device__ __forceinline__ unsigned pk2(float lo, float hi) { return pg8::cvt_pk_bf16(lo, hi); }
; __device__ __forceinline__ s16x4 vtr(const LAS unsigned char* p) { return __builtin_bit_cast(s16x4, __builtin_amdgcn_ds_read_tr16_b64_v4i16((LAS s16x4*)p)); }
; #define MFMA16(a, b, c) __builtin_amdgcn_mfma_f32_16x16x32_bf16((a), (b), (c), 0, 0, 0)
; __device__ __forceinline__ void pv_at(const LAS unsigned char* const (&vp)[4], int off, const f32x4& P0, const f32x4& P1, f32x4 (&O)[4]) {
;     v4u pw; pw.x = pk2(P0[0], P0[1]); pw.y = pk2(P0[2], P0[3]); pw.z = pk2(P1[0], P1[1]); pw.w = pk2(P1[2], P1[3]);
;     const bf16x8 pb = __builtin_bit_cast(bf16x8, pw);
; #pragma unroll
;     for (int db = 0; db < 4; ++db) {
;         const s16x4 lo = vtr(vp[db] + off), hi = vtr(vp[db] + off + 2048);
;         const bf16x8 vt = (bf16x8){lo[0], lo[1], lo[2], lo[3], hi[0], hi[1], hi[2], hi[3]};
;         O[db] = MFMA16(vt, pb, O[db]);
;     }
; }
; template <bool MASK> __device__ __forceinline__ void a_scores(f32x4& S0, f32x4& S1, float basef, float c1, float slope2, int krow0, int kstart) {
; #pragma unroll
;     for (int r = 0; r < 4; ++r) {
;         const float d0 = fabsf(basef - (float)r), d1 = fabsf(basef - (float)(16 + r));
;         const float v0 = S0[r] - slope2 * d0, v1 = S1[r] - slope2 * d1;
;         if (MASK) { const int p0 = kstart + krow0 + r, p1 = p0 + 16;
;             S0[r] = (d0 <= 128.f && p0 >= 0 && p0 < SEQ) ? v0 : -INFINITY; S1[r] = (d1 <= 128.f && p1 >= 0 && p1 < SEQ) ? v1 : -INFINITY; }
;         else { S0[r] = v0; S1[r] = v1; }
;     }
; }
	ds_read_b64_tr_b16 v[186:187], v124 offset:12288
	ds_read_b64_tr_b16 v[188:189], v124 offset:14336
	ds_read_b64_tr_b16 v[190:191], v125 offset:12288
	ds_read_b64_tr_b16 v[192:193], v125 offset:14336
	ds_read_b64_tr_b16 v[194:195], v126 offset:12288
	ds_read_b64_tr_b16 v[196:197], v126 offset:14336
	ds_read_b64_tr_b16 v[198:199], v127 offset:12288
	ds_read_b64_tr_b16 v[200:201], v127 offset:14336
	s_bitcmp1_b32 s87, 3
	s_cselect_b32 s21, 0, 0xff800000
	v_add_f32_e32 v120, s21, v132
	v_fmamk_f32 v50, v130, 0x43000000, v120
	v_fmamk_f32 v51, v130, 0x42fe0000, v120
	v_fmamk_f32 v52, v130, 0x42fc0000, v120
	v_fmamk_f32 v53, v130, 0x42fa0000, v120
	v_mov_b32_e32 v245, 0xff800000
	v_cndmask_b32_e64 v50, v245, v50, s[16:17]
	v_cndmask_b32_e64 v51, v245, v51, s[18:19]
	v_cndmask_b32_e64 v52, v245, v52, s[22:23]
	v_cndmask_b32_e64 v53, v245, v53, s[24:25]
	s_bitcmp1_b32 s87, 4
	s_cselect_b32 s21, 0, 0xff800000
	v_add_f32_e32 v120, s21, v132
	v_fmamk_f32 v54, v130, 0x42e00000, v120
	v_fmamk_f32 v55, v130, 0x42de0000, v120
	v_fmamk_f32 v56, v130, 0x42dc0000, v120
	v_fmamk_f32 v57, v130, 0x42da0000, v120
	s_waitcnt lgkmcnt(14)
	v_mfma_f32_16x16x32_bf16 v[210:213], v[202:205], v[240:243], v[210:213]
	s_waitcnt lgkmcnt(12)
	v_mfma_f32_16x16x32_bf16 v[214:217], v[206:209], v[240:243], v[214:217]
	s_waitcnt lgkmcnt(10)
	v_mfma_f32_16x16x32_bf16 v[220:223], v[228:231], v[240:243], v[220:223]
	s_waitcnt lgkmcnt(8)
	v_mfma_f32_16x16x32_bf16 v[224:227], v[232:235], v[240:243], v[224:227]
	v_cvt_pk_bf16_f32 v236, v66, v67
	v_cvt_pk_bf16_f32 v237, v68, v69
	v_cvt_pk_bf16_f32 v238, v70, v71
	v_cvt_pk_bf16_f32 v239, v72, v73
	s_waitcnt lgkmcnt(7)
	ds_read_b64_tr_b16 v[202:203], v124 offset:16384
	ds_read_b64_tr_b16 v[204:205], v124 offset:18432
	ds_read_b64_tr_b16 v[206:207], v125 offset:16384
	ds_read_b64_tr_b16 v[208:209], v125 offset:18432
	ds_read_b64_tr_b16 v[228:229], v126 offset:16384
	ds_read_b64_tr_b16 v[230:231], v126 offset:18432
	ds_read_b64_tr_b16 v[232:233], v127 offset:16384
	ds_read_b64_tr_b16 v[234:235], v127 offset:18432
	s_bitcmp1_b32 s87, 5
	s_cselect_b32 s21, 0, 0xff800000
	v_add_f32_e32 v120, s21, v132
	v_fmamk_f32 v58, v130, 0x42c00000, v120
	v_fmamk_f32 v59, v130, 0x42be0000, v120
	v_fmamk_f32 v60, v130, 0x42bc0000, v120
	v_fmamk_f32 v61, v130, 0x42ba0000, v120
	s_bitcmp1_b32 s87, 6
	s_cselect_b32 s21, 0, 0xff800000
	v_add_f32_e32 v120, s21, v132
	v_fmamk_f32 v62, v130, 0x42a00000, v120
	v_fmamk_f32 v63, v130, 0x429e0000, v120
	v_fmamk_f32 v64, v130, 0x429c0000, v120
	v_fmamk_f32 v65, v130, 0x429a0000, v120
	s_waitcnt lgkmcnt(14)
	v_mfma_f32_16x16x32_bf16 v[210:213], v[186:189], v[236:239], v[210:213]
	s_waitcnt lgkmcnt(12)
	v_mfma_f32_16x16x32_bf16 v[214:217], v[190:193], v[236:239], v[214:217]
	s_waitcnt lgkmcnt(10)
	v_mfma_f32_16x16x32_bf16 v[220:223], v[194:197], v[236:239], v[220:223]
	s_waitcnt lgkmcnt(8)
	v_mfma_f32_16x16x32_bf16 v[224:227], v[198:201], v[236:239], v[224:227]
	v_cvt_pk_bf16_f32 v240, v74, v75
	v_cvt_pk_bf16_f32 v241, v76, v77
	v_cvt_pk_bf16_f32 v242, v78, v79
	v_cvt_pk_bf16_f32 v243, v80, v81
	s_waitcnt lgkmcnt(7)
	ds_read_b64_tr_b16 v[186:187], v124 offset:20480
	ds_read_b64_tr_b16 v[188:189], v124 offset:22528
	ds_read_b64_tr_b16 v[190:191], v125 offset:20480
	ds_read_b64_tr_b16 v[192:193], v125 offset:22528
	ds_read_b64_tr_b16 v[194:195], v126 offset:20480
	ds_read_b64_tr_b16 v[196:197], v126 offset:22528
	ds_read_b64_tr_b16 v[198:199], v127 offset:20480
	ds_read_b64_tr_b16 v[200:201], v127 offset:22528
	s_bitcmp1_b32 s87, 7
	s_cselect_b32 s21, 0, 0xff800000
	v_add_f32_e32 v120, s21, v132
	v_fmamk_f32 v66, v130, 0x42800000, v120
	v_fmamk_f32 v67, v130, 0x427c0000, v120
	v_fmamk_f32 v68, v130, 0x42780000, v120
	v_fmamk_f32 v69, v130, 0x42740000, v120
	s_bitcmp1_b32 s87, 8
	s_cselect_b32 s21, 0, 0xff800000
	v_add_f32_e32 v120, s21, v132
	v_fmamk_f32 v70, v130, 0x42400000, v120
	v_fmamk_f32 v71, v130, 0x423c0000, v120
	v_fmamk_f32 v72, v130, 0x42380000, v120
	v_fmamk_f32 v73, v130, 0x42340000, v120
	s_waitcnt lgkmcnt(14)
	v_mfma_f32_16x16x32_bf16 v[210:213], v[202:205], v[240:243], v[210:213]
	s_waitcnt lgkmcnt(12)
	v_mfma_f32_16x16x32_bf16 v[214:217], v[206:209], v[240:243], v[214:217]
	s_waitcnt lgkmcnt(10)
	v_mfma_f32_16x16x32_bf16 v[220:223], v[228:231], v[240:243], v[220:223]
	s_waitcnt lgkmcnt(8)
	v_mfma_f32_16x16x32_bf16 v[224:227], v[232:235], v[240:243], v[224:227]
	v_cvt_pk_bf16_f32 v236, v82, v83
	v_cvt_pk_bf16_f32 v237, v84, v85
	v_cvt_pk_bf16_f32 v238, v86, v87
	v_cvt_pk_bf16_f32 v239, v88, v89
	s_waitcnt lgkmcnt(7)
	ds_read_b64_tr_b16 v[202:203], v124 offset:24576
	ds_read_b64_tr_b16 v[204:205], v124 offset:26624
	ds_read_b64_tr_b16 v[206:207], v125 offset:24576
	ds_read_b64_tr_b16 v[208:209], v125 offset:26624
	ds_read_b64_tr_b16 v[228:229], v126 offset:24576
	ds_read_b64_tr_b16 v[230:231], v126 offset:26624
	ds_read_b64_tr_b16 v[232:233], v127 offset:24576
	ds_read_b64_tr_b16 v[234:235], v127 offset:26624
	s_bitcmp1_b32 s87, 9
	s_cselect_b32 s21, 0, 0xff800000
	v_add_f32_e32 v120, s21, v132
	v_fmamk_f32 v74, v130, 0x42000000, v120
	v_fmamk_f32 v75, v130, 0x41f80000, v120
	v_fmamk_f32 v76, v130, 0x41f00000, v120
	v_fmamk_f32 v77, v130, 0x41e80000, v120
	s_bitcmp1_b32 s87, 10
	s_cselect_b32 s21, 0, 0xff800000
	v_add_f32_e32 v120, s21, v132
	v_fmamk_f32 v78, v130, 0x41800000, v120
	v_fmamk_f32 v79, v130, 0x41700000, v120
	v_fmamk_f32 v80, v130, 0x41600000, v120
	v_fmamk_f32 v81, v130, 0x41500000, v120
	s_waitcnt lgkmcnt(14)
	v_mfma_f32_16x16x32_bf16 v[210:213], v[186:189], v[236:239], v[210:213]
	s_waitcnt lgkmcnt(12)
	v_mfma_f32_16x16x32_bf16 v[214:217], v[190:193], v[236:239], v[214:217]
	s_waitcnt lgkmcnt(10)
; #define LAS __attribute__((address_space(3)))
; __device__ __forceinline__ unsigned pk2(float lo, float hi) { return pg8::cvt_pk_bf16(lo, hi); }
; __device__ __forceinline__ s16x4 vtr(const LAS unsigned char* p) { return __builtin_bit_cast(s16x4, __builtin_amdgcn_ds_read_tr16_b64_v4i16((LAS s16x4*)p)); }
; #define MFMA16(a, b, c) __builtin_amdgcn_mfma_f32_16x16x32_bf16((a), (b), (c), 0, 0, 0)
; __device__ __forceinline__ void pv_at(const LAS unsigned char* const (&vp)[4], int off, const f32x4& P0, const f32x4& P1, f32x4 (&O)[4]) {
;     v4u pw; pw.x = pk2(P0[0], P0[1]); pw.y = pk2(P0[2], P0[3]); pw.z = pk2(P1[0], P1[1]); pw.w = pk2(P1[2], P1[3]);
;     const bf16x8 pb = __builtin_bit_cast(bf16x8, pw);
; #pragma unroll
;     for (int db = 0; db < 4; ++db) {
;         const s16x4 lo = vtr(vp[db] + off), hi = vtr(vp[db] + off + 2048);
;         const bf16x8 vt = (bf16x8){lo[0], lo[1], lo[2], lo[3], hi[0], hi[1], hi[2], hi[3]};
;         O[db] = MFMA16(vt, pb, O[db]);
;     }
; }
; template <bool MASK> __device__ __forceinline__ void a_scores(f32x4& S0, f32x4& S1, float basef, float c1, float slope2, int krow0, int kstart) {
; #pragma unroll
;     for (int r = 0; r < 4; ++r) {
;         const float d0 = fabsf(basef - (float)r), d1 = fabsf(basef - (float)(16 + r));
;         const float v0 = S0[r] - slope2 * d0, v1 = S1[r] - slope2 * d1;
;         if (MASK) { const int p0 = kstart + krow0 + r, p1 = p0 + 16;
;             S0[r] = (d0 <= 128.f && p0 >= 0 && p0 < SEQ) ? v0 : -INFINITY; S1[r] = (d1 <= 128.f && p1 >= 0 && p1 < SEQ) ? v1 : -INFINITY; }
;         else { S0[r] = v0; S1[r] = v1; }
;     }
; }
	v_mfma_f32_16x16x32_bf16 v[220:223], v[194:197], v[236:239], v[220:223]
	s_waitcnt lgkmcnt(8)
	v_mfma_f32_16x16x32_bf16 v[224:227], v[198:201], v[236:239], v[224:227]
	v_cvt_pk_bf16_f32 v240, v90, v91
	v_cvt_pk_bf16_f32 v241, v92, v93
	v_cvt_pk_bf16_f32 v242, v94, v95
	v_cvt_pk_bf16_f32 v243, v96, v97
	s_waitcnt lgkmcnt(7)
	ds_read_b64_tr_b16 v[186:187], v124 offset:28672
	ds_read_b64_tr_b16 v[188:189], v124 offset:30720
	ds_read_b64_tr_b16 v[190:191], v125 offset:28672
	ds_read_b64_tr_b16 v[192:193], v125 offset:30720
	ds_read_b64_tr_b16 v[194:195], v126 offset:28672
	ds_read_b64_tr_b16 v[196:197], v126 offset:30720
	ds_read_b64_tr_b16 v[198:199], v127 offset:28672
	ds_read_b64_tr_b16 v[200:201], v127 offset:30720
	s_bitcmp1_b32 s87, 11
	s_cselect_b32 s21, 0, 0xff800000
	v_add_f32_e32 v219, 0, v129
	v_fma_f32 v82, v130, |v219|, s21
	v_add_f32_e32 v245, 0xbf800000, v129
	v_fma_f32 v83, v130, |v245|, s21
	v_add_f32_e32 v219, 0xc0000000, v129
	v_fma_f32 v84, v130, |v219|, s21
	v_add_f32_e32 v245, 0xc0400000, v129
	v_fma_f32 v85, v130, |v245|, s21
	s_bitcmp1_b32 s87, 12
	s_cselect_b32 s21, 0, 0xff800000
	v_add_f32_e32 v120, s21, v133
	v_fmamk_f32 v86, v131, 0xc1800000, v120
	v_fmamk_f32 v87, v131, 0xc1880000, v120
	v_fmamk_f32 v88, v131, 0xc1900000, v120
	v_fmamk_f32 v89, v131, 0xc1980000, v120
	s_waitcnt lgkmcnt(14)
	v_mfma_f32_16x16x32_bf16 v[210:213], v[202:205], v[240:243], v[210:213]
	s_waitcnt lgkmcnt(12)
	v_mfma_f32_16x16x32_bf16 v[214:217], v[206:209], v[240:243], v[214:217]
	s_waitcnt lgkmcnt(10)
	v_mfma_f32_16x16x32_bf16 v[220:223], v[228:231], v[240:243], v[220:223]
	s_waitcnt lgkmcnt(8)
	v_mfma_f32_16x16x32_bf16 v[224:227], v[232:235], v[240:243], v[224:227]
	v_cvt_pk_bf16_f32 v236, v98, v99
	v_cvt_pk_bf16_f32 v237, v100, v101
	v_cvt_pk_bf16_f32 v238, v102, v103
	v_cvt_pk_bf16_f32 v239, v104, v105
	s_waitcnt lgkmcnt(7)
	ds_read_b64_tr_b16 v[202:203], v124 offset:32768
	ds_read_b64_tr_b16 v[204:205], v124 offset:34816
	ds_read_b64_tr_b16 v[206:207], v125 offset:32768
	ds_read_b64_tr_b16 v[208:209], v125 offset:34816
	ds_read_b64_tr_b16 v[228:229], v126 offset:32768
	ds_read_b64_tr_b16 v[230:231], v126 offset:34816
	ds_read_b64_tr_b16 v[232:233], v127 offset:32768
	ds_read_b64_tr_b16 v[234:235], v127 offset:34816
	s_bitcmp1_b32 s87, 13
	s_cselect_b32 s21, 0, 0xff800000
	v_add_f32_e32 v120, s21, v133
	v_fmamk_f32 v90, v131, 0xc2000000, v120
	v_fmamk_f32 v91, v131, 0xc2040000, v120
	v_fmamk_f32 v92, v131, 0xc2080000, v120
	v_fmamk_f32 v93, v131, 0xc20c0000, v120
	s_bitcmp1_b32 s87, 14
	s_cselect_b32 s21, 0, 0xff800000
	v_add_f32_e32 v120, s21, v133
	v_fmamk_f32 v94, v131, 0xc2400000, v120
	v_fmamk_f32 v95, v131, 0xc2440000, v120
	v_fmamk_f32 v96, v131, 0xc2480000, v120
	v_fmamk_f32 v97, v131, 0xc24c0000, v120
	s_waitcnt lgkmcnt(14)
	v_mfma_f32_16x16x32_bf16 v[210:213], v[186:189], v[236:239], v[210:213]
	s_waitcnt lgkmcnt(12)
	v_mfma_f32_16x16x32_bf16 v[214:217], v[190:193], v[236:239], v[214:217]
	s_waitcnt lgkmcnt(10)
	v_mfma_f32_16x16x32_bf16 v[220:223], v[194:197], v[236:239], v[220:223]
	s_waitcnt lgkmcnt(8)
	v_mfma_f32_16x16x32_bf16 v[224:227], v[198:201], v[236:239], v[224:227]
	v_cvt_pk_bf16_f32 v240, v106, v107
	v_cvt_pk_bf16_f32 v241, v108, v109
	v_cvt_pk_bf16_f32 v242, v110, v111
	v_cvt_pk_bf16_f32 v243, v112, v113
	s_waitcnt lgkmcnt(7)
	ds_read_b64_tr_b16 v[186:187], v124 offset:36864
	ds_read_b64_tr_b16 v[188:189], v124 offset:38912
	ds_read_b64_tr_b16 v[190:191], v125 offset:36864
	ds_read_b64_tr_b16 v[192:193], v125 offset:38912
	ds_read_b64_tr_b16 v[194:195], v126 offset:36864
	ds_read_b64_tr_b16 v[196:197], v126 offset:38912
	ds_read_b64_tr_b16 v[198:199], v127 offset:36864
	ds_read_b64_tr_b16 v[200:201], v127 offset:38912
	s_bitcmp1_b32 s87, 15
	s_cselect_b32 s21, 0, 0xff800000
	v_add_f32_e32 v120, s21, v133
	v_fmamk_f32 v98, v131, 0xc2800000, v120
	v_fmamk_f32 v99, v131, 0xc2820000, v120
	v_fmamk_f32 v100, v131, 0xc2840000, v120
	v_fmamk_f32 v101, v131, 0xc2860000, v120
	s_bitcmp1_b32 s87, 16
	s_cselect_b32 s21, 0, 0xff800000
	v_add_f32_e32 v120, s21, v133
	v_fmamk_f32 v102, v131, 0xc2a00000, v120
	v_fmamk_f32 v103, v131, 0xc2a20000, v120
	v_fmamk_f32 v104, v131, 0xc2a40000, v120
	v_fmamk_f32 v105, v131, 0xc2a60000, v120
	s_waitcnt lgkmcnt(14)
	v_mfma_f32_16x16x32_bf16 v[210:213], v[202:205], v[240:243], v[210:213]
	s_waitcnt lgkmcnt(12)
	v_mfma_f32_16x16x32_bf16 v[214:217], v[206:209], v[240:243], v[214:217]
	s_waitcnt lgkmcnt(10)
	v_mfma_f32_16x16x32_bf16 v[220:223], v[228:231], v[240:243], v[220:223]
	s_waitcnt lgkmcnt(8)
	v_mfma_f32_16x16x32_bf16 v[224:227], v[232:235], v[240:243], v[224:227]
	v_cvt_pk_bf16_f32 v236, v114, v115
	v_cvt_pk_bf16_f32 v237, v116, v117
	v_mov_b32_e32 v238, 0
	v_mov_b32_e32 v239, 0
	s_nop 1
	s_bitcmp1_b32 s87, 17
	s_cselect_b32 s21, 0, 0xff800000
	v_add_f32_e32 v120, s21, v133
	v_fmamk_f32 v106, v131, 0xc2c00000, v120
	v_fmamk_f32 v107, v131, 0xc2c20000, v120
	v_fmamk_f32 v108, v131, 0xc2c40000, v120
	v_fmamk_f32 v109, v131, 0xc2c60000, v120
	s_bitcmp1_b32 s87, 18
	s_cselect_b32 s21, 0, 0xff800000
	v_add_f32_e32 v120, s21, v133
	v_fmamk_f32 v110, v131, 0xc2e00000, v120
	v_fmamk_f32 v111, v131, 0xc2e20000, v120
	v_fmamk_f32 v112, v131, 0xc2e40000, v120
	v_fmamk_f32 v113, v131, 0xc2e60000, v120
	s_waitcnt lgkmcnt(6)
	v_mfma_f32_16x16x32_bf16 v[210:213], v[186:189], v[236:239], v[210:213]
	s_waitcnt lgkmcnt(4)
	v_mfma_f32_16x16x32_bf16 v[214:217], v[190:193], v[236:239], v[214:217]
	s_waitcnt lgkmcnt(2)
	v_mfma_f32_16x16x32_bf16 v[220:223], v[194:197], v[236:239], v[220:223]
	s_waitcnt lgkmcnt(0)
; #define LAS __attribute__((address_space(3)))
; __device__ __forceinline__ unsigned pk2(float lo, float hi) { return pg8::cvt_pk_bf16(lo, hi); }
; #define MFMA16(a, b, c) __builtin_amdgcn_mfma_f32_16x16x32_bf16((a), (b), (c), 0, 0, 0)
; __device__ __forceinline__ void qk_at(const LAS unsigned char* kp0, const LAS unsigned char* kp1, int off, bf16x8 qf0, bf16x8 qf1, f32x4& S0, f32x4& S1) {
;     const bf16x8 k00 = *(const LAS bf16x8*)(kp0 + off), k01 = *(const LAS bf16x8*)(kp1 + off);
;     const bf16x8 k10 = *(const LAS bf16x8*)(kp0 + off + 2048), k11 = *(const LAS bf16x8*)(kp1 + off + 2048);
;     const f32x4 z = {0.f, 0.f, 0.f, 0.f};
;     S0 = MFMA16(k00, qf0, z); S0 = MFMA16(k01, qf1, S0);
;     S1 = MFMA16(k10, qf0, z); S1 = MFMA16(k11, qf1, S1);
; }
; __device__ __forceinline__ void store_o(bf16* yrow, int g, float l, const f32x4 (&O)[4]) {
;     const float inv = 1.0f / xrow16_sum(l);
;     unsigned wx[4], wy[4];
; #pragma unroll
;     for (int db = 0; db < 4; ++db) { wx[db] = pk2(O[db][0] * inv, O[db][1] * inv); wy[db] = pk2(O[db][2] * inv, O[db][3] * inv); }
; #pragma unroll
;     for (int p = 0; p < 2; ++p) {
;         auto rx = __builtin_amdgcn_permlane16_swap(wx[2 * p], wx[2 * p + 1], false, false); wx[2 * p] = rx[0]; wx[2 * p + 1] = rx[1];
;         auto ry = __builtin_amdgcn_permlane16_swap(wy[2 * p], wy[2 * p + 1], false, false); wy[2 * p] = ry[0]; wy[2 * p + 1] = ry[1]; }
; #pragma unroll
;     for (int p = 0; p < 2; ++p) {
;         auto rx = __builtin_amdgcn_permlane32_swap(wx[p], wx[p + 2], false, false); wx[p] = rx[0]; wx[p + 2] = rx[1];
;         auto ry = __builtin_amdgcn_permlane32_swap(wy[p], wy[p + 2], false, false); wy[p] = ry[0]; wy[p + 2] = ry[1]; }
;     v4u lo = {wx[0], wy[0], wx[1], wy[1]}, hi = {wx[2], wy[2], wx[3], wy[3]};
;     *(v4u*)(yrow + 16 * g) = lo; *(v4u*)(yrow + 16 * g + 8) = hi;
	v_mfma_f32_16x16x32_bf16 v[224:227], v[198:201], v[236:239], v[224:227]
	s_bitcmp1_b32 s87, 19
	s_cselect_b32 s21, 0, 0xff800000
	v_add_f32_e32 v120, s21, v133
	v_fmamk_f32 v114, v131, 0xc3000000, v120
	v_fmamk_f32 v115, v131, 0xc3010000, v120
	v_fmamk_f32 v116, v131, 0xc3020000, v120
	v_fmamk_f32 v117, v131, 0xc3030000, v120
	v_mov_b32_e32 v245, 0xff800000
	v_cndmask_b32_e64 v114, v245, v114, s[28:29]
	v_cndmask_b32_e64 v115, v245, v115, s[52:53]
	v_cndmask_b32_e64 v116, v245, v116, s[54:55]
	v_cndmask_b32_e64 v117, v245, v117, s[88:89]
	v_mov_b32_e32 v219, v185
	s_nop 1
	v_permlane16_swap_b32_e32 v185, v219
	v_add_f32_e32 v185, v185, v219
	v_mov_b32_e32 v219, v185
	s_nop 1
	v_permlane32_swap_b32_e32 v185, v219
	v_add_f32_e32 v185, v185, v219
	v_div_scale_f32 v236, s[78:79], v185, v185, 1.0
	v_div_scale_f32 v237, vcc, 1.0, v185, 1.0
	v_rcp_f32_e32 v238, v236
	s_nop 0
	v_fma_f32 v239, -v236, v238, 1.0
	v_fmac_f32_e32 v238, v239, v238
	v_mul_f32_e32 v240, v237, v238
	v_fma_f32 v241, -v236, v240, v237
	v_fmac_f32_e32 v240, v241, v238
	v_fma_f32 v237, -v236, v240, v237
	v_div_fmas_f32 v237, v237, v238, v240
	v_div_fixup_f32 v244, v237, v185, 1.0
	v_mul_f32_e32 v240, v210, v244
	v_mul_f32_e32 v241, v211, v244
	v_mul_f32_e32 v242, v212, v244
	v_mul_f32_e32 v243, v213, v244
	v_cvt_pk_bf16_f32 v186, v240, v241
	v_cvt_pk_bf16_f32 v187, v242, v243
	v_mul_f32_e32 v240, v214, v244
	v_mul_f32_e32 v241, v215, v244
	v_mul_f32_e32 v242, v216, v244
	v_mul_f32_e32 v243, v217, v244
	v_cvt_pk_bf16_f32 v188, v240, v241
	v_cvt_pk_bf16_f32 v189, v242, v243
	v_mul_f32_e32 v240, v220, v244
	v_mul_f32_e32 v241, v221, v244
	v_mul_f32_e32 v242, v222, v244
	v_mul_f32_e32 v243, v223, v244
	v_cvt_pk_bf16_f32 v190, v240, v241
	v_cvt_pk_bf16_f32 v191, v242, v243
	v_mul_f32_e32 v240, v224, v244
	v_mul_f32_e32 v241, v225, v244
	v_mul_f32_e32 v242, v226, v244
	v_mul_f32_e32 v243, v227, v244
	v_cvt_pk_bf16_f32 v192, v240, v241
	v_cvt_pk_bf16_f32 v193, v242, v243
	s_nop 1
	v_permlane16_swap_b32_e32 v186, v188
	v_permlane16_swap_b32_e32 v187, v189
	v_permlane16_swap_b32_e32 v190, v192
	v_permlane16_swap_b32_e32 v191, v193
	s_nop 0
	v_permlane32_swap_b32_e32 v186, v190
	v_permlane32_swap_b32_e32 v187, v191
	v_permlane32_swap_b32_e32 v188, v192
	v_permlane32_swap_b32_e32 v189, v193
	v_add_u32_e32 v219, 0x1000, v128
	global_store_dwordx4 v219, v[186:189], s[82:83] offset:0
	global_store_dwordx4 v219, v[190:193], s[82:83] offset:16
	s_nop 1
	ds_read_b128 v[186:189], v122 offset:6144
	ds_read_b128 v[190:193], v123 offset:6144
	ds_read_b128 v[194:197], v122 offset:8192
	ds_read_b128 v[198:201], v123 offset:8192
	ds_read_b128 v[202:205], v122 offset:10240
	ds_read_b128 v[206:209], v123 offset:10240
	ds_read_b128 v[210:213], v122 offset:12288
	ds_read_b128 v[214:217], v123 offset:12288
	ds_read_b128 v[220:223], v122 offset:14336
	ds_read_b128 v[224:227], v123 offset:14336
	ds_read_b128 v[228:231], v122 offset:16384
	ds_read_b128 v[232:235], v123 offset:16384
	ds_read_b128 v[236:239], v122 offset:18432
	ds_read_b128 v[240:243], v123 offset:18432
	s_waitcnt lgkmcnt(13)
	v_mfma_f32_16x16x32_bf16 v[50:53], v[186:189], v[170:173], v[50:53]
	s_waitcnt lgkmcnt(12)
	v_mfma_f32_16x16x32_bf16 v[50:53], v[190:193], v[174:177], v[50:53]
	ds_read_b128 v[186:189], v122 offset:20480
	ds_read_b128 v[190:193], v123 offset:20480
	s_waitcnt lgkmcnt(13)
	v_mfma_f32_16x16x32_bf16 v[54:57], v[194:197], v[170:173], v[54:57]
	s_waitcnt lgkmcnt(12)
	v_mfma_f32_16x16x32_bf16 v[54:57], v[198:201], v[174:177], v[54:57]
	ds_read_b128 v[194:197], v122 offset:22528
	ds_read_b128 v[198:201], v123 offset:22528
	s_waitcnt lgkmcnt(13)
	v_mfma_f32_16x16x32_bf16 v[58:61], v[202:205], v[170:173], v[58:61]
	s_waitcnt lgkmcnt(12)
	v_mfma_f32_16x16x32_bf16 v[58:61], v[206:209], v[174:177], v[58:61]
	ds_read_b128 v[202:205], v122 offset:24576
	ds_read_b128 v[206:209], v123 offset:24576
	s_waitcnt lgkmcnt(13)
	v_mfma_f32_16x16x32_bf16 v[62:65], v[210:213], v[170:173], v[62:65]
	s_waitcnt lgkmcnt(12)
	v_mfma_f32_16x16x32_bf16 v[62:65], v[214:217], v[174:177], v[62:65]
	ds_read_b128 v[210:213], v122 offset:26624
	ds_read_b128 v[214:217], v123 offset:26624
	s_waitcnt lgkmcnt(13)
	v_mfma_f32_16x16x32_bf16 v[66:69], v[220:223], v[170:173], v[66:69]
	s_waitcnt lgkmcnt(12)
	v_mfma_f32_16x16x32_bf16 v[66:69], v[224:227], v[174:177], v[66:69]
	ds_read_b128 v[220:223], v122 offset:28672
	ds_read_b128 v[224:227], v123 offset:28672
	s_waitcnt lgkmcnt(13)
	v_mfma_f32_16x16x32_bf16 v[70:73], v[228:231], v[170:173], v[70:73]
	s_waitcnt lgkmcnt(12)
	v_mfma_f32_16x16x32_bf16 v[70:73], v[232:235], v[174:177], v[70:73]
	ds_read_b128 v[228:231], v122 offset:30720
	ds_read_b128 v[232:235], v123 offset:30720
	s_waitcnt lgkmcnt(13)
	v_mfma_f32_16x16x32_bf16 v[74:77], v[236:239], v[170:173], v[74:77]
	s_waitcnt lgkmcnt(12)
	v_mfma_f32_16x16x32_bf16 v[74:77], v[240:243], v[174:177], v[74:77]
	ds_read_b128 v[236:239], v122 offset:32768
	ds_read_b128 v[240:243], v123 offset:32768
	s_waitcnt lgkmcnt(13)
	v_mfma_f32_16x16x32_bf16 v[78:81], v[186:189], v[170:173], v[78:81]
	s_waitcnt lgkmcnt(12)
	v_mfma_f32_16x16x32_bf16 v[78:81], v[190:193], v[174:177], v[78:81]
	ds_read_b128 v[186:189], v122 offset:34816
	ds_read_b128 v[190:193], v123 offset:34816
	s_waitcnt lgkmcnt(13)
	v_mfma_f32_16x16x32_bf16 v[82:85], v[194:197], v[170:173], v[82:85]
	s_waitcnt lgkmcnt(12)
	v_mfma_f32_16x16x32_bf16 v[82:85], v[198:201], v[174:177], v[82:85]
	ds_read_b128 v[194:197], v122 offset:36864
	ds_read_b128 v[198:201], v123 offset:36864
	s_waitcnt lgkmcnt(13)
	v_mfma_f32_16x16x32_bf16 v[86:89], v[202:205], v[170:173], v[86:89]
	s_waitcnt lgkmcnt(12)
; #define LAS __attribute__((address_space(3)))
; #define MFMA16(a, b, c) __builtin_amdgcn_mfma_f32_16x16x32_bf16((a), (b), (c), 0, 0, 0)
; __device__ __forceinline__ void qk_at(const LAS unsigned char* kp0, const LAS unsigned char* kp1, int off, bf16x8 qf0, bf16x8 qf1, f32x4& S0, f32x4& S1) {
;     const bf16x8 k00 = *(const LAS bf16x8*)(kp0 + off), k01 = *(const LAS bf16x8*)(kp1 + off);
;     const bf16x8 k10 = *(const LAS bf16x8*)(kp0 + off + 2048), k11 = *(const LAS bf16x8*)(kp1 + off + 2048);
;     const f32x4 z = {0.f, 0.f, 0.f, 0.f};
;     S0 = MFMA16(k00, qf0, z); S0 = MFMA16(k01, qf1, S0);
;     S1 = MFMA16(k10, qf0, z); S1 = MFMA16(k11, qf1, S1);
; }
; __device__ __forceinline__ void softmax_step(f32x4& s0, f32x4& s1, float& m, float& l, f32x4 (&O)[4]) {
;     float t = fmaxf(fmaxf(fmaxf(s0[0], s0[1]), fmaxf(s0[2], s0[3])), fmaxf(fmaxf(s1[0], s1[1]), fmaxf(s1[2], s1[3])));
;     t = xrow16_max(t);
;     const float mn = fmaxf(m, t), alpha = __builtin_amdgcn_exp2f(m - mn);
;     m = mn;
	v_mfma_f32_16x16x32_bf16 v[86:89], v[206:209], v[174:177], v[86:89]
	ds_read_b128 v[202:205], v122 offset:38912
	ds_read_b128 v[206:209], v123 offset:38912
	s_waitcnt lgkmcnt(13)
	v_mfma_f32_16x16x32_bf16 v[90:93], v[210:213], v[170:173], v[90:93]
	s_waitcnt lgkmcnt(12)
	v_mfma_f32_16x16x32_bf16 v[90:93], v[214:217], v[174:177], v[90:93]
	s_waitcnt lgkmcnt(11)
	v_mfma_f32_16x16x32_bf16 v[94:97], v[220:223], v[170:173], v[94:97]
	s_waitcnt lgkmcnt(10)
	v_mfma_f32_16x16x32_bf16 v[94:97], v[224:227], v[174:177], v[94:97]
	s_waitcnt lgkmcnt(9)
	v_mfma_f32_16x16x32_bf16 v[98:101], v[228:231], v[170:173], v[98:101]
	s_waitcnt lgkmcnt(8)
	v_mfma_f32_16x16x32_bf16 v[98:101], v[232:235], v[174:177], v[98:101]
	s_waitcnt lgkmcnt(7)
	v_mfma_f32_16x16x32_bf16 v[102:105], v[236:239], v[170:173], v[102:105]
	s_waitcnt lgkmcnt(6)
	v_mfma_f32_16x16x32_bf16 v[102:105], v[240:243], v[174:177], v[102:105]
	s_waitcnt lgkmcnt(5)
	v_mfma_f32_16x16x32_bf16 v[106:109], v[186:189], v[170:173], v[106:109]
	s_waitcnt lgkmcnt(4)
	v_mfma_f32_16x16x32_bf16 v[106:109], v[190:193], v[174:177], v[106:109]
	s_waitcnt lgkmcnt(3)
	v_mfma_f32_16x16x32_bf16 v[110:113], v[194:197], v[170:173], v[110:113]
	s_waitcnt lgkmcnt(2)
	v_mfma_f32_16x16x32_bf16 v[110:113], v[198:201], v[174:177], v[110:113]
	s_waitcnt lgkmcnt(1)
	v_mfma_f32_16x16x32_bf16 v[114:117], v[202:205], v[170:173], v[114:117]
	s_waitcnt lgkmcnt(0)
	v_mfma_f32_16x16x32_bf16 v[114:117], v[206:209], v[174:177], v[114:117]
	v_max3_f32 v219, v50, v51, v52
	v_max3_f32 v244, v54, v55, v56
	v_max3_f32 v245, v58, v59, v60
	v_max3_f32 v120, v62, v63, v64
	v_max3_f32 v219, v219, v53, v66
	v_max3_f32 v244, v244, v57, v70
	v_max3_f32 v245, v245, v61, v74
	v_max3_f32 v120, v120, v65, v78
	v_max3_f32 v219, v219, v67, v68
	v_max3_f32 v244, v244, v71, v72
	v_max3_f32 v245, v245, v75, v76
	v_max3_f32 v120, v120, v79, v80
	ds_read_b64_tr_b16 v[186:187], v124 offset:6144
	ds_read_b64_tr_b16 v[188:189], v124 offset:8192
	ds_read_b64_tr_b16 v[190:191], v125 offset:6144
	ds_read_b64_tr_b16 v[192:193], v125 offset:8192
	ds_read_b64_tr_b16 v[194:195], v126 offset:6144
	ds_read_b64_tr_b16 v[196:197], v126 offset:8192
	ds_read_b64_tr_b16 v[198:199], v127 offset:6144
	ds_read_b64_tr_b16 v[200:201], v127 offset:8192
	v_max3_f32 v219, v219, v69, v82
	v_max3_f32 v244, v244, v73, v86
	v_max3_f32 v245, v245, v77, v90
	v_max3_f32 v120, v120, v81, v94
	v_max3_f32 v219, v219, v83, v84
	v_max3_f32 v244, v244, v87, v88
	v_max3_f32 v245, v245, v91, v92
	v_max3_f32 v120, v120, v95, v96
	v_max3_f32 v219, v219, v85, v98
	v_max3_f32 v244, v244, v89, v102
	v_max3_f32 v245, v245, v93, v106
	v_max3_f32 v120, v120, v97, v110
	v_max3_f32 v219, v219, v99, v100
	v_max3_f32 v244, v244, v103, v104
	v_max3_f32 v245, v245, v107, v108
	v_max3_f32 v120, v120, v111, v112
	v_max3_f32 v219, v219, v101, v114
	v_max3_f32 v219, v219, v115, v116
	v_max_f32_e32 v219, v219, v117
	v_max_f32_e32 v244, v244, v105
	v_max_f32_e32 v245, v245, v109
	v_max_f32_e32 v120, v120, v113
	v_max3_f32 v178, v219, v244, v245
	v_max_f32_e32 v178, v178, v120
	v_mov_b32_e32 v219, v178
	s_nop 1
	v_permlane16_swap_b32_e32 v178, v219
	v_max_f32_e32 v178, v178, v219
	v_mov_b32_e32 v219, v178
	s_nop 1
	v_permlane32_swap_b32_e32 v178, v219
	v_max3_f32 v178, v178, v219, v145
	s_waitcnt lgkmcnt(7)
	ds_read_b64_tr_b16 v[202:203], v124 offset:10240
	ds_read_b64_tr_b16 v[204:205], v124 offset:12288
	ds_read_b64_tr_b16 v[206:207], v125 offset:10240
	ds_read_b64_tr_b16 v[208:209], v125 offset:12288
	ds_read_b64_tr_b16 v[228:229], v126 offset:10240
	ds_read_b64_tr_b16 v[230:231], v126 offset:12288
	ds_read_b64_tr_b16 v[232:233], v127 offset:10240
	ds_read_b64_tr_b16 v[234:235], v127 offset:12288
	v_mov_b32_e32 v244, v178
	v_pk_add_f32 v[50:51], v[50:51], v[244:245] op_sel_hi:[1,0] neg_lo:[0,1] neg_hi:[0,1]
	v_pk_add_f32 v[52:53], v[52:53], v[244:245] op_sel_hi:[1,0] neg_lo:[0,1] neg_hi:[0,1]
	v_pk_add_f32 v[54:55], v[54:55], v[244:245] op_sel_hi:[1,0] neg_lo:[0,1] neg_hi:[0,1]
	v_pk_add_f32 v[56:57], v[56:57], v[244:245] op_sel_hi:[1,0] neg_lo:[0,1] neg_hi:[0,1]
	v_pk_add_f32 v[58:59], v[58:59], v[244:245] op_sel_hi:[1,0] neg_lo:[0,1] neg_hi:[0,1]
	v_pk_add_f32 v[60:61], v[60:61], v[244:245] op_sel_hi:[1,0] neg_lo:[0,1] neg_hi:[0,1]
	v_pk_add_f32 v[62:63], v[62:63], v[244:245] op_sel_hi:[1,0] neg_lo:[0,1] neg_hi:[0,1]
	v_pk_add_f32 v[64:65], v[64:65], v[244:245] op_sel_hi:[1,0] neg_lo:[0,1] neg_hi:[0,1]
	v_pk_add_f32 v[66:67], v[66:67], v[244:245] op_sel_hi:[1,0] neg_lo:[0,1] neg_hi:[0,1]
	v_pk_add_f32 v[68:69], v[68:69], v[244:245] op_sel_hi:[1,0] neg_lo:[0,1] neg_hi:[0,1]
	v_pk_add_f32 v[70:71], v[70:71], v[244:245] op_sel_hi:[1,0] neg_lo:[0,1] neg_hi:[0,1]
	v_pk_add_f32 v[72:73], v[72:73], v[244:245] op_sel_hi:[1,0] neg_lo:[0,1] neg_hi:[0,1]
	v_pk_add_f32 v[74:75], v[74:75], v[244:245] op_sel_hi:[1,0] neg_lo:[0,1] neg_hi:[0,1]
	v_pk_add_f32 v[76:77], v[76:77], v[244:245] op_sel_hi:[1,0] neg_lo:[0,1] neg_hi:[0,1]
	v_pk_add_f32 v[78:79], v[78:79], v[244:245] op_sel_hi:[1,0] neg_lo:[0,1] neg_hi:[0,1]
	v_pk_add_f32 v[80:81], v[80:81], v[244:245] op_sel_hi:[1,0] neg_lo:[0,1] neg_hi:[0,1]
	v_pk_add_f32 v[82:83], v[82:83], v[244:245] op_sel_hi:[1,0] neg_lo:[0,1] neg_hi:[0,1]
	v_pk_add_f32 v[84:85], v[84:85], v[244:245] op_sel_hi:[1,0] neg_lo:[0,1] neg_hi:[0,1]
	v_pk_add_f32 v[86:87], v[86:87], v[244:245] op_sel_hi:[1,0] neg_lo:[0,1] neg_hi:[0,1]
	v_pk_add_f32 v[88:89], v[88:89], v[244:245] op_sel_hi:[1,0] neg_lo:[0,1] neg_hi:[0,1]
	v_pk_add_f32 v[90:91], v[90:91], v[244:245] op_sel_hi:[1,0] neg_lo:[0,1] neg_hi:[0,1]
	v_pk_add_f32 v[92:93], v[92:93], v[244:245] op_sel_hi:[1,0] neg_lo:[0,1] neg_hi:[0,1]
; __device__ __forceinline__ unsigned pk2(float lo, float hi) { return pg8::cvt_pk_bf16(lo, hi); }
; __device__ __forceinline__ void pv_at(const LAS unsigned char* const (&vp)[4], int off, const f32x4& P0, const f32x4& P1, f32x4 (&O)[4]) {
;     v4u pw; pw.x = pk2(P0[0], P0[1]); pw.y = pk2(P0[2], P0[3]); pw.z = pk2(P1[0], P1[1]); pw.w = pk2(P1[2], P1[3]);
;     const bf16x8 pb = __builtin_bit_cast(bf16x8, pw);
; __device__ __forceinline__ void softmax_step(f32x4& s0, f32x4& s1, float& m, float& l, f32x4 (&O)[4]) {
;     float t = fmaxf(fmaxf(fmaxf(s0[0], s0[1]), fmaxf(s0[2], s0[3])), fmaxf(fmaxf(s1[0], s1[1]), fmaxf(s1[2], s1[3])));
;     t = xrow16_max(t);
;     const float mn = fmaxf(m, t), alpha = __builtin_amdgcn_exp2f(m - mn);
;     m = mn;
; #pragma unroll
;     for (int k = 0; k < 4; ++k) { s0[k] = __builtin_amdgcn_exp2f(s0[k] - mn); s1[k] = __builtin_amdgcn_exp2f(s1[k] - mn); }
;     l = l * alpha + ((s0[0] + s0[1]) + (s0[2] + s0[3])) + ((s1[0] + s1[1]) + (s1[2] + s1[3]));
; #pragma unroll
;     for (int db = 0; db < 4; ++db) O[db] *= alpha;
; }
	v_pk_add_f32 v[94:95], v[94:95], v[244:245] op_sel_hi:[1,0] neg_lo:[0,1] neg_hi:[0,1]
	v_pk_add_f32 v[96:97], v[96:97], v[244:245] op_sel_hi:[1,0] neg_lo:[0,1] neg_hi:[0,1]
	v_pk_add_f32 v[98:99], v[98:99], v[244:245] op_sel_hi:[1,0] neg_lo:[0,1] neg_hi:[0,1]
	v_pk_add_f32 v[100:101], v[100:101], v[244:245] op_sel_hi:[1,0] neg_lo:[0,1] neg_hi:[0,1]
	v_pk_add_f32 v[102:103], v[102:103], v[244:245] op_sel_hi:[1,0] neg_lo:[0,1] neg_hi:[0,1]
	v_pk_add_f32 v[104:105], v[104:105], v[244:245] op_sel_hi:[1,0] neg_lo:[0,1] neg_hi:[0,1]
	v_pk_add_f32 v[106:107], v[106:107], v[244:245] op_sel_hi:[1,0] neg_lo:[0,1] neg_hi:[0,1]
	v_pk_add_f32 v[108:109], v[108:109], v[244:245] op_sel_hi:[1,0] neg_lo:[0,1] neg_hi:[0,1]
	v_pk_add_f32 v[110:111], v[110:111], v[244:245] op_sel_hi:[1,0] neg_lo:[0,1] neg_hi:[0,1]
	v_pk_add_f32 v[112:113], v[112:113], v[244:245] op_sel_hi:[1,0] neg_lo:[0,1] neg_hi:[0,1]
	v_pk_add_f32 v[114:115], v[114:115], v[244:245] op_sel_hi:[1,0] neg_lo:[0,1] neg_hi:[0,1]
	v_pk_add_f32 v[116:117], v[116:117], v[244:245] op_sel_hi:[1,0] neg_lo:[0,1] neg_hi:[0,1]
	v_sub_f32_e32 v219, v145, v178
	v_exp_f32_e32 v50, v50
	v_exp_f32_e32 v51, v51
	v_exp_f32_e32 v52, v52
	v_exp_f32_e32 v53, v53
	v_exp_f32_e32 v54, v54
	v_exp_f32_e32 v55, v55
	v_exp_f32_e32 v56, v56
	v_exp_f32_e32 v57, v57
	v_exp_f32_e32 v58, v58
	v_exp_f32_e32 v59, v59
	v_exp_f32_e32 v60, v60
	v_exp_f32_e32 v61, v61
	v_exp_f32_e32 v62, v62
	v_exp_f32_e32 v63, v63
	v_exp_f32_e32 v64, v64
	v_exp_f32_e32 v65, v65
	v_exp_f32_e32 v66, v66
	v_exp_f32_e32 v67, v67
	v_exp_f32_e32 v68, v68
	v_exp_f32_e32 v69, v69
	v_exp_f32_e32 v70, v70
	v_exp_f32_e32 v71, v71
	v_exp_f32_e32 v72, v72
	v_exp_f32_e32 v73, v73
	v_exp_f32_e32 v74, v74
	v_exp_f32_e32 v75, v75
	v_exp_f32_e32 v76, v76
	v_exp_f32_e32 v77, v77
	v_exp_f32_e32 v78, v78
	v_exp_f32_e32 v79, v79
	v_exp_f32_e32 v80, v80
	v_exp_f32_e32 v81, v81
	v_exp_f32_e32 v82, v82
	v_exp_f32_e32 v83, v83
	v_exp_f32_e32 v84, v84
	v_exp_f32_e32 v85, v85
	v_exp_f32_e32 v86, v86
	v_exp_f32_e32 v87, v87
	v_exp_f32_e32 v88, v88
	v_exp_f32_e32 v89, v89
	v_exp_f32_e32 v90, v90
	v_exp_f32_e32 v91, v91
	v_exp_f32_e32 v92, v92
	v_exp_f32_e32 v93, v93
	v_exp_f32_e32 v94, v94
	v_exp_f32_e32 v95, v95
	v_exp_f32_e32 v96, v96
	v_exp_f32_e32 v97, v97
	v_exp_f32_e32 v98, v98
	v_exp_f32_e32 v99, v99
	v_exp_f32_e32 v100, v100
	v_exp_f32_e32 v101, v101
	v_exp_f32_e32 v102, v102
	v_exp_f32_e32 v103, v103
	v_exp_f32_e32 v104, v104
	v_exp_f32_e32 v105, v105
	v_exp_f32_e32 v106, v106
	v_exp_f32_e32 v107, v107
	v_exp_f32_e32 v108, v108
	v_exp_f32_e32 v109, v109
	v_exp_f32_e32 v110, v110
	v_exp_f32_e32 v111, v111
	v_exp_f32_e32 v112, v112
	v_exp_f32_e32 v113, v113
	v_exp_f32_e32 v114, v114
	v_exp_f32_e32 v115, v115
	v_exp_f32_e32 v116, v116
	v_exp_f32_e32 v117, v117
	v_exp_f32_e32 v219, v219
	v_pk_add_f32 v[236:237], v[50:51], v[52:53]
	v_pk_add_f32 v[238:239], v[54:55], v[56:57]
	v_pk_add_f32 v[240:241], v[58:59], v[60:61]
	v_pk_add_f32 v[242:243], v[62:63], v[64:65]
	v_pk_add_f32 v[236:237], v[236:237], v[66:67]
	v_pk_add_f32 v[238:239], v[238:239], v[70:71]
	v_pk_add_f32 v[240:241], v[240:241], v[74:75]
	v_pk_add_f32 v[242:243], v[242:243], v[78:79]
	v_pk_add_f32 v[236:237], v[236:237], v[68:69]
	v_pk_add_f32 v[238:239], v[238:239], v[72:73]
	v_pk_add_f32 v[240:241], v[240:241], v[76:77]
	v_pk_add_f32 v[242:243], v[242:243], v[80:81]
	v_pk_add_f32 v[236:237], v[236:237], v[82:83]
	v_pk_add_f32 v[238:239], v[238:239], v[86:87]
	v_pk_add_f32 v[240:241], v[240:241], v[90:91]
	v_pk_add_f32 v[242:243], v[242:243], v[94:95]
	v_pk_add_f32 v[236:237], v[236:237], v[84:85]
	v_pk_add_f32 v[238:239], v[238:239], v[88:89]
	v_pk_add_f32 v[240:241], v[240:241], v[92:93]
	v_pk_add_f32 v[242:243], v[242:243], v[96:97]
	v_pk_add_f32 v[236:237], v[236:237], v[98:99]
	v_pk_add_f32 v[238:239], v[238:239], v[102:103]
	v_pk_add_f32 v[240:241], v[240:241], v[106:107]
	v_pk_add_f32 v[242:243], v[242:243], v[110:111]
	v_pk_add_f32 v[236:237], v[236:237], v[100:101]
	v_pk_add_f32 v[238:239], v[238:239], v[104:105]
	v_pk_add_f32 v[240:241], v[240:241], v[108:109]
	v_pk_add_f32 v[242:243], v[242:243], v[112:113]
	v_pk_add_f32 v[236:237], v[236:237], v[114:115]
	v_pk_add_f32 v[236:237], v[236:237], v[116:117]
	v_pk_add_f32 v[236:237], v[236:237], v[238:239]
	v_pk_add_f32 v[240:241], v[240:241], v[242:243]
	v_cndmask_b32_e64 v219, 0, v219, s[74:75]
	v_pk_add_f32 v[236:237], v[236:237], v[240:241]
	v_add_f32_e32 v185, v236, v237
	v_add_f32_e32 v185, v185, v219
	v_cvt_pk_bf16_f32 v236, v50, v51
	v_cvt_pk_bf16_f32 v237, v52, v53
	v_cvt_pk_bf16_f32 v238, v54, v55
	v_cvt_pk_bf16_f32 v239, v56, v57
	s_nop 1
	s_waitcnt lgkmcnt(14)
	v_mfma_f32_16x16x32_bf16 v[210:213], v[186:189], v[236:239], 0
	s_waitcnt lgkmcnt(12)
	v_mfma_f32_16x16x32_bf16 v[214:217], v[190:193], v[236:239], 0
	s_waitcnt lgkmcnt(10)
	v_mfma_f32_16x16x32_bf16 v[220:223], v[194:197], v[236:239], 0
	s_waitcnt lgkmcnt(8)
	v_mfma_f32_16x16x32_bf16 v[224:227], v[198:201], v[236:239], 0
	v_cvt_pk_bf16_f32 v240, v58, v59
	v_cvt_pk_bf16_f32 v241, v60, v61
	v_cvt_pk_bf16_f32 v242, v62, v63
	v_cvt_pk_bf16_f32 v243, v64, v65
	s_waitcnt lgkmcnt(7)
	ds_read_b64_tr_b16 v[186:187], v124 offset:14336
	ds_read_b64_tr_b16 v[188:189], v124 offset:16384
	ds_read_b64_tr_b16 v[190:191], v125 offset:14336
	ds_read_b64_tr_b16 v[192:193], v125 offset:16384
	ds_read_b64_tr_b16 v[194:195], v126 offset:14336
	ds_read_b64_tr_b16 v[196:197], v126 offset:16384
	ds_read_b64_tr_b16 v[198:199], v127 offset:14336
	ds_read_b64_tr_b16 v[200:201], v127 offset:16384
	s_waitcnt lgkmcnt(14)
	v_mfma_f32_16x16x32_bf16 v[210:213], v[202:205], v[240:243], v[210:213]
	s_waitcnt lgkmcnt(12)
; #define LAS __attribute__((address_space(3)))
; __device__ __forceinline__ unsigned pk2(float lo, float hi) { return pg8::cvt_pk_bf16(lo, hi); }
; __device__ __forceinline__ s16x4 vtr(const LAS unsigned char* p) { return __builtin_bit_cast(s16x4, __builtin_amdgcn_ds_read_tr16_b64_v4i16((LAS s16x4*)p)); }
; #define MFMA16(a, b, c) __builtin_amdgcn_mfma_f32_16x16x32_bf16((a), (b), (c), 0, 0, 0)
; __device__ __forceinline__ void pv_at(const LAS unsigned char* const (&vp)[4], int off, const f32x4& P0, const f32x4& P1, f32x4 (&O)[4]) {
;     v4u pw; pw.x = pk2(P0[0], P0[1]); pw.y = pk2(P0[2], P0[3]); pw.z = pk2(P1[0], P1[1]); pw.w = pk2(P1[2], P1[3]);
;     const bf16x8 pb = __builtin_bit_cast(bf16x8, pw);
; #pragma unroll
;     for (int db = 0; db < 4; ++db) {
;         const s16x4 lo = vtr(vp[db] + off), hi = vtr(vp[db] + off + 2048);
;         const bf16x8 vt = (bf16x8){lo[0], lo[1], lo[2], lo[3], hi[0], hi[1], hi[2], hi[3]};
;         O[db] = MFMA16(vt, pb, O[db]);
;     }
; }
	v_mfma_f32_16x16x32_bf16 v[214:217], v[206:209], v[240:243], v[214:217]
	s_waitcnt lgkmcnt(10)
	v_mfma_f32_16x16x32_bf16 v[220:223], v[228:231], v[240:243], v[220:223]
	s_waitcnt lgkmcnt(8)
	v_mfma_f32_16x16x32_bf16 v[224:227], v[232:235], v[240:243], v[224:227]
	v_cvt_pk_bf16_f32 v236, v66, v67
	v_cvt_pk_bf16_f32 v237, v68, v69
	v_cvt_pk_bf16_f32 v238, v70, v71
	v_cvt_pk_bf16_f32 v239, v72, v73
	s_waitcnt lgkmcnt(7)
	ds_read_b64_tr_b16 v[202:203], v124 offset:18432
	ds_read_b64_tr_b16 v[204:205], v124 offset:20480
	ds_read_b64_tr_b16 v[206:207], v125 offset:18432
	ds_read_b64_tr_b16 v[208:209], v125 offset:20480
	ds_read_b64_tr_b16 v[228:229], v126 offset:18432
	ds_read_b64_tr_b16 v[230:231], v126 offset:20480
	ds_read_b64_tr_b16 v[232:233], v127 offset:18432
	ds_read_b64_tr_b16 v[234:235], v127 offset:20480
	s_waitcnt lgkmcnt(14)
	v_mfma_f32_16x16x32_bf16 v[210:213], v[186:189], v[236:239], v[210:213]
	s_waitcnt lgkmcnt(12)
	v_mfma_f32_16x16x32_bf16 v[214:217], v[190:193], v[236:239], v[214:217]
	s_waitcnt lgkmcnt(10)
	v_mfma_f32_16x16x32_bf16 v[220:223], v[194:197], v[236:239], v[220:223]
	s_waitcnt lgkmcnt(8)
	v_mfma_f32_16x16x32_bf16 v[224:227], v[198:201], v[236:239], v[224:227]
	v_cvt_pk_bf16_f32 v240, v74, v75
	v_cvt_pk_bf16_f32 v241, v76, v77
	v_cvt_pk_bf16_f32 v242, v78, v79
	v_cvt_pk_bf16_f32 v243, v80, v81
	s_waitcnt lgkmcnt(7)
	ds_read_b64_tr_b16 v[186:187], v124 offset:22528
	ds_read_b64_tr_b16 v[188:189], v124 offset:24576
	ds_read_b64_tr_b16 v[190:191], v125 offset:22528
	ds_read_b64_tr_b16 v[192:193], v125 offset:24576
	ds_read_b64_tr_b16 v[194:195], v126 offset:22528
	ds_read_b64_tr_b16 v[196:197], v126 offset:24576
	ds_read_b64_tr_b16 v[198:199], v127 offset:22528
	ds_read_b64_tr_b16 v[200:201], v127 offset:24576
	s_waitcnt lgkmcnt(14)
	v_mfma_f32_16x16x32_bf16 v[210:213], v[202:205], v[240:243], v[210:213]
	s_waitcnt lgkmcnt(12)
	v_mfma_f32_16x16x32_bf16 v[214:217], v[206:209], v[240:243], v[214:217]
	s_waitcnt lgkmcnt(10)
	v_mfma_f32_16x16x32_bf16 v[220:223], v[228:231], v[240:243], v[220:223]
	s_waitcnt lgkmcnt(8)
	v_mfma_f32_16x16x32_bf16 v[224:227], v[232:235], v[240:243], v[224:227]
	v_cvt_pk_bf16_f32 v236, v82, v83
	v_cvt_pk_bf16_f32 v237, v84, v85
	v_cvt_pk_bf16_f32 v238, v86, v87
	v_cvt_pk_bf16_f32 v239, v88, v89
	s_waitcnt lgkmcnt(7)
	ds_read_b64_tr_b16 v[202:203], v124 offset:26624
	ds_read_b64_tr_b16 v[204:205], v124 offset:28672
	ds_read_b64_tr_b16 v[206:207], v125 offset:26624
	ds_read_b64_tr_b16 v[208:209], v125 offset:28672
	ds_read_b64_tr_b16 v[228:229], v126 offset:26624
	ds_read_b64_tr_b16 v[230:231], v126 offset:28672
	ds_read_b64_tr_b16 v[232:233], v127 offset:26624
	ds_read_b64_tr_b16 v[234:235], v127 offset:28672
	s_waitcnt lgkmcnt(14)
	v_mfma_f32_16x16x32_bf16 v[210:213], v[186:189], v[236:239], v[210:213]
	s_waitcnt lgkmcnt(12)
	v_mfma_f32_16x16x32_bf16 v[214:217], v[190:193], v[236:239], v[214:217]
	s_waitcnt lgkmcnt(10)
	v_mfma_f32_16x16x32_bf16 v[220:223], v[194:197], v[236:239], v[220:223]
	s_waitcnt lgkmcnt(8)
	v_mfma_f32_16x16x32_bf16 v[224:227], v[198:201], v[236:239], v[224:227]
	v_cvt_pk_bf16_f32 v240, v90, v91
	v_cvt_pk_bf16_f32 v241, v92, v93
	v_cvt_pk_bf16_f32 v242, v94, v95
	v_cvt_pk_bf16_f32 v243, v96, v97
	s_waitcnt lgkmcnt(7)
	ds_read_b64_tr_b16 v[186:187], v124 offset:30720
	ds_read_b64_tr_b16 v[188:189], v124 offset:32768
	ds_read_b64_tr_b16 v[190:191], v125 offset:30720
	ds_read_b64_tr_b16 v[192:193], v125 offset:32768
	ds_read_b64_tr_b16 v[194:195], v126 offset:30720
	ds_read_b64_tr_b16 v[196:197], v126 offset:32768
	ds_read_b64_tr_b16 v[198:199], v127 offset:30720
	ds_read_b64_tr_b16 v[200:201], v127 offset:32768
	s_waitcnt lgkmcnt(14)
	v_mfma_f32_16x16x32_bf16 v[210:213], v[202:205], v[240:243], v[210:213]
	s_waitcnt lgkmcnt(12)
	v_mfma_f32_16x16x32_bf16 v[214:217], v[206:209], v[240:243], v[214:217]
	s_waitcnt lgkmcnt(10)
	v_mfma_f32_16x16x32_bf16 v[220:223], v[228:231], v[240:243], v[220:223]
	s_waitcnt lgkmcnt(8)
	v_mfma_f32_16x16x32_bf16 v[224:227], v[232:235], v[240:243], v[224:227]
	v_cvt_pk_bf16_f32 v236, v98, v99
	v_cvt_pk_bf16_f32 v237, v100, v101
	v_cvt_pk_bf16_f32 v238, v102, v103
	v_cvt_pk_bf16_f32 v239, v104, v105
	s_waitcnt lgkmcnt(7)
; #define LAS __attribute__((address_space(3)))
; __device__ __forceinline__ unsigned pk2(float lo, float hi) { return pg8::cvt_pk_bf16(lo, hi); }
; __device__ __forceinline__ s16x4 vtr(const LAS unsigned char* p) { return __builtin_bit_cast(s16x4, __builtin_amdgcn_ds_read_tr16_b64_v4i16((LAS s16x4*)p)); }
; #define MFMA16(a, b, c) __builtin_amdgcn_mfma_f32_16x16x32_bf16((a), (b), (c), 0, 0, 0)
; __device__ __forceinline__ void pv_at(const LAS unsigned char* const (&vp)[4], int off, const f32x4& P0, const f32x4& P1, f32x4 (&O)[4]) {
;     v4u pw; pw.x = pk2(P0[0], P0[1]); pw.y = pk2(P0[2], P0[3]); pw.z = pk2(P1[0], P1[1]); pw.w = pk2(P1[2], P1[3]);
;     const bf16x8 pb = __builtin_bit_cast(bf16x8, pw);
; #pragma unroll
;     for (int db = 0; db < 4; ++db) {
;         const s16x4 lo = vtr(vp[db] + off), hi = vtr(vp[db] + off + 2048);
;         const bf16x8 vt = (bf16x8){lo[0], lo[1], lo[2], lo[3], hi[0], hi[1], hi[2], hi[3]};
;         O[db] = MFMA16(vt, pb, O[db]);
;     }
; }
; __device__ __forceinline__ void store_o(bf16* yrow, int g, float l, const f32x4 (&O)[4]) {
;     const float inv = 1.0f / xrow16_sum(l);
;     unsigned wx[4], wy[4];
; #pragma unroll
;     for (int db = 0; db < 4; ++db) { wx[db] = pk2(O[db][0] * inv, O[db][1] * inv); wy[db] = pk2(O[db][2] * inv, O[db][3] * inv); }
; #pragma unroll
;     for (int p = 0; p < 2; ++p) {
;         auto rx = __builtin_amdgcn_permlane16_swap(wx[2 * p], wx[2 * p + 1], false, false); wx[2 * p] = rx[0]; wx[2 * p + 1] = rx[1];
;         auto ry = __builtin_amdgcn_permlane16_swap(wy[2 * p], wy[2 * p + 1], false, false); wy[2 * p] = ry[0]; wy[2 * p + 1] = ry[1]; }
; #pragma unroll
;     for (int p = 0; p < 2; ++p) {
;         auto rx = __builtin_amdgcn_permlane32_swap(wx[p], wx[p + 2], false, false); wx[p] = rx[0]; wx[p + 2] = rx[1];
;         auto ry = __builtin_amdgcn_permlane32_swap(wy[p], wy[p + 2], false, false); wy[p] = ry[0]; wy[p + 2] = ry[1]; }
;     v4u lo = {wx[0], wy[0], wx[1], wy[1]}, hi = {wx[2], wy[2], wx[3], wy[3]};
;     *(v4u*)(yrow + 16 * g) = lo; *(v4u*)(yrow + 16 * g + 8) = hi;
	ds_read_b64_tr_b16 v[202:203], v124 offset:34816
	ds_read_b64_tr_b16 v[204:205], v124 offset:36864
	ds_read_b64_tr_b16 v[206:207], v125 offset:34816
	ds_read_b64_tr_b16 v[208:209], v125 offset:36864
	ds_read_b64_tr_b16 v[228:229], v126 offset:34816
	ds_read_b64_tr_b16 v[230:231], v126 offset:36864
	ds_read_b64_tr_b16 v[232:233], v127 offset:34816
	ds_read_b64_tr_b16 v[234:235], v127 offset:36864
	s_waitcnt lgkmcnt(14)
	v_mfma_f32_16x16x32_bf16 v[210:213], v[186:189], v[236:239], v[210:213]
	s_waitcnt lgkmcnt(12)
	v_mfma_f32_16x16x32_bf16 v[214:217], v[190:193], v[236:239], v[214:217]
	s_waitcnt lgkmcnt(10)
	v_mfma_f32_16x16x32_bf16 v[220:223], v[194:197], v[236:239], v[220:223]
	s_waitcnt lgkmcnt(8)
	v_mfma_f32_16x16x32_bf16 v[224:227], v[198:201], v[236:239], v[224:227]
	v_cvt_pk_bf16_f32 v240, v106, v107
	v_cvt_pk_bf16_f32 v241, v108, v109
	v_cvt_pk_bf16_f32 v242, v110, v111
	v_cvt_pk_bf16_f32 v243, v112, v113
	s_waitcnt lgkmcnt(7)
	ds_read_b64_tr_b16 v[186:187], v124 offset:38912
	ds_read_b64_tr_b16 v[188:189], v124 offset:40960
	ds_read_b64_tr_b16 v[190:191], v125 offset:38912
	ds_read_b64_tr_b16 v[192:193], v125 offset:40960
	ds_read_b64_tr_b16 v[194:195], v126 offset:38912
	ds_read_b64_tr_b16 v[196:197], v126 offset:40960
	ds_read_b64_tr_b16 v[198:199], v127 offset:38912
	ds_read_b64_tr_b16 v[200:201], v127 offset:40960
	s_waitcnt lgkmcnt(14)
	v_mfma_f32_16x16x32_bf16 v[210:213], v[202:205], v[240:243], v[210:213]
	s_waitcnt lgkmcnt(12)
	v_mfma_f32_16x16x32_bf16 v[214:217], v[206:209], v[240:243], v[214:217]
	s_waitcnt lgkmcnt(10)
	v_mfma_f32_16x16x32_bf16 v[220:223], v[228:231], v[240:243], v[220:223]
	s_waitcnt lgkmcnt(8)
	v_mfma_f32_16x16x32_bf16 v[224:227], v[232:235], v[240:243], v[224:227]
	v_cvt_pk_bf16_f32 v236, v114, v115
	v_cvt_pk_bf16_f32 v237, v116, v117
	v_mov_b32_e32 v238, 0
	v_mov_b32_e32 v239, 0
	s_nop 1
	s_waitcnt lgkmcnt(6)
	v_mfma_f32_16x16x32_bf16 v[210:213], v[186:189], v[236:239], v[210:213]
	s_waitcnt lgkmcnt(4)
	v_mfma_f32_16x16x32_bf16 v[214:217], v[190:193], v[236:239], v[214:217]
	s_waitcnt lgkmcnt(2)
	v_mfma_f32_16x16x32_bf16 v[220:223], v[194:197], v[236:239], v[220:223]
	s_waitcnt lgkmcnt(0)
	v_mfma_f32_16x16x32_bf16 v[224:227], v[198:201], v[236:239], v[224:227]
	v_mov_b32_e32 v219, v185
	s_nop 1
	v_permlane16_swap_b32_e32 v185, v219
	v_add_f32_e32 v185, v185, v219
	v_mov_b32_e32 v219, v185
	s_nop 1
	v_permlane32_swap_b32_e32 v185, v219
	v_add_f32_e32 v185, v185, v219
	v_div_scale_f32 v236, s[78:79], v185, v185, 1.0
	v_div_scale_f32 v237, vcc, 1.0, v185, 1.0
	v_rcp_f32_e32 v238, v236
	s_nop 0
	v_fma_f32 v239, -v236, v238, 1.0
	v_fmac_f32_e32 v238, v239, v238
	v_mul_f32_e32 v240, v237, v238
	v_fma_f32 v241, -v236, v240, v237
	v_fmac_f32_e32 v240, v241, v238
	v_fma_f32 v237, -v236, v240, v237
	v_div_fmas_f32 v237, v237, v238, v240
	v_div_fixup_f32 v244, v237, v185, 1.0
	v_mul_f32_e32 v240, v210, v244
	v_mul_f32_e32 v241, v211, v244
	v_mul_f32_e32 v242, v212, v244
	v_mul_f32_e32 v243, v213, v244
	v_cvt_pk_bf16_f32 v186, v240, v241
	v_cvt_pk_bf16_f32 v187, v242, v243
	v_mul_f32_e32 v240, v214, v244
	v_mul_f32_e32 v241, v215, v244
	v_mul_f32_e32 v242, v216, v244
	v_mul_f32_e32 v243, v217, v244
	v_cvt_pk_bf16_f32 v188, v240, v241
	v_cvt_pk_bf16_f32 v189, v242, v243
	v_mul_f32_e32 v240, v220, v244
	v_mul_f32_e32 v241, v221, v244
	v_mul_f32_e32 v242, v222, v244
	v_mul_f32_e32 v243, v223, v244
	v_cvt_pk_bf16_f32 v190, v240, v241
	v_cvt_pk_bf16_f32 v191, v242, v243
	v_mul_f32_e32 v240, v224, v244
	v_mul_f32_e32 v241, v225, v244
	v_mul_f32_e32 v242, v226, v244
	v_mul_f32_e32 v243, v227, v244
	v_cvt_pk_bf16_f32 v192, v240, v241
	v_cvt_pk_bf16_f32 v193, v242, v243
	s_nop 1
	v_permlane16_swap_b32_e32 v186, v188
	v_permlane16_swap_b32_e32 v187, v189
	v_permlane16_swap_b32_e32 v190, v192
	v_permlane16_swap_b32_e32 v191, v193
	s_nop 0
	v_permlane32_swap_b32_e32 v186, v190
	v_permlane32_swap_b32_e32 v187, v191
	v_permlane32_swap_b32_e32 v188, v192
	v_permlane32_swap_b32_e32 v189, v193
	v_add_u32_e32 v219, 0x1000, v128
	global_store_dwordx4 v219, v[186:189], s[82:83] offset:2048
	global_store_dwordx4 v219, v[190:193], s[82:83] offset:2064
	s_nop 1
	s_branch .LBB0_240
